# all s_setprio flips removed (GEMM K-loops); conv/rms load batches merged
# speedup vs baseline: 1.0283x; 1.0016x over previous
.LBB0_130:
	ds_read_b128 v[152:155], v148
	ds_read_b128 v[156:159], v148 offset:1024
	ds_read_b128 v[160:163], v148 offset:2048
	ds_read_b128 v[164:167], v148 offset:3072
	ds_read_b128 v[168:171], v149
	ds_read_b128 v[172:175], v149 offset:1024
	ds_read_b128 v[176:179], v149 offset:2048
	ds_read_b128 v[180:183], v149 offset:3072
	s_add_u32 s20, s16, s18
	s_addc_u32 s21, s17, s19
	s_add_u32 s20, s20, 0x100
	s_addc_u32 s21, s21, 0
	s_add_u32 s45, s42, s18
	s_addc_u32 s46, s43, s19
	s_cmpk_eq_i32 s18, 0x700
	s_cselect_b32 s21, s3, s21
	s_cselect_b32 s20, s2, s20
	s_cselect_b32 s47, s15, s46
	s_cselect_b32 s46, s14, s45
	v_lshl_add_u64 v[194:195], v[144:145], 0, s[18:19]
	s_add_i32 m0, s23, 0xc000
	ds_read_b128 v[186:189], v150
	ds_read_b128 v[190:193], v150 offset:1024
	ds_read_b128 v[196:199], v150 offset:2048
	ds_read_b128 v[200:203], v150 offset:3072
	ds_read_b128 v[204:207], v150 offset:4096
	ds_read_b128 v[208:211], v150 offset:5120
	ds_read_b128 v[212:215], v150 offset:6144
	ds_read_b128 v[216:219], v150 offset:7168
	global_load_lds_dwordx4 v[194:195], off
	v_lshl_add_u64 v[194:195], v[142:143], 0, s[18:19]
	s_add_i32 m0, s23, 0xe000
	s_nop 0
	global_load_lds_dwordx4 v[194:195], off
	s_waitcnt vmcnt(8)
	s_waitcnt lgkmcnt(0)
	s_barrier
	s_waitcnt lgkmcnt(0)
	v_mfma_f32_16x16x32_bf16 v[124:127], v[152:155], v[186:189], v[124:127]
	v_mfma_f32_16x16x32_bf16 v[116:119], v[160:163], v[186:189], v[116:119]
	v_mfma_f32_16x16x32_bf16 v[108:111], v[152:155], v[196:199], v[108:111]
	v_mfma_f32_16x16x32_bf16 v[100:103], v[160:163], v[196:199], v[100:103]
	v_mfma_f32_16x16x32_bf16 v[92:95], v[152:155], v[204:207], v[92:95]
	v_mfma_f32_16x16x32_bf16 v[84:87], v[160:163], v[204:207], v[84:87]
	v_mfma_f32_16x16x32_bf16 v[76:79], v[152:155], v[212:215], v[76:79]
	v_mfma_f32_16x16x32_bf16 v[68:71], v[160:163], v[212:215], v[68:71]
	v_mfma_f32_16x16x32_bf16 v[124:127], v[156:159], v[190:193], v[124:127]
	v_mfma_f32_16x16x32_bf16 v[116:119], v[164:167], v[190:193], v[116:119]
	v_mfma_f32_16x16x32_bf16 v[108:111], v[156:159], v[200:203], v[108:111]
	v_mfma_f32_16x16x32_bf16 v[100:103], v[164:167], v[200:203], v[100:103]
	v_mfma_f32_16x16x32_bf16 v[92:95], v[156:159], v[208:211], v[92:95]
	v_mfma_f32_16x16x32_bf16 v[84:87], v[164:167], v[208:211], v[84:87]
	v_mfma_f32_16x16x32_bf16 v[76:79], v[156:159], v[216:219], v[76:79]
	v_mfma_f32_16x16x32_bf16 v[68:71], v[164:167], v[216:219], v[68:71]
	v_mfma_f32_16x16x32_bf16 v[120:123], v[168:171], v[186:189], v[120:123]
	v_mfma_f32_16x16x32_bf16 v[112:115], v[176:179], v[186:189], v[112:115]
	v_mfma_f32_16x16x32_bf16 v[104:107], v[168:171], v[196:199], v[104:107]
	v_mfma_f32_16x16x32_bf16 v[96:99], v[176:179], v[196:199], v[96:99]
	v_mfma_f32_16x16x32_bf16 v[88:91], v[168:171], v[204:207], v[88:91]
	v_mfma_f32_16x16x32_bf16 v[80:83], v[176:179], v[204:207], v[80:83]
	v_mfma_f32_16x16x32_bf16 v[72:75], v[168:171], v[212:215], v[72:75]
	v_mfma_f32_16x16x32_bf16 v[64:67], v[176:179], v[212:215], v[64:67]
	v_mfma_f32_16x16x32_bf16 v[120:123], v[172:175], v[190:193], v[120:123]
	v_mfma_f32_16x16x32_bf16 v[112:115], v[180:183], v[190:193], v[112:115]
	v_mfma_f32_16x16x32_bf16 v[104:107], v[172:175], v[200:203], v[104:107]
	v_mfma_f32_16x16x32_bf16 v[96:99], v[180:183], v[200:203], v[96:99]
	v_mfma_f32_16x16x32_bf16 v[88:91], v[172:175], v[208:211], v[88:91]
	v_mfma_f32_16x16x32_bf16 v[80:83], v[180:183], v[208:211], v[80:83]
	v_mfma_f32_16x16x32_bf16 v[72:75], v[172:175], v[216:219], v[72:75]
	v_mfma_f32_16x16x32_bf16 v[64:67], v[180:183], v[216:219], v[64:67]
	s_barrier
	s_add_i32 s45, s30, s22
	v_lshl_add_u64 v[194:195], s[46:47], 0, v[132:133]
	s_mov_b32 m0, s45
	ds_read_b128 v[186:189], v150 offset:16384
	ds_read_b128 v[190:193], v150 offset:17408
	ds_read_b128 v[196:199], v150 offset:18432
	ds_read_b128 v[200:203], v150 offset:19456
	ds_read_b128 v[204:207], v150 offset:20480
	ds_read_b128 v[208:211], v150 offset:21504
	ds_read_b128 v[212:215], v150 offset:22528
	ds_read_b128 v[216:219], v150 offset:23552
	global_load_lds_dwordx4 v[194:195], off
	s_add_i32 m0, s45, 0x2000
	v_lshl_add_u64 v[220:221], s[46:47], 0, v[130:131]
	s_add_u32 s46, s46, s4
	s_addc_u32 s47, s47, s5
	s_add_i32 s45, s31, s22
	global_load_lds_dwordx4 v[220:221], off
	v_lshl_add_u64 v[222:223], s[46:47], 0, v[132:133]
	s_mov_b32 m0, s45
	v_lshl_add_u64 v[224:225], s[46:47], 0, v[130:131]
	global_load_lds_dwordx4 v[222:223], off
	s_add_i32 m0, s45, 0x2000
	v_lshl_add_u64 v[226:227], s[20:21], 0, v[132:133]
	global_load_lds_dwordx4 v[224:225], off
	s_mov_b32 m0, s23
	v_lshl_add_u64 v[228:229], s[20:21], 0, v[130:131]
	global_load_lds_dwordx4 v[226:227], off
	s_mov_b32 m0, s24
	s_nop 0
	global_load_lds_dwordx4 v[228:229], off
	s_waitcnt vmcnt(8)
	s_waitcnt lgkmcnt(0)
	s_barrier
	s_waitcnt lgkmcnt(0)
	v_mfma_f32_16x16x32_bf16 v[60:63], v[152:155], v[186:189], v[60:63]
	v_mfma_f32_16x16x32_bf16 v[52:55], v[160:163], v[186:189], v[52:55]
	v_mfma_f32_16x16x32_bf16 v[44:47], v[152:155], v[196:199], v[44:47]
	v_mfma_f32_16x16x32_bf16 v[36:39], v[160:163], v[196:199], v[36:39]
	v_mfma_f32_16x16x32_bf16 v[28:31], v[152:155], v[204:207], v[28:31]
	v_mfma_f32_16x16x32_bf16 v[20:23], v[160:163], v[204:207], v[20:23]
	v_mfma_f32_16x16x32_bf16 v[12:15], v[152:155], v[212:215], v[12:15]
	v_mfma_f32_16x16x32_bf16 v[4:7], v[160:163], v[212:215], v[4:7]
	v_mfma_f32_16x16x32_bf16 v[60:63], v[156:159], v[190:193], v[60:63]
	v_mfma_f32_16x16x32_bf16 v[52:55], v[164:167], v[190:193], v[52:55]
	v_mfma_f32_16x16x32_bf16 v[44:47], v[156:159], v[200:203], v[44:47]
	v_mfma_f32_16x16x32_bf16 v[36:39], v[164:167], v[200:203], v[36:39]
	v_mfma_f32_16x16x32_bf16 v[28:31], v[156:159], v[208:211], v[28:31]
	v_mfma_f32_16x16x32_bf16 v[20:23], v[164:167], v[208:211], v[20:23]
	v_mfma_f32_16x16x32_bf16 v[12:15], v[156:159], v[216:219], v[12:15]
	v_mfma_f32_16x16x32_bf16 v[4:7], v[164:167], v[216:219], v[4:7]
	v_mfma_f32_16x16x32_bf16 v[56:59], v[168:171], v[186:189], v[56:59]
	v_mfma_f32_16x16x32_bf16 v[48:51], v[176:179], v[186:189], v[48:51]
	v_mfma_f32_16x16x32_bf16 v[40:43], v[168:171], v[196:199], v[40:43]
	v_mfma_f32_16x16x32_bf16 v[32:35], v[176:179], v[196:199], v[32:35]
	v_mfma_f32_16x16x32_bf16 v[24:27], v[168:171], v[204:207], v[24:27]
	v_mfma_f32_16x16x32_bf16 v[16:19], v[176:179], v[204:207], v[16:19]
	v_mfma_f32_16x16x32_bf16 v[8:11], v[168:171], v[212:215], v[8:11]
	v_mfma_f32_16x16x32_bf16 v[0:3], v[176:179], v[212:215], v[0:3]
	v_mfma_f32_16x16x32_bf16 v[56:59], v[172:175], v[190:193], v[56:59]
	v_mfma_f32_16x16x32_bf16 v[48:51], v[180:183], v[190:193], v[48:51]
	v_mfma_f32_16x16x32_bf16 v[40:43], v[172:175], v[200:203], v[40:43]
	v_mfma_f32_16x16x32_bf16 v[32:35], v[180:183], v[200:203], v[32:35]
	v_mfma_f32_16x16x32_bf16 v[24:27], v[172:175], v[208:211], v[24:27]
	v_mfma_f32_16x16x32_bf16 v[16:19], v[180:183], v[208:211], v[16:19]
	v_mfma_f32_16x16x32_bf16 v[8:11], v[172:175], v[216:219], v[8:11]
	v_mfma_f32_16x16x32_bf16 v[0:3], v[180:183], v[216:219], v[0:3]
	s_barrier
	s_add_i32 s45, 0, 0x18000
	v_add_u32_e32 v151, s45, v146
	s_add_i32 s46, 0, 0x1c000
	ds_read_b128 v[152:155], v151
	ds_read_b128 v[156:159], v151 offset:1024
	ds_read_b128 v[160:163], v151 offset:2048
	ds_read_b128 v[164:167], v151 offset:3072
	v_add_u32_e32 v151, s46, v146
	ds_read_b128 v[168:171], v151
	ds_read_b128 v[172:175], v151 offset:1024
	ds_read_b128 v[176:179], v151 offset:2048
	ds_read_b128 v[180:183], v151 offset:3072
	s_add_u32 s20, s20, s4
	s_addc_u32 s21, s21, s5
	s_mov_b32 m0, s25
	v_lshl_add_u64 v[230:231], s[20:21], 0, v[132:133]
	ds_read_b128 v[186:189], v150 offset:32768
	ds_read_b128 v[190:193], v150 offset:33792
	ds_read_b128 v[196:199], v150 offset:34816
	ds_read_b128 v[200:203], v150 offset:35840
	ds_read_b128 v[204:207], v150 offset:36864
	ds_read_b128 v[208:211], v150 offset:37888
	ds_read_b128 v[212:215], v150 offset:38912
	ds_read_b128 v[216:219], v150 offset:39936
	global_load_lds_dwordx4 v[230:231], off
	v_lshl_add_u64 v[230:231], s[20:21], 0, v[130:131]
	s_mov_b32 m0, s26
	s_nop 0
	global_load_lds_dwordx4 v[230:231], off
	s_waitcnt vmcnt(8)
	s_waitcnt lgkmcnt(0)
	s_barrier
	s_waitcnt lgkmcnt(0)
	v_mfma_f32_16x16x32_bf16 v[124:127], v[152:155], v[186:189], v[124:127]
	v_mfma_f32_16x16x32_bf16 v[116:119], v[160:163], v[186:189], v[116:119]
	v_mfma_f32_16x16x32_bf16 v[108:111], v[152:155], v[196:199], v[108:111]
	v_mfma_f32_16x16x32_bf16 v[100:103], v[160:163], v[196:199], v[100:103]
	v_mfma_f32_16x16x32_bf16 v[92:95], v[152:155], v[204:207], v[92:95]
	v_mfma_f32_16x16x32_bf16 v[84:87], v[160:163], v[204:207], v[84:87]
	v_mfma_f32_16x16x32_bf16 v[76:79], v[152:155], v[212:215], v[76:79]
	v_mfma_f32_16x16x32_bf16 v[68:71], v[160:163], v[212:215], v[68:71]
	v_mfma_f32_16x16x32_bf16 v[124:127], v[156:159], v[190:193], v[124:127]
	v_mfma_f32_16x16x32_bf16 v[116:119], v[164:167], v[190:193], v[116:119]
	v_mfma_f32_16x16x32_bf16 v[108:111], v[156:159], v[200:203], v[108:111]
	v_mfma_f32_16x16x32_bf16 v[100:103], v[164:167], v[200:203], v[100:103]
	v_mfma_f32_16x16x32_bf16 v[92:95], v[156:159], v[208:211], v[92:95]
	v_mfma_f32_16x16x32_bf16 v[84:87], v[164:167], v[208:211], v[84:87]
	v_mfma_f32_16x16x32_bf16 v[76:79], v[156:159], v[216:219], v[76:79]
	v_mfma_f32_16x16x32_bf16 v[68:71], v[164:167], v[216:219], v[68:71]
	v_mfma_f32_16x16x32_bf16 v[120:123], v[168:171], v[186:189], v[120:123]
	v_mfma_f32_16x16x32_bf16 v[112:115], v[176:179], v[186:189], v[112:115]
	v_mfma_f32_16x16x32_bf16 v[104:107], v[168:171], v[196:199], v[104:107]
	v_mfma_f32_16x16x32_bf16 v[96:99], v[176:179], v[196:199], v[96:99]
	v_mfma_f32_16x16x32_bf16 v[88:91], v[168:171], v[204:207], v[88:91]
	v_mfma_f32_16x16x32_bf16 v[80:83], v[176:179], v[204:207], v[80:83]
	v_mfma_f32_16x16x32_bf16 v[72:75], v[168:171], v[212:215], v[72:75]
	v_mfma_f32_16x16x32_bf16 v[64:67], v[176:179], v[212:215], v[64:67]
	v_mfma_f32_16x16x32_bf16 v[120:123], v[172:175], v[190:193], v[120:123]
	v_mfma_f32_16x16x32_bf16 v[112:115], v[180:183], v[190:193], v[112:115]
	v_mfma_f32_16x16x32_bf16 v[104:107], v[172:175], v[200:203], v[104:107]
	v_mfma_f32_16x16x32_bf16 v[96:99], v[180:183], v[200:203], v[96:99]
	v_mfma_f32_16x16x32_bf16 v[88:91], v[172:175], v[208:211], v[88:91]
	v_mfma_f32_16x16x32_bf16 v[80:83], v[180:183], v[208:211], v[80:83]
	v_mfma_f32_16x16x32_bf16 v[72:75], v[172:175], v[216:219], v[72:75]
	v_mfma_f32_16x16x32_bf16 v[64:67], v[180:183], v[216:219], v[64:67]
	s_barrier
	s_add_i32 s20, s45, s22
	v_lshl_add_u64 v[194:195], v[194:195], 0, s[10:11]
	s_mov_b32 m0, s20
	ds_read_b128 v[186:189], v150 offset:49152
	ds_read_b128 v[190:193], v150 offset:50176
	ds_read_b128 v[196:199], v150 offset:51200
	ds_read_b128 v[200:203], v150 offset:52224
	ds_read_b128 v[204:207], v150 offset:53248
	ds_read_b128 v[208:211], v150 offset:54272
	ds_read_b128 v[212:215], v150 offset:55296
	ds_read_b128 v[216:219], v150 offset:56320
	global_load_lds_dwordx4 v[194:195], off
	v_lshl_add_u64 v[194:195], v[220:221], 0, s[10:11]
	s_add_i32 m0, s20, 0x2000
	s_add_i32 s20, s46, s22
	global_load_lds_dwordx4 v[194:195], off
	v_lshl_add_u64 v[194:195], v[222:223], 0, s[10:11]
	s_mov_b32 m0, s20
	s_nop 0
	global_load_lds_dwordx4 v[194:195], off
	v_lshl_add_u64 v[194:195], v[224:225], 0, s[10:11]
	s_add_i32 m0, s20, 0x2000
	s_nop 0
	global_load_lds_dwordx4 v[194:195], off
	v_lshl_add_u64 v[194:195], v[226:227], 0, s[10:11]
	s_mov_b32 m0, s28
	s_nop 0
	global_load_lds_dwordx4 v[194:195], off
	v_lshl_add_u64 v[194:195], v[228:229], 0, s[10:11]
	s_mov_b32 m0, s29
	s_nop 0
	global_load_lds_dwordx4 v[194:195], off
	s_waitcnt vmcnt(8)
	s_waitcnt lgkmcnt(0)
	s_barrier
	s_waitcnt lgkmcnt(0)
	v_mfma_f32_16x16x32_bf16 v[60:63], v[152:155], v[186:189], v[60:63]
	v_mfma_f32_16x16x32_bf16 v[52:55], v[160:163], v[186:189], v[52:55]
	v_mfma_f32_16x16x32_bf16 v[44:47], v[152:155], v[196:199], v[44:47]
	v_mfma_f32_16x16x32_bf16 v[36:39], v[160:163], v[196:199], v[36:39]
	v_mfma_f32_16x16x32_bf16 v[28:31], v[152:155], v[204:207], v[28:31]
	v_mfma_f32_16x16x32_bf16 v[20:23], v[160:163], v[204:207], v[20:23]
	v_mfma_f32_16x16x32_bf16 v[12:15], v[152:155], v[212:215], v[12:15]
	v_mfma_f32_16x16x32_bf16 v[4:7], v[160:163], v[212:215], v[4:7]
	v_mfma_f32_16x16x32_bf16 v[60:63], v[156:159], v[190:193], v[60:63]
	v_mfma_f32_16x16x32_bf16 v[52:55], v[164:167], v[190:193], v[52:55]
	v_mfma_f32_16x16x32_bf16 v[44:47], v[156:159], v[200:203], v[44:47]
	v_mfma_f32_16x16x32_bf16 v[36:39], v[164:167], v[200:203], v[36:39]
	v_mfma_f32_16x16x32_bf16 v[28:31], v[156:159], v[208:211], v[28:31]
	v_mfma_f32_16x16x32_bf16 v[20:23], v[164:167], v[208:211], v[20:23]
	v_mfma_f32_16x16x32_bf16 v[12:15], v[156:159], v[216:219], v[12:15]
	v_mfma_f32_16x16x32_bf16 v[4:7], v[164:167], v[216:219], v[4:7]
	v_mfma_f32_16x16x32_bf16 v[56:59], v[168:171], v[186:189], v[56:59]
	v_mfma_f32_16x16x32_bf16 v[48:51], v[176:179], v[186:189], v[48:51]
	v_mfma_f32_16x16x32_bf16 v[40:43], v[168:171], v[196:199], v[40:43]
	v_mfma_f32_16x16x32_bf16 v[32:35], v[176:179], v[196:199], v[32:35]
	v_mfma_f32_16x16x32_bf16 v[24:27], v[168:171], v[204:207], v[24:27]
	v_mfma_f32_16x16x32_bf16 v[16:19], v[176:179], v[204:207], v[16:19]
	v_mfma_f32_16x16x32_bf16 v[8:11], v[168:171], v[212:215], v[8:11]
	v_mfma_f32_16x16x32_bf16 v[0:3], v[176:179], v[212:215], v[0:3]
	v_mfma_f32_16x16x32_bf16 v[56:59], v[172:175], v[190:193], v[56:59]
	v_mfma_f32_16x16x32_bf16 v[48:51], v[180:183], v[190:193], v[48:51]
	v_mfma_f32_16x16x32_bf16 v[40:43], v[172:175], v[200:203], v[40:43]
	v_mfma_f32_16x16x32_bf16 v[32:35], v[180:183], v[200:203], v[32:35]
	v_mfma_f32_16x16x32_bf16 v[24:27], v[172:175], v[208:211], v[24:27]
	v_mfma_f32_16x16x32_bf16 v[16:19], v[180:183], v[208:211], v[16:19]
	v_mfma_f32_16x16x32_bf16 v[8:11], v[172:175], v[216:219], v[8:11]
	v_mfma_f32_16x16x32_bf16 v[0:3], v[180:183], v[216:219], v[0:3]
	s_barrier
	s_add_i32 s44, s44, 2
	s_add_u32 s18, s18, 0x100
	s_addc_u32 s19, s19, 0
	s_cmp_gt_u32 s44, 13
	s_cbranch_scc0 .LBB0_130
	s_and_b64 vcc, exec, s[12:13]
	s_cbranch_vccz .LBB0_133
	s_barrier

.LBB0_302:
	ds_read_b128 v[148:151], v157
	ds_read_b128 v[160:163], v157 offset:1024
	ds_read_b128 v[164:167], v157 offset:2048
	ds_read_b128 v[168:171], v157 offset:3072
	ds_read_b128 v[172:175], v158
	ds_read_b128 v[176:179], v158 offset:1024
	ds_read_b128 v[180:183], v158 offset:2048
	ds_read_b128 v[186:189], v158 offset:3072
	s_add_u32 s20, s16, s18
	s_addc_u32 s21, s17, s19
	s_add_u32 s20, s20, 0x100
	s_addc_u32 s21, s21, 0
	s_add_u32 s47, s44, s18
	s_addc_u32 s48, s45, s19
	s_cmpk_eq_i32 s18, 0x1500
	s_cselect_b32 s21, s3, s21
	s_cselect_b32 s20, s2, s20
	s_cselect_b32 s49, s15, s48
	s_cselect_b32 s48, s14, s47
	s_mov_b32 m0, s33
	v_lshl_add_u64 v[224:225], v[144:145], 0, s[18:19]
	ds_read_b128 v[190:193], v159
	ds_read_b128 v[196:199], v159 offset:1024
	ds_read_b128 v[200:203], v159 offset:2048
	ds_read_b128 v[204:207], v159 offset:3072
	ds_read_b128 v[208:211], v159 offset:4096
	ds_read_b128 v[212:215], v159 offset:5120
	ds_read_b128 v[216:219], v159 offset:6144
	ds_read_b128 v[220:223], v159 offset:7168
	global_load_lds_dwordx4 v[224:225], off
	v_lshl_add_u64 v[224:225], v[146:147], 0, s[18:19]
	s_mov_b32 m0, s36
	s_nop 0
	global_load_lds_dwordx4 v[224:225], off
	s_waitcnt vmcnt(8)
	s_waitcnt lgkmcnt(0)
	s_barrier
	s_waitcnt lgkmcnt(0)
	v_mfma_f32_16x16x32_bf16 v[124:127], v[148:151], v[190:193], v[124:127]
	v_mfma_f32_16x16x32_bf16 v[120:123], v[164:167], v[190:193], v[120:123]
	v_mfma_f32_16x16x32_bf16 v[108:111], v[148:151], v[200:203], v[108:111]
	v_mfma_f32_16x16x32_bf16 v[104:107], v[164:167], v[200:203], v[104:107]
	v_mfma_f32_16x16x32_bf16 v[92:95], v[148:151], v[208:211], v[92:95]
	v_mfma_f32_16x16x32_bf16 v[88:91], v[164:167], v[208:211], v[88:91]
	v_mfma_f32_16x16x32_bf16 v[76:79], v[148:151], v[216:219], v[76:79]
	v_mfma_f32_16x16x32_bf16 v[72:75], v[164:167], v[216:219], v[72:75]
	v_mfma_f32_16x16x32_bf16 v[124:127], v[160:163], v[196:199], v[124:127]
	v_mfma_f32_16x16x32_bf16 v[120:123], v[168:171], v[196:199], v[120:123]
	v_mfma_f32_16x16x32_bf16 v[108:111], v[160:163], v[204:207], v[108:111]
	v_mfma_f32_16x16x32_bf16 v[104:107], v[168:171], v[204:207], v[104:107]
	v_mfma_f32_16x16x32_bf16 v[92:95], v[160:163], v[212:215], v[92:95]
	v_mfma_f32_16x16x32_bf16 v[88:91], v[168:171], v[212:215], v[88:91]
	v_mfma_f32_16x16x32_bf16 v[76:79], v[160:163], v[220:223], v[76:79]
	v_mfma_f32_16x16x32_bf16 v[72:75], v[168:171], v[220:223], v[72:75]
	v_mfma_f32_16x16x32_bf16 v[116:119], v[172:175], v[190:193], v[116:119]
	v_mfma_f32_16x16x32_bf16 v[112:115], v[180:183], v[190:193], v[112:115]
	v_mfma_f32_16x16x32_bf16 v[100:103], v[172:175], v[200:203], v[100:103]
	v_mfma_f32_16x16x32_bf16 v[96:99], v[180:183], v[200:203], v[96:99]
	v_mfma_f32_16x16x32_bf16 v[84:87], v[172:175], v[208:211], v[84:87]
	v_mfma_f32_16x16x32_bf16 v[80:83], v[180:183], v[208:211], v[80:83]
	v_mfma_f32_16x16x32_bf16 v[68:71], v[172:175], v[216:219], v[68:71]
	v_mfma_f32_16x16x32_bf16 v[64:67], v[180:183], v[216:219], v[64:67]
	v_mfma_f32_16x16x32_bf16 v[116:119], v[176:179], v[196:199], v[116:119]
	v_mfma_f32_16x16x32_bf16 v[112:115], v[186:189], v[196:199], v[112:115]
	v_mfma_f32_16x16x32_bf16 v[100:103], v[176:179], v[204:207], v[100:103]
	v_mfma_f32_16x16x32_bf16 v[96:99], v[186:189], v[204:207], v[96:99]
	v_mfma_f32_16x16x32_bf16 v[84:87], v[176:179], v[212:215], v[84:87]
	v_mfma_f32_16x16x32_bf16 v[80:83], v[186:189], v[212:215], v[80:83]
	v_mfma_f32_16x16x32_bf16 v[68:71], v[176:179], v[220:223], v[68:71]
	v_mfma_f32_16x16x32_bf16 v[64:67], v[186:189], v[220:223], v[64:67]
	s_barrier
	s_mov_b32 m0, s37
	v_lshl_add_u64 v[224:225], s[48:49], 0, v[130:131]
	ds_read_b128 v[190:193], v159 offset:16384
	ds_read_b128 v[196:199], v159 offset:17408
	ds_read_b128 v[200:203], v159 offset:18432
	ds_read_b128 v[204:207], v159 offset:19456
	ds_read_b128 v[208:211], v159 offset:20480
	ds_read_b128 v[212:215], v159 offset:21504
	ds_read_b128 v[216:219], v159 offset:22528
	ds_read_b128 v[220:223], v159 offset:23552
	global_load_lds_dwordx4 v[224:225], off
	s_add_i32 m0, s37, 0x2000
	v_lshl_add_u64 v[226:227], s[48:49], 0, v[132:133]
	s_add_u32 s48, s48, s4
	s_addc_u32 s49, s49, s5
	s_add_i32 s47, s30, s22
	global_load_lds_dwordx4 v[226:227], off
	v_lshl_add_u64 v[228:229], s[48:49], 0, v[130:131]
	s_mov_b32 m0, s47
	v_lshl_add_u64 v[230:231], s[48:49], 0, v[132:133]
	global_load_lds_dwordx4 v[228:229], off
	s_add_i32 m0, s47, 0x2000
	v_lshl_add_u64 v[232:233], s[20:21], 0, v[130:131]
	global_load_lds_dwordx4 v[230:231], off
	s_mov_b32 m0, s23
	v_lshl_add_u64 v[234:235], s[20:21], 0, v[132:133]
	global_load_lds_dwordx4 v[232:233], off
	s_mov_b32 m0, s24
	s_nop 0
	global_load_lds_dwordx4 v[234:235], off
	s_waitcnt vmcnt(8)
	s_waitcnt lgkmcnt(0)
	s_barrier
	s_waitcnt lgkmcnt(0)
	v_mfma_f32_16x16x32_bf16 v[60:63], v[148:151], v[190:193], v[60:63]
	v_mfma_f32_16x16x32_bf16 v[56:59], v[164:167], v[190:193], v[56:59]
	v_mfma_f32_16x16x32_bf16 v[44:47], v[148:151], v[200:203], v[44:47]
	v_mfma_f32_16x16x32_bf16 v[40:43], v[164:167], v[200:203], v[40:43]
	v_mfma_f32_16x16x32_bf16 v[28:31], v[148:151], v[208:211], v[28:31]
	v_mfma_f32_16x16x32_bf16 v[24:27], v[164:167], v[208:211], v[24:27]
	v_mfma_f32_16x16x32_bf16 v[12:15], v[148:151], v[216:219], v[12:15]
	v_mfma_f32_16x16x32_bf16 v[8:11], v[164:167], v[216:219], v[8:11]
	v_mfma_f32_16x16x32_bf16 v[60:63], v[160:163], v[196:199], v[60:63]
	v_mfma_f32_16x16x32_bf16 v[56:59], v[168:171], v[196:199], v[56:59]
	v_mfma_f32_16x16x32_bf16 v[44:47], v[160:163], v[204:207], v[44:47]
	v_mfma_f32_16x16x32_bf16 v[40:43], v[168:171], v[204:207], v[40:43]
	v_mfma_f32_16x16x32_bf16 v[28:31], v[160:163], v[212:215], v[28:31]
	v_mfma_f32_16x16x32_bf16 v[24:27], v[168:171], v[212:215], v[24:27]
	v_mfma_f32_16x16x32_bf16 v[12:15], v[160:163], v[220:223], v[12:15]
	v_mfma_f32_16x16x32_bf16 v[8:11], v[168:171], v[220:223], v[8:11]
	v_mfma_f32_16x16x32_bf16 v[52:55], v[172:175], v[190:193], v[52:55]
	v_mfma_f32_16x16x32_bf16 v[48:51], v[180:183], v[190:193], v[48:51]
	v_mfma_f32_16x16x32_bf16 v[36:39], v[172:175], v[200:203], v[36:39]
	v_mfma_f32_16x16x32_bf16 v[32:35], v[180:183], v[200:203], v[32:35]
	v_mfma_f32_16x16x32_bf16 v[20:23], v[172:175], v[208:211], v[20:23]
	v_mfma_f32_16x16x32_bf16 v[16:19], v[180:183], v[208:211], v[16:19]
	v_mfma_f32_16x16x32_bf16 v[4:7], v[172:175], v[216:219], v[4:7]
	v_mfma_f32_16x16x32_bf16 v[0:3], v[180:183], v[216:219], v[0:3]
	v_mfma_f32_16x16x32_bf16 v[52:55], v[176:179], v[196:199], v[52:55]
	v_mfma_f32_16x16x32_bf16 v[48:51], v[186:189], v[196:199], v[48:51]
	v_mfma_f32_16x16x32_bf16 v[36:39], v[176:179], v[204:207], v[36:39]
	v_mfma_f32_16x16x32_bf16 v[32:35], v[186:189], v[204:207], v[32:35]
	v_mfma_f32_16x16x32_bf16 v[20:23], v[176:179], v[212:215], v[20:23]
	v_mfma_f32_16x16x32_bf16 v[16:19], v[186:189], v[212:215], v[16:19]
	v_mfma_f32_16x16x32_bf16 v[4:7], v[176:179], v[220:223], v[4:7]
	v_mfma_f32_16x16x32_bf16 v[0:3], v[186:189], v[220:223], v[0:3]
	s_barrier
	s_add_i32 s47, 0, 0x18000
	v_add_u32_e32 v134, s47, v152
	s_add_i32 s48, 0, 0x1c000
	ds_read_b128 v[148:151], v134
	ds_read_b128 v[160:163], v134 offset:1024
	ds_read_b128 v[164:167], v134 offset:2048
	ds_read_b128 v[168:171], v134 offset:3072
	v_add_u32_e32 v134, s48, v152
	ds_read_b128 v[172:175], v134
	ds_read_b128 v[176:179], v134 offset:1024
	ds_read_b128 v[180:183], v134 offset:2048
	ds_read_b128 v[186:189], v134 offset:3072
	s_add_u32 s20, s20, s4
	s_addc_u32 s21, s21, s5
	s_mov_b32 m0, s25
	v_lshl_add_u64 v[236:237], s[20:21], 0, v[130:131]
	ds_read_b128 v[190:193], v159 offset:32768
	ds_read_b128 v[196:199], v159 offset:33792
	ds_read_b128 v[200:203], v159 offset:34816
	ds_read_b128 v[204:207], v159 offset:35840
	ds_read_b128 v[208:211], v159 offset:36864
	ds_read_b128 v[212:215], v159 offset:37888
	ds_read_b128 v[216:219], v159 offset:38912
	ds_read_b128 v[220:223], v159 offset:39936
	global_load_lds_dwordx4 v[236:237], off
	v_lshl_add_u64 v[236:237], s[20:21], 0, v[132:133]
	s_mov_b32 m0, s26
	s_nop 0
	global_load_lds_dwordx4 v[236:237], off
	s_waitcnt vmcnt(8)
	s_waitcnt lgkmcnt(0)
	s_barrier
	s_waitcnt lgkmcnt(0)
	v_mfma_f32_16x16x32_bf16 v[124:127], v[148:151], v[190:193], v[124:127]
	v_mfma_f32_16x16x32_bf16 v[120:123], v[164:167], v[190:193], v[120:123]
	v_mfma_f32_16x16x32_bf16 v[108:111], v[148:151], v[200:203], v[108:111]
	v_mfma_f32_16x16x32_bf16 v[104:107], v[164:167], v[200:203], v[104:107]
	v_mfma_f32_16x16x32_bf16 v[92:95], v[148:151], v[208:211], v[92:95]
	v_mfma_f32_16x16x32_bf16 v[88:91], v[164:167], v[208:211], v[88:91]
	v_mfma_f32_16x16x32_bf16 v[76:79], v[148:151], v[216:219], v[76:79]
	v_mfma_f32_16x16x32_bf16 v[72:75], v[164:167], v[216:219], v[72:75]
	v_mfma_f32_16x16x32_bf16 v[124:127], v[160:163], v[196:199], v[124:127]
	v_mfma_f32_16x16x32_bf16 v[120:123], v[168:171], v[196:199], v[120:123]
	v_mfma_f32_16x16x32_bf16 v[108:111], v[160:163], v[204:207], v[108:111]
	v_mfma_f32_16x16x32_bf16 v[104:107], v[168:171], v[204:207], v[104:107]
	v_mfma_f32_16x16x32_bf16 v[92:95], v[160:163], v[212:215], v[92:95]
	v_mfma_f32_16x16x32_bf16 v[88:91], v[168:171], v[212:215], v[88:91]
	v_mfma_f32_16x16x32_bf16 v[76:79], v[160:163], v[220:223], v[76:79]
	v_mfma_f32_16x16x32_bf16 v[72:75], v[168:171], v[220:223], v[72:75]
	v_mfma_f32_16x16x32_bf16 v[116:119], v[172:175], v[190:193], v[116:119]
	v_mfma_f32_16x16x32_bf16 v[112:115], v[180:183], v[190:193], v[112:115]
	v_mfma_f32_16x16x32_bf16 v[100:103], v[172:175], v[200:203], v[100:103]
	v_mfma_f32_16x16x32_bf16 v[96:99], v[180:183], v[200:203], v[96:99]
	v_mfma_f32_16x16x32_bf16 v[84:87], v[172:175], v[208:211], v[84:87]
	v_mfma_f32_16x16x32_bf16 v[80:83], v[180:183], v[208:211], v[80:83]
	v_mfma_f32_16x16x32_bf16 v[68:71], v[172:175], v[216:219], v[68:71]
	v_mfma_f32_16x16x32_bf16 v[64:67], v[180:183], v[216:219], v[64:67]
	v_mfma_f32_16x16x32_bf16 v[116:119], v[176:179], v[196:199], v[116:119]
	v_mfma_f32_16x16x32_bf16 v[112:115], v[186:189], v[196:199], v[112:115]
	v_mfma_f32_16x16x32_bf16 v[100:103], v[176:179], v[204:207], v[100:103]
	v_mfma_f32_16x16x32_bf16 v[96:99], v[186:189], v[204:207], v[96:99]
	v_mfma_f32_16x16x32_bf16 v[84:87], v[176:179], v[212:215], v[84:87]
	v_mfma_f32_16x16x32_bf16 v[80:83], v[186:189], v[212:215], v[80:83]
	v_mfma_f32_16x16x32_bf16 v[68:71], v[176:179], v[220:223], v[68:71]
	v_mfma_f32_16x16x32_bf16 v[64:67], v[186:189], v[220:223], v[64:67]
	s_barrier
	s_add_i32 s20, s47, s22
	v_lshl_add_u64 v[224:225], v[224:225], 0, s[10:11]
	s_mov_b32 m0, s20
	ds_read_b128 v[190:193], v159 offset:49152
	ds_read_b128 v[196:199], v159 offset:50176
	ds_read_b128 v[200:203], v159 offset:51200
	ds_read_b128 v[204:207], v159 offset:52224
	ds_read_b128 v[208:211], v159 offset:53248
	ds_read_b128 v[212:215], v159 offset:54272
	ds_read_b128 v[216:219], v159 offset:55296
	ds_read_b128 v[220:223], v159 offset:56320
	global_load_lds_dwordx4 v[224:225], off
	v_lshl_add_u64 v[224:225], v[226:227], 0, s[10:11]
	s_add_i32 m0, s20, 0x2000
	s_add_i32 s20, s48, s22
	global_load_lds_dwordx4 v[224:225], off
	v_lshl_add_u64 v[224:225], v[228:229], 0, s[10:11]
	s_mov_b32 m0, s20
	s_nop 0
	global_load_lds_dwordx4 v[224:225], off
	v_lshl_add_u64 v[224:225], v[230:231], 0, s[10:11]
	s_add_i32 m0, s20, 0x2000
	s_nop 0
	global_load_lds_dwordx4 v[224:225], off
	v_lshl_add_u64 v[224:225], v[232:233], 0, s[10:11]
	s_mov_b32 m0, s28
	s_nop 0
	global_load_lds_dwordx4 v[224:225], off
	v_lshl_add_u64 v[224:225], v[234:235], 0, s[10:11]
	s_mov_b32 m0, s29
	s_nop 0
	global_load_lds_dwordx4 v[224:225], off
	s_waitcnt vmcnt(8)
	s_waitcnt lgkmcnt(0)
	s_barrier
	s_waitcnt lgkmcnt(0)
	v_mfma_f32_16x16x32_bf16 v[60:63], v[148:151], v[190:193], v[60:63]
	v_mfma_f32_16x16x32_bf16 v[56:59], v[164:167], v[190:193], v[56:59]
	v_mfma_f32_16x16x32_bf16 v[44:47], v[148:151], v[200:203], v[44:47]
	v_mfma_f32_16x16x32_bf16 v[40:43], v[164:167], v[200:203], v[40:43]
	v_mfma_f32_16x16x32_bf16 v[28:31], v[148:151], v[208:211], v[28:31]
	v_mfma_f32_16x16x32_bf16 v[24:27], v[164:167], v[208:211], v[24:27]
	v_mfma_f32_16x16x32_bf16 v[12:15], v[148:151], v[216:219], v[12:15]
	v_mfma_f32_16x16x32_bf16 v[8:11], v[164:167], v[216:219], v[8:11]
	v_mfma_f32_16x16x32_bf16 v[60:63], v[160:163], v[196:199], v[60:63]
	v_mfma_f32_16x16x32_bf16 v[56:59], v[168:171], v[196:199], v[56:59]
	v_mfma_f32_16x16x32_bf16 v[44:47], v[160:163], v[204:207], v[44:47]
	v_mfma_f32_16x16x32_bf16 v[40:43], v[168:171], v[204:207], v[40:43]
	v_mfma_f32_16x16x32_bf16 v[28:31], v[160:163], v[212:215], v[28:31]
	v_mfma_f32_16x16x32_bf16 v[24:27], v[168:171], v[212:215], v[24:27]
	v_mfma_f32_16x16x32_bf16 v[12:15], v[160:163], v[220:223], v[12:15]
	v_mfma_f32_16x16x32_bf16 v[8:11], v[168:171], v[220:223], v[8:11]
	v_mfma_f32_16x16x32_bf16 v[52:55], v[172:175], v[190:193], v[52:55]
	v_mfma_f32_16x16x32_bf16 v[48:51], v[180:183], v[190:193], v[48:51]
	v_mfma_f32_16x16x32_bf16 v[36:39], v[172:175], v[200:203], v[36:39]
	v_mfma_f32_16x16x32_bf16 v[32:35], v[180:183], v[200:203], v[32:35]
	v_mfma_f32_16x16x32_bf16 v[20:23], v[172:175], v[208:211], v[20:23]
	v_mfma_f32_16x16x32_bf16 v[16:19], v[180:183], v[208:211], v[16:19]
	v_mfma_f32_16x16x32_bf16 v[4:7], v[172:175], v[216:219], v[4:7]
	v_mfma_f32_16x16x32_bf16 v[0:3], v[180:183], v[216:219], v[0:3]
	v_mfma_f32_16x16x32_bf16 v[52:55], v[176:179], v[196:199], v[52:55]
	v_mfma_f32_16x16x32_bf16 v[48:51], v[186:189], v[196:199], v[48:51]
	v_mfma_f32_16x16x32_bf16 v[36:39], v[176:179], v[204:207], v[36:39]
	v_mfma_f32_16x16x32_bf16 v[32:35], v[186:189], v[204:207], v[32:35]
	v_mfma_f32_16x16x32_bf16 v[20:23], v[176:179], v[212:215], v[20:23]
	v_mfma_f32_16x16x32_bf16 v[16:19], v[186:189], v[212:215], v[16:19]
	v_mfma_f32_16x16x32_bf16 v[4:7], v[176:179], v[220:223], v[4:7]
	v_mfma_f32_16x16x32_bf16 v[0:3], v[186:189], v[220:223], v[0:3]
	s_barrier
	s_add_i32 s46, s46, 2
	s_add_u32 s18, s18, 0x100
	s_addc_u32 s19, s19, 0
	s_cmp_gt_u32 s46, 41
	s_cbranch_scc0 .LBB0_302
	s_and_b64 vcc, exec, s[12:13]
	s_cbranch_vccz .LBB0_305
	s_barrier

.LBB0_345:
	ds_read_b128 v[4:7], v77
	ds_read_b128 v[8:11], v77 offset:1024
	ds_read_b128 v[12:15], v77 offset:2048
	ds_read_b128 v[16:19], v77 offset:3072
	s_add_u32 s54, s22, s2
	s_addc_u32 s55, s23, s3
	v_lshl_add_u64 v[0:1], s[54:55], 0, v[66:67]
	s_mov_b32 m0, s36
	v_lshl_add_u64 v[2:3], v[0:1], 0, s[6:7]
	ds_read_b128 v[20:23], v78
	ds_read_b128 v[24:27], v78 offset:1024
	ds_read_b128 v[28:31], v78 offset:2048
	ds_read_b128 v[32:35], v78 offset:3072
	ds_read_b128 v[36:39], v78 offset:4096
	ds_read_b128 v[40:43], v78 offset:5120
	ds_read_b128 v[44:47], v78 offset:6144
	ds_read_b128 v[48:51], v78 offset:7168
	global_load_lds_dwordx4 v[2:3], off
	v_lshl_add_u64 v[2:3], s[54:55], 0, v[64:65]
	v_lshl_add_u64 v[52:53], v[2:3], 0, s[6:7]
	s_mov_b32 m0, s37
	s_nop 0
	global_load_lds_dwordx4 v[52:53], off
	s_waitcnt lgkmcnt(8)
	s_barrier
	s_waitcnt lgkmcnt(0)
	s_waitcnt lgkmcnt(0)
	v_mfma_f32_16x16x32_bf16 v[52:55], v[4:7], v[20:23], 0
	v_mfma_f32_16x16x32_bf16 v[56:59], v[12:15], v[20:23], 0
	v_mfma_f32_16x16x32_bf16 v[60:63], v[4:7], v[28:31], 0
	v_mfma_f32_16x16x32_bf16 v[68:71], v[12:15], v[28:31], 0
	v_mfma_f32_16x16x32_bf16 v[82:85], v[4:7], v[36:39], 0
	v_mfma_f32_16x16x32_bf16 v[86:89], v[12:15], v[36:39], 0
	v_mfma_f32_16x16x32_bf16 v[90:93], v[4:7], v[44:47], 0
	v_mfma_f32_16x16x32_bf16 v[94:97], v[12:15], v[44:47], 0
	v_mfma_f32_16x16x32_bf16 v[52:55], v[8:11], v[24:27], v[52:55]
	v_mfma_f32_16x16x32_bf16 v[56:59], v[16:19], v[24:27], v[56:59]
	v_mfma_f32_16x16x32_bf16 v[60:63], v[8:11], v[32:35], v[60:63]
	v_mfma_f32_16x16x32_bf16 v[68:71], v[16:19], v[32:35], v[68:71]
	v_mfma_f32_16x16x32_bf16 v[82:85], v[8:11], v[40:43], v[82:85]
	v_mfma_f32_16x16x32_bf16 v[86:89], v[16:19], v[40:43], v[86:89]
	v_mfma_f32_16x16x32_bf16 v[90:93], v[8:11], v[48:51], v[90:93]
	v_mfma_f32_16x16x32_bf16 v[94:97], v[16:19], v[48:51], v[94:97]
	s_barrier
	v_lshl_add_u64 v[126:127], s[20:21], 0, v[66:67]
	s_mov_b32 m0, s39
	v_lshl_add_u64 v[114:115], v[126:127], 0, s[8:9]
	v_lshl_add_u64 v[182:183], s[20:21], 0, v[64:65]
	ds_read_b128 v[98:101], v79
	ds_read_b128 v[102:105], v79 offset:1024
	ds_read_b128 v[106:109], v79 offset:2048
	ds_read_b128 v[110:113], v79 offset:3072
	global_load_lds_dwordx4 v[114:115], off
	v_lshl_add_u64 v[114:115], v[182:183], 0, s[8:9]
	s_mov_b32 m0, s41
	s_nop 0
	global_load_lds_dwordx4 v[114:115], off
	s_barrier
	s_waitcnt lgkmcnt(0)
	s_waitcnt lgkmcnt(0)
	v_mfma_f32_16x16x32_bf16 v[114:117], v[98:101], v[20:23], 0
	v_mfma_f32_16x16x32_bf16 v[20:23], v[106:109], v[20:23], 0
	v_mfma_f32_16x16x32_bf16 v[114:117], v[102:105], v[24:27], v[114:117]
	v_mfma_f32_16x16x32_bf16 v[20:23], v[110:113], v[24:27], v[20:23]
	v_mfma_f32_16x16x32_bf16 v[24:27], v[98:101], v[28:31], 0
	v_mfma_f32_16x16x32_bf16 v[28:31], v[106:109], v[28:31], 0
	v_mfma_f32_16x16x32_bf16 v[24:27], v[102:105], v[32:35], v[24:27]
	v_mfma_f32_16x16x32_bf16 v[28:31], v[110:113], v[32:35], v[28:31]
	v_mfma_f32_16x16x32_bf16 v[32:35], v[98:101], v[36:39], 0
	v_mfma_f32_16x16x32_bf16 v[36:39], v[106:109], v[36:39], 0
	v_mfma_f32_16x16x32_bf16 v[32:35], v[102:105], v[40:43], v[32:35]
	v_mfma_f32_16x16x32_bf16 v[36:39], v[110:113], v[40:43], v[36:39]
	v_mfma_f32_16x16x32_bf16 v[40:43], v[98:101], v[44:47], 0
	v_mfma_f32_16x16x32_bf16 v[44:47], v[106:109], v[44:47], 0
	v_mfma_f32_16x16x32_bf16 v[40:43], v[102:105], v[48:51], v[40:43]
	v_mfma_f32_16x16x32_bf16 v[44:47], v[110:113], v[48:51], v[44:47]
	v_lshl_add_u64 v[220:221], s[22:23], 0, v[66:67]
	s_mov_b32 m0, s25
	v_lshl_add_u64 v[150:151], v[220:221], 0, s[8:9]
	v_lshl_add_u64 v[222:223], s[22:23], 0, v[64:65]
	s_barrier
	ds_read_b128 v[48:51], v78 offset:16384
	ds_read_b128 v[118:121], v78 offset:17408
	ds_read_b128 v[122:125], v78 offset:18432
	ds_read_b128 v[130:133], v78 offset:19456
	ds_read_b128 v[134:137], v78 offset:20480
	ds_read_b128 v[138:141], v78 offset:21504
	ds_read_b128 v[142:145], v78 offset:22528
	ds_read_b128 v[146:149], v78 offset:23552
	global_load_lds_dwordx4 v[150:151], off
	v_lshl_add_u64 v[150:151], v[222:223], 0, s[8:9]
	s_mov_b32 m0, s26
	s_nop 0
	global_load_lds_dwordx4 v[150:151], off
	s_barrier
	s_waitcnt lgkmcnt(0)
	s_waitcnt lgkmcnt(0)
	v_mfma_f32_16x16x32_bf16 v[150:153], v[4:7], v[48:51], 0
	v_mfma_f32_16x16x32_bf16 v[158:161], v[4:7], v[122:125], 0
	v_mfma_f32_16x16x32_bf16 v[166:169], v[4:7], v[134:137], 0
	v_mfma_f32_16x16x32_bf16 v[4:7], v[4:7], v[142:145], 0
	v_mfma_f32_16x16x32_bf16 v[150:153], v[8:11], v[118:121], v[150:153]
	v_mfma_f32_16x16x32_bf16 v[154:157], v[12:15], v[48:51], 0
	v_mfma_f32_16x16x32_bf16 v[158:161], v[8:11], v[130:133], v[158:161]
	v_mfma_f32_16x16x32_bf16 v[162:165], v[12:15], v[122:125], 0
	v_mfma_f32_16x16x32_bf16 v[166:169], v[8:11], v[138:141], v[166:169]
	v_mfma_f32_16x16x32_bf16 v[170:173], v[12:15], v[134:137], 0
	v_mfma_f32_16x16x32_bf16 v[4:7], v[8:11], v[146:149], v[4:7]
	v_mfma_f32_16x16x32_bf16 v[8:11], v[12:15], v[142:145], 0
	v_mfma_f32_16x16x32_bf16 v[154:157], v[16:19], v[118:121], v[154:157]
	v_mfma_f32_16x16x32_bf16 v[162:165], v[16:19], v[130:133], v[162:165]
	v_mfma_f32_16x16x32_bf16 v[170:173], v[16:19], v[138:141], v[170:173]
	v_mfma_f32_16x16x32_bf16 v[8:11], v[16:19], v[146:149], v[8:11]
	s_barrier
	s_add_u32 s20, s20, s2
	s_addc_u32 s21, s21, s3
	v_lshl_add_u64 v[224:225], s[20:21], 0, v[66:67]
	s_mov_b32 m0, s42
	v_lshl_add_u64 v[12:13], v[224:225], 0, s[8:9]
	v_lshl_add_u64 v[226:227], s[20:21], 0, v[64:65]
	global_load_lds_dwordx4 v[12:13], off
	v_lshl_add_u64 v[12:13], v[226:227], 0, s[8:9]
	s_mov_b32 m0, s43
	s_nop 0
	global_load_lds_dwordx4 v[12:13], off
	s_waitcnt vmcnt(6)
	s_barrier
	v_mfma_f32_16x16x32_bf16 v[12:15], v[98:101], v[48:51], 0
	v_mfma_f32_16x16x32_bf16 v[16:19], v[106:109], v[48:51], 0
	v_mfma_f32_16x16x32_bf16 v[12:15], v[102:105], v[118:121], v[12:15]
	v_mfma_f32_16x16x32_bf16 v[16:19], v[110:113], v[118:121], v[16:19]
	v_mfma_f32_16x16x32_bf16 v[48:51], v[98:101], v[122:125], 0
	v_mfma_f32_16x16x32_bf16 v[118:121], v[106:109], v[122:125], 0
	v_mfma_f32_16x16x32_bf16 v[122:125], v[98:101], v[134:137], 0
	v_mfma_f32_16x16x32_bf16 v[98:101], v[98:101], v[142:145], 0
	v_mfma_f32_16x16x32_bf16 v[48:51], v[102:105], v[130:133], v[48:51]
	v_mfma_f32_16x16x32_bf16 v[118:121], v[110:113], v[130:133], v[118:121]
	v_mfma_f32_16x16x32_bf16 v[122:125], v[102:105], v[138:141], v[122:125]
	v_mfma_f32_16x16x32_bf16 v[130:133], v[106:109], v[134:137], 0
	v_mfma_f32_16x16x32_bf16 v[98:101], v[102:105], v[146:149], v[98:101]
	v_mfma_f32_16x16x32_bf16 v[102:105], v[106:109], v[142:145], 0
	v_mfma_f32_16x16x32_bf16 v[130:133], v[110:113], v[138:141], v[130:133]
	v_mfma_f32_16x16x32_bf16 v[102:105], v[110:113], v[146:149], v[102:105]
	s_barrier
	ds_read_b128 v[106:109], v80
	ds_read_b128 v[110:113], v80 offset:1024
	ds_read_b128 v[134:137], v80 offset:2048
	ds_read_b128 v[138:141], v80 offset:3072
	s_mov_b32 m0, s27
	v_lshl_add_u64 v[204:205], v[0:1], 0, s[8:9]
	ds_read_b128 v[142:145], v78 offset:32768
	ds_read_b128 v[146:149], v78 offset:33792
	ds_read_b128 v[174:177], v78 offset:34816
	ds_read_b128 v[178:181], v78 offset:35840
	ds_read_b128 v[186:189], v78 offset:36864
	ds_read_b128 v[190:193], v78 offset:37888
	ds_read_b128 v[196:199], v78 offset:38912
	ds_read_b128 v[200:203], v78 offset:39936
	global_load_lds_dwordx4 v[204:205], off
	v_lshl_add_u64 v[204:205], v[2:3], 0, s[8:9]
	s_mov_b32 m0, s28
	s_nop 0
	global_load_lds_dwordx4 v[204:205], off
	s_waitcnt lgkmcnt(8)
	s_barrier
	s_waitcnt lgkmcnt(0)
	s_waitcnt lgkmcnt(0)
	v_mfma_f32_16x16x32_bf16 v[52:55], v[106:109], v[142:145], v[52:55]
	v_mfma_f32_16x16x32_bf16 v[56:59], v[134:137], v[142:145], v[56:59]
	v_mfma_f32_16x16x32_bf16 v[60:63], v[106:109], v[174:177], v[60:63]
	v_mfma_f32_16x16x32_bf16 v[68:71], v[134:137], v[174:177], v[68:71]
	v_mfma_f32_16x16x32_bf16 v[82:85], v[106:109], v[186:189], v[82:85]
	v_mfma_f32_16x16x32_bf16 v[86:89], v[134:137], v[186:189], v[86:89]
	v_mfma_f32_16x16x32_bf16 v[90:93], v[106:109], v[196:199], v[90:93]
	v_mfma_f32_16x16x32_bf16 v[94:97], v[134:137], v[196:199], v[94:97]
	v_mfma_f32_16x16x32_bf16 v[52:55], v[110:113], v[146:149], v[52:55]
	v_mfma_f32_16x16x32_bf16 v[56:59], v[138:141], v[146:149], v[56:59]
	v_mfma_f32_16x16x32_bf16 v[60:63], v[110:113], v[178:181], v[60:63]
	v_mfma_f32_16x16x32_bf16 v[68:71], v[138:141], v[178:181], v[68:71]
	v_mfma_f32_16x16x32_bf16 v[82:85], v[110:113], v[190:193], v[82:85]
	v_mfma_f32_16x16x32_bf16 v[86:89], v[138:141], v[190:193], v[86:89]
	v_mfma_f32_16x16x32_bf16 v[90:93], v[110:113], v[200:203], v[90:93]
	v_mfma_f32_16x16x32_bf16 v[94:97], v[138:141], v[200:203], v[94:97]
	s_barrier
	s_mov_b32 m0, s44
	v_lshl_add_u64 v[126:127], v[126:127], 0, s[10:11]
	ds_read_b128 v[204:207], v81
	ds_read_b128 v[208:211], v81 offset:1024
	ds_read_b128 v[212:215], v81 offset:2048
	ds_read_b128 v[216:219], v81 offset:3072
	global_load_lds_dwordx4 v[126:127], off
	v_lshl_add_u64 v[126:127], v[182:183], 0, s[10:11]
	s_mov_b32 m0, s45
	s_nop 0
	global_load_lds_dwordx4 v[126:127], off
	s_barrier
	s_waitcnt lgkmcnt(0)
	s_waitcnt lgkmcnt(0)
	v_mfma_f32_16x16x32_bf16 v[114:117], v[204:207], v[142:145], v[114:117]
	v_mfma_f32_16x16x32_bf16 v[20:23], v[212:215], v[142:145], v[20:23]
	v_mfma_f32_16x16x32_bf16 v[24:27], v[204:207], v[174:177], v[24:27]
	v_mfma_f32_16x16x32_bf16 v[28:31], v[212:215], v[174:177], v[28:31]
	v_mfma_f32_16x16x32_bf16 v[32:35], v[204:207], v[186:189], v[32:35]
	v_mfma_f32_16x16x32_bf16 v[36:39], v[212:215], v[186:189], v[36:39]
	v_mfma_f32_16x16x32_bf16 v[40:43], v[204:207], v[196:199], v[40:43]
	v_mfma_f32_16x16x32_bf16 v[44:47], v[212:215], v[196:199], v[44:47]
	v_mfma_f32_16x16x32_bf16 v[114:117], v[208:211], v[146:149], v[114:117]
	v_mfma_f32_16x16x32_bf16 v[20:23], v[216:219], v[146:149], v[20:23]
	v_mfma_f32_16x16x32_bf16 v[24:27], v[208:211], v[178:181], v[24:27]
	v_mfma_f32_16x16x32_bf16 v[28:31], v[216:219], v[178:181], v[28:31]
	v_mfma_f32_16x16x32_bf16 v[32:35], v[208:211], v[190:193], v[32:35]
	v_mfma_f32_16x16x32_bf16 v[36:39], v[216:219], v[190:193], v[36:39]
	v_mfma_f32_16x16x32_bf16 v[40:43], v[208:211], v[200:203], v[40:43]
	v_mfma_f32_16x16x32_bf16 v[44:47], v[216:219], v[200:203], v[44:47]
	s_mov_b32 m0, s29
	v_lshl_add_u64 v[126:127], v[220:221], 0, s[10:11]
	s_barrier
	ds_read_b128 v[142:145], v78 offset:49152
	ds_read_b128 v[146:149], v78 offset:50176
	ds_read_b128 v[174:177], v78 offset:51200
	ds_read_b128 v[178:181], v78 offset:52224
	ds_read_b128 v[186:189], v78 offset:53248
	ds_read_b128 v[190:193], v78 offset:54272
	ds_read_b128 v[196:199], v78 offset:55296
	ds_read_b128 v[200:203], v78 offset:56320
	global_load_lds_dwordx4 v[126:127], off
	v_lshl_add_u64 v[126:127], v[222:223], 0, s[10:11]
	s_mov_b32 m0, s30
	s_nop 0
	global_load_lds_dwordx4 v[126:127], off
	s_barrier
	s_waitcnt lgkmcnt(0)
	s_waitcnt lgkmcnt(0)
	v_mfma_f32_16x16x32_bf16 v[150:153], v[106:109], v[142:145], v[150:153]
	v_mfma_f32_16x16x32_bf16 v[154:157], v[134:137], v[142:145], v[154:157]
	v_mfma_f32_16x16x32_bf16 v[158:161], v[106:109], v[174:177], v[158:161]
	v_mfma_f32_16x16x32_bf16 v[162:165], v[134:137], v[174:177], v[162:165]
	v_mfma_f32_16x16x32_bf16 v[166:169], v[106:109], v[186:189], v[166:169]
	v_mfma_f32_16x16x32_bf16 v[170:173], v[134:137], v[186:189], v[170:173]
	v_mfma_f32_16x16x32_bf16 v[4:7], v[106:109], v[196:199], v[4:7]
	v_mfma_f32_16x16x32_bf16 v[8:11], v[134:137], v[196:199], v[8:11]
	v_mfma_f32_16x16x32_bf16 v[150:153], v[110:113], v[146:149], v[150:153]
	v_mfma_f32_16x16x32_bf16 v[154:157], v[138:141], v[146:149], v[154:157]
	v_mfma_f32_16x16x32_bf16 v[158:161], v[110:113], v[178:181], v[158:161]
	v_mfma_f32_16x16x32_bf16 v[162:165], v[138:141], v[178:181], v[162:165]
	v_mfma_f32_16x16x32_bf16 v[166:169], v[110:113], v[190:193], v[166:169]
	v_mfma_f32_16x16x32_bf16 v[170:173], v[138:141], v[190:193], v[170:173]
	v_mfma_f32_16x16x32_bf16 v[4:7], v[110:113], v[200:203], v[4:7]
	v_mfma_f32_16x16x32_bf16 v[8:11], v[138:141], v[200:203], v[8:11]
	s_barrier
	s_mov_b32 m0, s46
	v_lshl_add_u64 v[106:107], v[224:225], 0, s[10:11]
	global_load_lds_dwordx4 v[106:107], off
	v_lshl_add_u64 v[106:107], v[226:227], 0, s[10:11]
	s_mov_b32 m0, s47
	s_nop 0
	global_load_lds_dwordx4 v[106:107], off
	s_waitcnt vmcnt(6)
	s_barrier
	v_mfma_f32_16x16x32_bf16 v[12:15], v[204:207], v[142:145], v[12:15]
	v_mfma_f32_16x16x32_bf16 v[16:19], v[212:215], v[142:145], v[16:19]
	v_mfma_f32_16x16x32_bf16 v[48:51], v[204:207], v[174:177], v[48:51]
	v_mfma_f32_16x16x32_bf16 v[106:109], v[212:215], v[174:177], v[118:121]
	v_mfma_f32_16x16x32_bf16 v[110:113], v[204:207], v[186:189], v[122:125]
	v_mfma_f32_16x16x32_bf16 v[118:121], v[212:215], v[186:189], v[130:133]
	v_mfma_f32_16x16x32_bf16 v[98:101], v[204:207], v[196:199], v[98:101]
	v_mfma_f32_16x16x32_bf16 v[102:105], v[212:215], v[196:199], v[102:105]
	v_mfma_f32_16x16x32_bf16 v[12:15], v[208:211], v[146:149], v[12:15]
	v_mfma_f32_16x16x32_bf16 v[16:19], v[216:219], v[146:149], v[16:19]
	v_mfma_f32_16x16x32_bf16 v[48:51], v[208:211], v[178:181], v[48:51]
	v_mfma_f32_16x16x32_bf16 v[106:109], v[216:219], v[178:181], v[106:109]
	v_mfma_f32_16x16x32_bf16 v[110:113], v[208:211], v[190:193], v[110:113]
	v_mfma_f32_16x16x32_bf16 v[118:121], v[216:219], v[190:193], v[118:121]
	v_mfma_f32_16x16x32_bf16 v[98:101], v[208:211], v[200:203], v[98:101]
	v_mfma_f32_16x16x32_bf16 v[102:105], v[216:219], v[200:203], v[102:105]
	s_barrier
	ds_read_b128 v[122:125], v77
	ds_read_b128 v[130:133], v77 offset:1024
	ds_read_b128 v[134:137], v77 offset:2048
	ds_read_b128 v[138:141], v77 offset:3072
	s_mov_b32 m0, s36
	v_lshl_add_u64 v[0:1], v[0:1], 0, s[10:11]
	ds_read_b128 v[142:145], v78
	ds_read_b128 v[146:149], v78 offset:1024
	ds_read_b128 v[174:177], v78 offset:2048
	ds_read_b128 v[178:181], v78 offset:3072
	ds_read_b128 v[186:189], v78 offset:4096
	ds_read_b128 v[190:193], v78 offset:5120
	ds_read_b128 v[196:199], v78 offset:6144
	ds_read_b128 v[200:203], v78 offset:7168
	global_load_lds_dwordx4 v[0:1], off
	v_lshl_add_u64 v[0:1], v[2:3], 0, s[10:11]
	s_mov_b32 m0, s37
	s_nop 0
	global_load_lds_dwordx4 v[0:1], off
	s_waitcnt lgkmcnt(8)
	s_barrier
	s_waitcnt lgkmcnt(0)
	s_waitcnt lgkmcnt(0)
	v_mfma_f32_16x16x32_bf16 v[0:3], v[122:125], v[142:145], v[52:55]
	v_mfma_f32_16x16x32_bf16 v[52:55], v[134:137], v[142:145], v[56:59]
	v_mfma_f32_16x16x32_bf16 v[56:59], v[122:125], v[174:177], v[60:63]
	v_mfma_f32_16x16x32_bf16 v[60:63], v[134:137], v[174:177], v[68:71]
	v_mfma_f32_16x16x32_bf16 v[68:71], v[122:125], v[186:189], v[82:85]
	v_mfma_f32_16x16x32_bf16 v[82:85], v[134:137], v[186:189], v[86:89]
	v_mfma_f32_16x16x32_bf16 v[86:89], v[122:125], v[196:199], v[90:93]
	v_mfma_f32_16x16x32_bf16 v[90:93], v[134:137], v[196:199], v[94:97]
	v_mfma_f32_16x16x32_bf16 v[0:3], v[130:133], v[146:149], v[0:3]
	v_mfma_f32_16x16x32_bf16 v[52:55], v[138:141], v[146:149], v[52:55]
	v_mfma_f32_16x16x32_bf16 v[56:59], v[130:133], v[178:181], v[56:59]
	v_mfma_f32_16x16x32_bf16 v[60:63], v[138:141], v[178:181], v[60:63]
	v_mfma_f32_16x16x32_bf16 v[68:71], v[130:133], v[190:193], v[68:71]
	v_mfma_f32_16x16x32_bf16 v[82:85], v[138:141], v[190:193], v[82:85]
	v_mfma_f32_16x16x32_bf16 v[86:89], v[130:133], v[200:203], v[86:89]
	v_mfma_f32_16x16x32_bf16 v[90:93], v[138:141], v[200:203], v[90:93]
	s_barrier
	s_mov_b32 m0, s39
	v_lshl_add_u64 v[126:127], s[0:1], 0, v[66:67]
	ds_read_b128 v[94:97], v79
	ds_read_b128 v[204:207], v79 offset:1024
	ds_read_b128 v[208:211], v79 offset:2048
	ds_read_b128 v[212:215], v79 offset:3072
	global_load_lds_dwordx4 v[126:127], off
	v_lshl_add_u64 v[182:183], s[0:1], 0, v[64:65]
	s_mov_b32 m0, s41
	s_nop 0
	global_load_lds_dwordx4 v[182:183], off
	s_barrier
	s_waitcnt lgkmcnt(0)
	s_waitcnt lgkmcnt(0)
	v_mfma_f32_16x16x32_bf16 v[114:117], v[94:97], v[142:145], v[114:117]
	v_mfma_f32_16x16x32_bf16 v[20:23], v[208:211], v[142:145], v[20:23]
	v_mfma_f32_16x16x32_bf16 v[24:27], v[94:97], v[174:177], v[24:27]
	v_mfma_f32_16x16x32_bf16 v[28:31], v[208:211], v[174:177], v[28:31]
	v_mfma_f32_16x16x32_bf16 v[32:35], v[94:97], v[186:189], v[32:35]
	v_mfma_f32_16x16x32_bf16 v[36:39], v[208:211], v[186:189], v[36:39]
	v_mfma_f32_16x16x32_bf16 v[40:43], v[94:97], v[196:199], v[40:43]
	v_mfma_f32_16x16x32_bf16 v[44:47], v[208:211], v[196:199], v[44:47]
	v_mfma_f32_16x16x32_bf16 v[114:117], v[204:207], v[146:149], v[114:117]
	v_mfma_f32_16x16x32_bf16 v[20:23], v[212:215], v[146:149], v[20:23]
	v_mfma_f32_16x16x32_bf16 v[24:27], v[204:207], v[178:181], v[24:27]
	v_mfma_f32_16x16x32_bf16 v[28:31], v[212:215], v[178:181], v[28:31]
	v_mfma_f32_16x16x32_bf16 v[32:35], v[204:207], v[190:193], v[32:35]
	v_mfma_f32_16x16x32_bf16 v[36:39], v[212:215], v[190:193], v[36:39]
	v_mfma_f32_16x16x32_bf16 v[40:43], v[204:207], v[200:203], v[40:43]
	v_mfma_f32_16x16x32_bf16 v[44:47], v[212:215], v[200:203], v[44:47]
	s_mov_b32 m0, s25
	v_lshl_add_u64 v[244:245], s[16:17], 0, v[66:67]
	s_barrier
	ds_read_b128 v[142:145], v78 offset:16384
	ds_read_b128 v[146:149], v78 offset:17408
	ds_read_b128 v[174:177], v78 offset:18432
	ds_read_b128 v[178:181], v78 offset:19456
	ds_read_b128 v[186:189], v78 offset:20480
	ds_read_b128 v[190:193], v78 offset:21504
	ds_read_b128 v[196:199], v78 offset:22528
	ds_read_b128 v[200:203], v78 offset:23552
	global_load_lds_dwordx4 v[244:245], off
	v_lshl_add_u64 v[246:247], s[16:17], 0, v[64:65]
	s_mov_b32 m0, s26
	s_nop 0
	global_load_lds_dwordx4 v[246:247], off
	s_barrier
	s_waitcnt lgkmcnt(0)
	s_waitcnt lgkmcnt(0)
	v_mfma_f32_16x16x32_bf16 v[150:153], v[122:125], v[142:145], v[150:153]
	v_mfma_f32_16x16x32_bf16 v[154:157], v[134:137], v[142:145], v[154:157]
	v_mfma_f32_16x16x32_bf16 v[158:161], v[122:125], v[174:177], v[158:161]
	v_mfma_f32_16x16x32_bf16 v[162:165], v[134:137], v[174:177], v[162:165]
	v_mfma_f32_16x16x32_bf16 v[166:169], v[122:125], v[186:189], v[166:169]
	v_mfma_f32_16x16x32_bf16 v[170:173], v[134:137], v[186:189], v[170:173]
	v_mfma_f32_16x16x32_bf16 v[4:7], v[122:125], v[196:199], v[4:7]
	v_mfma_f32_16x16x32_bf16 v[8:11], v[134:137], v[196:199], v[8:11]
	v_mfma_f32_16x16x32_bf16 v[150:153], v[130:133], v[146:149], v[150:153]
	v_mfma_f32_16x16x32_bf16 v[154:157], v[138:141], v[146:149], v[154:157]
	v_mfma_f32_16x16x32_bf16 v[158:161], v[130:133], v[178:181], v[158:161]
	v_mfma_f32_16x16x32_bf16 v[162:165], v[138:141], v[178:181], v[162:165]
	v_mfma_f32_16x16x32_bf16 v[166:169], v[130:133], v[190:193], v[166:169]
	v_mfma_f32_16x16x32_bf16 v[170:173], v[138:141], v[190:193], v[170:173]
	v_mfma_f32_16x16x32_bf16 v[4:7], v[130:133], v[200:203], v[4:7]
	v_mfma_f32_16x16x32_bf16 v[8:11], v[138:141], v[200:203], v[8:11]
	s_barrier
	s_add_u32 s20, s0, s2
	s_addc_u32 s21, s1, s3
	s_mov_b32 m0, s42
	v_lshl_add_u64 v[248:249], s[20:21], 0, v[66:67]
	global_load_lds_dwordx4 v[248:249], off
	v_lshl_add_u64 v[194:195], s[20:21], 0, v[64:65]
	s_mov_b32 m0, s43
	s_nop 0
	global_load_lds_dwordx4 v[194:195], off
	s_waitcnt vmcnt(6)
	s_barrier
	v_mfma_f32_16x16x32_bf16 v[16:19], v[208:211], v[142:145], v[16:19]
	v_mfma_f32_16x16x32_bf16 v[122:125], v[212:215], v[146:149], v[16:19]
	v_mfma_f32_16x16x32_bf16 v[16:19], v[94:97], v[174:177], v[48:51]
	v_mfma_f32_16x16x32_bf16 v[130:133], v[204:207], v[178:181], v[16:19]
	v_mfma_f32_16x16x32_bf16 v[16:19], v[208:211], v[174:177], v[106:109]
	v_mfma_f32_16x16x32_bf16 v[106:109], v[212:215], v[178:181], v[16:19]
	v_mfma_f32_16x16x32_bf16 v[16:19], v[94:97], v[186:189], v[110:113]
	v_mfma_f32_16x16x32_bf16 v[110:113], v[204:207], v[190:193], v[16:19]
	v_mfma_f32_16x16x32_bf16 v[16:19], v[208:211], v[186:189], v[118:121]
	v_mfma_f32_16x16x32_bf16 v[118:121], v[212:215], v[190:193], v[16:19]
	v_mfma_f32_16x16x32_bf16 v[16:19], v[94:97], v[196:199], v[98:101]
	v_mfma_f32_16x16x32_bf16 v[12:15], v[94:97], v[142:145], v[12:15]
	v_mfma_f32_16x16x32_bf16 v[94:97], v[204:207], v[200:203], v[16:19]
	v_mfma_f32_16x16x32_bf16 v[16:19], v[208:211], v[196:199], v[102:105]
	v_mfma_f32_16x16x32_bf16 v[12:15], v[204:207], v[146:149], v[12:15]
	v_mfma_f32_16x16x32_bf16 v[98:101], v[212:215], v[200:203], v[16:19]
	s_barrier
	ds_read_b128 v[102:105], v80
	ds_read_b128 v[134:137], v80 offset:1024
	ds_read_b128 v[138:141], v80 offset:2048
	ds_read_b128 v[142:145], v80 offset:3072
	s_add_u32 s20, s16, s2
	s_addc_u32 s21, s17, s3
	s_mov_b32 m0, s27
	v_lshl_add_u64 v[48:49], s[20:21], 0, v[66:67]
	ds_read_b128 v[16:19], v78 offset:32768
	ds_read_b128 v[146:149], v78 offset:33792
	ds_read_b128 v[174:177], v78 offset:34816
	ds_read_b128 v[178:181], v78 offset:35840
	ds_read_b128 v[186:189], v78 offset:36864
	ds_read_b128 v[190:193], v78 offset:37888
	ds_read_b128 v[196:199], v78 offset:38912
	ds_read_b128 v[200:203], v78 offset:39936
	global_load_lds_dwordx4 v[48:49], off
	v_lshl_add_u64 v[48:49], s[20:21], 0, v[64:65]
	s_mov_b32 m0, s28
	s_nop 0
	global_load_lds_dwordx4 v[48:49], off
	s_waitcnt lgkmcnt(8)
	s_barrier
	s_waitcnt lgkmcnt(0)
	s_waitcnt lgkmcnt(0)
	v_mfma_f32_16x16x32_bf16 v[0:3], v[102:105], v[16:19], v[0:3]
	v_mfma_f32_16x16x32_bf16 v[204:207], v[134:137], v[146:149], v[0:3]
	v_mfma_f32_16x16x32_bf16 v[0:3], v[138:141], v[16:19], v[52:55]
	v_mfma_f32_16x16x32_bf16 v[208:211], v[142:145], v[146:149], v[0:3]
	v_mfma_f32_16x16x32_bf16 v[0:3], v[102:105], v[174:177], v[56:59]
	v_mfma_f32_16x16x32_bf16 v[212:215], v[134:137], v[178:181], v[0:3]
	v_mfma_f32_16x16x32_bf16 v[0:3], v[138:141], v[174:177], v[60:63]
	v_mfma_f32_16x16x32_bf16 v[216:219], v[142:145], v[178:181], v[0:3]
	v_mfma_f32_16x16x32_bf16 v[0:3], v[102:105], v[186:189], v[68:71]
	v_mfma_f32_16x16x32_bf16 v[220:223], v[134:137], v[190:193], v[0:3]
	v_mfma_f32_16x16x32_bf16 v[0:3], v[138:141], v[186:189], v[82:85]
	v_mfma_f32_16x16x32_bf16 v[82:85], v[142:145], v[190:193], v[0:3]
	v_mfma_f32_16x16x32_bf16 v[0:3], v[102:105], v[196:199], v[86:89]
	v_mfma_f32_16x16x32_bf16 v[52:55], v[134:137], v[200:203], v[0:3]
	v_mfma_f32_16x16x32_bf16 v[0:3], v[138:141], v[196:199], v[90:93]
	v_mfma_f32_16x16x32_bf16 v[48:51], v[142:145], v[200:203], v[0:3]
	s_barrier
	s_mov_b32 m0, s44
	s_nop 3
	v_lshl_add_u64 v[0:1], v[126:127], 0, s[6:7]
	ds_read_b128 v[68:71], v81
	ds_read_b128 v[86:89], v81 offset:1024
	ds_read_b128 v[90:93], v81 offset:2048
	ds_read_b128 v[224:227], v81 offset:3072
	global_load_lds_dwordx4 v[0:1], off
	v_lshl_add_u64 v[0:1], v[182:183], 0, s[6:7]
	s_mov_b32 m0, s45
	s_nop 0
	global_load_lds_dwordx4 v[0:1], off
	s_barrier
	s_waitcnt lgkmcnt(0)
	s_waitcnt lgkmcnt(0)
	v_mfma_f32_16x16x32_bf16 v[0:3], v[68:71], v[16:19], v[114:117]
	v_mfma_f32_16x16x32_bf16 v[114:117], v[86:89], v[146:149], v[0:3]
	v_mfma_f32_16x16x32_bf16 v[0:3], v[90:93], v[16:19], v[20:23]
	v_mfma_f32_16x16x32_bf16 v[146:149], v[224:227], v[146:149], v[0:3]
	v_mfma_f32_16x16x32_bf16 v[0:3], v[68:71], v[174:177], v[24:27]
	v_mfma_f32_16x16x32_bf16 v[228:231], v[86:89], v[178:181], v[0:3]
	v_mfma_f32_16x16x32_bf16 v[0:3], v[90:93], v[174:177], v[28:31]
	v_mfma_f32_16x16x32_bf16 v[174:177], v[224:227], v[178:181], v[0:3]
	v_mfma_f32_16x16x32_bf16 v[0:3], v[68:71], v[186:189], v[32:35]
	v_mfma_f32_16x16x32_bf16 v[178:181], v[86:89], v[190:193], v[0:3]
	v_mfma_f32_16x16x32_bf16 v[0:3], v[90:93], v[186:189], v[36:39]
	v_mfma_f32_16x16x32_bf16 v[186:189], v[224:227], v[190:193], v[0:3]
	v_mfma_f32_16x16x32_bf16 v[0:3], v[68:71], v[196:199], v[40:43]
	v_mfma_f32_16x16x32_bf16 v[190:193], v[86:89], v[200:203], v[0:3]
	v_mfma_f32_16x16x32_bf16 v[0:3], v[90:93], v[196:199], v[44:47]
	v_mfma_f32_16x16x32_bf16 v[60:63], v[224:227], v[200:203], v[0:3]
	s_mov_b32 m0, s29
	s_nop 4
	v_lshl_add_u64 v[0:1], v[244:245], 0, s[6:7]
	s_barrier
	ds_read_b128 v[24:27], v78 offset:49152
	ds_read_b128 v[28:31], v78 offset:50176
	ds_read_b128 v[40:43], v78 offset:51200
	ds_read_b128 v[196:199], v78 offset:52224
	ds_read_b128 v[200:203], v78 offset:53248
	ds_read_b128 v[232:235], v78 offset:54272
	ds_read_b128 v[236:239], v78 offset:55296
	ds_read_b128 v[240:243], v78 offset:56320
	global_load_lds_dwordx4 v[0:1], off
	v_lshl_add_u64 v[0:1], v[246:247], 0, s[6:7]
	s_mov_b32 m0, s30
	s_nop 0
	global_load_lds_dwordx4 v[0:1], off
	s_barrier
	s_waitcnt lgkmcnt(0)
	s_waitcnt lgkmcnt(0)
	v_mfma_f32_16x16x32_bf16 v[0:3], v[102:105], v[24:27], v[150:153]
	v_mfma_f32_16x16x32_bf16 v[150:153], v[134:137], v[28:31], v[0:3]
	v_mfma_f32_16x16x32_bf16 v[0:3], v[138:141], v[24:27], v[154:157]
	v_mfma_f32_16x16x32_bf16 v[56:59], v[142:145], v[28:31], v[0:3]
	v_mfma_f32_16x16x32_bf16 v[0:3], v[102:105], v[40:43], v[158:161]
	v_mfma_f32_16x16x32_bf16 v[36:39], v[134:137], v[196:199], v[0:3]
	v_mfma_f32_16x16x32_bf16 v[0:3], v[138:141], v[40:43], v[162:165]
	v_mfma_f32_16x16x32_bf16 v[32:35], v[142:145], v[196:199], v[0:3]
	v_mfma_f32_16x16x32_bf16 v[0:3], v[102:105], v[200:203], v[166:169]
	v_mfma_f32_16x16x32_bf16 v[20:23], v[134:137], v[232:235], v[0:3]
	v_mfma_f32_16x16x32_bf16 v[0:3], v[138:141], v[200:203], v[170:173]
	v_mfma_f32_16x16x32_bf16 v[16:19], v[142:145], v[232:235], v[0:3]
	v_mfma_f32_16x16x32_bf16 v[0:3], v[102:105], v[236:239], v[4:7]
	v_mfma_f32_16x16x32_bf16 v[4:7], v[134:137], v[240:243], v[0:3]
	v_mfma_f32_16x16x32_bf16 v[0:3], v[138:141], v[236:239], v[8:11]
	v_mfma_f32_16x16x32_bf16 v[0:3], v[142:145], v[240:243], v[0:3]
	s_barrier
	s_mov_b32 m0, s46
	v_lshl_add_u64 v[8:9], v[248:249], 0, s[6:7]
	global_load_lds_dwordx4 v[8:9], off
	v_lshl_add_u64 v[8:9], v[194:195], 0, s[6:7]
	s_mov_b32 m0, s47
	s_nop 0
	global_load_lds_dwordx4 v[8:9], off
	s_waitcnt vmcnt(6)
	s_barrier
	v_mfma_f32_16x16x32_bf16 v[8:11], v[68:71], v[24:27], v[12:15]
	v_mfma_f32_16x16x32_bf16 v[102:105], v[86:89], v[28:31], v[8:11]
	v_mfma_f32_16x16x32_bf16 v[8:11], v[90:93], v[24:27], v[122:125]
	v_mfma_f32_16x16x32_bf16 v[122:125], v[224:227], v[28:31], v[8:11]
	v_mfma_f32_16x16x32_bf16 v[8:11], v[68:71], v[40:43], v[130:133]
	v_mfma_f32_16x16x32_bf16 v[44:47], v[86:89], v[196:199], v[8:11]
	v_mfma_f32_16x16x32_bf16 v[8:11], v[90:93], v[40:43], v[106:109]
	v_mfma_f32_16x16x32_bf16 v[40:43], v[224:227], v[196:199], v[8:11]
	v_mfma_f32_16x16x32_bf16 v[8:11], v[68:71], v[200:203], v[110:113]
	v_mfma_f32_16x16x32_bf16 v[28:31], v[86:89], v[232:235], v[8:11]
	v_mfma_f32_16x16x32_bf16 v[8:11], v[90:93], v[200:203], v[118:121]
	v_mfma_f32_16x16x32_bf16 v[24:27], v[224:227], v[232:235], v[8:11]
	v_mfma_f32_16x16x32_bf16 v[8:11], v[68:71], v[236:239], v[94:97]
	v_mfma_f32_16x16x32_bf16 v[12:15], v[86:89], v[240:243], v[8:11]
	v_mfma_f32_16x16x32_bf16 v[8:11], v[90:93], v[236:239], v[98:101]
	v_mfma_f32_16x16x32_bf16 v[8:11], v[224:227], v[240:243], v[8:11]
	s_ashr_i32 s18, s18, 8
	s_ashr_i32 s19, s18, 31
	s_lshl_b64 s[18:19], s[18:19], 21
	s_add_u32 s18, s66, s18
	s_addc_u32 s19, s67, s19
	s_lshl_b32 s13, s52, 8
	v_add_u32_e32 v68, s13, v72
	v_ashrrev_i32_e32 v69, 31, v68
	v_lshlrev_b64 v[70:71], 12, v[68:69]
	v_lshl_add_u64 v[90:91], s[18:19], 0, v[70:71]
	v_lshl_or_b32 v70, s51, 8, v76
	v_ashrrev_i32_e32 v71, 31, v70
	v_lshlrev_b64 v[70:71], 2, v[70:71]
	v_pk_mul_f32 v[88:89], v[206:207], 0.5 op_sel_hi:[1,0]
	v_pk_mul_f32 v[86:87], v[204:205], 0.5 op_sel_hi:[1,0]
	v_lshl_add_u64 v[90:91], v[90:91], 0, v[70:71]
	s_barrier
	global_store_dwordx4 v[90:91], v[86:89], off
	v_pk_mul_f32 v[84:85], v[84:85], 0.5 op_sel_hi:[1,0]
	v_pk_mul_f32 v[82:83], v[82:83], 0.5 op_sel_hi:[1,0]
	v_pk_mul_f32 v[88:89], v[210:211], 0.5 op_sel_hi:[1,0]
	v_pk_mul_f32 v[86:87], v[208:209], 0.5 op_sel_hi:[1,0]
	global_store_dwordx4 v[90:91], v[86:89], off offset:64
	v_pk_mul_f32 v[50:51], v[50:51], 0.5 op_sel_hi:[1,0]
	v_pk_mul_f32 v[48:49], v[48:49], 0.5 op_sel_hi:[1,0]
	v_pk_mul_f32 v[88:89], v[116:117], 0.5 op_sel_hi:[1,0]
	v_pk_mul_f32 v[86:87], v[114:115], 0.5 op_sel_hi:[1,0]
	global_store_dwordx4 v[90:91], v[86:89], off offset:512
	v_pk_mul_f32 v[54:55], v[54:55], 0.5 op_sel_hi:[1,0]
	v_pk_mul_f32 v[52:53], v[52:53], 0.5 op_sel_hi:[1,0]
	v_pk_mul_f32 v[88:89], v[148:149], 0.5 op_sel_hi:[1,0]
	v_pk_mul_f32 v[86:87], v[146:147], 0.5 op_sel_hi:[1,0]
	global_store_dwordx4 v[90:91], v[86:89], off offset:576
	v_pk_mul_f32 v[34:35], v[34:35], 0.5 op_sel_hi:[1,0]
	v_pk_mul_f32 v[32:33], v[32:33], 0.5 op_sel_hi:[1,0]
	v_add_u32_e32 v86, s13, v73
	v_ashrrev_i32_e32 v87, 31, v86
	v_lshlrev_b64 v[86:87], 12, v[86:87]
	v_lshl_add_u64 v[90:91], s[18:19], 0, v[86:87]
	v_pk_mul_f32 v[88:89], v[214:215], 0.5 op_sel_hi:[1,0]
	v_pk_mul_f32 v[86:87], v[212:213], 0.5 op_sel_hi:[1,0]
	v_lshl_add_u64 v[90:91], v[90:91], 0, v[70:71]
	global_store_dwordx4 v[90:91], v[86:89], off
	v_pk_mul_f32 v[18:19], v[18:19], 0.5 op_sel_hi:[1,0]
	v_pk_mul_f32 v[16:17], v[16:17], 0.5 op_sel_hi:[1,0]
	v_pk_mul_f32 v[88:89], v[218:219], 0.5 op_sel_hi:[1,0]
	v_pk_mul_f32 v[86:87], v[216:217], 0.5 op_sel_hi:[1,0]
	global_store_dwordx4 v[90:91], v[86:89], off offset:64
	v_pk_mul_f32 v[2:3], v[2:3], 0.5 op_sel_hi:[1,0]
	v_pk_mul_f32 v[0:1], v[0:1], 0.5 op_sel_hi:[1,0]
	v_pk_mul_f32 v[88:89], v[230:231], 0.5 op_sel_hi:[1,0]
	v_pk_mul_f32 v[86:87], v[228:229], 0.5 op_sel_hi:[1,0]
	global_store_dwordx4 v[90:91], v[86:89], off offset:512
	v_pk_mul_f32 v[38:39], v[38:39], 0.5 op_sel_hi:[1,0]
	v_pk_mul_f32 v[36:37], v[36:37], 0.5 op_sel_hi:[1,0]
	v_pk_mul_f32 v[88:89], v[176:177], 0.5 op_sel_hi:[1,0]
	v_pk_mul_f32 v[86:87], v[174:175], 0.5 op_sel_hi:[1,0]
	global_store_dwordx4 v[90:91], v[86:89], off offset:576
	v_pk_mul_f32 v[22:23], v[22:23], 0.5 op_sel_hi:[1,0]
	v_pk_mul_f32 v[20:21], v[20:21], 0.5 op_sel_hi:[1,0]
	v_add_u32_e32 v86, s13, v74
	v_ashrrev_i32_e32 v87, 31, v86
	v_lshlrev_b64 v[86:87], 12, v[86:87]
	v_lshl_add_u64 v[90:91], s[18:19], 0, v[86:87]
	v_lshl_add_u64 v[90:91], v[90:91], 0, v[70:71]
	global_store_dwordx4 v[90:91], v[82:85], off offset:64
	v_pk_mul_f32 v[88:89], v[222:223], 0.5 op_sel_hi:[1,0]
	v_pk_mul_f32 v[86:87], v[220:221], 0.5 op_sel_hi:[1,0]
	v_pk_mul_f32 v[84:85], v[180:181], 0.5 op_sel_hi:[1,0]
	v_pk_mul_f32 v[82:83], v[178:179], 0.5 op_sel_hi:[1,0]
	global_store_dwordx4 v[90:91], v[82:85], off offset:512
	v_pk_mul_f32 v[6:7], v[6:7], 0.5 op_sel_hi:[1,0]
	v_pk_mul_f32 v[4:5], v[4:5], 0.5 op_sel_hi:[1,0]
	v_pk_mul_f32 v[84:85], v[188:189], 0.5 op_sel_hi:[1,0]
	v_pk_mul_f32 v[82:83], v[186:187], 0.5 op_sel_hi:[1,0]
	global_store_dwordx4 v[90:91], v[82:85], off offset:576
	s_add_i32 s31, s31, s33
	s_andn2_b64 vcc, exec, s[14:15]
	v_add_u32_e32 v82, s13, v75
	v_ashrrev_i32_e32 v83, 31, v82
	v_lshlrev_b64 v[82:83], 12, v[82:83]
	v_lshl_add_u64 v[82:83], s[18:19], 0, v[82:83]
	v_lshl_add_u64 v[82:83], v[82:83], 0, v[70:71]
	global_store_dwordx4 v[82:83], v[48:51], off offset:64
	global_store_dwordx4 v[82:83], v[52:55], off
	s_mov_b32 s51, s49
	v_pk_mul_f32 v[50:51], v[192:193], 0.5 op_sel_hi:[1,0]
	v_pk_mul_f32 v[48:49], v[190:191], 0.5 op_sel_hi:[1,0]
	global_store_dwordx4 v[82:83], v[48:51], off offset:512
	s_mov_b32 s52, s50
	s_mov_b64 s[20:21], s[0:1]
	v_pk_mul_f32 v[50:51], v[62:63], 0.5 op_sel_hi:[1,0]
	v_pk_mul_f32 v[48:49], v[60:61], 0.5 op_sel_hi:[1,0]
	global_store_dwordx4 v[82:83], v[48:51], off offset:576
	s_mov_b64 s[22:23], s[16:17]
	global_store_dwordx4 v[90:91], v[86:89], off
	v_add_u32_e32 v48, 0x80, v68
	v_ashrrev_i32_e32 v49, 31, v48
	v_lshlrev_b64 v[48:49], 12, v[48:49]
	v_lshl_add_u64 v[52:53], s[18:19], 0, v[48:49]
	v_pk_mul_f32 v[50:51], v[152:153], 0.5 op_sel_hi:[1,0]
	v_pk_mul_f32 v[48:49], v[150:151], 0.5 op_sel_hi:[1,0]
	v_lshl_add_u64 v[52:53], v[52:53], 0, v[70:71]
	global_store_dwordx4 v[52:53], v[48:51], off
	s_nop 1
	v_pk_mul_f32 v[50:51], v[58:59], 0.5 op_sel_hi:[1,0]
	v_pk_mul_f32 v[48:49], v[56:57], 0.5 op_sel_hi:[1,0]
	global_store_dwordx4 v[52:53], v[48:51], off offset:64
	s_nop 1
	v_pk_mul_f32 v[50:51], v[104:105], 0.5 op_sel_hi:[1,0]
	v_pk_mul_f32 v[48:49], v[102:103], 0.5 op_sel_hi:[1,0]
	global_store_dwordx4 v[52:53], v[48:51], off offset:512
	s_nop 1
	v_pk_mul_f32 v[50:51], v[124:125], 0.5 op_sel_hi:[1,0]
	v_pk_mul_f32 v[48:49], v[122:123], 0.5 op_sel_hi:[1,0]
	global_store_dwordx4 v[52:53], v[48:51], off offset:576
	s_nop 1
	v_add_u32_e32 v48, 0x90, v68
	v_ashrrev_i32_e32 v49, 31, v48
	v_lshlrev_b64 v[48:49], 12, v[48:49]
	v_lshl_add_u64 v[48:49], s[18:19], 0, v[48:49]
	v_lshl_add_u64 v[48:49], v[48:49], 0, v[70:71]
	global_store_dwordx4 v[48:49], v[32:35], off offset:64
	global_store_dwordx4 v[48:49], v[36:39], off
	s_nop 0
	v_pk_mul_f32 v[34:35], v[46:47], 0.5 op_sel_hi:[1,0]
	v_pk_mul_f32 v[32:33], v[44:45], 0.5 op_sel_hi:[1,0]
	global_store_dwordx4 v[48:49], v[32:35], off offset:512
	s_nop 1
	v_pk_mul_f32 v[34:35], v[42:43], 0.5 op_sel_hi:[1,0]
	v_pk_mul_f32 v[32:33], v[40:41], 0.5 op_sel_hi:[1,0]
	global_store_dwordx4 v[48:49], v[32:35], off offset:576
	s_nop 1
	v_add_u32_e32 v32, 0xa0, v68
	v_ashrrev_i32_e32 v33, 31, v32
	v_lshlrev_b64 v[32:33], 12, v[32:33]
	v_lshl_add_u64 v[32:33], s[18:19], 0, v[32:33]
	v_lshl_add_u64 v[32:33], v[32:33], 0, v[70:71]
	global_store_dwordx4 v[32:33], v[16:19], off offset:64
	global_store_dwordx4 v[32:33], v[20:23], off
	s_nop 0
	v_pk_mul_f32 v[18:19], v[30:31], 0.5 op_sel_hi:[1,0]
	v_pk_mul_f32 v[16:17], v[28:29], 0.5 op_sel_hi:[1,0]
	global_store_dwordx4 v[32:33], v[16:19], off offset:512
	s_nop 1
	v_pk_mul_f32 v[18:19], v[26:27], 0.5 op_sel_hi:[1,0]
	v_pk_mul_f32 v[16:17], v[24:25], 0.5 op_sel_hi:[1,0]
	global_store_dwordx4 v[32:33], v[16:19], off offset:576
	s_nop 1
	v_add_u32_e32 v16, 0xb0, v68
	v_ashrrev_i32_e32 v17, 31, v16
	v_lshlrev_b64 v[16:17], 12, v[16:17]
	v_lshl_add_u64 v[16:17], s[18:19], 0, v[16:17]
	v_lshl_add_u64 v[16:17], v[16:17], 0, v[70:71]
	global_store_dwordx4 v[16:17], v[0:3], off offset:64
	s_mov_b32 s18, s12
	global_store_dwordx4 v[16:17], v[4:7], off
	v_pk_mul_f32 v[2:3], v[14:15], 0.5 op_sel_hi:[1,0]
	v_pk_mul_f32 v[0:1], v[12:13], 0.5 op_sel_hi:[1,0]
	global_store_dwordx4 v[16:17], v[0:3], off offset:512
	s_nop 1
	v_pk_mul_f32 v[2:3], v[10:11], 0.5 op_sel_hi:[1,0]
	v_pk_mul_f32 v[0:1], v[8:9], 0.5 op_sel_hi:[1,0]
	global_store_dwordx4 v[16:17], v[0:3], off offset:576
	s_cbranch_vccz .LBB0_352

.LBB0_561:
	global_load_dwordx4 v[80:83], v[70:71], off
	global_load_dwordx4 v[84:87], v[70:71], off offset:1024
	global_load_dwordx4 v[88:91], v[70:71], off offset:2048
	global_load_dwordx4 v[92:95], v[70:71], off offset:3072
	v_add_co_u32_e32 v0, vcc, 0x1000, v70
	s_add_i32 s6, s6, s0
	s_nop 0
	v_addc_co_u32_e32 v1, vcc, 0, v71, vcc
	global_load_dwordx4 v[60:63], v[0:1], off
	global_load_dwordx4 v[56:59], v[0:1], off offset:1024
	global_load_dwordx4 v[52:55], v[0:1], off offset:2048
	global_load_dwordx4 v[48:51], v[0:1], off offset:3072
	v_add_co_u32_e32 v0, vcc, 0x2000, v70
	s_cmpk_gt_i32 s6, 0x3fff
	s_nop 0
	v_addc_co_u32_e32 v1, vcc, 0, v71, vcc
	global_load_dwordx4 v[44:47], v[0:1], off
	global_load_dwordx4 v[32:35], v[0:1], off offset:1024
	global_load_dwordx4 v[24:27], v[0:1], off offset:2048
	global_load_dwordx4 v[16:19], v[0:1], off offset:3072
	v_add_co_u32_e32 v0, vcc, 0x3000, v70
	v_addc_co_u32_e32 v1, vcc, 0, v71, vcc
	global_load_dwordx4 v[12:15], v[0:1], off
	global_load_dwordx4 v[8:11], v[0:1], off offset:1024
	global_load_dwordx4 v[4:7], v[0:1], off offset:2048
	s_nop 0
	global_load_dwordx4 v[0:3], v[0:1], off offset:3072
	s_nop 0
	global_load_dwordx4 v[40:43], v[66:67], off
	global_load_dwordx4 v[36:39], v[66:67], off offset:1024
	global_load_dwordx4 v[28:31], v[66:67], off offset:2048
	global_load_dwordx4 v[20:23], v[66:67], off offset:3072
	s_waitcnt vmcnt(8)
	v_pk_mul_f32 v[96:97], v[82:83], v[82:83]
	v_pk_mul_f32 v[98:99], v[80:81], v[80:81]
	v_mul_f32_e32 v79, v92, v92
	v_pk_mov_b32 v[100:101], v[98:99], v[96:97] op_sel:[1,0]
	v_mov_b32_e32 v99, v97
	v_pk_add_f32 v[96:97], v[100:101], v[98:99]
	v_pk_mul_f32 v[98:99], v[86:87], v[86:87]
	v_pk_mul_f32 v[100:101], v[84:85], v[84:85]
	v_pk_add_f32 v[96:97], v[96:97], v[96:97] op_sel:[0,1] op_sel_hi:[1,0]
	v_pk_mov_b32 v[102:103], v[100:101], v[98:99] op_sel:[1,0]
	v_mov_b32_e32 v101, v99
	v_pk_add_f32 v[98:99], v[102:103], v[100:101]
	v_mul_f32_e32 v100, v93, v93
	v_pk_add_f32 v[98:99], v[98:99], v[98:99] op_sel:[0,1] op_sel_hi:[1,0]
	v_mov_b32_e32 v97, v79
	v_mov_b32_e32 v99, v100
	v_pk_add_f32 v[96:97], v[96:97], v[98:99]
	v_mul_f32_e32 v98, v89, v89
	v_mul_f32_e32 v101, v94, v94
	v_pk_fma_f32 v[98:99], v[88:89], v[88:89], v[98:99] op_sel_hi:[1,1,0]
	v_mul_f32_e32 v100, v91, v91
	v_mul_f32_e32 v102, v95, v95
	v_mov_b32_e32 v99, v101
	v_pk_fma_f32 v[100:101], v[90:91], v[90:91], v[100:101] op_sel_hi:[1,1,0]
	v_lshl_add_u64 v[70:71], v[70:71], 0, s[4:5]
	v_mov_b32_e32 v101, v102
	v_pk_add_f32 v[98:99], v[98:99], v[100:101]
	s_nop 0
	v_pk_add_f32 v[96:97], v[96:97], v[98:99]
	s_nop 0
	v_add_f32_e32 v79, v96, v97
	ds_bpermute_b32 v96, v72, v79
	s_waitcnt lgkmcnt(0)
	v_add_f32_e32 v79, v79, v96
	ds_bpermute_b32 v96, v73, v79
	s_waitcnt lgkmcnt(0)
	v_add_f32_e32 v79, v79, v96
	ds_bpermute_b32 v96, v74, v79
	s_waitcnt lgkmcnt(0)
	v_add_f32_e32 v79, v79, v96
	ds_bpermute_b32 v96, v75, v79
	s_waitcnt lgkmcnt(0)
	v_add_f32_e32 v79, v79, v96
	ds_bpermute_b32 v96, v76, v79
	s_waitcnt lgkmcnt(0)
	v_add_f32_e32 v79, v79, v96
	ds_bpermute_b32 v96, v77, v79
	s_waitcnt lgkmcnt(0)
	v_add_f32_e32 v79, v79, v96
	v_fmamk_f32 v79, v79, 0x3a800000, v78
	v_cmp_gt_f32_e32 vcc, s1, v79
	v_mul_f32_e32 v96, 0x4b800000, v79
	s_nop 0
	v_cndmask_b32_e32 v79, v79, v96, vcc
	v_rsq_f32_e32 v79, v79
	s_nop 0
	v_mul_f32_e32 v96, 0x45800000, v79
	v_cndmask_b32_e32 v79, v79, v96, vcc
	v_mul_f32_e32 v80, v80, v79
	v_mul_f32_e32 v81, v81, v79
	s_waitcnt vmcnt(3)
	v_mul_f32_e32 v80, v40, v80
	v_mul_f32_e32 v81, v41, v81
	v_cvt_pk_bf16_f32 v80, v80, v81
	v_mul_f32_e32 v81, v82, v79
	v_mul_f32_e32 v81, v42, v81
	v_mul_f32_e32 v82, v83, v79
	v_mul_f32_e32 v82, v43, v82
	v_cvt_pk_bf16_f32 v81, v81, v82
	global_store_dwordx2 v[68:69], v[80:81], off
	v_mul_f32_e32 v80, v84, v79
	v_mul_f32_e32 v81, v85, v79
	s_waitcnt vmcnt(3)
	v_mul_f32_e32 v80, v36, v80
	v_mul_f32_e32 v81, v37, v81
	v_cvt_pk_bf16_f32 v80, v80, v81
	v_mul_f32_e32 v81, v86, v79
	v_mul_f32_e32 v81, v38, v81
	v_mul_f32_e32 v82, v87, v79
	v_mul_f32_e32 v82, v39, v82
	v_cvt_pk_bf16_f32 v81, v81, v82
	global_store_dwordx2 v[68:69], v[80:81], off offset:512
	v_mul_f32_e32 v80, v88, v79
	v_mul_f32_e32 v81, v89, v79
	s_waitcnt vmcnt(3)
	v_mul_f32_e32 v80, v28, v80
	v_mul_f32_e32 v81, v29, v81
	v_cvt_pk_bf16_f32 v80, v80, v81
	v_mul_f32_e32 v81, v90, v79
	v_mul_f32_e32 v81, v30, v81
	v_mul_f32_e32 v82, v91, v79
	v_mul_f32_e32 v82, v31, v82
	v_cvt_pk_bf16_f32 v81, v81, v82
	global_store_dwordx2 v[68:69], v[80:81], off offset:1024
	v_mul_f32_e32 v80, v92, v79
	v_mul_f32_e32 v81, v93, v79
	s_waitcnt vmcnt(3)
	v_mul_f32_e32 v80, v20, v80
	v_mul_f32_e32 v81, v21, v81
	v_cvt_pk_bf16_f32 v80, v80, v81
	v_mul_f32_e32 v81, v94, v79
	v_mul_f32_e32 v81, v22, v81
	v_mul_f32_e32 v79, v95, v79
	v_mul_f32_e32 v79, v23, v79
	v_cvt_pk_bf16_f32 v81, v81, v79
	global_store_dwordx2 v[68:69], v[80:81], off offset:1536
	v_pk_mul_f32 v[80:81], v[62:63], v[62:63]
	v_pk_mul_f32 v[82:83], v[60:61], v[60:61]
	v_mul_f32_e32 v79, v48, v48
	v_pk_mov_b32 v[84:85], v[82:83], v[80:81] op_sel:[1,0]
	v_mov_b32_e32 v83, v81
	v_pk_add_f32 v[80:81], v[84:85], v[82:83]
	v_pk_mul_f32 v[82:83], v[58:59], v[58:59]
	v_pk_mul_f32 v[84:85], v[56:57], v[56:57]
	v_pk_add_f32 v[80:81], v[80:81], v[80:81] op_sel:[0,1] op_sel_hi:[1,0]
	v_pk_mov_b32 v[86:87], v[84:85], v[82:83] op_sel:[1,0]
	v_mov_b32_e32 v85, v83
	v_pk_add_f32 v[82:83], v[86:87], v[84:85]
	v_mul_f32_e32 v84, v49, v49
	v_pk_add_f32 v[82:83], v[82:83], v[82:83] op_sel:[0,1] op_sel_hi:[1,0]
	v_mov_b32_e32 v81, v79
	v_mov_b32_e32 v83, v84
	v_pk_add_f32 v[80:81], v[80:81], v[82:83]
	v_mul_f32_e32 v82, v53, v53
	v_mul_f32_e32 v85, v50, v50
	v_pk_fma_f32 v[82:83], v[52:53], v[52:53], v[82:83] op_sel_hi:[1,1,0]
	v_mul_f32_e32 v84, v55, v55
	v_mul_f32_e32 v86, v51, v51
	v_mov_b32_e32 v83, v85
	v_pk_fma_f32 v[84:85], v[54:55], v[54:55], v[84:85] op_sel_hi:[1,1,0]
	s_nop 0
	v_mov_b32_e32 v85, v86
	v_pk_add_f32 v[82:83], v[82:83], v[84:85]
	s_nop 0
	v_pk_add_f32 v[80:81], v[80:81], v[82:83]
	s_nop 0
	v_add_f32_e32 v79, v80, v81
	ds_bpermute_b32 v80, v72, v79
	s_waitcnt lgkmcnt(0)
	v_add_f32_e32 v79, v79, v80
	ds_bpermute_b32 v80, v73, v79
	s_waitcnt lgkmcnt(0)
	v_add_f32_e32 v79, v79, v80
	ds_bpermute_b32 v80, v74, v79
	s_waitcnt lgkmcnt(0)
	v_add_f32_e32 v79, v79, v80
	ds_bpermute_b32 v80, v75, v79
	s_waitcnt lgkmcnt(0)
	v_add_f32_e32 v79, v79, v80
	ds_bpermute_b32 v80, v76, v79
	s_waitcnt lgkmcnt(0)
	v_add_f32_e32 v79, v79, v80
	ds_bpermute_b32 v80, v77, v79
	s_waitcnt lgkmcnt(0)
	v_add_f32_e32 v79, v79, v80
	v_fmamk_f32 v79, v79, 0x3a800000, v78
	v_cmp_gt_f32_e32 vcc, s1, v79
	v_mul_f32_e32 v80, 0x4b800000, v79
	s_nop 0
	v_cndmask_b32_e32 v79, v79, v80, vcc
	v_rsq_f32_e32 v79, v79
	s_nop 0
	v_mul_f32_e32 v80, 0x45800000, v79
	v_cndmask_b32_e32 v79, v79, v80, vcc
	v_mul_f32_e32 v48, v48, v79
	v_mul_f32_e32 v49, v49, v79
	v_mul_f32_e32 v52, v52, v79
	v_mul_f32_e32 v53, v53, v79
	v_mul_f32_e32 v48, v20, v48
	v_mul_f32_e32 v49, v21, v49
	v_mul_f32_e32 v52, v28, v52
	v_mul_f32_e32 v53, v29, v53
	v_cvt_pk_bf16_f32 v48, v48, v49
	v_mul_f32_e32 v49, v50, v79
	v_cvt_pk_bf16_f32 v52, v52, v53
	v_mul_f32_e32 v53, v54, v79
	v_mul_f32_e32 v49, v22, v49
	v_mul_f32_e32 v50, v51, v79
	v_mul_f32_e32 v53, v30, v53
	v_mul_f32_e32 v54, v55, v79
	v_mul_f32_e32 v50, v23, v50
	v_cvt_pk_bf16_f32 v49, v49, v50
	v_mul_f32_e32 v54, v31, v54
	v_cvt_pk_bf16_f32 v53, v53, v54
	global_store_dwordx2 v[68:69], v[48:49], off offset:3584
	v_pk_mul_f32 v[48:49], v[46:47], v[46:47]
	v_pk_mul_f32 v[50:51], v[44:45], v[44:45]
	global_store_dwordx2 v[68:69], v[52:53], off offset:3072
	v_pk_mov_b32 v[52:53], v[50:51], v[48:49] op_sel:[1,0]
	v_mov_b32_e32 v51, v49
	v_pk_add_f32 v[48:49], v[52:53], v[50:51]
	v_pk_mul_f32 v[50:51], v[34:35], v[34:35]
	v_pk_mul_f32 v[52:53], v[32:33], v[32:33]
	v_pk_add_f32 v[48:49], v[48:49], v[48:49] op_sel:[0,1] op_sel_hi:[1,0]
	v_pk_mov_b32 v[54:55], v[52:53], v[50:51] op_sel:[1,0]
	v_mov_b32_e32 v53, v51
	v_pk_add_f32 v[50:51], v[54:55], v[52:53]
	v_mul_f32_e32 v52, v16, v16
	v_mul_f32_e32 v53, v17, v17
	v_pk_add_f32 v[50:51], v[50:51], v[50:51] op_sel:[0,1] op_sel_hi:[1,0]
	v_mov_b32_e32 v49, v52
	v_mov_b32_e32 v51, v53
	v_pk_add_f32 v[48:49], v[48:49], v[50:51]
	v_mul_f32_e32 v50, v25, v25
	v_mul_f32_e32 v52, v27, v27
	v_mul_f32_e32 v54, v18, v18
	v_mul_f32_e32 v55, v19, v19
	v_pk_fma_f32 v[50:51], v[24:25], v[24:25], v[50:51] op_sel_hi:[1,1,0]
	v_pk_fma_f32 v[52:53], v[26:27], v[26:27], v[52:53] op_sel_hi:[1,1,0]
	v_mov_b32_e32 v51, v54
	v_mov_b32_e32 v53, v55
	v_pk_add_f32 v[50:51], v[50:51], v[52:53]
	v_mul_f32_e32 v60, v60, v79
	v_pk_add_f32 v[48:49], v[48:49], v[50:51]
	v_mul_f32_e32 v61, v61, v79
	v_add_f32_e32 v48, v48, v49
	ds_bpermute_b32 v49, v72, v48
	v_mul_f32_e32 v56, v56, v79
	v_mul_f32_e32 v57, v57, v79
	v_mul_f32_e32 v60, v40, v60
	v_mul_f32_e32 v61, v41, v61
	s_waitcnt lgkmcnt(0)
	v_add_f32_e32 v48, v48, v49
	ds_bpermute_b32 v49, v73, v48
	v_mul_f32_e32 v56, v36, v56
	v_mul_f32_e32 v57, v37, v57
	v_cvt_pk_bf16_f32 v60, v60, v61
	v_mul_f32_e32 v61, v62, v79
	s_waitcnt lgkmcnt(0)
	v_add_f32_e32 v48, v48, v49
	ds_bpermute_b32 v49, v74, v48
	v_cvt_pk_bf16_f32 v56, v56, v57
	v_mul_f32_e32 v57, v58, v79
	v_mul_f32_e32 v61, v42, v61
	v_mul_f32_e32 v62, v63, v79
	s_waitcnt lgkmcnt(0)
	v_add_f32_e32 v48, v48, v49
	ds_bpermute_b32 v49, v75, v48
	v_mul_f32_e32 v57, v38, v57
	v_mul_f32_e32 v58, v59, v79
	v_mul_f32_e32 v62, v43, v62
	v_cvt_pk_bf16_f32 v61, v61, v62
	s_waitcnt lgkmcnt(0)
	v_add_f32_e32 v48, v48, v49
	ds_bpermute_b32 v49, v76, v48
	global_store_dwordx2 v[68:69], v[60:61], off offset:2048
	v_mul_f32_e32 v58, v39, v58
	v_cvt_pk_bf16_f32 v57, v57, v58
	global_store_dwordx2 v[68:69], v[56:57], off offset:2560
	s_waitcnt lgkmcnt(0)
	v_add_f32_e32 v48, v48, v49
	ds_bpermute_b32 v49, v77, v48
	s_waitcnt lgkmcnt(0)
	v_add_f32_e32 v48, v48, v49
	v_fmamk_f32 v48, v48, 0x3a800000, v78
	v_cmp_gt_f32_e32 vcc, s1, v48
	v_mul_f32_e32 v49, 0x4b800000, v48
	s_nop 0
	v_cndmask_b32_e32 v48, v48, v49, vcc
	v_rsq_f32_e32 v48, v48
	s_nop 0
	v_mul_f32_e32 v49, 0x45800000, v48
	v_cndmask_b32_e32 v48, v48, v49, vcc
	v_mul_f32_e32 v44, v44, v48
	v_mul_f32_e32 v45, v45, v48
	v_mul_f32_e32 v44, v40, v44
	v_mul_f32_e32 v45, v41, v45
	v_mul_f32_e32 v16, v16, v48
	v_mul_f32_e32 v17, v17, v48
	v_cvt_pk_bf16_f32 v44, v44, v45
	v_mul_f32_e32 v45, v46, v48
	v_mul_f32_e32 v46, v47, v48
	v_mul_f32_e32 v24, v24, v48
	v_mul_f32_e32 v25, v25, v48
	v_mul_f32_e32 v16, v20, v16
	v_mul_f32_e32 v17, v21, v17
	v_mul_f32_e32 v45, v42, v45
	v_mul_f32_e32 v46, v43, v46
	v_mul_f32_e32 v24, v28, v24
	v_mul_f32_e32 v25, v29, v25
	v_cvt_pk_bf16_f32 v16, v16, v17
	v_mul_f32_e32 v17, v18, v48
	v_cvt_pk_bf16_f32 v45, v45, v46
	v_add_co_u32_e32 v46, vcc, s7, v68
	v_cvt_pk_bf16_f32 v24, v24, v25
	v_mul_f32_e32 v25, v26, v48
	v_mul_f32_e32 v17, v22, v17
	v_mul_f32_e32 v18, v19, v48
	v_addc_co_u32_e32 v47, vcc, 0, v69, vcc
	v_mul_f32_e32 v25, v30, v25
	v_mul_f32_e32 v26, v27, v48
	v_mul_f32_e32 v18, v23, v18
	v_cvt_pk_bf16_f32 v17, v17, v18
	v_mul_f32_e32 v26, v31, v26
	v_cvt_pk_bf16_f32 v25, v25, v26
	global_store_dwordx2 v[46:47], v[16:17], off offset:1536
	v_pk_mul_f32 v[16:17], v[14:15], v[14:15]
	v_pk_mul_f32 v[18:19], v[12:13], v[12:13]
	global_store_dwordx2 v[46:47], v[24:25], off offset:1024
	v_pk_mov_b32 v[24:25], v[18:19], v[16:17] op_sel:[1,0]
	v_mov_b32_e32 v19, v17
	v_pk_add_f32 v[16:17], v[24:25], v[18:19]
	v_pk_mul_f32 v[18:19], v[10:11], v[10:11]
	v_pk_mul_f32 v[24:25], v[8:9], v[8:9]
	v_pk_add_f32 v[16:17], v[16:17], v[16:17] op_sel:[0,1] op_sel_hi:[1,0]
	v_pk_mov_b32 v[26:27], v[24:25], v[18:19] op_sel:[1,0]
	v_mov_b32_e32 v25, v19
	v_pk_add_f32 v[18:19], v[26:27], v[24:25]
	v_mul_f32_e32 v24, v0, v0
	v_mul_f32_e32 v25, v1, v1
	v_pk_add_f32 v[18:19], v[18:19], v[18:19] op_sel:[0,1] op_sel_hi:[1,0]
	v_mov_b32_e32 v17, v24
	v_mov_b32_e32 v19, v25
	v_pk_add_f32 v[16:17], v[16:17], v[18:19]
	v_mul_f32_e32 v18, v5, v5
	v_mul_f32_e32 v24, v7, v7
	v_mul_f32_e32 v26, v2, v2
	v_mul_f32_e32 v27, v3, v3
	v_pk_fma_f32 v[18:19], v[4:5], v[4:5], v[18:19] op_sel_hi:[1,1,0]
	v_pk_fma_f32 v[24:25], v[6:7], v[6:7], v[24:25] op_sel_hi:[1,1,0]
	v_mov_b32_e32 v19, v26
	v_mov_b32_e32 v25, v27
	v_pk_add_f32 v[18:19], v[18:19], v[24:25]
	v_mul_f32_e32 v32, v32, v48
	v_pk_add_f32 v[16:17], v[16:17], v[18:19]
	v_mul_f32_e32 v33, v33, v48
	v_add_f32_e32 v16, v16, v17
	ds_bpermute_b32 v17, v72, v16
	v_mul_f32_e32 v32, v36, v32
	v_mul_f32_e32 v33, v37, v33
	v_cvt_pk_bf16_f32 v32, v32, v33
	v_mul_f32_e32 v33, v34, v48
	s_waitcnt lgkmcnt(0)
	v_add_f32_e32 v16, v16, v17
	ds_bpermute_b32 v17, v73, v16
	v_mul_f32_e32 v33, v38, v33
	v_mul_f32_e32 v34, v35, v48
	v_lshl_add_u64 v[68:69], v[68:69], 0, s[2:3]
	global_store_dwordx2 v[46:47], v[44:45], off
	s_waitcnt lgkmcnt(0)
	v_add_f32_e32 v16, v16, v17
	ds_bpermute_b32 v17, v74, v16
	v_mul_f32_e32 v34, v39, v34
	v_cvt_pk_bf16_f32 v33, v33, v34
	global_store_dwordx2 v[46:47], v[32:33], off offset:512
	s_waitcnt lgkmcnt(0)
	v_add_f32_e32 v16, v16, v17
	ds_bpermute_b32 v17, v75, v16
	s_waitcnt lgkmcnt(0)
	v_add_f32_e32 v16, v16, v17
	ds_bpermute_b32 v17, v76, v16
	s_waitcnt lgkmcnt(0)
	v_add_f32_e32 v16, v16, v17
	ds_bpermute_b32 v17, v77, v16
	s_waitcnt lgkmcnt(0)
	v_add_f32_e32 v16, v16, v17
	v_fmamk_f32 v16, v16, 0x3a800000, v78
	v_cmp_gt_f32_e32 vcc, s1, v16
	v_mul_f32_e32 v17, 0x4b800000, v16
	s_nop 0
	v_cndmask_b32_e32 v16, v16, v17, vcc
	v_rsq_f32_e32 v16, v16
	s_nop 0
	v_mul_f32_e32 v17, 0x45800000, v16
	v_cndmask_b32_e32 v16, v16, v17, vcc
	v_mul_f32_e32 v12, v12, v16
	v_mul_f32_e32 v13, v13, v16
	v_mul_f32_e32 v8, v8, v16
	v_mul_f32_e32 v9, v9, v16
	v_mul_f32_e32 v4, v4, v16
	v_mul_f32_e32 v5, v5, v16
	v_mul_f32_e32 v0, v0, v16
	v_mul_f32_e32 v1, v1, v16
	v_mul_f32_e32 v12, v40, v12
	v_mul_f32_e32 v13, v41, v13
	v_mul_f32_e32 v8, v36, v8
	v_mul_f32_e32 v9, v37, v9
	v_mul_f32_e32 v4, v28, v4
	v_mul_f32_e32 v5, v29, v5
	v_mul_f32_e32 v0, v20, v0
	v_mul_f32_e32 v1, v21, v1
	v_cvt_pk_bf16_f32 v12, v12, v13
	v_mul_f32_e32 v13, v14, v16
	v_cvt_pk_bf16_f32 v8, v8, v9
	v_mul_f32_e32 v9, v10, v16
	v_cvt_pk_bf16_f32 v4, v4, v5
	v_mul_f32_e32 v5, v6, v16
	v_cvt_pk_bf16_f32 v0, v0, v1
	v_mul_f32_e32 v1, v2, v16
	v_mul_f32_e32 v13, v42, v13
	v_mul_f32_e32 v14, v15, v16
	v_mul_f32_e32 v9, v38, v9
	v_mul_f32_e32 v10, v11, v16
	v_mul_f32_e32 v5, v30, v5
	v_mul_f32_e32 v6, v7, v16
	v_mul_f32_e32 v1, v22, v1
	v_mul_f32_e32 v2, v3, v16
	v_mul_f32_e32 v14, v43, v14
	v_cvt_pk_bf16_f32 v13, v13, v14
	global_store_dwordx2 v[46:47], v[12:13], off offset:2048
	v_mul_f32_e32 v10, v39, v10
	v_cvt_pk_bf16_f32 v9, v9, v10
	global_store_dwordx2 v[46:47], v[8:9], off offset:2560
	v_mul_f32_e32 v6, v31, v6
	v_cvt_pk_bf16_f32 v5, v5, v6
	global_store_dwordx2 v[46:47], v[4:5], off offset:3072
	v_mul_f32_e32 v2, v23, v2
	v_cvt_pk_bf16_f32 v1, v1, v2
	global_store_dwordx2 v[46:47], v[0:1], off offset:3584
	s_cbranch_scc0 .LBB0_561

.LBB0_632:
	ds_read_b128 v[156:159], v152
	ds_read_b128 v[160:163], v152 offset:1024
	ds_read_b128 v[164:167], v152 offset:2048
	ds_read_b128 v[168:171], v152 offset:3072
	ds_read_b128 v[172:175], v153
	ds_read_b128 v[176:179], v153 offset:1024
	ds_read_b128 v[180:183], v153 offset:2048
	ds_read_b128 v[186:189], v153 offset:3072
	s_add_u32 s20, s4, s2
	s_addc_u32 s21, s5, s3
	s_add_u32 s20, s20, 0x100
	s_addc_u32 s21, s21, 0
	s_add_u32 s47, s44, s2
	s_addc_u32 s48, s45, s3
	s_cmpk_eq_i32 s2, 0x700
	s_cselect_b32 s21, s17, s21
	s_cselect_b32 s20, s16, s20
	s_cselect_b32 s49, s19, s48
	s_cselect_b32 s48, s18, s47
	s_mov_b32 m0, s37
	v_lshl_add_u64 v[148:149], v[146:147], 0, s[2:3]
	ds_read_b128 v[190:193], v154
	ds_read_b128 v[196:199], v154 offset:1024
	ds_read_b128 v[200:203], v154 offset:2048
	ds_read_b128 v[204:207], v154 offset:3072
	ds_read_b128 v[208:211], v154 offset:4096
	ds_read_b128 v[212:215], v154 offset:5120
	ds_read_b128 v[216:219], v154 offset:6144
	ds_read_b128 v[220:223], v154 offset:7168
	global_load_lds_dwordx4 v[148:149], off
	v_lshl_add_u64 v[148:149], v[144:145], 0, s[2:3]
	s_add_i32 m0, s24, 0xe000
	s_nop 0
	global_load_lds_dwordx4 v[148:149], off
	s_waitcnt vmcnt(8)
	s_waitcnt lgkmcnt(0)
	s_barrier
	s_waitcnt lgkmcnt(0)
	v_mfma_f32_16x16x32_bf16 v[124:127], v[156:159], v[190:193], v[124:127]
	v_mfma_f32_16x16x32_bf16 v[120:123], v[164:167], v[190:193], v[120:123]
	v_mfma_f32_16x16x32_bf16 v[108:111], v[156:159], v[200:203], v[108:111]
	v_mfma_f32_16x16x32_bf16 v[104:107], v[164:167], v[200:203], v[104:107]
	v_mfma_f32_16x16x32_bf16 v[92:95], v[156:159], v[208:211], v[92:95]
	v_mfma_f32_16x16x32_bf16 v[88:91], v[164:167], v[208:211], v[88:91]
	v_mfma_f32_16x16x32_bf16 v[76:79], v[156:159], v[216:219], v[76:79]
	v_mfma_f32_16x16x32_bf16 v[72:75], v[164:167], v[216:219], v[72:75]
	v_mfma_f32_16x16x32_bf16 v[124:127], v[160:163], v[196:199], v[124:127]
	v_mfma_f32_16x16x32_bf16 v[120:123], v[168:171], v[196:199], v[120:123]
	v_mfma_f32_16x16x32_bf16 v[108:111], v[160:163], v[204:207], v[108:111]
	v_mfma_f32_16x16x32_bf16 v[104:107], v[168:171], v[204:207], v[104:107]
	v_mfma_f32_16x16x32_bf16 v[92:95], v[160:163], v[212:215], v[92:95]
	v_mfma_f32_16x16x32_bf16 v[88:91], v[168:171], v[212:215], v[88:91]
	v_mfma_f32_16x16x32_bf16 v[76:79], v[160:163], v[220:223], v[76:79]
	v_mfma_f32_16x16x32_bf16 v[72:75], v[168:171], v[220:223], v[72:75]
	v_mfma_f32_16x16x32_bf16 v[116:119], v[172:175], v[190:193], v[116:119]
	v_mfma_f32_16x16x32_bf16 v[112:115], v[180:183], v[190:193], v[112:115]
	v_mfma_f32_16x16x32_bf16 v[100:103], v[172:175], v[200:203], v[100:103]
	v_mfma_f32_16x16x32_bf16 v[96:99], v[180:183], v[200:203], v[96:99]
	v_mfma_f32_16x16x32_bf16 v[84:87], v[172:175], v[208:211], v[84:87]
	v_mfma_f32_16x16x32_bf16 v[80:83], v[180:183], v[208:211], v[80:83]
	v_mfma_f32_16x16x32_bf16 v[68:71], v[172:175], v[216:219], v[68:71]
	v_mfma_f32_16x16x32_bf16 v[64:67], v[180:183], v[216:219], v[64:67]
	v_mfma_f32_16x16x32_bf16 v[116:119], v[176:179], v[196:199], v[116:119]
	v_mfma_f32_16x16x32_bf16 v[112:115], v[186:189], v[196:199], v[112:115]
	v_mfma_f32_16x16x32_bf16 v[100:103], v[176:179], v[204:207], v[100:103]
	v_mfma_f32_16x16x32_bf16 v[96:99], v[186:189], v[204:207], v[96:99]
	v_mfma_f32_16x16x32_bf16 v[84:87], v[176:179], v[212:215], v[84:87]
	v_mfma_f32_16x16x32_bf16 v[80:83], v[186:189], v[212:215], v[80:83]
	v_mfma_f32_16x16x32_bf16 v[68:71], v[176:179], v[220:223], v[68:71]
	v_mfma_f32_16x16x32_bf16 v[64:67], v[186:189], v[220:223], v[64:67]
	s_barrier
	s_add_i32 s47, s30, s22
	v_lshl_add_u64 v[148:149], s[48:49], 0, v[130:131]
	s_mov_b32 m0, s47
	ds_read_b128 v[190:193], v154 offset:16384
	ds_read_b128 v[196:199], v154 offset:17408
	ds_read_b128 v[200:203], v154 offset:18432
	ds_read_b128 v[204:207], v154 offset:19456
	ds_read_b128 v[208:211], v154 offset:20480
	ds_read_b128 v[212:215], v154 offset:21504
	ds_read_b128 v[216:219], v154 offset:22528
	ds_read_b128 v[220:223], v154 offset:23552
	global_load_lds_dwordx4 v[148:149], off
	s_add_i32 m0, s47, 0x2000
	v_lshl_add_u64 v[194:195], s[48:49], 0, v[132:133]
	s_add_u32 s48, s48, s6
	s_addc_u32 s49, s49, s7
	s_add_i32 s47, s31, s22
	global_load_lds_dwordx4 v[194:195], off
	v_lshl_add_u64 v[224:225], s[48:49], 0, v[130:131]
	s_mov_b32 m0, s47
	v_lshl_add_u64 v[226:227], s[48:49], 0, v[132:133]
	global_load_lds_dwordx4 v[224:225], off
	s_add_i32 m0, s47, 0x2000
	v_lshl_add_u64 v[228:229], s[20:21], 0, v[130:131]
	global_load_lds_dwordx4 v[226:227], off
	s_mov_b32 m0, s24
	v_lshl_add_u64 v[230:231], s[20:21], 0, v[132:133]
	global_load_lds_dwordx4 v[228:229], off
	s_mov_b32 m0, s25
	s_nop 0
	global_load_lds_dwordx4 v[230:231], off
	s_waitcnt vmcnt(8)
	s_waitcnt lgkmcnt(0)
	s_barrier
	s_waitcnt lgkmcnt(0)
	v_mfma_f32_16x16x32_bf16 v[60:63], v[156:159], v[190:193], v[60:63]
	v_mfma_f32_16x16x32_bf16 v[56:59], v[164:167], v[190:193], v[56:59]
	v_mfma_f32_16x16x32_bf16 v[44:47], v[156:159], v[200:203], v[44:47]
	v_mfma_f32_16x16x32_bf16 v[40:43], v[164:167], v[200:203], v[40:43]
	v_mfma_f32_16x16x32_bf16 v[28:31], v[156:159], v[208:211], v[28:31]
	v_mfma_f32_16x16x32_bf16 v[24:27], v[164:167], v[208:211], v[24:27]
	v_mfma_f32_16x16x32_bf16 v[12:15], v[156:159], v[216:219], v[12:15]
	v_mfma_f32_16x16x32_bf16 v[8:11], v[164:167], v[216:219], v[8:11]
	v_mfma_f32_16x16x32_bf16 v[60:63], v[160:163], v[196:199], v[60:63]
	v_mfma_f32_16x16x32_bf16 v[56:59], v[168:171], v[196:199], v[56:59]
	v_mfma_f32_16x16x32_bf16 v[44:47], v[160:163], v[204:207], v[44:47]
	v_mfma_f32_16x16x32_bf16 v[40:43], v[168:171], v[204:207], v[40:43]
	v_mfma_f32_16x16x32_bf16 v[28:31], v[160:163], v[212:215], v[28:31]
	v_mfma_f32_16x16x32_bf16 v[24:27], v[168:171], v[212:215], v[24:27]
	v_mfma_f32_16x16x32_bf16 v[12:15], v[160:163], v[220:223], v[12:15]
	v_mfma_f32_16x16x32_bf16 v[8:11], v[168:171], v[220:223], v[8:11]
	v_mfma_f32_16x16x32_bf16 v[52:55], v[172:175], v[190:193], v[52:55]
	v_mfma_f32_16x16x32_bf16 v[48:51], v[180:183], v[190:193], v[48:51]
	v_mfma_f32_16x16x32_bf16 v[36:39], v[172:175], v[200:203], v[36:39]
	v_mfma_f32_16x16x32_bf16 v[32:35], v[180:183], v[200:203], v[32:35]
	v_mfma_f32_16x16x32_bf16 v[20:23], v[172:175], v[208:211], v[20:23]
	v_mfma_f32_16x16x32_bf16 v[16:19], v[180:183], v[208:211], v[16:19]
	v_mfma_f32_16x16x32_bf16 v[4:7], v[172:175], v[216:219], v[4:7]
	v_mfma_f32_16x16x32_bf16 v[0:3], v[180:183], v[216:219], v[0:3]
	v_mfma_f32_16x16x32_bf16 v[52:55], v[176:179], v[196:199], v[52:55]
	v_mfma_f32_16x16x32_bf16 v[48:51], v[186:189], v[196:199], v[48:51]
	v_mfma_f32_16x16x32_bf16 v[36:39], v[176:179], v[204:207], v[36:39]
	v_mfma_f32_16x16x32_bf16 v[32:35], v[186:189], v[204:207], v[32:35]
	v_mfma_f32_16x16x32_bf16 v[20:23], v[176:179], v[212:215], v[20:23]
	v_mfma_f32_16x16x32_bf16 v[16:19], v[186:189], v[212:215], v[16:19]
	v_mfma_f32_16x16x32_bf16 v[4:7], v[176:179], v[220:223], v[4:7]
	v_mfma_f32_16x16x32_bf16 v[0:3], v[186:189], v[220:223], v[0:3]
	s_barrier
	s_add_i32 s47, 0, 0x18000
	v_add_u32_e32 v134, s47, v150
	s_add_i32 s48, 0, 0x1c000
	ds_read_b128 v[156:159], v134
	ds_read_b128 v[160:163], v134 offset:1024
	ds_read_b128 v[164:167], v134 offset:2048
	ds_read_b128 v[168:171], v134 offset:3072
	v_add_u32_e32 v134, s48, v150
	ds_read_b128 v[172:175], v134
	ds_read_b128 v[176:179], v134 offset:1024
	ds_read_b128 v[180:183], v134 offset:2048
	ds_read_b128 v[186:189], v134 offset:3072
	s_add_u32 s20, s20, s6
	s_addc_u32 s21, s21, s7
	s_mov_b32 m0, s26
	v_lshl_add_u64 v[232:233], s[20:21], 0, v[130:131]
	ds_read_b128 v[190:193], v154 offset:32768
	ds_read_b128 v[196:199], v154 offset:33792
	ds_read_b128 v[200:203], v154 offset:34816
	ds_read_b128 v[204:207], v154 offset:35840
	ds_read_b128 v[208:211], v154 offset:36864
	ds_read_b128 v[212:215], v154 offset:37888
	ds_read_b128 v[216:219], v154 offset:38912
	ds_read_b128 v[220:223], v154 offset:39936
	global_load_lds_dwordx4 v[232:233], off
	v_lshl_add_u64 v[232:233], s[20:21], 0, v[132:133]
	s_mov_b32 m0, s27
	s_nop 0
	global_load_lds_dwordx4 v[232:233], off
	s_waitcnt vmcnt(8)
	s_waitcnt lgkmcnt(0)
	s_barrier
	s_waitcnt lgkmcnt(0)
	v_mfma_f32_16x16x32_bf16 v[124:127], v[156:159], v[190:193], v[124:127]
	v_mfma_f32_16x16x32_bf16 v[120:123], v[164:167], v[190:193], v[120:123]
	v_mfma_f32_16x16x32_bf16 v[108:111], v[156:159], v[200:203], v[108:111]
	v_mfma_f32_16x16x32_bf16 v[104:107], v[164:167], v[200:203], v[104:107]
	v_mfma_f32_16x16x32_bf16 v[92:95], v[156:159], v[208:211], v[92:95]
	v_mfma_f32_16x16x32_bf16 v[88:91], v[164:167], v[208:211], v[88:91]
	v_mfma_f32_16x16x32_bf16 v[76:79], v[156:159], v[216:219], v[76:79]
	v_mfma_f32_16x16x32_bf16 v[72:75], v[164:167], v[216:219], v[72:75]
	v_mfma_f32_16x16x32_bf16 v[124:127], v[160:163], v[196:199], v[124:127]
	v_mfma_f32_16x16x32_bf16 v[120:123], v[168:171], v[196:199], v[120:123]
	v_mfma_f32_16x16x32_bf16 v[108:111], v[160:163], v[204:207], v[108:111]
	v_mfma_f32_16x16x32_bf16 v[104:107], v[168:171], v[204:207], v[104:107]
	v_mfma_f32_16x16x32_bf16 v[92:95], v[160:163], v[212:215], v[92:95]
	v_mfma_f32_16x16x32_bf16 v[88:91], v[168:171], v[212:215], v[88:91]
	v_mfma_f32_16x16x32_bf16 v[76:79], v[160:163], v[220:223], v[76:79]
	v_mfma_f32_16x16x32_bf16 v[72:75], v[168:171], v[220:223], v[72:75]
	v_mfma_f32_16x16x32_bf16 v[116:119], v[172:175], v[190:193], v[116:119]
	v_mfma_f32_16x16x32_bf16 v[112:115], v[180:183], v[190:193], v[112:115]
	v_mfma_f32_16x16x32_bf16 v[100:103], v[172:175], v[200:203], v[100:103]
	v_mfma_f32_16x16x32_bf16 v[96:99], v[180:183], v[200:203], v[96:99]
	v_mfma_f32_16x16x32_bf16 v[84:87], v[172:175], v[208:211], v[84:87]
	v_mfma_f32_16x16x32_bf16 v[80:83], v[180:183], v[208:211], v[80:83]
	v_mfma_f32_16x16x32_bf16 v[68:71], v[172:175], v[216:219], v[68:71]
	v_mfma_f32_16x16x32_bf16 v[64:67], v[180:183], v[216:219], v[64:67]
	v_mfma_f32_16x16x32_bf16 v[116:119], v[176:179], v[196:199], v[116:119]
	v_mfma_f32_16x16x32_bf16 v[112:115], v[186:189], v[196:199], v[112:115]
	v_mfma_f32_16x16x32_bf16 v[100:103], v[176:179], v[204:207], v[100:103]
	v_mfma_f32_16x16x32_bf16 v[96:99], v[186:189], v[204:207], v[96:99]
	v_mfma_f32_16x16x32_bf16 v[84:87], v[176:179], v[212:215], v[84:87]
	v_mfma_f32_16x16x32_bf16 v[80:83], v[186:189], v[212:215], v[80:83]
	v_mfma_f32_16x16x32_bf16 v[68:71], v[176:179], v[220:223], v[68:71]
	v_mfma_f32_16x16x32_bf16 v[64:67], v[186:189], v[220:223], v[64:67]
	s_barrier
	s_add_i32 s20, s47, s22
	v_lshl_add_u64 v[148:149], v[148:149], 0, s[12:13]
	s_mov_b32 m0, s20
	ds_read_b128 v[190:193], v154 offset:49152
	ds_read_b128 v[196:199], v154 offset:50176
	ds_read_b128 v[200:203], v154 offset:51200
	ds_read_b128 v[204:207], v154 offset:52224
	ds_read_b128 v[208:211], v154 offset:53248
	ds_read_b128 v[212:215], v154 offset:54272
	ds_read_b128 v[216:219], v154 offset:55296
	ds_read_b128 v[220:223], v154 offset:56320
	global_load_lds_dwordx4 v[148:149], off
	v_lshl_add_u64 v[148:149], v[194:195], 0, s[12:13]
	s_add_i32 m0, s20, 0x2000
	s_add_i32 s20, s48, s22
	global_load_lds_dwordx4 v[148:149], off
	v_lshl_add_u64 v[148:149], v[224:225], 0, s[12:13]
	s_mov_b32 m0, s20
	s_nop 0
	global_load_lds_dwordx4 v[148:149], off
	v_lshl_add_u64 v[148:149], v[226:227], 0, s[12:13]
	s_add_i32 m0, s20, 0x2000
	s_nop 0
	global_load_lds_dwordx4 v[148:149], off
	v_lshl_add_u64 v[148:149], v[228:229], 0, s[12:13]
	s_mov_b32 m0, s28
	s_nop 0
	global_load_lds_dwordx4 v[148:149], off
	v_lshl_add_u64 v[148:149], v[230:231], 0, s[12:13]
	s_mov_b32 m0, s29
	s_nop 0
	global_load_lds_dwordx4 v[148:149], off
	s_waitcnt vmcnt(8)
	s_waitcnt lgkmcnt(0)
	s_barrier
	s_waitcnt lgkmcnt(0)
	v_mfma_f32_16x16x32_bf16 v[60:63], v[156:159], v[190:193], v[60:63]
	v_mfma_f32_16x16x32_bf16 v[56:59], v[164:167], v[190:193], v[56:59]
	v_mfma_f32_16x16x32_bf16 v[44:47], v[156:159], v[200:203], v[44:47]
	v_mfma_f32_16x16x32_bf16 v[40:43], v[164:167], v[200:203], v[40:43]
	v_mfma_f32_16x16x32_bf16 v[28:31], v[156:159], v[208:211], v[28:31]
	v_mfma_f32_16x16x32_bf16 v[24:27], v[164:167], v[208:211], v[24:27]
	v_mfma_f32_16x16x32_bf16 v[12:15], v[156:159], v[216:219], v[12:15]
	v_mfma_f32_16x16x32_bf16 v[8:11], v[164:167], v[216:219], v[8:11]
	v_mfma_f32_16x16x32_bf16 v[60:63], v[160:163], v[196:199], v[60:63]
	v_mfma_f32_16x16x32_bf16 v[56:59], v[168:171], v[196:199], v[56:59]
	v_mfma_f32_16x16x32_bf16 v[44:47], v[160:163], v[204:207], v[44:47]
	v_mfma_f32_16x16x32_bf16 v[40:43], v[168:171], v[204:207], v[40:43]
	v_mfma_f32_16x16x32_bf16 v[28:31], v[160:163], v[212:215], v[28:31]
	v_mfma_f32_16x16x32_bf16 v[24:27], v[168:171], v[212:215], v[24:27]
	v_mfma_f32_16x16x32_bf16 v[12:15], v[160:163], v[220:223], v[12:15]
	v_mfma_f32_16x16x32_bf16 v[8:11], v[168:171], v[220:223], v[8:11]
	v_mfma_f32_16x16x32_bf16 v[52:55], v[172:175], v[190:193], v[52:55]
	v_mfma_f32_16x16x32_bf16 v[48:51], v[180:183], v[190:193], v[48:51]
	v_mfma_f32_16x16x32_bf16 v[36:39], v[172:175], v[200:203], v[36:39]
	v_mfma_f32_16x16x32_bf16 v[32:35], v[180:183], v[200:203], v[32:35]
	v_mfma_f32_16x16x32_bf16 v[20:23], v[172:175], v[208:211], v[20:23]
	v_mfma_f32_16x16x32_bf16 v[16:19], v[180:183], v[208:211], v[16:19]
	v_mfma_f32_16x16x32_bf16 v[4:7], v[172:175], v[216:219], v[4:7]
	v_mfma_f32_16x16x32_bf16 v[0:3], v[180:183], v[216:219], v[0:3]
	v_mfma_f32_16x16x32_bf16 v[52:55], v[176:179], v[196:199], v[52:55]
	v_mfma_f32_16x16x32_bf16 v[48:51], v[186:189], v[196:199], v[48:51]
	v_mfma_f32_16x16x32_bf16 v[36:39], v[176:179], v[204:207], v[36:39]
	v_mfma_f32_16x16x32_bf16 v[32:35], v[186:189], v[204:207], v[32:35]
	v_mfma_f32_16x16x32_bf16 v[20:23], v[176:179], v[212:215], v[20:23]
	v_mfma_f32_16x16x32_bf16 v[16:19], v[186:189], v[212:215], v[16:19]
	v_mfma_f32_16x16x32_bf16 v[4:7], v[176:179], v[220:223], v[4:7]
	v_mfma_f32_16x16x32_bf16 v[0:3], v[186:189], v[220:223], v[0:3]
	s_barrier
	s_add_i32 s46, s46, 2
	s_add_u32 s2, s2, 0x100
	s_addc_u32 s3, s3, 0
	s_cmp_gt_u32 s46, 13
	s_cbranch_scc0 .LBB0_632
	s_and_b64 vcc, exec, s[14:15]
	s_cbranch_vccz .LBB0_635
	s_barrier

.LBB0_990:
	s_or_b64 exec, exec, s[20:21]
	v_mov_b64_e32 v[4:5], s[76:77]
	v_mad_i64_i32 v[0:1], s[0:1], v124, s24, v[4:5]
	v_lshlrev_b64 v[6:7], 1, v[122:123]
	v_lshl_add_u64 v[0:1], v[0:1], 0, v[6:7]
	v_or_b32_e32 v126, 1, v124
	v_add_co_u32_e32 v0, vcc, 0x1000, v0
	v_mad_i64_i32 v[8:9], s[0:1], v126, s24, v[4:5]
	s_nop 0
	v_addc_co_u32_e32 v1, vcc, 0, v1, vcc
	v_lshl_add_u64 v[8:9], v[8:9], 0, v[6:7]
	v_add_co_u32_e32 v8, vcc, 0x1000, v8
	v_or_b32_e32 v130, 2, v124
	s_nop 0
	v_addc_co_u32_e32 v9, vcc, 0, v9, vcc
	global_load_dwordx4 v[36:39], v[8:9], off
	v_mad_i64_i32 v[8:9], s[0:1], v130, s24, v[4:5]
	v_lshl_add_u64 v[8:9], v[8:9], 0, v[6:7]
	v_add_co_u32_e32 v8, vcc, 0x1000, v8
	v_or_b32_e32 v132, 3, v124
	s_nop 0
	v_addc_co_u32_e32 v9, vcc, 0, v9, vcc
	global_load_dwordx4 v[48:51], v[8:9], off
	v_mad_i64_i32 v[8:9], s[0:1], v132, s24, v[4:5]
	v_lshl_add_u64 v[8:9], v[8:9], 0, v[6:7]
	v_add_co_u32_e32 v8, vcc, 0x1000, v8
	v_or_b32_e32 v134, 4, v124
	s_nop 0
	v_addc_co_u32_e32 v9, vcc, 0, v9, vcc
	global_load_dwordx4 v[52:55], v[8:9], off
	v_mad_i64_i32 v[8:9], s[0:1], v134, s24, v[4:5]
	v_lshl_add_u64 v[8:9], v[8:9], 0, v[6:7]
	v_add_co_u32_e32 v8, vcc, 0x1000, v8
	v_or_b32_e32 v136, 5, v124
	s_nop 0
	v_addc_co_u32_e32 v9, vcc, 0, v9, vcc
	global_load_dwordx4 v[56:59], v[8:9], off
	v_mad_i64_i32 v[8:9], s[0:1], v136, s24, v[4:5]
	v_lshl_add_u64 v[8:9], v[8:9], 0, v[6:7]
	v_add_co_u32_e32 v8, vcc, 0x1000, v8
	v_or_b32_e32 v138, 6, v124
	s_nop 0
	v_addc_co_u32_e32 v9, vcc, 0, v9, vcc
	global_load_dwordx4 v[76:79], v[8:9], off
	v_mad_i64_i32 v[8:9], s[0:1], v138, s24, v[4:5]
	v_lshl_add_u64 v[8:9], v[8:9], 0, v[6:7]
	v_add_co_u32_e32 v8, vcc, 0x1000, v8
	v_or_b32_e32 v140, 7, v124
	s_nop 0
	v_addc_co_u32_e32 v9, vcc, 0, v9, vcc
	global_load_dwordx4 v[80:83], v[8:9], off
	v_mad_i64_i32 v[8:9], s[0:1], v140, s24, v[4:5]
	v_lshl_add_u64 v[8:9], v[8:9], 0, v[6:7]
	v_add_co_u32_e32 v8, vcc, 0x1000, v8
	v_or_b32_e32 v142, 8, v124
	s_nop 0
	v_addc_co_u32_e32 v9, vcc, 0, v9, vcc
	global_load_dwordx4 v[84:87], v[8:9], off
	v_mad_i64_i32 v[8:9], s[0:1], v142, s24, v[4:5]
	v_lshl_add_u64 v[8:9], v[8:9], 0, v[6:7]
	v_add_co_u32_e32 v8, vcc, 0x1000, v8
	v_or_b32_e32 v144, 9, v124
	s_nop 0
	v_addc_co_u32_e32 v9, vcc, 0, v9, vcc
	global_load_dwordx4 v[68:71], v[8:9], off
	v_mad_i64_i32 v[8:9], s[0:1], v144, s24, v[4:5]
	v_lshl_add_u64 v[8:9], v[8:9], 0, v[6:7]
	v_add_co_u32_e32 v8, vcc, 0x1000, v8
	v_or_b32_e32 v146, 10, v124
	s_nop 0
	v_addc_co_u32_e32 v9, vcc, 0, v9, vcc
	global_load_dwordx4 v[72:75], v[8:9], off
	v_mad_i64_i32 v[8:9], s[0:1], v146, s24, v[4:5]
	v_lshl_add_u64 v[8:9], v[8:9], 0, v[6:7]
	v_add_co_u32_e32 v8, vcc, 0x1000, v8
	v_or_b32_e32 v148, 11, v124
	s_nop 0
	v_addc_co_u32_e32 v9, vcc, 0, v9, vcc
	global_load_dwordx4 v[40:43], v[8:9], off
	v_mad_i64_i32 v[8:9], s[0:1], v148, s24, v[4:5]
	v_lshl_add_u64 v[8:9], v[8:9], 0, v[6:7]
	v_add_co_u32_e32 v8, vcc, 0x1000, v8
	v_or_b32_e32 v150, 12, v124
	s_nop 0
	v_addc_co_u32_e32 v9, vcc, 0, v9, vcc
	global_load_dwordx4 v[44:47], v[8:9], off
	v_mad_i64_i32 v[8:9], s[0:1], v150, s24, v[4:5]
	v_lshl_add_u64 v[8:9], v[8:9], 0, v[6:7]
	v_add_co_u32_e32 v8, vcc, 0x1000, v8
	v_or_b32_e32 v152, 13, v124
	s_nop 0
	v_addc_co_u32_e32 v9, vcc, 0, v9, vcc
	global_load_dwordx4 v[60:63], v[8:9], off
	v_mad_i64_i32 v[8:9], s[0:1], v152, s24, v[4:5]
	v_lshl_add_u64 v[8:9], v[8:9], 0, v[6:7]
	v_add_co_u32_e32 v8, vcc, 0x1000, v8
	v_or_b32_e32 v154, 14, v124
	s_nop 0
	v_addc_co_u32_e32 v9, vcc, 0, v9, vcc
	global_load_dwordx4 v[64:67], v[8:9], off
	v_mad_i64_i32 v[8:9], s[0:1], v154, s24, v[4:5]
	v_lshl_add_u64 v[8:9], v[8:9], 0, v[6:7]
	v_or_b32_e32 v156, 15, v124
	v_readlane_b32 s80, v252, 32
	v_add_co_u32_e32 v8, vcc, 0x1000, v8
	v_mad_i64_i32 v[4:5], s[0:1], v156, s24, v[4:5]
	v_readlane_b32 s84, v252, 36
	v_readlane_b32 s85, v252, 37
	v_readlane_b32 s86, v252, 38
	v_readlane_b32 s87, v252, 39
	v_readlane_b32 s88, v252, 40
	v_readlane_b32 s89, v252, 41
	v_readlane_b32 s90, v252, 42
	v_readlane_b32 s91, v252, 43
	v_addc_co_u32_e32 v9, vcc, 0, v9, vcc
	v_lshl_add_u64 v[4:5], v[4:5], 0, v[6:7]
	v_readlane_b32 s92, v252, 44
	v_readlane_b32 s93, v252, 45
	v_readlane_b32 s94, v252, 46
	v_readlane_b32 s95, v252, 47
	s_mov_b64 s[84:85], s[88:89]
	global_load_dwordx4 v[20:23], v[8:9], off
	v_add_co_u32_e32 v4, vcc, 0x1000, v4
	v_lshlrev_b64 v[8:9], 2, v[122:123]
	s_mov_b64 s[86:87], s[90:91]
	s_mov_b64 s[88:89], s[92:93]
	s_mov_b64 s[90:91], s[94:95]
	v_addc_co_u32_e32 v5, vcc, 0, v5, vcc
	v_lshl_add_u64 v[12:13], s[88:89], 0, v[8:9]
	v_lshl_add_u64 v[14:15], s[2:3], 0, v[8:9]
	v_lshl_add_u64 v[16:17], s[4:5], 0, v[8:9]
	v_lshl_add_u64 v[18:19], s[8:9], 0, v[8:9]
	v_lshl_add_u64 v[32:33], s[90:91], 0, v[8:9]
	global_load_dwordx4 v[0:3], v[0:1], off
	global_load_dwordx4 v[4:7], v[4:5], off
	s_nop 0
	global_load_dwordx4 v[8:11], v[12:13], off offset:16
	global_load_dwordx4 v[24:27], v[12:13], off
	global_load_dwordx4 v[108:111], v[14:15], off offset:16
	global_load_dwordx4 v[112:115], v[14:15], off
	s_nop 0
	global_load_dwordx4 v[12:15], v[16:17], off offset:16
	global_load_dwordx4 v[28:31], v[16:17], off
	global_load_dwordx4 v[88:91], v[18:19], off offset:16
	global_load_dwordx4 v[104:107], v[18:19], off
	s_nop 0
	global_load_dwordx4 v[16:19], v[32:33], off offset:16
	s_nop 0
	global_load_dwordx4 v[32:35], v[32:33], off
	s_waitcnt vmcnt(0)
	v_lshlrev_b32_e32 v177, 16, v96
	v_lshlrev_b32_e32 v161, 16, v100
	v_and_b32_e32 v163, 0xffff0000, v100
	v_ashrrev_i32_e32 v100, 14, v125
	v_mov_b32_e32 v160, v177
	v_lshlrev_b32_e32 v165, 16, v101
	v_and_b32_e32 v167, 0xffff0000, v101
	v_add_u32_e32 v200, v100, v127
	v_lshlrev_b32_e32 v176, 16, v92
	v_and_b32_e32 v179, 0xffff0000, v96
	v_mov_b32_e32 v162, v179
	v_and_b32_e32 v178, 0xffff0000, v92
	v_lshlrev_b32_e32 v169, 16, v102
	v_and_b32_e32 v171, 0xffff0000, v102
	v_lshlrev_b32_e32 v173, 16, v103
	v_and_b32_e32 v175, 0xffff0000, v103
	s_movk_i32 s0, 0x7f0
	v_cmp_eq_u32_e32 vcc, s0, v199
	v_mul_i32_i24_e32 v125, 3, v200
	v_readlane_b32 s81, v252, 33
	v_readlane_b32 s82, v252, 34
	v_readlane_b32 s83, v252, 35
	s_waitcnt vmcnt(8)
	v_mov_b32_e32 v159, v24
	s_waitcnt vmcnt(6)
	v_mov_b32_e32 v158, v112
	v_pk_mul_f32 v[100:101], v[158:159], v[160:161]
	v_mov_b32_e32 v160, v114
	v_mov_b32_e32 v161, v26
	v_mov_b32_e32 v112, v108
	v_lshlrev_b32_e32 v114, 16, v94
	s_waitcnt vmcnt(0)
	v_add_f32_e32 v24, v101, v32
	v_add_f32_e32 v127, v100, v24
	v_pk_mul_f32 v[100:101], v[158:159], v[176:177]
	v_mov_b32_e32 v108, v110
	v_add_f32_e32 v24, v101, v32
	v_add_f32_e32 v133, v100, v24
	v_mov_b32_e32 v24, v113
	v_pk_mul_f32 v[100:101], v[24:25], v[162:163]
	v_mov_b32_e32 v113, v8
	v_add_f32_e32 v92, v101, v33
	v_add_f32_e32 v135, v100, v92
	v_pk_mul_f32 v[100:101], v[24:25], v[178:179]
	v_lshlrev_b32_e32 v163, 16, v99
	v_add_f32_e32 v92, v101, v33
	v_lshlrev_b32_e32 v101, 16, v97
	v_mov_b32_e32 v164, v101
	v_pk_mul_f32 v[102:103], v[160:161], v[164:165]
	v_add_f32_e32 v137, v100, v92
	v_lshlrev_b32_e32 v100, 16, v93
	v_add_f32_e32 v26, v103, v34
	v_add_f32_e32 v139, v102, v26
	v_pk_mul_f32 v[102:103], v[160:161], v[100:101]
	v_mov_b32_e32 v172, v163
	v_add_f32_e32 v26, v103, v34
	v_and_b32_e32 v103, 0xffff0000, v97
	v_add_f32_e32 v141, v102, v26
	v_mov_b32_e32 v26, v115
	v_mov_b32_e32 v166, v103
	v_and_b32_e32 v102, 0xffff0000, v93
	v_pk_mul_f32 v[92:93], v[26:27], v[166:167]
	v_lshlrev_b32_e32 v115, 16, v98
	v_add_f32_e32 v93, v93, v35
	v_add_f32_e32 v153, v92, v93
	v_pk_mul_f32 v[92:93], v[26:27], v[102:103]
	v_mov_b32_e32 v168, v115
	v_add_f32_e32 v93, v93, v35
	v_add_f32_e32 v155, v92, v93
	v_pk_mul_f32 v[92:93], v[112:113], v[168:169]
	v_and_b32_e32 v167, 0xffff0000, v98
	v_add_f32_e32 v8, v93, v16
	v_add_f32_e32 v157, v92, v8
	v_pk_mul_f32 v[92:93], v[112:113], v[114:115]
	v_mov_b32_e32 v170, v167
	v_add_f32_e32 v8, v93, v16
	v_add_f32_e32 v115, v92, v8
	v_mov_b32_e32 v8, v109
	v_pk_mul_f32 v[92:93], v[8:9], v[170:171]
	v_and_b32_e32 v166, 0xffff0000, v94
	v_add_f32_e32 v93, v93, v17
	v_add_f32_e32 v170, v92, v93
	v_pk_mul_f32 v[92:93], v[8:9], v[166:167]
	v_mov_b32_e32 v109, v10
	v_add_f32_e32 v93, v93, v17
	v_add_f32_e32 v171, v92, v93
	v_pk_mul_f32 v[92:93], v[108:109], v[172:173]
	v_lshlrev_b32_e32 v162, 16, v95
	v_add_f32_e32 v10, v93, v18
	v_add_f32_e32 v169, v92, v10
	v_pk_mul_f32 v[92:93], v[108:109], v[162:163]
	v_and_b32_e32 v165, 0xffff0000, v99
	v_add_f32_e32 v10, v93, v18
	v_add_f32_e32 v145, v92, v10
	v_mov_b32_e32 v10, v111
	v_mov_b32_e32 v174, v165
	v_pk_mul_f32 v[92:93], v[10:11], v[174:175]
	v_and_b32_e32 v164, 0xffff0000, v95
	v_add_f32_e32 v93, v93, v19
	v_add_f32_e32 v147, v92, v93
	v_pk_mul_f32 v[92:93], v[10:11], v[164:165]
	v_mov_b32_e32 v98, v104
	v_add_f32_e32 v93, v93, v19
	v_add_f32_e32 v131, v92, v93
	v_lshlrev_b32_e32 v93, 16, v0
	v_lshlrev_b32_e32 v92, 16, v36
	v_mov_b32_e32 v99, v28
	v_pk_mov_b32 v[94:95], v[92:93], v[176:177] op_sel:[1,0]
	s_nop 0
	v_pk_mul_f32 v[96:97], v[98:99], v[94:95]
	v_pk_mul_f32 v[94:95], v[158:159], v[94:95]
	v_add_f32_e32 v28, v97, v127
	v_add_f32_e32 v28, v96, v28
	v_mul_f32_e32 v96, 0xbfb8aa3b, v28
	v_exp_f32_e32 v96, v96
	s_nop 0
	v_add_f32_e32 v96, 1.0, v96
	v_rcp_f32_e32 v96, v96
	s_nop 0
	v_mul_f32_e32 v101, v28, v96
	v_pk_mul_f32 v[96:97], v[98:99], v[92:93]
	s_nop 0
	v_add_f32_e32 v28, v97, v133
	v_add_f32_e32 v28, v96, v28
	v_mul_f32_e32 v96, 0xbfb8aa3b, v28
	v_exp_f32_e32 v96, v96
	s_nop 0
	v_add_f32_e32 v96, 1.0, v96
	v_rcp_f32_e32 v96, v96
	s_nop 0
	v_mul_f32_e32 v168, v28, v96
	v_add_f32_e32 v28, v95, v32
	v_add_f32_e32 v143, v94, v28
	v_pk_mul_f32 v[94:95], v[158:159], v[92:93]
	s_nop 0
	v_add_f32_e32 v28, v95, v32
	v_add_f32_e32 v127, v94, v28
	v_and_b32_e32 v95, 0xffff0000, v0
	v_and_b32_e32 v94, 0xffff0000, v36
	v_mov_b32_e32 v28, v105
	v_pk_mov_b32 v[96:97], v[94:95], v[178:179] op_sel:[1,0]
	v_lshlrev_b32_e32 v179, 16, v41
	v_pk_mul_f32 v[104:105], v[28:29], v[96:97]
	v_pk_mul_f32 v[96:97], v[24:25], v[96:97]
	v_add_f32_e32 v0, v105, v135
	v_add_f32_e32 v0, v104, v0
	v_mul_f32_e32 v36, 0xbfb8aa3b, v0
	v_exp_f32_e32 v36, v36
	v_pk_mul_f32 v[104:105], v[28:29], v[94:95]
	v_add_f32_e32 v36, 1.0, v36
	v_rcp_f32_e32 v36, v36
	s_nop 0
	v_mul_f32_e32 v0, v0, v36
	v_add_f32_e32 v36, v105, v137
	v_add_f32_e32 v36, v104, v36
	v_mul_f32_e32 v104, 0xbfb8aa3b, v36
	v_exp_f32_e32 v104, v104
	v_cvt_pk_bf16_f32 v0, v101, v0
	v_mov_b32_e32 v105, v30
	v_add_f32_e32 v104, 1.0, v104
	v_rcp_f32_e32 v104, v104
	s_nop 0
	v_mul_f32_e32 v174, v36, v104
	v_add_f32_e32 v36, v97, v33
	v_add_f32_e32 v149, v96, v36
	v_pk_mul_f32 v[96:97], v[24:25], v[94:95]
	v_mov_b32_e32 v104, v106
	v_add_f32_e32 v36, v97, v33
	v_add_f32_e32 v133, v96, v36
	v_lshlrev_b32_e32 v97, 16, v1
	v_lshlrev_b32_e32 v96, 16, v37
	v_pk_mov_b32 v[100:101], v[96:97], v[100:101] op_sel:[1,0]
	s_nop 0
	v_pk_mul_f32 v[110:111], v[104:105], v[100:101]
	v_pk_mul_f32 v[100:101], v[160:161], v[100:101]
	v_add_f32_e32 v30, v111, v139
	v_add_f32_e32 v30, v110, v30
	v_mul_f32_e32 v36, 0xbfb8aa3b, v30
	v_exp_f32_e32 v36, v36
	v_pk_mul_f32 v[110:111], v[104:105], v[96:97]
	v_add_f32_e32 v36, 1.0, v36
	v_rcp_f32_e32 v36, v36
	s_nop 0
	v_mul_f32_e32 v106, v30, v36
	v_add_f32_e32 v30, v111, v141
	v_add_f32_e32 v30, v110, v30
	v_mul_f32_e32 v36, 0xbfb8aa3b, v30
	v_exp_f32_e32 v36, v36
	s_nop 0
	v_add_f32_e32 v36, 1.0, v36
	v_rcp_f32_e32 v36, v36
	s_nop 0
	v_mul_f32_e32 v175, v30, v36
	v_add_f32_e32 v30, v101, v34
	v_add_f32_e32 v151, v100, v30
	v_pk_mul_f32 v[100:101], v[160:161], v[96:97]
	s_nop 0
	v_add_f32_e32 v30, v101, v34
	v_add_f32_e32 v135, v100, v30
	v_and_b32_e32 v101, 0xffff0000, v1
	v_and_b32_e32 v100, 0xffff0000, v37
	v_mov_b32_e32 v30, v107
	v_pk_mov_b32 v[36:37], v[100:101], v[102:103] op_sel:[1,0]
	v_mov_b32_e32 v107, v12
	v_pk_mul_f32 v[102:103], v[30:31], v[36:37]
	v_pk_mul_f32 v[36:37], v[26:27], v[36:37]
	v_add_f32_e32 v1, v103, v153
	v_add_f32_e32 v1, v102, v1
	v_mul_f32_e32 v102, 0xbfb8aa3b, v1
	v_exp_f32_e32 v102, v102
	v_add_f32_e32 v37, v37, v35
	v_add_f32_e32 v153, v36, v37
	v_pk_mul_f32 v[36:37], v[26:27], v[100:101]
	v_add_f32_e32 v102, 1.0, v102
	v_rcp_f32_e32 v102, v102
	v_add_f32_e32 v37, v37, v35
	v_add_f32_e32 v137, v36, v37
	v_mul_f32_e32 v1, v1, v102
	v_pk_mul_f32 v[102:103], v[30:31], v[100:101]
	v_cvt_pk_bf16_f32 v1, v106, v1
	v_mov_b32_e32 v106, v88
	v_add_f32_e32 v103, v103, v155
	v_add_f32_e32 v102, v102, v103
	v_mul_f32_e32 v103, 0xbfb8aa3b, v102
	v_exp_f32_e32 v103, v103
	s_nop 0
	v_add_f32_e32 v103, 1.0, v103
	v_rcp_f32_e32 v103, v103
	s_nop 0
	v_mul_f32_e32 v176, v102, v103
	v_lshlrev_b32_e32 v103, 16, v2
	v_lshlrev_b32_e32 v102, 16, v38
	v_pk_mov_b32 v[36:37], v[102:103], v[114:115] op_sel:[1,0]
	v_and_b32_e32 v114, 0xffff0000, v38
	v_pk_mul_f32 v[110:111], v[106:107], v[36:37]
	v_pk_mul_f32 v[36:37], v[112:113], v[36:37]
	v_add_f32_e32 v12, v111, v157
	v_add_f32_e32 v12, v110, v12
	v_mul_f32_e32 v88, 0xbfb8aa3b, v12
	v_exp_f32_e32 v88, v88
	v_pk_mul_f32 v[110:111], v[106:107], v[102:103]
	v_add_f32_e32 v88, 1.0, v88
	v_rcp_f32_e32 v88, v88
	s_nop 0
	v_mul_f32_e32 v141, v12, v88
	v_add_f32_e32 v12, v111, v115
	v_add_f32_e32 v12, v110, v12
	v_mul_f32_e32 v88, 0xbfb8aa3b, v12
	v_exp_f32_e32 v88, v88
	v_and_b32_e32 v115, 0xffff0000, v2
	v_mov_b32_e32 v110, v90
	v_mov_b32_e32 v111, v14
	v_add_f32_e32 v88, 1.0, v88
	v_rcp_f32_e32 v88, v88
	s_nop 0
	v_mul_f32_e32 v177, v12, v88
	v_add_f32_e32 v12, v37, v16
	v_add_f32_e32 v155, v36, v12
	v_pk_mul_f32 v[36:37], v[112:113], v[102:103]
	s_nop 0
	v_add_f32_e32 v12, v37, v16
	v_add_f32_e32 v139, v36, v12
	v_mov_b32_e32 v12, v89
	v_pk_mov_b32 v[36:37], v[114:115], v[166:167] op_sel:[1,0]
	s_nop 0
	v_pk_mul_f32 v[88:89], v[12:13], v[36:37]
	v_pk_mul_f32 v[36:37], v[8:9], v[36:37]
	v_add_f32_e32 v2, v89, v170
	v_add_f32_e32 v2, v88, v2
	v_mul_f32_e32 v38, 0xbfb8aa3b, v2
	v_exp_f32_e32 v38, v38
	v_pk_mul_f32 v[88:89], v[12:13], v[114:115]
	v_add_f32_e32 v37, v37, v17
	v_add_f32_e32 v157, v36, v37
	v_add_f32_e32 v38, 1.0, v38
	v_rcp_f32_e32 v38, v38
	v_pk_mul_f32 v[36:37], v[8:9], v[114:115]
	v_lshlrev_b32_e32 v170, 16, v52
	v_add_f32_e32 v37, v37, v17
	v_mul_f32_e32 v2, v2, v38
	v_add_f32_e32 v38, v89, v171
	v_add_f32_e32 v38, v88, v38
	v_mul_f32_e32 v88, 0xbfb8aa3b, v38
	v_exp_f32_e32 v88, v88
	v_lshlrev_b32_e32 v89, 16, v3
	v_cvt_pk_bf16_f32 v2, v141, v2
	v_add_f32_e32 v141, v36, v37
	v_add_f32_e32 v88, 1.0, v88
	v_rcp_f32_e32 v88, v88
	v_lshlrev_b32_e32 v171, 16, v48
	v_mul_f32_e32 v166, v38, v88
	v_lshlrev_b32_e32 v88, 16, v39
	v_pk_mov_b32 v[36:37], v[88:89], v[162:163] op_sel:[1,0]
	s_nop 0
	v_pk_mul_f32 v[162:163], v[110:111], v[36:37]
	v_pk_mul_f32 v[36:37], v[108:109], v[36:37]
	v_add_f32_e32 v14, v163, v169
	v_add_f32_e32 v14, v162, v14
	v_mul_f32_e32 v38, 0xbfb8aa3b, v14
	v_exp_f32_e32 v38, v38
	v_pk_mul_f32 v[162:163], v[110:111], v[88:89]
	v_lshlrev_b32_e32 v169, 16, v49
	v_add_f32_e32 v38, 1.0, v38
	v_rcp_f32_e32 v38, v38
	s_nop 0
	v_mul_f32_e32 v90, v14, v38
	v_add_f32_e32 v14, v163, v145
	v_add_f32_e32 v14, v162, v14
	v_mul_f32_e32 v38, 0xbfb8aa3b, v14
	v_exp_f32_e32 v38, v38
	v_and_b32_e32 v163, 0xffff0000, v3
	v_and_b32_e32 v162, 0xffff0000, v39
	v_add_f32_e32 v38, 1.0, v38
	v_rcp_f32_e32 v38, v38
	s_nop 0
	v_mul_f32_e32 v167, v14, v38
	v_add_f32_e32 v14, v37, v18
	v_add_f32_e32 v172, v36, v14
	v_pk_mul_f32 v[36:37], v[108:109], v[88:89]
	s_nop 0
	v_add_f32_e32 v14, v37, v18
	v_add_f32_e32 v145, v36, v14
	v_mov_b32_e32 v14, v91
	v_pk_mov_b32 v[36:37], v[162:163], v[164:165] op_sel:[1,0]
	v_lshlrev_b32_e32 v165, 16, v51
	v_pk_mul_f32 v[38:39], v[14:15], v[36:37]
	v_pk_mul_f32 v[36:37], v[10:11], v[36:37]
	v_add_f32_e32 v3, v39, v147
	v_add_f32_e32 v3, v38, v3
	v_mul_f32_e32 v38, 0xbfb8aa3b, v3
	v_exp_f32_e32 v38, v38
	v_add_f32_e32 v37, v37, v19
	v_add_f32_e32 v173, v36, v37
	v_cvt_pk_bf16_f32 v36, v168, v174
	v_add_f32_e32 v38, 1.0, v38
	v_rcp_f32_e32 v38, v38
	v_cvt_pk_bf16_f32 v37, v175, v176
	v_lshlrev_b32_e32 v168, 16, v53
	v_lshlrev_b32_e32 v164, 16, v55
	v_mul_f32_e32 v3, v3, v38
	v_cvt_pk_bf16_f32 v3, v90, v3
	v_pk_mul_f32 v[90:91], v[10:11], v[162:163]
	v_pk_mul_f32 v[38:39], v[14:15], v[162:163]
	v_add_f32_e32 v91, v91, v19
	v_add_f32_e32 v147, v90, v91
	v_pk_mov_b32 v[90:91], v[170:171], v[92:93] op_sel:[1,0]
	v_add_f32_e32 v39, v39, v131
	v_pk_mul_f32 v[92:93], v[98:99], v[90:91]
	v_pk_mul_f32 v[90:91], v[158:159], v[90:91]
	v_add_f32_e32 v93, v93, v143
	v_add_f32_e32 v92, v92, v93
	v_mul_f32_e32 v93, 0xbfb8aa3b, v92
	v_exp_f32_e32 v93, v93
	v_add_f32_e32 v91, v91, v32
	v_add_f32_e32 v174, v90, v91
	v_pk_mul_f32 v[90:91], v[158:159], v[170:171]
	v_add_f32_e32 v93, 1.0, v93
	v_rcp_f32_e32 v93, v93
	v_add_f32_e32 v91, v91, v32
	v_add_f32_e32 v38, v38, v39
	v_mul_f32_e32 v39, 0xbfb8aa3b, v38
	v_mul_f32_e32 v131, v92, v93
	v_pk_mul_f32 v[92:93], v[98:99], v[170:171]
	v_exp_f32_e32 v39, v39
	v_add_f32_e32 v93, v93, v127
	v_add_f32_e32 v92, v92, v93
	v_mul_f32_e32 v93, 0xbfb8aa3b, v92
	v_exp_f32_e32 v93, v93
	v_add_f32_e32 v127, v90, v91
	v_and_b32_e32 v91, 0xffff0000, v48
	v_and_b32_e32 v90, 0xffff0000, v52
	v_add_f32_e32 v93, 1.0, v93
	v_rcp_f32_e32 v93, v93
	v_add_f32_e32 v39, 1.0, v39
	v_rcp_f32_e32 v39, v39
	v_mul_f32_e32 v175, v92, v93
	v_pk_mov_b32 v[92:93], v[90:91], v[94:95] op_sel:[1,0]
	v_mul_f32_e32 v39, v38, v39
	v_pk_mul_f32 v[94:95], v[28:29], v[92:93]
	v_pk_mul_f32 v[92:93], v[24:25], v[92:93]
	v_add_f32_e32 v48, v95, v149
	v_add_f32_e32 v48, v94, v48
	v_mul_f32_e32 v52, 0xbfb8aa3b, v48
	v_exp_f32_e32 v52, v52
	v_pk_mul_f32 v[94:95], v[28:29], v[90:91]
	v_cvt_pk_bf16_f32 v38, v177, v166
	v_cvt_pk_bf16_f32 v39, v167, v39
	v_add_f32_e32 v52, 1.0, v52
	v_rcp_f32_e32 v52, v52
	v_lshlrev_b32_e32 v167, 16, v50
	v_lshlrev_b32_e32 v166, 16, v54
	v_mul_f32_e32 v48, v48, v52
	v_add_f32_e32 v52, v95, v133
	v_add_f32_e32 v52, v94, v52
	v_mul_f32_e32 v94, 0xbfb8aa3b, v52
	v_exp_f32_e32 v94, v94
	v_cvt_pk_bf16_f32 v48, v131, v48
	s_nop 0
	v_add_f32_e32 v94, 1.0, v94
	v_rcp_f32_e32 v94, v94
	s_nop 0
	v_mul_f32_e32 v176, v52, v94
	v_add_f32_e32 v52, v93, v33
	v_add_f32_e32 v149, v92, v52
	v_pk_mul_f32 v[92:93], v[24:25], v[90:91]
	s_nop 0
	v_add_f32_e32 v52, v93, v33
	v_add_f32_e32 v143, v92, v52
	v_pk_mov_b32 v[92:93], v[168:169], v[96:97] op_sel:[1,0]
	s_nop 0
	v_pk_mul_f32 v[94:95], v[104:105], v[92:93]
	v_pk_mul_f32 v[92:93], v[160:161], v[92:93]
	v_add_f32_e32 v52, v95, v151
	v_add_f32_e32 v52, v94, v52
	v_mul_f32_e32 v94, 0xbfb8aa3b, v52
	v_exp_f32_e32 v94, v94
	s_nop 0
	v_add_f32_e32 v94, 1.0, v94
	v_rcp_f32_e32 v94, v94
	s_nop 0
	v_mul_f32_e32 v96, v52, v94
	v_pk_mul_f32 v[94:95], v[104:105], v[168:169]
	s_nop 0
	v_add_f32_e32 v52, v95, v135
	v_add_f32_e32 v52, v94, v52
	v_mul_f32_e32 v94, 0xbfb8aa3b, v52
	v_exp_f32_e32 v94, v94
	s_nop 0
	v_add_f32_e32 v94, 1.0, v94
	v_rcp_f32_e32 v94, v94
	s_nop 0
	v_mul_f32_e32 v177, v52, v94
	v_add_f32_e32 v52, v93, v34
	v_add_f32_e32 v151, v92, v52
	v_pk_mul_f32 v[92:93], v[160:161], v[168:169]
	s_nop 0
	v_add_f32_e32 v52, v93, v34
	v_add_f32_e32 v131, v92, v52
	v_and_b32_e32 v93, 0xffff0000, v49
	v_and_b32_e32 v92, 0xffff0000, v53
	v_pk_mov_b32 v[52:53], v[92:93], v[100:101] op_sel:[1,0]
	s_nop 0
	v_pk_mul_f32 v[94:95], v[30:31], v[52:53]
	v_pk_mul_f32 v[52:53], v[26:27], v[52:53]
	v_add_f32_e32 v49, v95, v153
	v_add_f32_e32 v49, v94, v49
	v_mul_f32_e32 v94, 0xbfb8aa3b, v49
	v_exp_f32_e32 v94, v94
	v_add_f32_e32 v53, v53, v35
	v_add_f32_e32 v153, v52, v53
	v_pk_mul_f32 v[52:53], v[26:27], v[92:93]
	v_add_f32_e32 v94, 1.0, v94
	v_rcp_f32_e32 v94, v94
	v_add_f32_e32 v53, v53, v35
	v_mul_f32_e32 v49, v49, v94
	v_pk_mul_f32 v[94:95], v[30:31], v[92:93]
	v_cvt_pk_bf16_f32 v49, v96, v49
	s_nop 0
	v_add_f32_e32 v95, v95, v137
	v_add_f32_e32 v94, v94, v95
	v_mul_f32_e32 v95, 0xbfb8aa3b, v94
	v_exp_f32_e32 v95, v95
	v_add_f32_e32 v137, v52, v53
	v_pk_mov_b32 v[52:53], v[166:167], v[102:103] op_sel:[1,0]
	v_lshlrev_b32_e32 v103, 16, v56
	v_add_f32_e32 v95, 1.0, v95
	v_rcp_f32_e32 v95, v95
	s_nop 0
	v_mul_f32_e32 v100, v94, v95
	v_pk_mul_f32 v[94:95], v[106:107], v[52:53]
	v_pk_mul_f32 v[52:53], v[112:113], v[52:53]
	v_add_f32_e32 v95, v95, v155
	v_add_f32_e32 v94, v94, v95
	v_mul_f32_e32 v95, 0xbfb8aa3b, v94
	v_exp_f32_e32 v95, v95
	v_add_f32_e32 v53, v53, v16
	v_add_f32_e32 v155, v52, v53
	v_pk_mul_f32 v[52:53], v[112:113], v[166:167]
	v_add_f32_e32 v95, 1.0, v95
	v_rcp_f32_e32 v95, v95
	v_add_f32_e32 v53, v53, v16
	v_add_f32_e32 v133, v52, v53
	v_mul_f32_e32 v101, v94, v95
	v_pk_mul_f32 v[94:95], v[106:107], v[166:167]
	s_nop 0
	v_add_f32_e32 v95, v95, v139
	v_add_f32_e32 v94, v94, v95
	v_mul_f32_e32 v95, 0xbfb8aa3b, v94
	v_exp_f32_e32 v95, v95
	s_nop 0
	v_add_f32_e32 v95, 1.0, v95
	v_rcp_f32_e32 v95, v95
	s_nop 0
	v_mul_f32_e32 v102, v94, v95
	v_and_b32_e32 v95, 0xffff0000, v50
	v_and_b32_e32 v94, 0xffff0000, v54
	v_pk_mov_b32 v[52:53], v[94:95], v[114:115] op_sel:[1,0]
	s_nop 0
	v_pk_mul_f32 v[96:97], v[12:13], v[52:53]
	v_pk_mul_f32 v[52:53], v[8:9], v[52:53]
	v_add_f32_e32 v50, v97, v157
	v_add_f32_e32 v50, v96, v50
	v_mul_f32_e32 v54, 0xbfb8aa3b, v50
	v_exp_f32_e32 v54, v54
	v_pk_mul_f32 v[96:97], v[12:13], v[94:95]
	v_add_f32_e32 v53, v53, v17
	v_add_f32_e32 v157, v52, v53
	v_add_f32_e32 v54, 1.0, v54
	v_rcp_f32_e32 v54, v54
	v_pk_mul_f32 v[52:53], v[8:9], v[94:95]
	v_mul_f32_e32 v50, v50, v54
	v_add_f32_e32 v54, v97, v141
	v_add_f32_e32 v54, v96, v54
	v_mul_f32_e32 v96, 0xbfb8aa3b, v54
	v_exp_f32_e32 v96, v96
	v_add_f32_e32 v53, v53, v17
	v_add_f32_e32 v139, v52, v53
	v_pk_mov_b32 v[52:53], v[164:165], v[88:89] op_sel:[1,0]
	v_add_f32_e32 v96, 1.0, v96
	v_rcp_f32_e32 v96, v96
	v_pk_mul_f32 v[88:89], v[110:111], v[52:53]
	v_pk_mul_f32 v[52:53], v[108:109], v[52:53]
	v_cvt_pk_bf16_f32 v50, v101, v50
	v_mul_f32_e32 v96, v54, v96
	v_add_f32_e32 v54, v89, v172
	v_add_f32_e32 v54, v88, v54
	v_mul_f32_e32 v88, 0xbfb8aa3b, v54
	v_exp_f32_e32 v88, v88
	v_add_f32_e32 v53, v53, v18
	v_add_f32_e32 v172, v52, v53
	v_pk_mul_f32 v[52:53], v[108:109], v[164:165]
	v_add_f32_e32 v88, 1.0, v88
	v_rcp_f32_e32 v88, v88
	v_add_f32_e32 v53, v53, v18
	v_add_f32_e32 v135, v52, v53
	v_mul_f32_e32 v97, v54, v88
	v_pk_mul_f32 v[88:89], v[110:111], v[164:165]
	s_nop 0
	v_add_f32_e32 v54, v89, v145
	v_add_f32_e32 v54, v88, v54
	v_mul_f32_e32 v88, 0xbfb8aa3b, v54
	v_exp_f32_e32 v88, v88
	v_and_b32_e32 v89, 0xffff0000, v51
	v_add_f32_e32 v88, 1.0, v88
	v_rcp_f32_e32 v88, v88
	s_nop 0
	v_mul_f32_e32 v101, v54, v88
	v_and_b32_e32 v88, 0xffff0000, v55
	v_pk_mov_b32 v[52:53], v[88:89], v[162:163] op_sel:[1,0]
	v_lshlrev_b32_e32 v163, 16, v59
	v_pk_mul_f32 v[54:55], v[14:15], v[52:53]
	v_pk_mul_f32 v[52:53], v[10:11], v[52:53]
	v_add_f32_e32 v51, v55, v173
	v_add_f32_e32 v51, v54, v51
	v_mul_f32_e32 v54, 0xbfb8aa3b, v51
	v_exp_f32_e32 v54, v54
	v_add_f32_e32 v53, v53, v19
	v_add_f32_e32 v54, 1.0, v54
	v_rcp_f32_e32 v54, v54
	s_nop 0
	v_mul_f32_e32 v51, v51, v54
	v_pk_mul_f32 v[54:55], v[14:15], v[88:89]
	v_cvt_pk_bf16_f32 v51, v97, v51
	s_nop 0
	v_add_f32_e32 v55, v55, v147
	v_add_f32_e32 v54, v54, v55
	v_mul_f32_e32 v55, 0xbfb8aa3b, v54
	v_exp_f32_e32 v55, v55
	v_add_f32_e32 v147, v52, v53
	v_cvt_pk_bf16_f32 v53, v177, v100
	v_cvt_pk_bf16_f32 v52, v175, v176
	v_add_f32_e32 v55, 1.0, v55
	v_rcp_f32_e32 v55, v55
	v_lshlrev_b32_e32 v177, 16, v69
	v_mul_f32_e32 v55, v54, v55
	v_cvt_pk_bf16_f32 v54, v102, v96
	v_pk_mul_f32 v[96:97], v[10:11], v[88:89]
	v_lshlrev_b32_e32 v102, 16, v76
	v_add_f32_e32 v97, v97, v19
	v_add_f32_e32 v145, v96, v97
	v_pk_mov_b32 v[96:97], v[102:103], v[170:171] op_sel:[1,0]
	v_cvt_pk_bf16_f32 v55, v101, v55
	s_nop 0
	v_pk_mul_f32 v[100:101], v[98:99], v[96:97]
	v_pk_mul_f32 v[96:97], v[158:159], v[96:97]
	v_add_f32_e32 v101, v101, v174
	v_add_f32_e32 v100, v100, v101
	v_mul_f32_e32 v101, 0xbfb8aa3b, v100
	v_exp_f32_e32 v101, v101
	v_add_f32_e32 v97, v97, v32
	v_add_f32_e32 v170, v96, v97
	v_pk_mul_f32 v[96:97], v[158:159], v[102:103]
	v_add_f32_e32 v101, 1.0, v101
	v_rcp_f32_e32 v101, v101
	v_add_f32_e32 v97, v97, v32
	v_mul_f32_e32 v114, v100, v101
	v_pk_mul_f32 v[100:101], v[98:99], v[102:103]
	s_nop 0
	v_add_f32_e32 v101, v101, v127
	v_add_f32_e32 v100, v100, v101
	v_mul_f32_e32 v101, 0xbfb8aa3b, v100
	v_exp_f32_e32 v101, v101
	v_add_f32_e32 v127, v96, v97
	v_and_b32_e32 v97, 0xffff0000, v56
	v_and_b32_e32 v96, 0xffff0000, v76
	v_add_f32_e32 v101, 1.0, v101
	v_rcp_f32_e32 v101, v101
	v_pk_mov_b32 v[90:91], v[96:97], v[90:91] op_sel:[1,0]
	v_mul_f32_e32 v173, v100, v101
	v_pk_mul_f32 v[100:101], v[28:29], v[90:91]
	v_pk_mul_f32 v[90:91], v[24:25], v[90:91]
	v_add_f32_e32 v56, v101, v149
	v_add_f32_e32 v56, v100, v56
	v_mul_f32_e32 v76, 0xbfb8aa3b, v56
	v_exp_f32_e32 v76, v76
	v_pk_mul_f32 v[100:101], v[28:29], v[96:97]
	v_add_f32_e32 v76, 1.0, v76
	v_rcp_f32_e32 v76, v76
	s_nop 0
	v_mul_f32_e32 v56, v56, v76
	v_add_f32_e32 v76, v101, v143
	v_add_f32_e32 v76, v100, v76
	v_mul_f32_e32 v100, 0xbfb8aa3b, v76
	v_exp_f32_e32 v100, v100
	v_lshlrev_b32_e32 v101, 16, v57
	v_cvt_pk_bf16_f32 v56, v114, v56
	v_add_f32_e32 v100, 1.0, v100
	v_rcp_f32_e32 v100, v100
	s_nop 0
	v_mul_f32_e32 v143, v76, v100
	v_add_f32_e32 v76, v91, v33
	v_add_f32_e32 v149, v90, v76
	v_pk_mul_f32 v[90:91], v[24:25], v[96:97]
	v_lshlrev_b32_e32 v100, 16, v77
	v_add_f32_e32 v76, v91, v33
	v_add_f32_e32 v141, v90, v76
	v_pk_mov_b32 v[90:91], v[100:101], v[168:169] op_sel:[1,0]
	s_nop 0
	v_pk_mul_f32 v[114:115], v[104:105], v[90:91]
	v_pk_mul_f32 v[90:91], v[160:161], v[90:91]
	v_add_f32_e32 v76, v115, v151
	v_add_f32_e32 v76, v114, v76
	v_mul_f32_e32 v114, 0xbfb8aa3b, v76
	v_exp_f32_e32 v114, v114
	s_nop 0
	v_add_f32_e32 v114, 1.0, v114
	v_rcp_f32_e32 v114, v114
	s_nop 0
	v_mul_f32_e32 v162, v76, v114
	v_pk_mul_f32 v[114:115], v[104:105], v[100:101]
	s_nop 0
	v_add_f32_e32 v76, v115, v131
	v_add_f32_e32 v76, v114, v76
	v_mul_f32_e32 v114, 0xbfb8aa3b, v76
	v_exp_f32_e32 v114, v114
	v_lshlrev_b32_e32 v115, 16, v58
	v_add_f32_e32 v114, 1.0, v114
	v_rcp_f32_e32 v114, v114
	s_nop 0
	v_mul_f32_e32 v168, v76, v114
	v_add_f32_e32 v76, v91, v34
	v_add_f32_e32 v151, v90, v76
	v_pk_mul_f32 v[90:91], v[160:161], v[100:101]
	v_lshlrev_b32_e32 v114, 16, v78
	v_add_f32_e32 v76, v91, v34
	v_add_f32_e32 v131, v90, v76
	v_and_b32_e32 v91, 0xffff0000, v57
	v_and_b32_e32 v90, 0xffff0000, v77
	v_pk_mov_b32 v[76:77], v[90:91], v[92:93] op_sel:[1,0]
	s_nop 0
	v_pk_mul_f32 v[92:93], v[30:31], v[76:77]
	v_pk_mul_f32 v[76:77], v[26:27], v[76:77]
	v_add_f32_e32 v57, v93, v153
	v_add_f32_e32 v57, v92, v57
	v_mul_f32_e32 v92, 0xbfb8aa3b, v57
	v_exp_f32_e32 v92, v92
	v_add_f32_e32 v77, v77, v35
	v_add_f32_e32 v153, v76, v77
	v_pk_mul_f32 v[76:77], v[26:27], v[90:91]
	v_add_f32_e32 v92, 1.0, v92
	v_rcp_f32_e32 v92, v92
	v_add_f32_e32 v77, v77, v35
	v_mul_f32_e32 v57, v57, v92
	v_pk_mul_f32 v[92:93], v[30:31], v[90:91]
	v_cvt_pk_bf16_f32 v57, v162, v57
	s_nop 0
	v_add_f32_e32 v93, v93, v137
	v_add_f32_e32 v92, v92, v93
	v_mul_f32_e32 v93, 0xbfb8aa3b, v92
	v_exp_f32_e32 v93, v93
	v_add_f32_e32 v137, v76, v77
	v_pk_mov_b32 v[76:77], v[114:115], v[166:167] op_sel:[1,0]
	v_add_f32_e32 v93, 1.0, v93
	v_rcp_f32_e32 v93, v93
	s_nop 0
	v_mul_f32_e32 v169, v92, v93
	v_pk_mul_f32 v[92:93], v[106:107], v[76:77]
	v_pk_mul_f32 v[76:77], v[112:113], v[76:77]
	v_add_f32_e32 v93, v93, v155
	v_add_f32_e32 v92, v92, v93
	v_mul_f32_e32 v93, 0xbfb8aa3b, v92
	v_exp_f32_e32 v93, v93
	v_add_f32_e32 v77, v77, v16
	v_add_f32_e32 v155, v76, v77
	v_pk_mul_f32 v[76:77], v[112:113], v[114:115]
	v_add_f32_e32 v93, 1.0, v93
	v_rcp_f32_e32 v93, v93
	v_add_f32_e32 v77, v77, v16
	v_mul_f32_e32 v162, v92, v93
	v_pk_mul_f32 v[92:93], v[106:107], v[114:115]
	s_nop 0
	v_add_f32_e32 v93, v93, v133
	v_add_f32_e32 v92, v92, v93
	v_mul_f32_e32 v93, 0xbfb8aa3b, v92
	v_exp_f32_e32 v93, v93
	v_add_f32_e32 v133, v76, v77
	v_add_f32_e32 v93, 1.0, v93
	v_rcp_f32_e32 v93, v93
	s_nop 0
	v_mul_f32_e32 v166, v92, v93
	v_and_b32_e32 v93, 0xffff0000, v58
	v_and_b32_e32 v92, 0xffff0000, v78
	v_pk_mov_b32 v[76:77], v[92:93], v[94:95] op_sel:[1,0]
	s_nop 0
	v_pk_mul_f32 v[94:95], v[12:13], v[76:77]
	v_pk_mul_f32 v[76:77], v[8:9], v[76:77]
	v_add_f32_e32 v58, v95, v157
	v_add_f32_e32 v58, v94, v58
	v_mul_f32_e32 v78, 0xbfb8aa3b, v58
	v_exp_f32_e32 v78, v78
	v_pk_mul_f32 v[94:95], v[12:13], v[92:93]
	v_add_f32_e32 v77, v77, v17
	v_add_f32_e32 v157, v76, v77
	v_add_f32_e32 v78, 1.0, v78
	v_rcp_f32_e32 v78, v78
	v_pk_mul_f32 v[76:77], v[8:9], v[92:93]
	v_mul_f32_e32 v58, v58, v78
	v_add_f32_e32 v78, v95, v139
	v_add_f32_e32 v78, v94, v78
	v_mul_f32_e32 v94, 0xbfb8aa3b, v78
	v_exp_f32_e32 v94, v94
	v_cvt_pk_bf16_f32 v58, v162, v58
	v_add_f32_e32 v77, v77, v17
	v_lshlrev_b32_e32 v162, 16, v79
	v_add_f32_e32 v94, 1.0, v94
	v_rcp_f32_e32 v94, v94
	v_add_f32_e32 v139, v76, v77
	v_pk_mov_b32 v[76:77], v[162:163], v[164:165] op_sel:[1,0]
	v_mul_f32_e32 v167, v78, v94
	v_pk_mul_f32 v[94:95], v[110:111], v[76:77]
	v_pk_mul_f32 v[76:77], v[108:109], v[76:77]
	v_add_f32_e32 v78, v95, v172
	v_add_f32_e32 v78, v94, v78
	v_mul_f32_e32 v94, 0xbfb8aa3b, v78
	v_exp_f32_e32 v94, v94
	v_add_f32_e32 v77, v77, v18
	v_add_f32_e32 v171, v76, v77
	v_pk_mul_f32 v[76:77], v[108:109], v[162:163]
	v_add_f32_e32 v94, 1.0, v94
	v_rcp_f32_e32 v94, v94
	v_add_f32_e32 v77, v77, v18
	v_mul_f32_e32 v164, v78, v94
	v_pk_mul_f32 v[94:95], v[110:111], v[162:163]
	s_nop 0
	v_add_f32_e32 v78, v95, v135
	v_add_f32_e32 v78, v94, v78
	v_mul_f32_e32 v94, 0xbfb8aa3b, v78
	v_exp_f32_e32 v94, v94
	v_and_b32_e32 v95, 0xffff0000, v59
	v_add_f32_e32 v135, v76, v77
	v_add_f32_e32 v94, 1.0, v94
	v_rcp_f32_e32 v94, v94
	s_nop 0
	v_mul_f32_e32 v165, v78, v94
	v_and_b32_e32 v94, 0xffff0000, v79
	v_pk_mov_b32 v[76:77], v[94:95], v[88:89] op_sel:[1,0]
	v_pk_mul_f32 v[88:89], v[10:11], v[94:95]
	v_pk_mul_f32 v[78:79], v[14:15], v[76:77]
	v_pk_mul_f32 v[76:77], v[10:11], v[76:77]
	v_add_f32_e32 v59, v79, v147
	v_add_f32_e32 v59, v78, v59
	v_mul_f32_e32 v78, 0xbfb8aa3b, v59
	v_exp_f32_e32 v78, v78
	v_add_f32_e32 v77, v77, v19
	v_add_f32_e32 v89, v89, v19
	v_add_f32_e32 v78, 1.0, v78
	v_rcp_f32_e32 v78, v78
	s_nop 0
	v_mul_f32_e32 v59, v59, v78
	v_pk_mul_f32 v[78:79], v[14:15], v[94:95]
	v_cvt_pk_bf16_f32 v59, v164, v59
	s_nop 0
	v_add_f32_e32 v79, v79, v145
	v_add_f32_e32 v145, v76, v77
	v_cvt_pk_bf16_f32 v77, v168, v169
	v_lshlrev_b32_e32 v169, 16, v80
	v_lshlrev_b32_e32 v168, 16, v84
	v_cvt_pk_bf16_f32 v76, v173, v143
	v_add_f32_e32 v143, v88, v89
	v_pk_mov_b32 v[88:89], v[168:169], v[102:103] op_sel:[1,0]
	v_add_f32_e32 v78, v78, v79
	v_pk_mul_f32 v[102:103], v[98:99], v[88:89]
	v_pk_mul_f32 v[88:89], v[158:159], v[88:89]
	v_add_f32_e32 v103, v103, v170
	v_add_f32_e32 v102, v102, v103
	v_mul_f32_e32 v103, 0xbfb8aa3b, v102
	v_exp_f32_e32 v103, v103
	v_add_f32_e32 v89, v89, v32
	v_add_f32_e32 v147, v88, v89
	v_pk_mul_f32 v[88:89], v[158:159], v[168:169]
	v_add_f32_e32 v103, 1.0, v103
	v_rcp_f32_e32 v103, v103
	v_add_f32_e32 v89, v89, v32
	v_mul_f32_e32 v79, 0xbfb8aa3b, v78
	v_exp_f32_e32 v79, v79
	v_mul_f32_e32 v164, v102, v103
	v_pk_mul_f32 v[102:103], v[98:99], v[168:169]
	v_add_f32_e32 v79, 1.0, v79
	v_add_f32_e32 v103, v103, v127
	v_add_f32_e32 v102, v102, v103
	v_mul_f32_e32 v103, 0xbfb8aa3b, v102
	v_exp_f32_e32 v103, v103
	v_add_f32_e32 v127, v88, v89
	v_and_b32_e32 v89, 0xffff0000, v80
	v_and_b32_e32 v88, 0xffff0000, v84
	v_add_f32_e32 v103, 1.0, v103
	v_rcp_f32_e32 v103, v103
	v_pk_mov_b32 v[96:97], v[88:89], v[96:97] op_sel:[1,0]
	v_rcp_f32_e32 v79, v79
	v_mul_f32_e32 v170, v102, v103
	v_pk_mul_f32 v[102:103], v[28:29], v[96:97]
	v_pk_mul_f32 v[96:97], v[24:25], v[96:97]
	v_add_f32_e32 v80, v103, v149
	v_add_f32_e32 v80, v102, v80
	v_mul_f32_e32 v84, 0xbfb8aa3b, v80
	v_exp_f32_e32 v84, v84
	v_pk_mul_f32 v[102:103], v[28:29], v[88:89]
	v_mul_f32_e32 v79, v78, v79
	v_cvt_pk_bf16_f32 v78, v166, v167
	v_add_f32_e32 v84, 1.0, v84
	v_rcp_f32_e32 v84, v84
	v_lshlrev_b32_e32 v167, 16, v82
	v_lshlrev_b32_e32 v166, 16, v86
	v_cvt_pk_bf16_f32 v79, v165, v79
	v_mul_f32_e32 v80, v80, v84
	v_add_f32_e32 v84, v103, v141
	v_add_f32_e32 v84, v102, v84
	v_mul_f32_e32 v102, 0xbfb8aa3b, v84
	v_exp_f32_e32 v102, v102
	v_lshlrev_b32_e32 v103, 16, v81
	v_cvt_pk_bf16_f32 v80, v164, v80
	v_lshlrev_b32_e32 v165, 16, v83
	v_add_f32_e32 v102, 1.0, v102
	v_rcp_f32_e32 v102, v102
	s_nop 0
	v_mul_f32_e32 v175, v84, v102
	v_add_f32_e32 v84, v97, v33
	v_add_f32_e32 v149, v96, v84
	v_pk_mul_f32 v[96:97], v[24:25], v[88:89]
	v_lshlrev_b32_e32 v102, 16, v85
	v_add_f32_e32 v84, v97, v33
	v_add_f32_e32 v141, v96, v84
	v_pk_mov_b32 v[96:97], v[102:103], v[100:101] op_sel:[1,0]
	s_nop 0
	v_pk_mul_f32 v[100:101], v[104:105], v[96:97]
	v_pk_mul_f32 v[96:97], v[160:161], v[96:97]
	v_add_f32_e32 v84, v101, v151
	v_add_f32_e32 v84, v100, v84
	v_mul_f32_e32 v100, 0xbfb8aa3b, v84
	v_exp_f32_e32 v100, v100
	s_nop 0
	v_add_f32_e32 v100, 1.0, v100
	v_rcp_f32_e32 v100, v100
	s_nop 0
	v_mul_f32_e32 v164, v84, v100
	v_pk_mul_f32 v[100:101], v[104:105], v[102:103]
	s_nop 0
	v_add_f32_e32 v84, v101, v131
	v_add_f32_e32 v84, v100, v84
	v_mul_f32_e32 v100, 0xbfb8aa3b, v84
	v_exp_f32_e32 v100, v100
	v_and_b32_e32 v101, 0xffff0000, v81
	v_add_f32_e32 v100, 1.0, v100
	v_rcp_f32_e32 v100, v100
	s_nop 0
	v_mul_f32_e32 v176, v84, v100
	v_add_f32_e32 v84, v97, v34
	v_add_f32_e32 v151, v96, v84
	v_pk_mul_f32 v[96:97], v[160:161], v[102:103]
	v_and_b32_e32 v100, 0xffff0000, v85
	v_add_f32_e32 v84, v97, v34
	v_add_f32_e32 v131, v96, v84
	v_pk_mov_b32 v[84:85], v[100:101], v[90:91] op_sel:[1,0]
	s_nop 0
	v_pk_mul_f32 v[90:91], v[30:31], v[84:85]
	v_pk_mul_f32 v[84:85], v[26:27], v[84:85]
	v_add_f32_e32 v81, v91, v153
	v_add_f32_e32 v81, v90, v81
	v_mul_f32_e32 v90, 0xbfb8aa3b, v81
	v_exp_f32_e32 v90, v90
	v_add_f32_e32 v85, v85, v35
	v_add_f32_e32 v172, v84, v85
	v_pk_mul_f32 v[84:85], v[26:27], v[100:101]
	v_add_f32_e32 v90, 1.0, v90
	v_rcp_f32_e32 v90, v90
	v_add_f32_e32 v85, v85, v35
	v_mul_f32_e32 v81, v81, v90
	v_pk_mul_f32 v[90:91], v[30:31], v[100:101]
	v_cvt_pk_bf16_f32 v81, v164, v81
	v_lshlrev_b32_e32 v164, 16, v87
	v_add_f32_e32 v91, v91, v137
	v_add_f32_e32 v90, v90, v91
	v_mul_f32_e32 v91, 0xbfb8aa3b, v90
	v_exp_f32_e32 v91, v91
	v_add_f32_e32 v137, v84, v85
	v_pk_mov_b32 v[84:85], v[166:167], v[114:115] op_sel:[1,0]
	v_and_b32_e32 v115, 0xffff0000, v82
	v_add_f32_e32 v91, 1.0, v91
	v_rcp_f32_e32 v91, v91
	v_and_b32_e32 v114, 0xffff0000, v86
	v_mul_f32_e32 v96, v90, v91
	v_pk_mul_f32 v[90:91], v[106:107], v[84:85]
	v_pk_mul_f32 v[84:85], v[112:113], v[84:85]
	v_add_f32_e32 v91, v91, v155
	v_add_f32_e32 v90, v90, v91
	v_mul_f32_e32 v91, 0xbfb8aa3b, v90
	v_exp_f32_e32 v91, v91
	v_add_f32_e32 v85, v85, v16
	v_add_f32_e32 v173, v84, v85
	v_pk_mul_f32 v[84:85], v[112:113], v[166:167]
	v_add_f32_e32 v91, 1.0, v91
	v_rcp_f32_e32 v91, v91
	v_add_f32_e32 v85, v85, v16
	v_mul_f32_e32 v97, v90, v91
	v_pk_mul_f32 v[90:91], v[106:107], v[166:167]
	s_nop 0
	v_add_f32_e32 v91, v91, v133
	v_add_f32_e32 v90, v90, v91
	v_mul_f32_e32 v91, 0xbfb8aa3b, v90
	v_exp_f32_e32 v91, v91
	v_add_f32_e32 v133, v84, v85
	v_pk_mov_b32 v[84:85], v[114:115], v[92:93] op_sel:[1,0]
	v_add_f32_e32 v91, 1.0, v91
	v_rcp_f32_e32 v91, v91
	s_nop 0
	v_mul_f32_e32 v153, v90, v91
	v_pk_mul_f32 v[90:91], v[12:13], v[84:85]
	v_pk_mul_f32 v[84:85], v[8:9], v[84:85]
	v_add_f32_e32 v82, v91, v157
	v_add_f32_e32 v82, v90, v82
	v_mul_f32_e32 v86, 0xbfb8aa3b, v82
	v_exp_f32_e32 v86, v86
	v_pk_mul_f32 v[90:91], v[12:13], v[114:115]
	v_add_f32_e32 v85, v85, v17
	v_add_f32_e32 v93, v84, v85
	v_add_f32_e32 v86, 1.0, v86
	v_rcp_f32_e32 v86, v86
	v_pk_mul_f32 v[84:85], v[8:9], v[114:115]
	v_mul_f32_e32 v82, v82, v86
	v_add_f32_e32 v86, v91, v139
	v_add_f32_e32 v86, v90, v86
	v_mul_f32_e32 v90, 0xbfb8aa3b, v86
	v_exp_f32_e32 v90, v90
	v_add_f32_e32 v85, v85, v17
	v_add_f32_e32 v92, v84, v85
	v_pk_mov_b32 v[84:85], v[164:165], v[162:163] op_sel:[1,0]
	v_add_f32_e32 v90, 1.0, v90
	v_rcp_f32_e32 v90, v90
	v_cvt_pk_bf16_f32 v82, v97, v82
	v_and_b32_e32 v163, 0xffff0000, v83
	v_and_b32_e32 v162, 0xffff0000, v87
	v_mul_f32_e32 v139, v86, v90
	v_pk_mul_f32 v[90:91], v[110:111], v[84:85]
	v_pk_mul_f32 v[84:85], v[108:109], v[84:85]
	v_add_f32_e32 v86, v91, v171
	v_add_f32_e32 v86, v90, v86
	v_mul_f32_e32 v90, 0xbfb8aa3b, v86
	v_exp_f32_e32 v90, v90
	v_add_f32_e32 v85, v85, v18
	v_add_f32_e32 v171, v84, v85
	v_pk_mul_f32 v[84:85], v[108:109], v[164:165]
	v_add_f32_e32 v90, 1.0, v90
	v_rcp_f32_e32 v90, v90
	v_add_f32_e32 v85, v85, v18
	v_mul_f32_e32 v97, v86, v90
	v_pk_mul_f32 v[90:91], v[110:111], v[164:165]
	s_nop 0
	v_add_f32_e32 v86, v91, v135
	v_add_f32_e32 v86, v90, v86
	v_mul_f32_e32 v90, 0xbfb8aa3b, v86
	v_exp_f32_e32 v90, v90
	v_add_f32_e32 v135, v84, v85
	v_pk_mov_b32 v[84:85], v[162:163], v[94:95] op_sel:[1,0]
	v_add_f32_e32 v90, 1.0, v90
	v_rcp_f32_e32 v90, v90
	s_nop 0
	v_mul_f32_e32 v90, v86, v90
	v_pk_mul_f32 v[86:87], v[14:15], v[84:85]
	v_pk_mul_f32 v[84:85], v[10:11], v[84:85]
	v_add_f32_e32 v83, v87, v145
	v_add_f32_e32 v83, v86, v83
	v_mul_f32_e32 v86, 0xbfb8aa3b, v83
	v_exp_f32_e32 v86, v86
	v_add_f32_e32 v85, v85, v19
	v_add_f32_e32 v174, v84, v85
	v_cvt_pk_bf16_f32 v84, v170, v175
	v_add_f32_e32 v86, 1.0, v86
	v_rcp_f32_e32 v86, v86
	v_cvt_pk_bf16_f32 v85, v176, v96
	v_lshlrev_b32_e32 v176, 16, v73
	v_lshlrev_b32_e32 v175, 16, v60
	v_mul_f32_e32 v83, v83, v86
	v_pk_mul_f32 v[86:87], v[14:15], v[162:163]
	v_cvt_pk_bf16_f32 v83, v97, v83
	s_nop 0
	v_add_f32_e32 v87, v87, v143
	v_add_f32_e32 v86, v86, v87
	v_mul_f32_e32 v87, 0xbfb8aa3b, v86
	v_exp_f32_e32 v87, v87
	s_nop 0
	v_add_f32_e32 v87, 1.0, v87
	v_rcp_f32_e32 v87, v87
	s_nop 0
	v_mul_f32_e32 v87, v86, v87
	v_cvt_pk_bf16_f32 v87, v90, v87
	v_pk_mul_f32 v[90:91], v[10:11], v[162:163]
	v_cvt_pk_bf16_f32 v86, v153, v139
	s_nop 0
	v_add_f32_e32 v91, v91, v19
	v_add_f32_e32 v170, v90, v91
	v_lshlrev_b32_e32 v91, 16, v68
	v_lshlrev_b32_e32 v90, 16, v72
	v_pk_mov_b32 v[94:95], v[90:91], v[168:169] op_sel:[1,0]
	s_nop 0
	v_pk_mul_f32 v[96:97], v[98:99], v[94:95]
	v_pk_mul_f32 v[94:95], v[158:159], v[94:95]
	v_add_f32_e32 v97, v97, v147
	v_add_f32_e32 v96, v96, v97
	v_mul_f32_e32 v97, 0xbfb8aa3b, v96
	v_exp_f32_e32 v97, v97
	v_add_f32_e32 v95, v95, v32
	v_add_f32_e32 v178, v94, v95
	v_pk_mul_f32 v[94:95], v[158:159], v[90:91]
	v_add_f32_e32 v97, 1.0, v97
	v_rcp_f32_e32 v97, v97
	v_add_f32_e32 v95, v95, v32
	v_add_f32_e32 v157, v94, v95
	v_mul_f32_e32 v139, v96, v97
	v_pk_mul_f32 v[96:97], v[98:99], v[90:91]
	s_nop 0
	v_add_f32_e32 v97, v97, v127
	v_add_f32_e32 v96, v96, v97
	v_mul_f32_e32 v97, 0xbfb8aa3b, v96
	v_exp_f32_e32 v97, v97
	s_nop 0
	v_add_f32_e32 v97, 1.0, v97
	v_rcp_f32_e32 v97, v97
	s_nop 0
	v_mul_f32_e32 v127, v96, v97
	v_and_b32_e32 v97, 0xffff0000, v68
	v_and_b32_e32 v96, 0xffff0000, v72
	v_pk_mov_b32 v[88:89], v[96:97], v[88:89] op_sel:[1,0]
	s_nop 0
	v_pk_mul_f32 v[94:95], v[28:29], v[88:89]
	v_pk_mul_f32 v[88:89], v[24:25], v[88:89]
	v_add_f32_e32 v68, v95, v149
	v_add_f32_e32 v68, v94, v68
	v_mul_f32_e32 v72, 0xbfb8aa3b, v68
	v_exp_f32_e32 v72, v72
	v_pk_mul_f32 v[94:95], v[28:29], v[96:97]
	v_add_f32_e32 v72, 1.0, v72
	v_rcp_f32_e32 v72, v72
	s_nop 0
	v_mul_f32_e32 v68, v68, v72
	v_add_f32_e32 v72, v95, v141
	v_add_f32_e32 v72, v94, v72
	v_mul_f32_e32 v94, 0xbfb8aa3b, v72
	v_exp_f32_e32 v94, v94
	v_cvt_pk_bf16_f32 v68, v139, v68
	s_nop 0
	v_add_f32_e32 v94, 1.0, v94
	v_rcp_f32_e32 v94, v94
	s_nop 0
	v_mul_f32_e32 v168, v72, v94
	v_add_f32_e32 v72, v89, v33
	v_add_f32_e32 v155, v88, v72
	v_pk_mul_f32 v[88:89], v[24:25], v[96:97]
	s_nop 0
	v_add_f32_e32 v72, v89, v33
	v_add_f32_e32 v153, v88, v72
	v_pk_mov_b32 v[88:89], v[176:177], v[102:103] op_sel:[1,0]
	v_and_b32_e32 v103, 0xffff0000, v69
	v_pk_mul_f32 v[94:95], v[104:105], v[88:89]
	v_pk_mul_f32 v[88:89], v[160:161], v[88:89]
	v_add_f32_e32 v72, v95, v151
	v_add_f32_e32 v72, v94, v72
	v_mul_f32_e32 v94, 0xbfb8aa3b, v72
	v_exp_f32_e32 v94, v94
	v_and_b32_e32 v102, 0xffff0000, v73
	v_add_f32_e32 v94, 1.0, v94
	v_rcp_f32_e32 v94, v94
	s_nop 0
	v_mul_f32_e32 v139, v72, v94
	v_pk_mul_f32 v[94:95], v[104:105], v[176:177]
	s_nop 0
	v_add_f32_e32 v72, v95, v131
	v_add_f32_e32 v72, v94, v72
	v_mul_f32_e32 v94, 0xbfb8aa3b, v72
	v_exp_f32_e32 v94, v94
	v_and_b32_e32 v95, 0xffff0000, v70
	v_add_f32_e32 v94, 1.0, v94
	v_rcp_f32_e32 v94, v94
	s_nop 0
	v_mul_f32_e32 v169, v72, v94
	v_add_f32_e32 v72, v89, v34
	v_add_f32_e32 v151, v88, v72
	v_pk_mul_f32 v[88:89], v[160:161], v[176:177]
	v_and_b32_e32 v94, 0xffff0000, v74
	v_add_f32_e32 v72, v89, v34
	v_add_f32_e32 v149, v88, v72
	v_pk_mov_b32 v[72:73], v[102:103], v[100:101] op_sel:[1,0]
	v_lshlrev_b32_e32 v101, 16, v70
	v_pk_mul_f32 v[88:89], v[30:31], v[72:73]
	v_pk_mul_f32 v[72:73], v[26:27], v[72:73]
	v_add_f32_e32 v69, v89, v172
	v_add_f32_e32 v69, v88, v69
	v_mul_f32_e32 v88, 0xbfb8aa3b, v69
	v_exp_f32_e32 v88, v88
	v_add_f32_e32 v73, v73, v35
	v_add_f32_e32 v147, v72, v73
	v_pk_mul_f32 v[72:73], v[26:27], v[102:103]
	v_add_f32_e32 v88, 1.0, v88
	v_rcp_f32_e32 v88, v88
	v_add_f32_e32 v73, v73, v35
	v_lshlrev_b32_e32 v100, 16, v74
	v_add_f32_e32 v145, v72, v73
	v_mul_f32_e32 v69, v69, v88
	v_pk_mul_f32 v[88:89], v[30:31], v[102:103]
	v_pk_mov_b32 v[72:73], v[100:101], v[166:167] op_sel:[1,0]
	v_add_f32_e32 v89, v89, v137
	v_add_f32_e32 v88, v88, v89
	v_mul_f32_e32 v89, 0xbfb8aa3b, v88
	v_exp_f32_e32 v89, v89
	v_cvt_pk_bf16_f32 v69, v139, v69
	v_lshlrev_b32_e32 v167, 16, v62
	v_add_f32_e32 v89, 1.0, v89
	v_rcp_f32_e32 v89, v89
	s_nop 0
	v_mul_f32_e32 v172, v88, v89
	v_pk_mul_f32 v[88:89], v[106:107], v[72:73]
	v_pk_mul_f32 v[72:73], v[112:113], v[72:73]
	v_add_f32_e32 v89, v89, v173
	v_add_f32_e32 v88, v88, v89
	v_mul_f32_e32 v89, 0xbfb8aa3b, v88
	v_exp_f32_e32 v89, v89
	v_add_f32_e32 v73, v73, v16
	v_add_f32_e32 v143, v72, v73
	v_pk_mul_f32 v[72:73], v[112:113], v[100:101]
	v_add_f32_e32 v89, 1.0, v89
	v_rcp_f32_e32 v89, v89
	v_add_f32_e32 v73, v73, v16
	v_add_f32_e32 v141, v72, v73
	v_pk_mov_b32 v[72:73], v[94:95], v[114:115] op_sel:[1,0]
	v_mul_f32_e32 v131, v88, v89
	v_pk_mul_f32 v[88:89], v[106:107], v[100:101]
	v_and_b32_e32 v173, 0xffff0000, v60
	v_add_f32_e32 v89, v89, v133
	v_add_f32_e32 v88, v88, v89
	v_mul_f32_e32 v89, 0xbfb8aa3b, v88
	v_exp_f32_e32 v89, v89
	s_nop 0
	v_add_f32_e32 v89, 1.0, v89
	v_rcp_f32_e32 v89, v89
	s_nop 0
	v_mul_f32_e32 v166, v88, v89
	v_pk_mul_f32 v[88:89], v[12:13], v[72:73]
	v_pk_mul_f32 v[72:73], v[8:9], v[72:73]
	v_add_f32_e32 v70, v89, v93
	v_add_f32_e32 v70, v88, v70
	v_mul_f32_e32 v74, 0xbfb8aa3b, v70
	v_exp_f32_e32 v74, v74
	v_pk_mul_f32 v[88:89], v[12:13], v[94:95]
	v_add_f32_e32 v73, v73, v17
	v_add_f32_e32 v139, v72, v73
	v_add_f32_e32 v74, 1.0, v74
	v_rcp_f32_e32 v74, v74
	v_pk_mul_f32 v[72:73], v[8:9], v[94:95]
	v_lshlrev_b32_e32 v93, 16, v71
	v_add_f32_e32 v73, v73, v17
	v_mul_f32_e32 v70, v70, v74
	v_add_f32_e32 v74, v89, v92
	v_add_f32_e32 v74, v88, v74
	v_mul_f32_e32 v88, 0xbfb8aa3b, v74
	v_exp_f32_e32 v88, v88
	v_lshlrev_b32_e32 v92, 16, v75
	v_add_f32_e32 v137, v72, v73
	v_pk_mov_b32 v[72:73], v[92:93], v[164:165] op_sel:[1,0]
	v_add_f32_e32 v88, 1.0, v88
	v_rcp_f32_e32 v88, v88
	v_cvt_pk_bf16_f32 v70, v131, v70
	v_and_b32_e32 v165, 0xffff0000, v62
	v_lshlrev_b32_e32 v62, 16, v44
	v_mul_f32_e32 v114, v74, v88
	v_pk_mul_f32 v[88:89], v[110:111], v[72:73]
	v_pk_mul_f32 v[72:73], v[108:109], v[72:73]
	v_add_f32_e32 v74, v89, v171
	v_add_f32_e32 v74, v88, v74
	v_mul_f32_e32 v88, 0xbfb8aa3b, v74
	v_exp_f32_e32 v88, v88
	v_add_f32_e32 v73, v73, v18
	v_lshlrev_b32_e32 v171, 16, v61
	v_add_f32_e32 v88, 1.0, v88
	v_rcp_f32_e32 v88, v88
	s_nop 0
	v_mul_f32_e32 v115, v74, v88
	v_pk_mul_f32 v[88:89], v[110:111], v[92:93]
	s_nop 0
	v_add_f32_e32 v74, v89, v135
	v_add_f32_e32 v74, v88, v74
	v_mul_f32_e32 v88, 0xbfb8aa3b, v74
	v_exp_f32_e32 v88, v88
	v_add_f32_e32 v135, v72, v73
	v_pk_mul_f32 v[72:73], v[108:109], v[92:93]
	v_and_b32_e32 v89, 0xffff0000, v71
	v_add_f32_e32 v88, 1.0, v88
	v_rcp_f32_e32 v88, v88
	v_add_f32_e32 v73, v73, v18
	v_add_f32_e32 v133, v72, v73
	v_mul_f32_e32 v164, v74, v88
	v_and_b32_e32 v88, 0xffff0000, v75
	v_pk_mov_b32 v[72:73], v[88:89], v[162:163] op_sel:[1,0]
	v_lshlrev_b32_e32 v163, 16, v63
	v_pk_mul_f32 v[74:75], v[14:15], v[72:73]
	v_pk_mul_f32 v[72:73], v[10:11], v[72:73]
	v_add_f32_e32 v71, v75, v174
	v_add_f32_e32 v71, v74, v71
	v_mul_f32_e32 v74, 0xbfb8aa3b, v71
	v_exp_f32_e32 v74, v74
	v_add_f32_e32 v73, v73, v19
	v_add_f32_e32 v131, v72, v73
	v_cvt_pk_bf16_f32 v72, v127, v168
	v_add_f32_e32 v74, 1.0, v74
	v_rcp_f32_e32 v74, v74
	v_cvt_pk_bf16_f32 v73, v169, v172
	v_lshlrev_b32_e32 v174, 16, v64
	v_and_b32_e32 v172, 0xffff0000, v64
	v_mul_f32_e32 v71, v71, v74
	v_pk_mul_f32 v[74:75], v[14:15], v[88:89]
	v_cvt_pk_bf16_f32 v71, v115, v71
	v_and_b32_e32 v168, 0xffff0000, v65
	v_add_f32_e32 v75, v75, v170
	v_add_f32_e32 v74, v74, v75
	v_mul_f32_e32 v75, 0xbfb8aa3b, v74
	v_exp_f32_e32 v75, v75
	v_lshlrev_b32_e32 v170, 16, v65
	v_and_b32_e32 v169, 0xffff0000, v61
	v_lshlrev_b32_e32 v162, 16, v67
	v_add_f32_e32 v75, 1.0, v75
	v_rcp_f32_e32 v75, v75
	s_nop 0
	v_mul_f32_e32 v75, v74, v75
	v_cvt_pk_bf16_f32 v74, v166, v114
	v_pk_mul_f32 v[114:115], v[10:11], v[88:89]
	v_cvt_pk_bf16_f32 v75, v164, v75
	v_lshlrev_b32_e32 v166, 16, v66
	v_add_f32_e32 v115, v115, v19
	v_add_f32_e32 v127, v114, v115
	v_and_b32_e32 v115, 0xffff0000, v63
	v_lshlrev_b32_e32 v63, 16, v40
	v_pk_mov_b32 v[64:65], v[62:63], v[90:91] op_sel:[1,0]
	v_pk_mov_b32 v[90:91], v[174:175], v[62:63] op_sel:[1,0]
	v_pk_mul_f32 v[60:61], v[98:99], v[64:65]
	v_pk_mul_f32 v[64:65], v[158:159], v[64:65]
	v_add_f32_e32 v61, v61, v178
	v_add_f32_e32 v60, v60, v61
	v_mul_f32_e32 v61, 0xbfb8aa3b, v60
	v_exp_f32_e32 v61, v61
	v_and_b32_e32 v164, 0xffff0000, v66
	v_and_b32_e32 v114, 0xffff0000, v67
	v_and_b32_e32 v67, 0xffff0000, v40
	v_add_f32_e32 v61, 1.0, v61
	v_rcp_f32_e32 v61, v61
	v_and_b32_e32 v66, 0xffff0000, v44
	v_mul_f32_e32 v178, v60, v61
	v_pk_mul_f32 v[60:61], v[98:99], v[62:63]
	v_pk_mul_f32 v[62:63], v[158:159], v[62:63]
	v_add_f32_e32 v61, v61, v157
	v_add_f32_e32 v60, v60, v61
	v_mul_f32_e32 v61, 0xbfb8aa3b, v60
	v_exp_f32_e32 v61, v61
	v_add_f32_e32 v63, v63, v32
	v_add_f32_e32 v61, 1.0, v61
	v_rcp_f32_e32 v61, v61
	s_nop 0
	v_mul_f32_e32 v60, v60, v61
	v_add_f32_e32 v61, v65, v32
	v_add_f32_e32 v61, v64, v61
	v_pk_mul_f32 v[64:65], v[98:99], v[90:91]
	s_nop 0
	v_add_f32_e32 v61, v65, v61
	v_add_f32_e32 v61, v64, v61
	v_mul_f32_e32 v64, 0xbfb8aa3b, v61
	v_exp_f32_e32 v64, v64
	s_nop 0
	v_add_f32_e32 v64, 1.0, v64
	v_rcp_f32_e32 v64, v64
	s_nop 0
	v_mul_f32_e32 v61, v61, v64
	v_add_f32_e32 v64, v62, v63
	v_pk_mul_f32 v[62:63], v[98:99], v[174:175]
	s_nop 0
	v_add_f32_e32 v63, v63, v64
	v_add_f32_e32 v62, v62, v63
	v_mul_f32_e32 v63, 0xbfb8aa3b, v62
	v_exp_f32_e32 v63, v63
	s_nop 0
	v_add_f32_e32 v63, 1.0, v63
	v_rcp_f32_e32 v63, v63
	s_nop 0
	v_mul_f32_e32 v64, v62, v63
	v_pk_mov_b32 v[62:63], v[66:67], v[96:97] op_sel:[1,0]
	s_nop 0
	v_pk_mul_f32 v[96:97], v[28:29], v[62:63]
	v_pk_mul_f32 v[62:63], v[24:25], v[62:63]
	v_add_f32_e32 v40, v97, v155
	v_add_f32_e32 v40, v96, v40
	v_mul_f32_e32 v44, 0xbfb8aa3b, v40
	v_exp_f32_e32 v44, v44
	v_pk_mul_f32 v[96:97], v[28:29], v[66:67]
	v_add_f32_e32 v63, v63, v33
	v_add_f32_e32 v44, 1.0, v44
	v_rcp_f32_e32 v44, v44
	s_nop 0
	v_mul_f32_e32 v40, v40, v44
	v_add_f32_e32 v44, v97, v153
	v_add_f32_e32 v44, v96, v44
	v_mul_f32_e32 v65, 0xbfb8aa3b, v44
	v_exp_f32_e32 v65, v65
	v_pk_mov_b32 v[96:97], v[172:173], v[66:67] op_sel:[1,0]
	v_pk_mul_f32 v[66:67], v[24:25], v[66:67]
	v_cvt_pk_bf16_f32 v40, v178, v40
	v_add_f32_e32 v65, 1.0, v65
	v_rcp_f32_e32 v65, v65
	v_lshlrev_b32_e32 v178, 16, v45
	v_mul_f32_e32 v44, v44, v65
	v_add_f32_e32 v65, v62, v63
	v_pk_mul_f32 v[62:63], v[28:29], v[96:97]
	v_cvt_pk_bf16_f32 v44, v60, v44
	s_nop 0
	v_add_f32_e32 v63, v63, v65
	v_add_f32_e32 v62, v62, v63
	v_mul_f32_e32 v63, 0xbfb8aa3b, v62
	v_exp_f32_e32 v63, v63
	s_nop 0
	v_add_f32_e32 v63, 1.0, v63
	v_rcp_f32_e32 v63, v63
	s_nop 0
	v_mul_f32_e32 v62, v62, v63
	v_add_f32_e32 v63, v67, v33
	v_add_f32_e32 v63, v66, v63
	v_pk_mul_f32 v[66:67], v[28:29], v[172:173]
	v_cvt_pk_bf16_f32 v60, v61, v62
	s_nop 0
	v_add_f32_e32 v63, v67, v63
	v_add_f32_e32 v63, v66, v63
	v_mul_f32_e32 v65, 0xbfb8aa3b, v63
	v_exp_f32_e32 v65, v65
	v_pk_mov_b32 v[66:67], v[178:179], v[176:177] op_sel:[1,0]
	v_add_f32_e32 v65, 1.0, v65
	v_rcp_f32_e32 v65, v65
	v_pk_mul_f32 v[176:177], v[104:105], v[66:67]
	v_pk_mul_f32 v[66:67], v[160:161], v[66:67]
	v_mul_f32_e32 v65, v63, v65
	v_add_f32_e32 v63, v177, v151
	v_add_f32_e32 v63, v176, v63
	v_mul_f32_e32 v151, 0xbfb8aa3b, v63
	v_exp_f32_e32 v151, v151
	v_pk_mul_f32 v[176:177], v[104:105], v[178:179]
	v_add_f32_e32 v67, v67, v34
	v_cvt_pk_bf16_f32 v64, v64, v65
	v_add_f32_e32 v151, 1.0, v151
	v_rcp_f32_e32 v151, v151
	s_nop 0
	v_mul_f32_e32 v151, v63, v151
	v_add_f32_e32 v63, v177, v149
	v_add_f32_e32 v63, v176, v63
	v_mul_f32_e32 v149, 0xbfb8aa3b, v63
	v_exp_f32_e32 v149, v149
	v_pk_mov_b32 v[176:177], v[170:171], v[178:179] op_sel:[1,0]
	v_pk_mul_f32 v[178:179], v[160:161], v[178:179]
	v_add_f32_e32 v149, 1.0, v149
	v_rcp_f32_e32 v149, v149
	s_nop 0
	v_mul_f32_e32 v63, v63, v149
	v_add_f32_e32 v149, v66, v67
	v_pk_mul_f32 v[66:67], v[104:105], v[176:177]
	s_nop 0
	v_add_f32_e32 v67, v67, v149
	v_add_f32_e32 v66, v66, v67
	v_mul_f32_e32 v67, 0xbfb8aa3b, v66
	v_exp_f32_e32 v67, v67
	s_nop 0
	v_add_f32_e32 v67, 1.0, v67
	v_rcp_f32_e32 v67, v67
	s_nop 0
	v_mul_f32_e32 v67, v66, v67
	v_add_f32_e32 v66, v179, v34
	v_add_f32_e32 v66, v178, v66
	v_pk_mul_f32 v[178:179], v[104:105], v[170:171]
	s_nop 0
	v_add_f32_e32 v66, v179, v66
	v_add_f32_e32 v66, v178, v66
	v_and_b32_e32 v179, 0xffff0000, v41
	v_and_b32_e32 v178, 0xffff0000, v45
	v_pk_mov_b32 v[102:103], v[178:179], v[102:103] op_sel:[1,0]
	v_mul_f32_e32 v149, 0xbfb8aa3b, v66
	v_pk_mul_f32 v[180:181], v[30:31], v[102:103]
	v_pk_mul_f32 v[102:103], v[26:27], v[102:103]
	v_add_f32_e32 v41, v181, v147
	v_add_f32_e32 v41, v180, v41
	v_mul_f32_e32 v45, 0xbfb8aa3b, v41
	v_exp_f32_e32 v45, v45
	v_pk_mul_f32 v[180:181], v[30:31], v[178:179]
	v_add_f32_e32 v103, v103, v35
	v_exp_f32_e32 v149, v149
	v_add_f32_e32 v45, 1.0, v45
	v_rcp_f32_e32 v45, v45
	v_add_f32_e32 v149, 1.0, v149
	v_rcp_f32_e32 v149, v149
	v_mul_f32_e32 v41, v41, v45
	v_add_f32_e32 v45, v181, v145
	v_add_f32_e32 v45, v180, v45
	v_mul_f32_e32 v145, 0xbfb8aa3b, v45
	v_exp_f32_e32 v145, v145
	v_mul_f32_e32 v66, v66, v149
	v_cvt_pk_bf16_f32 v41, v151, v41
	v_add_f32_e32 v145, 1.0, v145
	v_rcp_f32_e32 v145, v145
	s_nop 0
	v_mul_f32_e32 v45, v45, v145
	v_add_f32_e32 v145, v102, v103
	v_pk_mov_b32 v[102:103], v[168:169], v[178:179] op_sel:[1,0]
	v_pk_mul_f32 v[178:179], v[26:27], v[178:179]
	v_pk_mul_f32 v[180:181], v[30:31], v[102:103]
	v_cvt_pk_bf16_f32 v45, v63, v45
	s_nop 0
	v_add_f32_e32 v145, v181, v145
	v_add_f32_e32 v145, v180, v145
	v_mul_f32_e32 v147, 0xbfb8aa3b, v145
	v_exp_f32_e32 v147, v147
	s_nop 0
	v_add_f32_e32 v147, 1.0, v147
	v_rcp_f32_e32 v147, v147
	s_nop 0
	v_mul_f32_e32 v145, v145, v147
	v_add_f32_e32 v147, v179, v35
	v_add_f32_e32 v147, v178, v147
	v_pk_mul_f32 v[178:179], v[30:31], v[168:169]
	v_cvt_pk_bf16_f32 v61, v67, v145
	s_nop 0
	v_add_f32_e32 v147, v179, v147
	v_add_f32_e32 v147, v178, v147
	v_mul_f32_e32 v149, 0xbfb8aa3b, v147
	v_exp_f32_e32 v149, v149
	v_lshlrev_b32_e32 v179, 16, v42
	v_lshlrev_b32_e32 v178, 16, v46
	v_pk_mov_b32 v[100:101], v[178:179], v[100:101] op_sel:[1,0]
	v_add_f32_e32 v149, 1.0, v149
	v_rcp_f32_e32 v149, v149
	v_pk_mul_f32 v[180:181], v[106:107], v[100:101]
	v_pk_mul_f32 v[100:101], v[112:113], v[100:101]
	v_add_f32_e32 v143, v181, v143
	v_add_f32_e32 v143, v180, v143
	v_mul_f32_e32 v147, v147, v149
	v_mul_f32_e32 v149, 0xbfb8aa3b, v143
	v_exp_f32_e32 v149, v149
	v_pk_mul_f32 v[180:181], v[106:107], v[178:179]
	v_add_f32_e32 v101, v101, v16
	v_add_f32_e32 v141, v181, v141
	v_add_f32_e32 v149, 1.0, v149
	v_rcp_f32_e32 v149, v149
	v_add_f32_e32 v141, v180, v141
	v_cvt_pk_bf16_f32 v65, v66, v147
	v_mul_f32_e32 v143, v143, v149
	v_mul_f32_e32 v149, 0xbfb8aa3b, v141
	v_exp_f32_e32 v149, v149
	s_nop 0
	v_add_f32_e32 v149, 1.0, v149
	v_rcp_f32_e32 v149, v149
	s_nop 0
	v_mul_f32_e32 v141, v141, v149
	v_add_f32_e32 v149, v100, v101
	v_pk_mov_b32 v[100:101], v[166:167], v[178:179] op_sel:[1,0]
	v_pk_mul_f32 v[178:179], v[112:113], v[178:179]
	v_pk_mul_f32 v[180:181], v[106:107], v[100:101]
	s_nop 0
	v_add_f32_e32 v149, v181, v149
	v_add_f32_e32 v149, v180, v149
	v_mul_f32_e32 v151, 0xbfb8aa3b, v149
	v_exp_f32_e32 v151, v151
	v_and_b32_e32 v181, 0xffff0000, v42
	v_and_b32_e32 v180, 0xffff0000, v46
	v_pk_mov_b32 v[94:95], v[180:181], v[94:95] op_sel:[1,0]
	v_add_f32_e32 v151, 1.0, v151
	v_rcp_f32_e32 v151, v151
	s_nop 0
	v_mul_f32_e32 v149, v149, v151
	v_add_f32_e32 v151, v179, v16
	v_add_f32_e32 v151, v178, v151
	v_pk_mul_f32 v[178:179], v[106:107], v[166:167]
	s_nop 0
	v_add_f32_e32 v151, v179, v151
	v_add_f32_e32 v151, v178, v151
	v_pk_mul_f32 v[178:179], v[12:13], v[94:95]
	v_pk_mul_f32 v[94:95], v[8:9], v[94:95]
	v_add_f32_e32 v42, v179, v139
	v_add_f32_e32 v42, v178, v42
	v_mul_f32_e32 v46, 0xbfb8aa3b, v42
	v_exp_f32_e32 v46, v46
	v_pk_mul_f32 v[178:179], v[12:13], v[180:181]
	v_mul_f32_e32 v153, 0xbfb8aa3b, v151
	v_exp_f32_e32 v153, v153
	v_add_f32_e32 v46, 1.0, v46
	v_rcp_f32_e32 v46, v46
	v_add_f32_e32 v153, 1.0, v153
	v_rcp_f32_e32 v153, v153
	v_mul_f32_e32 v42, v42, v46
	v_add_f32_e32 v46, v179, v137
	v_add_f32_e32 v46, v178, v46
	v_mul_f32_e32 v137, 0xbfb8aa3b, v46
	v_exp_f32_e32 v137, v137
	v_pk_mov_b32 v[178:179], v[164:165], v[180:181] op_sel:[1,0]
	v_cvt_pk_bf16_f32 v42, v143, v42
	v_mul_f32_e32 v151, v151, v153
	v_add_f32_e32 v137, 1.0, v137
	v_rcp_f32_e32 v137, v137
	s_nop 0
	v_mul_f32_e32 v137, v46, v137
	v_add_f32_e32 v46, v95, v17
	v_add_f32_e32 v46, v94, v46
	v_pk_mul_f32 v[94:95], v[12:13], v[178:179]
	s_nop 0
	v_add_f32_e32 v46, v95, v46
	v_add_f32_e32 v46, v94, v46
	v_mul_f32_e32 v94, 0xbfb8aa3b, v46
	v_exp_f32_e32 v94, v94
	s_nop 0
	v_add_f32_e32 v94, 1.0, v94
	v_rcp_f32_e32 v94, v94
	s_nop 0
	v_mul_f32_e32 v139, v46, v94
	v_pk_mul_f32 v[94:95], v[8:9], v[180:181]
	v_cvt_pk_bf16_f32 v62, v149, v139
	s_nop 0
	v_add_f32_e32 v46, v95, v17
	v_add_f32_e32 v46, v94, v46
	v_pk_mul_f32 v[94:95], v[12:13], v[164:165]
	s_nop 0
	v_add_f32_e32 v46, v95, v46
	v_add_f32_e32 v46, v94, v46
	v_mul_f32_e32 v94, 0xbfb8aa3b, v46
	v_exp_f32_e32 v94, v94
	v_lshlrev_b32_e32 v95, 16, v43
	v_add_f32_e32 v94, 1.0, v94
	v_rcp_f32_e32 v94, v94
	s_nop 0
	v_mul_f32_e32 v143, v46, v94
	v_lshlrev_b32_e32 v94, 16, v47
	v_pk_mov_b32 v[92:93], v[94:95], v[92:93] op_sel:[1,0]
	v_cvt_pk_bf16_f32 v66, v151, v143
	s_nop 0
	v_pk_mul_f32 v[180:181], v[110:111], v[92:93]
	v_pk_mul_f32 v[92:93], v[108:109], v[92:93]
	v_add_f32_e32 v46, v181, v135
	v_add_f32_e32 v46, v180, v46
	v_mul_f32_e32 v135, 0xbfb8aa3b, v46
	v_exp_f32_e32 v135, v135
	v_pk_mul_f32 v[180:181], v[110:111], v[94:95]
	v_add_f32_e32 v135, 1.0, v135
	v_rcp_f32_e32 v135, v135
	s_nop 0
	v_mul_f32_e32 v135, v46, v135
	v_add_f32_e32 v46, v181, v133
	v_add_f32_e32 v46, v180, v46
	v_mul_f32_e32 v133, 0xbfb8aa3b, v46
	v_exp_f32_e32 v133, v133
	v_pk_mov_b32 v[180:181], v[162:163], v[94:95] op_sel:[1,0]
	v_add_f32_e32 v133, 1.0, v133
	v_rcp_f32_e32 v133, v133
	s_nop 0
	v_mul_f32_e32 v133, v46, v133
	v_add_f32_e32 v46, v93, v18
	v_add_f32_e32 v46, v92, v46
	v_pk_mul_f32 v[92:93], v[110:111], v[180:181]
	s_nop 0
	v_add_f32_e32 v46, v93, v46
	v_add_f32_e32 v46, v92, v46
	v_mul_f32_e32 v92, 0xbfb8aa3b, v46
	v_exp_f32_e32 v92, v92
	s_nop 0
	v_add_f32_e32 v92, 1.0, v92
	v_rcp_f32_e32 v92, v92
	s_nop 0
	v_mul_f32_e32 v153, v46, v92
	v_pk_mul_f32 v[92:93], v[108:109], v[94:95]
	s_nop 0
	v_add_f32_e32 v46, v93, v18
	v_add_f32_e32 v46, v92, v46
	v_pk_mul_f32 v[92:93], v[110:111], v[162:163]
	s_nop 0
	v_add_f32_e32 v46, v93, v46
	v_add_f32_e32 v46, v92, v46
	v_mul_f32_e32 v92, 0xbfb8aa3b, v46
	v_exp_f32_e32 v92, v92
	v_and_b32_e32 v93, 0xffff0000, v43
	v_add_f32_e32 v92, 1.0, v92
	v_rcp_f32_e32 v92, v92
	s_nop 0
	v_mul_f32_e32 v94, v46, v92
	v_and_b32_e32 v92, 0xffff0000, v47
	v_pk_mov_b32 v[46:47], v[92:93], v[88:89] op_sel:[1,0]
	v_pk_mov_b32 v[186:187], v[114:115], v[92:93] op_sel:[1,0]
	v_pk_mul_f32 v[88:89], v[14:15], v[46:47]
	v_pk_mul_f32 v[46:47], v[10:11], v[46:47]
	v_add_f32_e32 v43, v89, v131
	v_add_f32_e32 v43, v88, v43
	v_mul_f32_e32 v88, 0xbfb8aa3b, v43
	v_exp_f32_e32 v88, v88
	v_add_f32_e32 v47, v47, v19
	v_add_f32_e32 v88, 1.0, v88
	v_rcp_f32_e32 v88, v88
	s_nop 0
	v_mul_f32_e32 v43, v43, v88
	v_pk_mul_f32 v[88:89], v[14:15], v[92:93]
	v_cvt_pk_bf16_f32 v43, v135, v43
	s_nop 0
	v_add_f32_e32 v89, v89, v127
	v_add_f32_e32 v88, v88, v89
	v_mul_f32_e32 v89, 0xbfb8aa3b, v88
	v_exp_f32_e32 v89, v89
	s_nop 0
	v_add_f32_e32 v89, 1.0, v89
	v_rcp_f32_e32 v89, v89
	s_nop 0
	v_mul_f32_e32 v88, v88, v89
	v_add_f32_e32 v89, v46, v47
	v_pk_mul_f32 v[46:47], v[14:15], v[186:187]
	s_nop 0
	v_add_f32_e32 v47, v47, v89
	v_add_f32_e32 v46, v46, v47
	v_mul_f32_e32 v47, 0xbfb8aa3b, v46
	v_exp_f32_e32 v47, v47
	s_nop 0
	v_add_f32_e32 v47, 1.0, v47
	v_rcp_f32_e32 v47, v47
	s_nop 0
	v_mul_f32_e32 v89, v46, v47
	v_cvt_pk_bf16_f32 v47, v133, v88
	v_cvt_pk_bf16_f32 v63, v153, v89
	v_pk_mul_f32 v[88:89], v[10:11], v[92:93]
	v_cvt_pk_bf16_f32 v46, v141, v137
	s_nop 0
	v_add_f32_e32 v67, v89, v19
	v_add_f32_e32 v67, v88, v67
	v_pk_mul_f32 v[88:89], v[14:15], v[114:115]
	s_nop 0
	v_add_f32_e32 v67, v89, v67
	v_add_f32_e32 v67, v88, v67
	v_mul_f32_e32 v88, 0xbfb8aa3b, v67
	v_exp_f32_e32 v88, v88
	s_nop 0
	v_add_f32_e32 v88, 1.0, v88
	v_rcp_f32_e32 v88, v88
	s_nop 0
	v_mul_f32_e32 v67, v67, v88
	v_cvt_pk_bf16_f32 v67, v94, v67
	s_and_saveexec_b64 s[0:1], vcc
	s_cbranch_execz .LBB0_992
	v_mov_b64_e32 v[88:89], s[12:13]
	v_mad_i64_i32 v[88:89], s[20:21], v125, s26, v[88:89]
	v_lshl_add_u64 v[88:89], v[122:123], 2, v[88:89]
	v_mov_b32_e32 v92, v174
	v_mov_b32_e32 v93, v172
	v_mov_b32_e32 v94, v170
	v_mov_b32_e32 v95, v168
	global_store_dwordx4 v[88:89], v[92:95], off
	s_nop 1
	v_mov_b32_e32 v92, v166
	v_mov_b32_e32 v93, v164
	v_mov_b32_e32 v94, v162
	v_mov_b32_e32 v95, v114
	global_store_dwordx4 v[88:89], v[92:95], off offset:16

.LBB0_1336:
	ds_read_b128 v[144:147], v153
	ds_read_b128 v[156:159], v153 offset:1024
	ds_read_b128 v[160:163], v153 offset:2048
	ds_read_b128 v[164:167], v153 offset:3072
	ds_read_b128 v[168:171], v154
	ds_read_b128 v[172:175], v154 offset:1024
	ds_read_b128 v[176:179], v154 offset:2048
	ds_read_b128 v[180:183], v154 offset:3072
	s_add_u32 s22, s18, s20
	s_addc_u32 s23, s19, s21
	s_add_u32 s22, s22, 0x100
	s_addc_u32 s23, s23, 0
	s_add_u32 s42, s39, s20
	s_addc_u32 s43, s40, s21
	s_cmpk_eq_i32 s20, 0x300
	s_cselect_b32 s23, s1, s23
	s_cselect_b32 s22, s0, s22
	s_cselect_b32 s43, s17, s43
	s_cselect_b32 s42, s16, s42
	v_lshl_add_u64 v[148:149], v[142:143], 0, s[20:21]
	s_add_i32 m0, s26, 0xc000
	ds_read_b128 v[186:189], v155
	ds_read_b128 v[190:193], v155 offset:1024
	ds_read_b128 v[194:197], v155 offset:2048
	ds_read_b128 v[200:203], v155 offset:3072
	ds_read_b128 v[204:207], v155 offset:4096
	ds_read_b128 v[208:211], v155 offset:5120
	ds_read_b128 v[212:215], v155 offset:6144
	ds_read_b128 v[216:219], v155 offset:7168
	global_load_lds_dwordx4 v[148:149], off
	v_lshl_add_u64 v[148:149], v[140:141], 0, s[20:21]
	s_add_i32 m0, s26, 0xe000
	s_nop 0
	global_load_lds_dwordx4 v[148:149], off
	s_waitcnt vmcnt(8)
	s_waitcnt lgkmcnt(0)
	s_barrier
	s_waitcnt lgkmcnt(0)
	v_mfma_f32_16x16x32_bf16 v[124:127], v[144:147], v[186:189], v[124:127]
	v_mfma_f32_16x16x32_bf16 v[120:123], v[160:163], v[186:189], v[120:123]
	v_mfma_f32_16x16x32_bf16 v[108:111], v[144:147], v[194:197], v[108:111]
	v_mfma_f32_16x16x32_bf16 v[104:107], v[160:163], v[194:197], v[104:107]
	v_mfma_f32_16x16x32_bf16 v[92:95], v[144:147], v[204:207], v[92:95]
	v_mfma_f32_16x16x32_bf16 v[88:91], v[160:163], v[204:207], v[88:91]
	v_mfma_f32_16x16x32_bf16 v[76:79], v[144:147], v[212:215], v[76:79]
	v_mfma_f32_16x16x32_bf16 v[72:75], v[160:163], v[212:215], v[72:75]
	v_mfma_f32_16x16x32_bf16 v[124:127], v[156:159], v[190:193], v[124:127]
	v_mfma_f32_16x16x32_bf16 v[120:123], v[164:167], v[190:193], v[120:123]
	v_mfma_f32_16x16x32_bf16 v[108:111], v[156:159], v[200:203], v[108:111]
	v_mfma_f32_16x16x32_bf16 v[104:107], v[164:167], v[200:203], v[104:107]
	v_mfma_f32_16x16x32_bf16 v[92:95], v[156:159], v[208:211], v[92:95]
	v_mfma_f32_16x16x32_bf16 v[88:91], v[164:167], v[208:211], v[88:91]
	v_mfma_f32_16x16x32_bf16 v[76:79], v[156:159], v[216:219], v[76:79]
	v_mfma_f32_16x16x32_bf16 v[72:75], v[164:167], v[216:219], v[72:75]
	v_mfma_f32_16x16x32_bf16 v[116:119], v[168:171], v[186:189], v[116:119]
	v_mfma_f32_16x16x32_bf16 v[112:115], v[176:179], v[186:189], v[112:115]
	v_mfma_f32_16x16x32_bf16 v[100:103], v[168:171], v[194:197], v[100:103]
	v_mfma_f32_16x16x32_bf16 v[96:99], v[176:179], v[194:197], v[96:99]
	v_mfma_f32_16x16x32_bf16 v[84:87], v[168:171], v[204:207], v[84:87]
	v_mfma_f32_16x16x32_bf16 v[80:83], v[176:179], v[204:207], v[80:83]
	v_mfma_f32_16x16x32_bf16 v[68:71], v[168:171], v[212:215], v[68:71]
	v_mfma_f32_16x16x32_bf16 v[64:67], v[176:179], v[212:215], v[64:67]
	v_mfma_f32_16x16x32_bf16 v[116:119], v[172:175], v[190:193], v[116:119]
	v_mfma_f32_16x16x32_bf16 v[112:115], v[180:183], v[190:193], v[112:115]
	v_mfma_f32_16x16x32_bf16 v[100:103], v[172:175], v[200:203], v[100:103]
	v_mfma_f32_16x16x32_bf16 v[96:99], v[180:183], v[200:203], v[96:99]
	v_mfma_f32_16x16x32_bf16 v[84:87], v[172:175], v[208:211], v[84:87]
	v_mfma_f32_16x16x32_bf16 v[80:83], v[180:183], v[208:211], v[80:83]
	v_mfma_f32_16x16x32_bf16 v[68:71], v[172:175], v[216:219], v[68:71]
	v_mfma_f32_16x16x32_bf16 v[64:67], v[180:183], v[216:219], v[64:67]
	s_barrier
	s_add_i32 s44, s33, s24
	v_lshl_add_u64 v[148:149], s[42:43], 0, v[128:129]
	s_mov_b32 m0, s44
	ds_read_b128 v[186:189], v155 offset:16384
	ds_read_b128 v[190:193], v155 offset:17408
	ds_read_b128 v[194:197], v155 offset:18432
	ds_read_b128 v[200:203], v155 offset:19456
	ds_read_b128 v[204:207], v155 offset:20480
	ds_read_b128 v[208:211], v155 offset:21504
	ds_read_b128 v[212:215], v155 offset:22528
	ds_read_b128 v[216:219], v155 offset:23552
	global_load_lds_dwordx4 v[148:149], off
	s_add_i32 m0, s44, 0x2000
	v_lshl_add_u64 v[220:221], s[42:43], 0, v[130:131]
	s_add_u32 s42, s42, s4
	s_addc_u32 s43, s43, s5
	s_add_i32 s44, s34, s24
	global_load_lds_dwordx4 v[220:221], off
	v_lshl_add_u64 v[222:223], s[42:43], 0, v[128:129]
	s_mov_b32 m0, s44
	v_lshl_add_u64 v[224:225], s[42:43], 0, v[130:131]
	global_load_lds_dwordx4 v[222:223], off
	s_add_i32 m0, s44, 0x2000
	v_lshl_add_u64 v[226:227], s[22:23], 0, v[128:129]
	global_load_lds_dwordx4 v[224:225], off
	s_mov_b32 m0, s26
	v_lshl_add_u64 v[228:229], s[22:23], 0, v[130:131]
	global_load_lds_dwordx4 v[226:227], off
	s_mov_b32 m0, s27
	s_nop 0
	global_load_lds_dwordx4 v[228:229], off
	s_waitcnt vmcnt(8)
	s_waitcnt lgkmcnt(0)
	s_barrier
	s_waitcnt lgkmcnt(0)
	v_mfma_f32_16x16x32_bf16 v[60:63], v[144:147], v[186:189], v[60:63]
	v_mfma_f32_16x16x32_bf16 v[56:59], v[160:163], v[186:189], v[56:59]
	v_mfma_f32_16x16x32_bf16 v[44:47], v[144:147], v[194:197], v[44:47]
	v_mfma_f32_16x16x32_bf16 v[40:43], v[160:163], v[194:197], v[40:43]
	v_mfma_f32_16x16x32_bf16 v[28:31], v[144:147], v[204:207], v[28:31]
	v_mfma_f32_16x16x32_bf16 v[24:27], v[160:163], v[204:207], v[24:27]
	v_mfma_f32_16x16x32_bf16 v[12:15], v[144:147], v[212:215], v[12:15]
	v_mfma_f32_16x16x32_bf16 v[8:11], v[160:163], v[212:215], v[8:11]
	v_mfma_f32_16x16x32_bf16 v[60:63], v[156:159], v[190:193], v[60:63]
	v_mfma_f32_16x16x32_bf16 v[56:59], v[164:167], v[190:193], v[56:59]
	v_mfma_f32_16x16x32_bf16 v[44:47], v[156:159], v[200:203], v[44:47]
	v_mfma_f32_16x16x32_bf16 v[40:43], v[164:167], v[200:203], v[40:43]
	v_mfma_f32_16x16x32_bf16 v[28:31], v[156:159], v[208:211], v[28:31]
	v_mfma_f32_16x16x32_bf16 v[24:27], v[164:167], v[208:211], v[24:27]
	v_mfma_f32_16x16x32_bf16 v[12:15], v[156:159], v[216:219], v[12:15]
	v_mfma_f32_16x16x32_bf16 v[8:11], v[164:167], v[216:219], v[8:11]
	v_mfma_f32_16x16x32_bf16 v[52:55], v[168:171], v[186:189], v[52:55]
	v_mfma_f32_16x16x32_bf16 v[48:51], v[176:179], v[186:189], v[48:51]
	v_mfma_f32_16x16x32_bf16 v[36:39], v[168:171], v[194:197], v[36:39]
	v_mfma_f32_16x16x32_bf16 v[32:35], v[176:179], v[194:197], v[32:35]
	v_mfma_f32_16x16x32_bf16 v[20:23], v[168:171], v[204:207], v[20:23]
	v_mfma_f32_16x16x32_bf16 v[16:19], v[176:179], v[204:207], v[16:19]
	v_mfma_f32_16x16x32_bf16 v[4:7], v[168:171], v[212:215], v[4:7]
	v_mfma_f32_16x16x32_bf16 v[0:3], v[176:179], v[212:215], v[0:3]
	v_mfma_f32_16x16x32_bf16 v[52:55], v[172:175], v[190:193], v[52:55]
	v_mfma_f32_16x16x32_bf16 v[48:51], v[180:183], v[190:193], v[48:51]
	v_mfma_f32_16x16x32_bf16 v[36:39], v[172:175], v[200:203], v[36:39]
	v_mfma_f32_16x16x32_bf16 v[32:35], v[180:183], v[200:203], v[32:35]
	v_mfma_f32_16x16x32_bf16 v[20:23], v[172:175], v[208:211], v[20:23]
	v_mfma_f32_16x16x32_bf16 v[16:19], v[180:183], v[208:211], v[16:19]
	v_mfma_f32_16x16x32_bf16 v[4:7], v[172:175], v[216:219], v[4:7]
	v_mfma_f32_16x16x32_bf16 v[0:3], v[180:183], v[216:219], v[0:3]
	s_barrier
	s_add_i32 s42, 0, 0x18000
	s_add_i32 s43, 0, 0x1c000
	v_add_u32_e32 v164, s42, v151
	v_add_u32_e32 v180, s43, v151
	ds_read_b128 v[144:147], v164
	ds_read_b128 v[156:159], v164 offset:1024
	ds_read_b128 v[160:163], v164 offset:2048
	ds_read_b128 v[164:167], v164 offset:3072
	ds_read_b128 v[168:171], v180
	ds_read_b128 v[172:175], v180 offset:1024
	ds_read_b128 v[176:179], v180 offset:2048
	ds_read_b128 v[180:183], v180 offset:3072
	s_add_u32 s22, s22, s4
	s_addc_u32 s23, s23, s5
	s_mov_b32 m0, s28
	v_lshl_add_u64 v[230:231], s[22:23], 0, v[128:129]
	ds_read_b128 v[186:189], v155 offset:32768
	ds_read_b128 v[190:193], v155 offset:33792
	ds_read_b128 v[194:197], v155 offset:34816
	ds_read_b128 v[200:203], v155 offset:35840
	ds_read_b128 v[204:207], v155 offset:36864
	ds_read_b128 v[208:211], v155 offset:37888
	ds_read_b128 v[212:215], v155 offset:38912
	ds_read_b128 v[216:219], v155 offset:39936
	global_load_lds_dwordx4 v[230:231], off
	v_lshl_add_u64 v[230:231], s[22:23], 0, v[130:131]
	s_mov_b32 m0, s29
	s_nop 0
	global_load_lds_dwordx4 v[230:231], off
	s_waitcnt vmcnt(8)
	s_waitcnt lgkmcnt(0)
	s_barrier
	s_waitcnt lgkmcnt(0)
	v_mfma_f32_16x16x32_bf16 v[124:127], v[144:147], v[186:189], v[124:127]
	v_mfma_f32_16x16x32_bf16 v[120:123], v[160:163], v[186:189], v[120:123]
	v_mfma_f32_16x16x32_bf16 v[108:111], v[144:147], v[194:197], v[108:111]
	v_mfma_f32_16x16x32_bf16 v[104:107], v[160:163], v[194:197], v[104:107]
	v_mfma_f32_16x16x32_bf16 v[92:95], v[144:147], v[204:207], v[92:95]
	v_mfma_f32_16x16x32_bf16 v[88:91], v[160:163], v[204:207], v[88:91]
	v_mfma_f32_16x16x32_bf16 v[76:79], v[144:147], v[212:215], v[76:79]
	v_mfma_f32_16x16x32_bf16 v[72:75], v[160:163], v[212:215], v[72:75]
	v_mfma_f32_16x16x32_bf16 v[124:127], v[156:159], v[190:193], v[124:127]
	v_mfma_f32_16x16x32_bf16 v[120:123], v[164:167], v[190:193], v[120:123]
	v_mfma_f32_16x16x32_bf16 v[108:111], v[156:159], v[200:203], v[108:111]
	v_mfma_f32_16x16x32_bf16 v[104:107], v[164:167], v[200:203], v[104:107]
	v_mfma_f32_16x16x32_bf16 v[92:95], v[156:159], v[208:211], v[92:95]
	v_mfma_f32_16x16x32_bf16 v[88:91], v[164:167], v[208:211], v[88:91]
	v_mfma_f32_16x16x32_bf16 v[76:79], v[156:159], v[216:219], v[76:79]
	v_mfma_f32_16x16x32_bf16 v[72:75], v[164:167], v[216:219], v[72:75]
	v_mfma_f32_16x16x32_bf16 v[116:119], v[168:171], v[186:189], v[116:119]
	v_mfma_f32_16x16x32_bf16 v[112:115], v[176:179], v[186:189], v[112:115]
	v_mfma_f32_16x16x32_bf16 v[100:103], v[168:171], v[194:197], v[100:103]
	v_mfma_f32_16x16x32_bf16 v[96:99], v[176:179], v[194:197], v[96:99]
	v_mfma_f32_16x16x32_bf16 v[84:87], v[168:171], v[204:207], v[84:87]
	v_mfma_f32_16x16x32_bf16 v[80:83], v[176:179], v[204:207], v[80:83]
	v_mfma_f32_16x16x32_bf16 v[68:71], v[168:171], v[212:215], v[68:71]
	v_mfma_f32_16x16x32_bf16 v[64:67], v[176:179], v[212:215], v[64:67]
	v_mfma_f32_16x16x32_bf16 v[116:119], v[172:175], v[190:193], v[116:119]
	v_mfma_f32_16x16x32_bf16 v[112:115], v[180:183], v[190:193], v[112:115]
	v_mfma_f32_16x16x32_bf16 v[100:103], v[172:175], v[200:203], v[100:103]
	v_mfma_f32_16x16x32_bf16 v[96:99], v[180:183], v[200:203], v[96:99]
	v_mfma_f32_16x16x32_bf16 v[84:87], v[172:175], v[208:211], v[84:87]
	v_mfma_f32_16x16x32_bf16 v[80:83], v[180:183], v[208:211], v[80:83]
	v_mfma_f32_16x16x32_bf16 v[68:71], v[172:175], v[216:219], v[68:71]
	v_mfma_f32_16x16x32_bf16 v[64:67], v[180:183], v[216:219], v[64:67]
	s_barrier
	s_add_i32 s22, s42, s24
	v_lshl_add_u64 v[148:149], v[148:149], 0, s[12:13]
	s_mov_b32 m0, s22
	ds_read_b128 v[186:189], v155 offset:49152
	ds_read_b128 v[190:193], v155 offset:50176
	ds_read_b128 v[194:197], v155 offset:51200
	ds_read_b128 v[200:203], v155 offset:52224
	ds_read_b128 v[204:207], v155 offset:53248
	ds_read_b128 v[208:211], v155 offset:54272
	ds_read_b128 v[212:215], v155 offset:55296
	ds_read_b128 v[216:219], v155 offset:56320
	global_load_lds_dwordx4 v[148:149], off
	v_lshl_add_u64 v[148:149], v[220:221], 0, s[12:13]
	s_add_i32 m0, s22, 0x2000
	s_add_i32 s22, s43, s24
	global_load_lds_dwordx4 v[148:149], off
	v_lshl_add_u64 v[148:149], v[222:223], 0, s[12:13]
	s_mov_b32 m0, s22
	s_nop 0
	global_load_lds_dwordx4 v[148:149], off
	v_lshl_add_u64 v[148:149], v[224:225], 0, s[12:13]
	s_add_i32 m0, s22, 0x2000
	s_nop 0
	global_load_lds_dwordx4 v[148:149], off
	v_lshl_add_u64 v[148:149], v[226:227], 0, s[12:13]
	s_mov_b32 m0, s30
	s_nop 0
	global_load_lds_dwordx4 v[148:149], off
	v_lshl_add_u64 v[148:149], v[228:229], 0, s[12:13]
	s_mov_b32 m0, s31
	s_nop 0
	global_load_lds_dwordx4 v[148:149], off
	s_waitcnt vmcnt(8)
	s_waitcnt lgkmcnt(0)
	s_barrier
	s_waitcnt lgkmcnt(0)
	v_mfma_f32_16x16x32_bf16 v[60:63], v[144:147], v[186:189], v[60:63]
	v_mfma_f32_16x16x32_bf16 v[56:59], v[160:163], v[186:189], v[56:59]
	v_mfma_f32_16x16x32_bf16 v[44:47], v[144:147], v[194:197], v[44:47]
	v_mfma_f32_16x16x32_bf16 v[40:43], v[160:163], v[194:197], v[40:43]
	v_mfma_f32_16x16x32_bf16 v[28:31], v[144:147], v[204:207], v[28:31]
	v_mfma_f32_16x16x32_bf16 v[24:27], v[160:163], v[204:207], v[24:27]
	v_mfma_f32_16x16x32_bf16 v[12:15], v[144:147], v[212:215], v[12:15]
	v_mfma_f32_16x16x32_bf16 v[8:11], v[160:163], v[212:215], v[8:11]
	v_mfma_f32_16x16x32_bf16 v[60:63], v[156:159], v[190:193], v[60:63]
	v_mfma_f32_16x16x32_bf16 v[56:59], v[164:167], v[190:193], v[56:59]
	v_mfma_f32_16x16x32_bf16 v[44:47], v[156:159], v[200:203], v[44:47]
	v_mfma_f32_16x16x32_bf16 v[40:43], v[164:167], v[200:203], v[40:43]
	v_mfma_f32_16x16x32_bf16 v[28:31], v[156:159], v[208:211], v[28:31]
	v_mfma_f32_16x16x32_bf16 v[24:27], v[164:167], v[208:211], v[24:27]
	v_mfma_f32_16x16x32_bf16 v[12:15], v[156:159], v[216:219], v[12:15]
	v_mfma_f32_16x16x32_bf16 v[8:11], v[164:167], v[216:219], v[8:11]
	v_mfma_f32_16x16x32_bf16 v[52:55], v[168:171], v[186:189], v[52:55]
	v_mfma_f32_16x16x32_bf16 v[48:51], v[176:179], v[186:189], v[48:51]
	v_mfma_f32_16x16x32_bf16 v[36:39], v[168:171], v[194:197], v[36:39]
	v_mfma_f32_16x16x32_bf16 v[32:35], v[176:179], v[194:197], v[32:35]
	v_mfma_f32_16x16x32_bf16 v[20:23], v[168:171], v[204:207], v[20:23]
	v_mfma_f32_16x16x32_bf16 v[16:19], v[176:179], v[204:207], v[16:19]
	v_mfma_f32_16x16x32_bf16 v[4:7], v[168:171], v[212:215], v[4:7]
	v_mfma_f32_16x16x32_bf16 v[0:3], v[176:179], v[212:215], v[0:3]
	v_mfma_f32_16x16x32_bf16 v[52:55], v[172:175], v[190:193], v[52:55]
	v_mfma_f32_16x16x32_bf16 v[48:51], v[180:183], v[190:193], v[48:51]
	v_mfma_f32_16x16x32_bf16 v[36:39], v[172:175], v[200:203], v[36:39]
	v_mfma_f32_16x16x32_bf16 v[32:35], v[180:183], v[200:203], v[32:35]
	v_mfma_f32_16x16x32_bf16 v[20:23], v[172:175], v[208:211], v[20:23]
	v_mfma_f32_16x16x32_bf16 v[16:19], v[180:183], v[208:211], v[16:19]
	v_mfma_f32_16x16x32_bf16 v[4:7], v[172:175], v[216:219], v[4:7]
	v_mfma_f32_16x16x32_bf16 v[0:3], v[180:183], v[216:219], v[0:3]
	s_barrier
	s_add_i32 s41, s41, 2
	s_add_u32 s20, s20, 0x100
	s_addc_u32 s21, s21, 0
	s_cmp_gt_u32 s41, 5
	s_cbranch_scc0 .LBB0_1336
	s_and_b64 vcc, exec, s[14:15]
	s_cbranch_vccz .LBB0_1339
	s_barrier

.LBB0_1611:
	ds_read_b128 v[146:149], v156
	ds_read_b128 v[160:163], v156 offset:1024
	ds_read_b128 v[164:167], v156 offset:2048
	ds_read_b128 v[168:171], v156 offset:3072
	ds_read_b128 v[172:175], v157
	ds_read_b128 v[176:179], v157 offset:1024
	ds_read_b128 v[180:183], v157 offset:2048
	ds_read_b128 v[186:189], v157 offset:3072
	s_add_u32 s20, s16, s18
	s_addc_u32 s21, s17, s19
	s_add_u32 s20, s20, 0x100
	s_addc_u32 s21, s21, 0
	s_add_u32 s49, s46, s18
	s_addc_u32 s50, s47, s19
	s_cmpk_eq_i32 s18, 0xf00
	s_cselect_b32 s21, s3, s21
	s_cselect_b32 s20, s2, s20
	s_cselect_b32 s51, s15, s50
	s_cselect_b32 s50, s14, s49
	s_mov_b32 m0, s33
	v_lshl_add_u64 v[224:225], v[142:143], 0, s[18:19]
	ds_read_b128 v[190:193], v158
	ds_read_b128 v[194:197], v158 offset:1024
	ds_read_b128 v[200:203], v158 offset:2048
	ds_read_b128 v[204:207], v158 offset:3072
	ds_read_b128 v[208:211], v158 offset:4096
	ds_read_b128 v[212:215], v158 offset:5120
	ds_read_b128 v[216:219], v158 offset:6144
	ds_read_b128 v[220:223], v158 offset:7168
	global_load_lds_dwordx4 v[224:225], off
	v_lshl_add_u64 v[224:225], v[144:145], 0, s[18:19]
	s_mov_b32 m0, s40
	s_nop 0
	global_load_lds_dwordx4 v[224:225], off
	s_waitcnt vmcnt(8)
	s_waitcnt lgkmcnt(0)
	s_barrier
	s_waitcnt lgkmcnt(0)
	v_mfma_f32_16x16x32_bf16 v[124:127], v[146:149], v[190:193], v[124:127]
	v_mfma_f32_16x16x32_bf16 v[120:123], v[164:167], v[190:193], v[120:123]
	v_mfma_f32_16x16x32_bf16 v[108:111], v[146:149], v[200:203], v[108:111]
	v_mfma_f32_16x16x32_bf16 v[104:107], v[164:167], v[200:203], v[104:107]
	v_mfma_f32_16x16x32_bf16 v[92:95], v[146:149], v[208:211], v[92:95]
	v_mfma_f32_16x16x32_bf16 v[88:91], v[164:167], v[208:211], v[88:91]
	v_mfma_f32_16x16x32_bf16 v[76:79], v[146:149], v[216:219], v[76:79]
	v_mfma_f32_16x16x32_bf16 v[72:75], v[164:167], v[216:219], v[72:75]
	v_mfma_f32_16x16x32_bf16 v[124:127], v[160:163], v[194:197], v[124:127]
	v_mfma_f32_16x16x32_bf16 v[120:123], v[168:171], v[194:197], v[120:123]
	v_mfma_f32_16x16x32_bf16 v[108:111], v[160:163], v[204:207], v[108:111]
	v_mfma_f32_16x16x32_bf16 v[104:107], v[168:171], v[204:207], v[104:107]
	v_mfma_f32_16x16x32_bf16 v[92:95], v[160:163], v[212:215], v[92:95]
	v_mfma_f32_16x16x32_bf16 v[88:91], v[168:171], v[212:215], v[88:91]
	v_mfma_f32_16x16x32_bf16 v[76:79], v[160:163], v[220:223], v[76:79]
	v_mfma_f32_16x16x32_bf16 v[72:75], v[168:171], v[220:223], v[72:75]
	v_mfma_f32_16x16x32_bf16 v[116:119], v[172:175], v[190:193], v[116:119]
	v_mfma_f32_16x16x32_bf16 v[112:115], v[180:183], v[190:193], v[112:115]
	v_mfma_f32_16x16x32_bf16 v[100:103], v[172:175], v[200:203], v[100:103]
	v_mfma_f32_16x16x32_bf16 v[96:99], v[180:183], v[200:203], v[96:99]
	v_mfma_f32_16x16x32_bf16 v[84:87], v[172:175], v[208:211], v[84:87]
	v_mfma_f32_16x16x32_bf16 v[80:83], v[180:183], v[208:211], v[80:83]
	v_mfma_f32_16x16x32_bf16 v[68:71], v[172:175], v[216:219], v[68:71]
	v_mfma_f32_16x16x32_bf16 v[64:67], v[180:183], v[216:219], v[64:67]
	v_mfma_f32_16x16x32_bf16 v[116:119], v[176:179], v[194:197], v[116:119]
	v_mfma_f32_16x16x32_bf16 v[112:115], v[186:189], v[194:197], v[112:115]
	v_mfma_f32_16x16x32_bf16 v[100:103], v[176:179], v[204:207], v[100:103]
	v_mfma_f32_16x16x32_bf16 v[96:99], v[186:189], v[204:207], v[96:99]
	v_mfma_f32_16x16x32_bf16 v[84:87], v[176:179], v[212:215], v[84:87]
	v_mfma_f32_16x16x32_bf16 v[80:83], v[186:189], v[212:215], v[80:83]
	v_mfma_f32_16x16x32_bf16 v[68:71], v[176:179], v[220:223], v[68:71]
	v_mfma_f32_16x16x32_bf16 v[64:67], v[186:189], v[220:223], v[64:67]
	s_barrier
	s_mov_b32 m0, s41
	v_lshl_add_u64 v[224:225], s[50:51], 0, v[128:129]
	ds_read_b128 v[190:193], v158 offset:16384
	ds_read_b128 v[194:197], v158 offset:17408
	ds_read_b128 v[200:203], v158 offset:18432
	ds_read_b128 v[204:207], v158 offset:19456
	ds_read_b128 v[208:211], v158 offset:20480
	ds_read_b128 v[212:215], v158 offset:21504
	ds_read_b128 v[216:219], v158 offset:22528
	ds_read_b128 v[220:223], v158 offset:23552
	global_load_lds_dwordx4 v[224:225], off
	s_add_i32 m0, s41, 0x2000
	v_lshl_add_u64 v[226:227], s[50:51], 0, v[130:131]
	s_add_u32 s50, s50, s4
	s_addc_u32 s51, s51, s5
	s_add_i32 s49, s30, s22
	global_load_lds_dwordx4 v[226:227], off
	v_lshl_add_u64 v[228:229], s[50:51], 0, v[128:129]
	s_mov_b32 m0, s49
	v_lshl_add_u64 v[230:231], s[50:51], 0, v[130:131]
	global_load_lds_dwordx4 v[228:229], off
	s_add_i32 m0, s49, 0x2000
	v_lshl_add_u64 v[232:233], s[20:21], 0, v[128:129]
	global_load_lds_dwordx4 v[230:231], off
	s_mov_b32 m0, s23
	v_lshl_add_u64 v[234:235], s[20:21], 0, v[130:131]
	global_load_lds_dwordx4 v[232:233], off
	s_mov_b32 m0, s24
	s_nop 0
	global_load_lds_dwordx4 v[234:235], off
	s_waitcnt vmcnt(8)
	s_waitcnt lgkmcnt(0)
	s_barrier
	s_waitcnt lgkmcnt(0)
	v_mfma_f32_16x16x32_bf16 v[60:63], v[146:149], v[190:193], v[60:63]
	v_mfma_f32_16x16x32_bf16 v[56:59], v[164:167], v[190:193], v[56:59]
	v_mfma_f32_16x16x32_bf16 v[44:47], v[146:149], v[200:203], v[44:47]
	v_mfma_f32_16x16x32_bf16 v[40:43], v[164:167], v[200:203], v[40:43]
	v_mfma_f32_16x16x32_bf16 v[28:31], v[146:149], v[208:211], v[28:31]
	v_mfma_f32_16x16x32_bf16 v[24:27], v[164:167], v[208:211], v[24:27]
	v_mfma_f32_16x16x32_bf16 v[12:15], v[146:149], v[216:219], v[12:15]
	v_mfma_f32_16x16x32_bf16 v[8:11], v[164:167], v[216:219], v[8:11]
	v_mfma_f32_16x16x32_bf16 v[60:63], v[160:163], v[194:197], v[60:63]
	v_mfma_f32_16x16x32_bf16 v[56:59], v[168:171], v[194:197], v[56:59]
	v_mfma_f32_16x16x32_bf16 v[44:47], v[160:163], v[204:207], v[44:47]
	v_mfma_f32_16x16x32_bf16 v[40:43], v[168:171], v[204:207], v[40:43]
	v_mfma_f32_16x16x32_bf16 v[28:31], v[160:163], v[212:215], v[28:31]
	v_mfma_f32_16x16x32_bf16 v[24:27], v[168:171], v[212:215], v[24:27]
	v_mfma_f32_16x16x32_bf16 v[12:15], v[160:163], v[220:223], v[12:15]
	v_mfma_f32_16x16x32_bf16 v[8:11], v[168:171], v[220:223], v[8:11]
	v_mfma_f32_16x16x32_bf16 v[52:55], v[172:175], v[190:193], v[52:55]
	v_mfma_f32_16x16x32_bf16 v[48:51], v[180:183], v[190:193], v[48:51]
	v_mfma_f32_16x16x32_bf16 v[36:39], v[172:175], v[200:203], v[36:39]
	v_mfma_f32_16x16x32_bf16 v[32:35], v[180:183], v[200:203], v[32:35]
	v_mfma_f32_16x16x32_bf16 v[20:23], v[172:175], v[208:211], v[20:23]
	v_mfma_f32_16x16x32_bf16 v[16:19], v[180:183], v[208:211], v[16:19]
	v_mfma_f32_16x16x32_bf16 v[4:7], v[172:175], v[216:219], v[4:7]
	v_mfma_f32_16x16x32_bf16 v[0:3], v[180:183], v[216:219], v[0:3]
	v_mfma_f32_16x16x32_bf16 v[52:55], v[176:179], v[194:197], v[52:55]
	v_mfma_f32_16x16x32_bf16 v[48:51], v[186:189], v[194:197], v[48:51]
	v_mfma_f32_16x16x32_bf16 v[36:39], v[176:179], v[204:207], v[36:39]
	v_mfma_f32_16x16x32_bf16 v[32:35], v[186:189], v[204:207], v[32:35]
	v_mfma_f32_16x16x32_bf16 v[20:23], v[176:179], v[212:215], v[20:23]
	v_mfma_f32_16x16x32_bf16 v[16:19], v[186:189], v[212:215], v[16:19]
	v_mfma_f32_16x16x32_bf16 v[4:7], v[176:179], v[220:223], v[4:7]
	v_mfma_f32_16x16x32_bf16 v[0:3], v[186:189], v[220:223], v[0:3]
	s_barrier
	s_add_i32 s49, 0, 0x18000
	v_add_u32_e32 v132, s49, v151
	s_add_i32 s50, 0, 0x1c000
	ds_read_b128 v[146:149], v132
	ds_read_b128 v[160:163], v132 offset:1024
	ds_read_b128 v[164:167], v132 offset:2048
	ds_read_b128 v[168:171], v132 offset:3072
	v_add_u32_e32 v132, s50, v151
	ds_read_b128 v[172:175], v132
	ds_read_b128 v[176:179], v132 offset:1024
	ds_read_b128 v[180:183], v132 offset:2048
	ds_read_b128 v[186:189], v132 offset:3072
	s_add_u32 s20, s20, s4
	s_addc_u32 s21, s21, s5
	s_mov_b32 m0, s25
	v_lshl_add_u64 v[236:237], s[20:21], 0, v[128:129]
	ds_read_b128 v[190:193], v158 offset:32768
	ds_read_b128 v[194:197], v158 offset:33792
	ds_read_b128 v[200:203], v158 offset:34816
	ds_read_b128 v[204:207], v158 offset:35840
	ds_read_b128 v[208:211], v158 offset:36864
	ds_read_b128 v[212:215], v158 offset:37888
	ds_read_b128 v[216:219], v158 offset:38912
	ds_read_b128 v[220:223], v158 offset:39936
	global_load_lds_dwordx4 v[236:237], off
	v_lshl_add_u64 v[236:237], s[20:21], 0, v[130:131]
	s_mov_b32 m0, s26
	s_nop 0
	global_load_lds_dwordx4 v[236:237], off
	s_waitcnt vmcnt(8)
	s_waitcnt lgkmcnt(0)
	s_barrier
	s_waitcnt lgkmcnt(0)
	v_mfma_f32_16x16x32_bf16 v[124:127], v[146:149], v[190:193], v[124:127]
	v_mfma_f32_16x16x32_bf16 v[120:123], v[164:167], v[190:193], v[120:123]
	v_mfma_f32_16x16x32_bf16 v[108:111], v[146:149], v[200:203], v[108:111]
	v_mfma_f32_16x16x32_bf16 v[104:107], v[164:167], v[200:203], v[104:107]
	v_mfma_f32_16x16x32_bf16 v[92:95], v[146:149], v[208:211], v[92:95]
	v_mfma_f32_16x16x32_bf16 v[88:91], v[164:167], v[208:211], v[88:91]
	v_mfma_f32_16x16x32_bf16 v[76:79], v[146:149], v[216:219], v[76:79]
	v_mfma_f32_16x16x32_bf16 v[72:75], v[164:167], v[216:219], v[72:75]
	v_mfma_f32_16x16x32_bf16 v[124:127], v[160:163], v[194:197], v[124:127]
	v_mfma_f32_16x16x32_bf16 v[120:123], v[168:171], v[194:197], v[120:123]
	v_mfma_f32_16x16x32_bf16 v[108:111], v[160:163], v[204:207], v[108:111]
	v_mfma_f32_16x16x32_bf16 v[104:107], v[168:171], v[204:207], v[104:107]
	v_mfma_f32_16x16x32_bf16 v[92:95], v[160:163], v[212:215], v[92:95]
	v_mfma_f32_16x16x32_bf16 v[88:91], v[168:171], v[212:215], v[88:91]
	v_mfma_f32_16x16x32_bf16 v[76:79], v[160:163], v[220:223], v[76:79]
	v_mfma_f32_16x16x32_bf16 v[72:75], v[168:171], v[220:223], v[72:75]
	v_mfma_f32_16x16x32_bf16 v[116:119], v[172:175], v[190:193], v[116:119]
	v_mfma_f32_16x16x32_bf16 v[112:115], v[180:183], v[190:193], v[112:115]
	v_mfma_f32_16x16x32_bf16 v[100:103], v[172:175], v[200:203], v[100:103]
	v_mfma_f32_16x16x32_bf16 v[96:99], v[180:183], v[200:203], v[96:99]
	v_mfma_f32_16x16x32_bf16 v[84:87], v[172:175], v[208:211], v[84:87]
	v_mfma_f32_16x16x32_bf16 v[80:83], v[180:183], v[208:211], v[80:83]
	v_mfma_f32_16x16x32_bf16 v[68:71], v[172:175], v[216:219], v[68:71]
	v_mfma_f32_16x16x32_bf16 v[64:67], v[180:183], v[216:219], v[64:67]
	v_mfma_f32_16x16x32_bf16 v[116:119], v[176:179], v[194:197], v[116:119]
	v_mfma_f32_16x16x32_bf16 v[112:115], v[186:189], v[194:197], v[112:115]
	v_mfma_f32_16x16x32_bf16 v[100:103], v[176:179], v[204:207], v[100:103]
	v_mfma_f32_16x16x32_bf16 v[96:99], v[186:189], v[204:207], v[96:99]
	v_mfma_f32_16x16x32_bf16 v[84:87], v[176:179], v[212:215], v[84:87]
	v_mfma_f32_16x16x32_bf16 v[80:83], v[186:189], v[212:215], v[80:83]
	v_mfma_f32_16x16x32_bf16 v[68:71], v[176:179], v[220:223], v[68:71]
	v_mfma_f32_16x16x32_bf16 v[64:67], v[186:189], v[220:223], v[64:67]
	s_barrier
	s_add_i32 s20, s49, s22
	v_lshl_add_u64 v[224:225], v[224:225], 0, s[10:11]
	s_mov_b32 m0, s20
	ds_read_b128 v[190:193], v158 offset:49152
	ds_read_b128 v[194:197], v158 offset:50176
	ds_read_b128 v[200:203], v158 offset:51200
	ds_read_b128 v[204:207], v158 offset:52224
	ds_read_b128 v[208:211], v158 offset:53248
	ds_read_b128 v[212:215], v158 offset:54272
	ds_read_b128 v[216:219], v158 offset:55296
	ds_read_b128 v[220:223], v158 offset:56320
	global_load_lds_dwordx4 v[224:225], off
	v_lshl_add_u64 v[224:225], v[226:227], 0, s[10:11]
	s_add_i32 m0, s20, 0x2000
	s_add_i32 s20, s50, s22
	global_load_lds_dwordx4 v[224:225], off
	v_lshl_add_u64 v[224:225], v[228:229], 0, s[10:11]
	s_mov_b32 m0, s20
	s_nop 0
	global_load_lds_dwordx4 v[224:225], off
	v_lshl_add_u64 v[224:225], v[230:231], 0, s[10:11]
	s_add_i32 m0, s20, 0x2000
	s_nop 0
	global_load_lds_dwordx4 v[224:225], off
	v_lshl_add_u64 v[224:225], v[232:233], 0, s[10:11]
	s_mov_b32 m0, s28
	s_nop 0
	global_load_lds_dwordx4 v[224:225], off
	v_lshl_add_u64 v[224:225], v[234:235], 0, s[10:11]
	s_mov_b32 m0, s29
	s_nop 0
	global_load_lds_dwordx4 v[224:225], off
	s_waitcnt vmcnt(8)
	s_waitcnt lgkmcnt(0)
	s_barrier
	s_waitcnt lgkmcnt(0)
	v_mfma_f32_16x16x32_bf16 v[60:63], v[146:149], v[190:193], v[60:63]
	v_mfma_f32_16x16x32_bf16 v[56:59], v[164:167], v[190:193], v[56:59]
	v_mfma_f32_16x16x32_bf16 v[44:47], v[146:149], v[200:203], v[44:47]
	v_mfma_f32_16x16x32_bf16 v[40:43], v[164:167], v[200:203], v[40:43]
	v_mfma_f32_16x16x32_bf16 v[28:31], v[146:149], v[208:211], v[28:31]
	v_mfma_f32_16x16x32_bf16 v[24:27], v[164:167], v[208:211], v[24:27]
	v_mfma_f32_16x16x32_bf16 v[12:15], v[146:149], v[216:219], v[12:15]
	v_mfma_f32_16x16x32_bf16 v[8:11], v[164:167], v[216:219], v[8:11]
	v_mfma_f32_16x16x32_bf16 v[60:63], v[160:163], v[194:197], v[60:63]
	v_mfma_f32_16x16x32_bf16 v[56:59], v[168:171], v[194:197], v[56:59]
	v_mfma_f32_16x16x32_bf16 v[44:47], v[160:163], v[204:207], v[44:47]
	v_mfma_f32_16x16x32_bf16 v[40:43], v[168:171], v[204:207], v[40:43]
	v_mfma_f32_16x16x32_bf16 v[28:31], v[160:163], v[212:215], v[28:31]
	v_mfma_f32_16x16x32_bf16 v[24:27], v[168:171], v[212:215], v[24:27]
	v_mfma_f32_16x16x32_bf16 v[12:15], v[160:163], v[220:223], v[12:15]
	v_mfma_f32_16x16x32_bf16 v[8:11], v[168:171], v[220:223], v[8:11]
	v_mfma_f32_16x16x32_bf16 v[52:55], v[172:175], v[190:193], v[52:55]
	v_mfma_f32_16x16x32_bf16 v[48:51], v[180:183], v[190:193], v[48:51]
	v_mfma_f32_16x16x32_bf16 v[36:39], v[172:175], v[200:203], v[36:39]
	v_mfma_f32_16x16x32_bf16 v[32:35], v[180:183], v[200:203], v[32:35]
	v_mfma_f32_16x16x32_bf16 v[20:23], v[172:175], v[208:211], v[20:23]
	v_mfma_f32_16x16x32_bf16 v[16:19], v[180:183], v[208:211], v[16:19]
	v_mfma_f32_16x16x32_bf16 v[4:7], v[172:175], v[216:219], v[4:7]
	v_mfma_f32_16x16x32_bf16 v[0:3], v[180:183], v[216:219], v[0:3]
	v_mfma_f32_16x16x32_bf16 v[52:55], v[176:179], v[194:197], v[52:55]
	v_mfma_f32_16x16x32_bf16 v[48:51], v[186:189], v[194:197], v[48:51]
	v_mfma_f32_16x16x32_bf16 v[36:39], v[176:179], v[204:207], v[36:39]
	v_mfma_f32_16x16x32_bf16 v[32:35], v[186:189], v[204:207], v[32:35]
	v_mfma_f32_16x16x32_bf16 v[20:23], v[176:179], v[212:215], v[20:23]
	v_mfma_f32_16x16x32_bf16 v[16:19], v[186:189], v[212:215], v[16:19]
	v_mfma_f32_16x16x32_bf16 v[4:7], v[176:179], v[220:223], v[4:7]
	v_mfma_f32_16x16x32_bf16 v[0:3], v[186:189], v[220:223], v[0:3]
	s_barrier
	s_add_i32 s48, s48, 2
	s_add_u32 s18, s18, 0x100
	s_addc_u32 s19, s19, 0
	s_cmp_gt_u32 s48, 29
	s_cbranch_scc0 .LBB0_1611
	s_and_b64 vcc, exec, s[12:13]
	s_cbranch_vccz .LBB0_1614
	s_barrier

.LBB0_1654:
	ds_read_b128 v[18:21], v13
	ds_read_b128 v[22:25], v13 offset:1024
	ds_read_b128 v[26:29], v13 offset:2048
	ds_read_b128 v[30:33], v13 offset:3072
	s_add_u32 s56, s22, s2
	s_addc_u32 s57, s23, s3
	v_lshl_add_u64 v[4:5], s[56:57], 0, v[2:3]
	s_mov_b32 m0, s41
	v_lshl_add_u64 v[6:7], v[4:5], 0, s[6:7]
	ds_read_b128 v[34:37], v14
	ds_read_b128 v[38:41], v14 offset:1024
	ds_read_b128 v[42:45], v14 offset:2048
	ds_read_b128 v[46:49], v14 offset:3072
	ds_read_b128 v[50:53], v14 offset:4096
	ds_read_b128 v[54:57], v14 offset:5120
	ds_read_b128 v[58:61], v14 offset:6144
	ds_read_b128 v[62:65], v14 offset:7168
	global_load_lds_dwordx4 v[6:7], off
	v_lshl_add_u64 v[6:7], s[56:57], 0, v[0:1]
	v_lshl_add_u64 v[66:67], v[6:7], 0, s[6:7]
	s_mov_b32 m0, s42
	s_nop 0
	global_load_lds_dwordx4 v[66:67], off
	s_waitcnt lgkmcnt(8)
	s_barrier
	s_waitcnt lgkmcnt(0)
	s_waitcnt lgkmcnt(0)
	v_mfma_f32_16x16x32_bf16 v[66:69], v[18:21], v[34:37], 0
	v_mfma_f32_16x16x32_bf16 v[70:73], v[26:29], v[34:37], 0
	v_mfma_f32_16x16x32_bf16 v[74:77], v[18:21], v[42:45], 0
	v_mfma_f32_16x16x32_bf16 v[78:81], v[26:29], v[42:45], 0
	v_mfma_f32_16x16x32_bf16 v[82:85], v[18:21], v[50:53], 0
	v_mfma_f32_16x16x32_bf16 v[86:89], v[26:29], v[50:53], 0
	v_mfma_f32_16x16x32_bf16 v[90:93], v[18:21], v[58:61], 0
	v_mfma_f32_16x16x32_bf16 v[94:97], v[26:29], v[58:61], 0
	v_mfma_f32_16x16x32_bf16 v[66:69], v[22:25], v[38:41], v[66:69]
	v_mfma_f32_16x16x32_bf16 v[70:73], v[30:33], v[38:41], v[70:73]
	v_mfma_f32_16x16x32_bf16 v[74:77], v[22:25], v[46:49], v[74:77]
	v_mfma_f32_16x16x32_bf16 v[78:81], v[30:33], v[46:49], v[78:81]
	v_mfma_f32_16x16x32_bf16 v[82:85], v[22:25], v[54:57], v[82:85]
	v_mfma_f32_16x16x32_bf16 v[86:89], v[30:33], v[54:57], v[86:89]
	v_mfma_f32_16x16x32_bf16 v[90:93], v[22:25], v[62:65], v[90:93]
	v_mfma_f32_16x16x32_bf16 v[94:97], v[30:33], v[62:65], v[94:97]
	s_barrier
	v_lshl_add_u64 v[182:183], s[20:21], 0, v[2:3]
	s_mov_b32 m0, s43
	v_lshl_add_u64 v[114:115], v[182:183], 0, s[10:11]
	v_lshl_add_u64 v[216:217], s[20:21], 0, v[0:1]
	ds_read_b128 v[98:101], v15
	ds_read_b128 v[102:105], v15 offset:1024
	ds_read_b128 v[106:109], v15 offset:2048
	ds_read_b128 v[110:113], v15 offset:3072
	global_load_lds_dwordx4 v[114:115], off
	v_lshl_add_u64 v[114:115], v[216:217], 0, s[10:11]
	s_mov_b32 m0, s44
	s_nop 0
	global_load_lds_dwordx4 v[114:115], off
	s_barrier
	s_waitcnt lgkmcnt(0)
	s_waitcnt lgkmcnt(0)
	v_mfma_f32_16x16x32_bf16 v[114:117], v[98:101], v[34:37], 0
	v_mfma_f32_16x16x32_bf16 v[34:37], v[106:109], v[34:37], 0
	v_mfma_f32_16x16x32_bf16 v[114:117], v[102:105], v[38:41], v[114:117]
	v_mfma_f32_16x16x32_bf16 v[34:37], v[110:113], v[38:41], v[34:37]
	v_mfma_f32_16x16x32_bf16 v[38:41], v[98:101], v[42:45], 0
	v_mfma_f32_16x16x32_bf16 v[42:45], v[106:109], v[42:45], 0
	v_mfma_f32_16x16x32_bf16 v[38:41], v[102:105], v[46:49], v[38:41]
	v_mfma_f32_16x16x32_bf16 v[42:45], v[110:113], v[46:49], v[42:45]
	v_mfma_f32_16x16x32_bf16 v[46:49], v[98:101], v[50:53], 0
	v_mfma_f32_16x16x32_bf16 v[50:53], v[106:109], v[50:53], 0
	v_mfma_f32_16x16x32_bf16 v[46:49], v[102:105], v[54:57], v[46:49]
	v_mfma_f32_16x16x32_bf16 v[50:53], v[110:113], v[54:57], v[50:53]
	v_mfma_f32_16x16x32_bf16 v[54:57], v[98:101], v[58:61], 0
	v_mfma_f32_16x16x32_bf16 v[58:61], v[106:109], v[58:61], 0
	v_mfma_f32_16x16x32_bf16 v[54:57], v[102:105], v[62:65], v[54:57]
	v_mfma_f32_16x16x32_bf16 v[58:61], v[110:113], v[62:65], v[58:61]
	v_lshl_add_u64 v[218:219], s[22:23], 0, v[2:3]
	s_mov_b32 m0, s9
	v_lshl_add_u64 v[146:147], v[218:219], 0, s[10:11]
	v_lshl_add_u64 v[220:221], s[22:23], 0, v[0:1]
	s_barrier
	ds_read_b128 v[62:65], v14 offset:16384
	ds_read_b128 v[118:121], v14 offset:17408
	ds_read_b128 v[122:125], v14 offset:18432
	ds_read_b128 v[126:129], v14 offset:19456
	ds_read_b128 v[130:133], v14 offset:20480
	ds_read_b128 v[134:137], v14 offset:21504
	ds_read_b128 v[138:141], v14 offset:22528
	ds_read_b128 v[142:145], v14 offset:23552
	global_load_lds_dwordx4 v[146:147], off
	v_lshl_add_u64 v[146:147], v[220:221], 0, s[10:11]
	s_mov_b32 m0, s27
	s_nop 0
	global_load_lds_dwordx4 v[146:147], off
	s_barrier
	s_waitcnt lgkmcnt(0)
	s_waitcnt lgkmcnt(0)
	v_mfma_f32_16x16x32_bf16 v[146:149], v[18:21], v[62:65], 0
	v_mfma_f32_16x16x32_bf16 v[154:157], v[18:21], v[122:125], 0
	v_mfma_f32_16x16x32_bf16 v[162:165], v[18:21], v[130:133], 0
	v_mfma_f32_16x16x32_bf16 v[18:21], v[18:21], v[138:141], 0
	v_mfma_f32_16x16x32_bf16 v[146:149], v[22:25], v[118:121], v[146:149]
	v_mfma_f32_16x16x32_bf16 v[150:153], v[26:29], v[62:65], 0
	v_mfma_f32_16x16x32_bf16 v[154:157], v[22:25], v[126:129], v[154:157]
	v_mfma_f32_16x16x32_bf16 v[158:161], v[26:29], v[122:125], 0
	v_mfma_f32_16x16x32_bf16 v[162:165], v[22:25], v[134:137], v[162:165]
	v_mfma_f32_16x16x32_bf16 v[166:169], v[26:29], v[130:133], 0
	v_mfma_f32_16x16x32_bf16 v[18:21], v[22:25], v[142:145], v[18:21]
	v_mfma_f32_16x16x32_bf16 v[22:25], v[26:29], v[138:141], 0
	v_mfma_f32_16x16x32_bf16 v[150:153], v[30:33], v[118:121], v[150:153]
	v_mfma_f32_16x16x32_bf16 v[158:161], v[30:33], v[126:129], v[158:161]
	v_mfma_f32_16x16x32_bf16 v[166:169], v[30:33], v[134:137], v[166:169]
	v_mfma_f32_16x16x32_bf16 v[22:25], v[30:33], v[142:145], v[22:25]
	s_barrier
	s_add_u32 s20, s20, s2
	s_addc_u32 s21, s21, s3
	v_lshl_add_u64 v[222:223], s[20:21], 0, v[2:3]
	s_mov_b32 m0, s45
	v_lshl_add_u64 v[26:27], v[222:223], 0, s[10:11]
	v_lshl_add_u64 v[224:225], s[20:21], 0, v[0:1]
	global_load_lds_dwordx4 v[26:27], off
	v_lshl_add_u64 v[26:27], v[224:225], 0, s[10:11]
	s_mov_b32 m0, s46
	s_nop 0
	global_load_lds_dwordx4 v[26:27], off
	s_waitcnt vmcnt(6)
	s_barrier
	v_mfma_f32_16x16x32_bf16 v[26:29], v[98:101], v[62:65], 0
	v_mfma_f32_16x16x32_bf16 v[30:33], v[106:109], v[62:65], 0
	v_mfma_f32_16x16x32_bf16 v[26:29], v[102:105], v[118:121], v[26:29]
	v_mfma_f32_16x16x32_bf16 v[30:33], v[110:113], v[118:121], v[30:33]
	v_mfma_f32_16x16x32_bf16 v[62:65], v[98:101], v[122:125], 0
	v_mfma_f32_16x16x32_bf16 v[118:121], v[106:109], v[122:125], 0
	v_mfma_f32_16x16x32_bf16 v[122:125], v[98:101], v[130:133], 0
	v_mfma_f32_16x16x32_bf16 v[98:101], v[98:101], v[138:141], 0
	v_mfma_f32_16x16x32_bf16 v[62:65], v[102:105], v[126:129], v[62:65]
	v_mfma_f32_16x16x32_bf16 v[118:121], v[110:113], v[126:129], v[118:121]
	v_mfma_f32_16x16x32_bf16 v[122:125], v[102:105], v[134:137], v[122:125]
	v_mfma_f32_16x16x32_bf16 v[126:129], v[106:109], v[130:133], 0
	v_mfma_f32_16x16x32_bf16 v[98:101], v[102:105], v[142:145], v[98:101]
	v_mfma_f32_16x16x32_bf16 v[102:105], v[106:109], v[138:141], 0
	v_mfma_f32_16x16x32_bf16 v[126:129], v[110:113], v[134:137], v[126:129]
	v_mfma_f32_16x16x32_bf16 v[102:105], v[110:113], v[142:145], v[102:105]
	s_barrier
	ds_read_b128 v[106:109], v16
	ds_read_b128 v[110:113], v16 offset:1024
	ds_read_b128 v[130:133], v16 offset:2048
	ds_read_b128 v[134:137], v16 offset:3072
	s_mov_b32 m0, s28
	v_lshl_add_u64 v[200:201], v[4:5], 0, s[10:11]
	ds_read_b128 v[138:141], v14 offset:32768
	ds_read_b128 v[142:145], v14 offset:33792
	ds_read_b128 v[170:173], v14 offset:34816
	ds_read_b128 v[174:177], v14 offset:35840
	ds_read_b128 v[178:181], v14 offset:36864
	ds_read_b128 v[186:189], v14 offset:37888
	ds_read_b128 v[190:193], v14 offset:38912
	ds_read_b128 v[194:197], v14 offset:39936
	global_load_lds_dwordx4 v[200:201], off
	v_lshl_add_u64 v[200:201], v[6:7], 0, s[10:11]
	s_mov_b32 m0, s29
	s_nop 0
	global_load_lds_dwordx4 v[200:201], off
	s_waitcnt lgkmcnt(8)
	s_barrier
	s_waitcnt lgkmcnt(0)
	s_waitcnt lgkmcnt(0)
	v_mfma_f32_16x16x32_bf16 v[66:69], v[106:109], v[138:141], v[66:69]
	v_mfma_f32_16x16x32_bf16 v[70:73], v[130:133], v[138:141], v[70:73]
	v_mfma_f32_16x16x32_bf16 v[74:77], v[106:109], v[170:173], v[74:77]
	v_mfma_f32_16x16x32_bf16 v[78:81], v[130:133], v[170:173], v[78:81]
	v_mfma_f32_16x16x32_bf16 v[82:85], v[106:109], v[178:181], v[82:85]
	v_mfma_f32_16x16x32_bf16 v[86:89], v[130:133], v[178:181], v[86:89]
	v_mfma_f32_16x16x32_bf16 v[90:93], v[106:109], v[190:193], v[90:93]
	v_mfma_f32_16x16x32_bf16 v[94:97], v[130:133], v[190:193], v[94:97]
	v_mfma_f32_16x16x32_bf16 v[66:69], v[110:113], v[142:145], v[66:69]
	v_mfma_f32_16x16x32_bf16 v[70:73], v[134:137], v[142:145], v[70:73]
	v_mfma_f32_16x16x32_bf16 v[74:77], v[110:113], v[174:177], v[74:77]
	v_mfma_f32_16x16x32_bf16 v[78:81], v[134:137], v[174:177], v[78:81]
	v_mfma_f32_16x16x32_bf16 v[82:85], v[110:113], v[186:189], v[82:85]
	v_mfma_f32_16x16x32_bf16 v[86:89], v[134:137], v[186:189], v[86:89]
	v_mfma_f32_16x16x32_bf16 v[90:93], v[110:113], v[194:197], v[90:93]
	v_mfma_f32_16x16x32_bf16 v[94:97], v[134:137], v[194:197], v[94:97]
	s_barrier
	s_mov_b32 m0, s47
	v_lshl_add_u64 v[182:183], v[182:183], 0, s[12:13]
	ds_read_b128 v[200:203], v17
	ds_read_b128 v[204:207], v17 offset:1024
	ds_read_b128 v[208:211], v17 offset:2048
	ds_read_b128 v[212:215], v17 offset:3072
	global_load_lds_dwordx4 v[182:183], off
	v_lshl_add_u64 v[182:183], v[216:217], 0, s[12:13]
	s_mov_b32 m0, s48
	s_nop 0
	global_load_lds_dwordx4 v[182:183], off
	s_barrier
	s_waitcnt lgkmcnt(0)
	s_waitcnt lgkmcnt(0)
	v_mfma_f32_16x16x32_bf16 v[114:117], v[200:203], v[138:141], v[114:117]
	v_mfma_f32_16x16x32_bf16 v[34:37], v[208:211], v[138:141], v[34:37]
	v_mfma_f32_16x16x32_bf16 v[38:41], v[200:203], v[170:173], v[38:41]
	v_mfma_f32_16x16x32_bf16 v[42:45], v[208:211], v[170:173], v[42:45]
	v_mfma_f32_16x16x32_bf16 v[46:49], v[200:203], v[178:181], v[46:49]
	v_mfma_f32_16x16x32_bf16 v[50:53], v[208:211], v[178:181], v[50:53]
	v_mfma_f32_16x16x32_bf16 v[54:57], v[200:203], v[190:193], v[54:57]
	v_mfma_f32_16x16x32_bf16 v[58:61], v[208:211], v[190:193], v[58:61]
	v_mfma_f32_16x16x32_bf16 v[114:117], v[204:207], v[142:145], v[114:117]
	v_mfma_f32_16x16x32_bf16 v[34:37], v[212:215], v[142:145], v[34:37]
	v_mfma_f32_16x16x32_bf16 v[38:41], v[204:207], v[174:177], v[38:41]
	v_mfma_f32_16x16x32_bf16 v[42:45], v[212:215], v[174:177], v[42:45]
	v_mfma_f32_16x16x32_bf16 v[46:49], v[204:207], v[186:189], v[46:49]
	v_mfma_f32_16x16x32_bf16 v[50:53], v[212:215], v[186:189], v[50:53]
	v_mfma_f32_16x16x32_bf16 v[54:57], v[204:207], v[194:197], v[54:57]
	v_mfma_f32_16x16x32_bf16 v[58:61], v[212:215], v[194:197], v[58:61]
	s_mov_b32 m0, s30
	v_lshl_add_u64 v[182:183], v[218:219], 0, s[12:13]
	s_barrier
	ds_read_b128 v[138:141], v14 offset:49152
	ds_read_b128 v[142:145], v14 offset:50176
	ds_read_b128 v[170:173], v14 offset:51200
	ds_read_b128 v[174:177], v14 offset:52224
	ds_read_b128 v[178:181], v14 offset:53248
	ds_read_b128 v[186:189], v14 offset:54272
	ds_read_b128 v[190:193], v14 offset:55296
	ds_read_b128 v[194:197], v14 offset:56320
	global_load_lds_dwordx4 v[182:183], off
	v_lshl_add_u64 v[182:183], v[220:221], 0, s[12:13]
	s_mov_b32 m0, s31
	s_nop 0
	global_load_lds_dwordx4 v[182:183], off
	s_barrier
	s_waitcnt lgkmcnt(0)
	s_waitcnt lgkmcnt(0)
	v_mfma_f32_16x16x32_bf16 v[146:149], v[106:109], v[138:141], v[146:149]
	v_mfma_f32_16x16x32_bf16 v[150:153], v[130:133], v[138:141], v[150:153]
	v_mfma_f32_16x16x32_bf16 v[154:157], v[106:109], v[170:173], v[154:157]
	v_mfma_f32_16x16x32_bf16 v[158:161], v[130:133], v[170:173], v[158:161]
	v_mfma_f32_16x16x32_bf16 v[162:165], v[106:109], v[178:181], v[162:165]
	v_mfma_f32_16x16x32_bf16 v[166:169], v[130:133], v[178:181], v[166:169]
	v_mfma_f32_16x16x32_bf16 v[18:21], v[106:109], v[190:193], v[18:21]
	v_mfma_f32_16x16x32_bf16 v[22:25], v[130:133], v[190:193], v[22:25]
	v_mfma_f32_16x16x32_bf16 v[146:149], v[110:113], v[142:145], v[146:149]
	v_mfma_f32_16x16x32_bf16 v[150:153], v[134:137], v[142:145], v[150:153]
	v_mfma_f32_16x16x32_bf16 v[154:157], v[110:113], v[174:177], v[154:157]
	v_mfma_f32_16x16x32_bf16 v[158:161], v[134:137], v[174:177], v[158:161]
	v_mfma_f32_16x16x32_bf16 v[162:165], v[110:113], v[186:189], v[162:165]
	v_mfma_f32_16x16x32_bf16 v[166:169], v[134:137], v[186:189], v[166:169]
	v_mfma_f32_16x16x32_bf16 v[18:21], v[110:113], v[194:197], v[18:21]
	v_mfma_f32_16x16x32_bf16 v[22:25], v[134:137], v[194:197], v[22:25]
	s_barrier
	s_mov_b32 m0, s49
	v_lshl_add_u64 v[106:107], v[222:223], 0, s[12:13]
	global_load_lds_dwordx4 v[106:107], off
	v_lshl_add_u64 v[106:107], v[224:225], 0, s[12:13]
	s_mov_b32 m0, s50
	s_nop 0
	global_load_lds_dwordx4 v[106:107], off
	s_waitcnt vmcnt(6)
	s_barrier
	v_mfma_f32_16x16x32_bf16 v[26:29], v[200:203], v[138:141], v[26:29]
	v_mfma_f32_16x16x32_bf16 v[30:33], v[208:211], v[138:141], v[30:33]
	v_mfma_f32_16x16x32_bf16 v[62:65], v[200:203], v[170:173], v[62:65]
	v_mfma_f32_16x16x32_bf16 v[106:109], v[208:211], v[170:173], v[118:121]
	v_mfma_f32_16x16x32_bf16 v[110:113], v[200:203], v[178:181], v[122:125]
	v_mfma_f32_16x16x32_bf16 v[118:121], v[208:211], v[178:181], v[126:129]
	v_mfma_f32_16x16x32_bf16 v[98:101], v[200:203], v[190:193], v[98:101]
	v_mfma_f32_16x16x32_bf16 v[102:105], v[208:211], v[190:193], v[102:105]
	v_mfma_f32_16x16x32_bf16 v[26:29], v[204:207], v[142:145], v[26:29]
	v_mfma_f32_16x16x32_bf16 v[30:33], v[212:215], v[142:145], v[30:33]
	v_mfma_f32_16x16x32_bf16 v[62:65], v[204:207], v[174:177], v[62:65]
	v_mfma_f32_16x16x32_bf16 v[106:109], v[212:215], v[174:177], v[106:109]
	v_mfma_f32_16x16x32_bf16 v[110:113], v[204:207], v[186:189], v[110:113]
	v_mfma_f32_16x16x32_bf16 v[118:121], v[212:215], v[186:189], v[118:121]
	v_mfma_f32_16x16x32_bf16 v[98:101], v[204:207], v[194:197], v[98:101]
	v_mfma_f32_16x16x32_bf16 v[102:105], v[212:215], v[194:197], v[102:105]
	s_barrier
	ds_read_b128 v[122:125], v13
	ds_read_b128 v[126:129], v13 offset:1024
	ds_read_b128 v[130:133], v13 offset:2048
	ds_read_b128 v[134:137], v13 offset:3072
	s_mov_b32 m0, s41
	v_lshl_add_u64 v[4:5], v[4:5], 0, s[12:13]
	ds_read_b128 v[138:141], v14
	ds_read_b128 v[142:145], v14 offset:1024
	ds_read_b128 v[170:173], v14 offset:2048
	ds_read_b128 v[174:177], v14 offset:3072
	ds_read_b128 v[178:181], v14 offset:4096
	ds_read_b128 v[186:189], v14 offset:5120
	ds_read_b128 v[190:193], v14 offset:6144
	ds_read_b128 v[194:197], v14 offset:7168
	global_load_lds_dwordx4 v[4:5], off
	v_lshl_add_u64 v[4:5], v[6:7], 0, s[12:13]
	s_mov_b32 m0, s42
	s_nop 0
	global_load_lds_dwordx4 v[4:5], off
	s_waitcnt lgkmcnt(8)
	s_barrier
	s_waitcnt lgkmcnt(0)
	s_waitcnt lgkmcnt(0)
	v_mfma_f32_16x16x32_bf16 v[4:7], v[122:125], v[138:141], v[66:69]
	v_mfma_f32_16x16x32_bf16 v[66:69], v[130:133], v[138:141], v[70:73]
	v_mfma_f32_16x16x32_bf16 v[70:73], v[122:125], v[170:173], v[74:77]
	v_mfma_f32_16x16x32_bf16 v[74:77], v[130:133], v[170:173], v[78:81]
	v_mfma_f32_16x16x32_bf16 v[78:81], v[122:125], v[178:181], v[82:85]
	v_mfma_f32_16x16x32_bf16 v[82:85], v[130:133], v[178:181], v[86:89]
	v_mfma_f32_16x16x32_bf16 v[86:89], v[122:125], v[190:193], v[90:93]
	v_mfma_f32_16x16x32_bf16 v[90:93], v[130:133], v[190:193], v[94:97]
	v_mfma_f32_16x16x32_bf16 v[4:7], v[126:129], v[142:145], v[4:7]
	v_mfma_f32_16x16x32_bf16 v[66:69], v[134:137], v[142:145], v[66:69]
	v_mfma_f32_16x16x32_bf16 v[70:73], v[126:129], v[174:177], v[70:73]
	v_mfma_f32_16x16x32_bf16 v[74:77], v[134:137], v[174:177], v[74:77]
	v_mfma_f32_16x16x32_bf16 v[78:81], v[126:129], v[186:189], v[78:81]
	v_mfma_f32_16x16x32_bf16 v[82:85], v[134:137], v[186:189], v[82:85]
	v_mfma_f32_16x16x32_bf16 v[86:89], v[126:129], v[194:197], v[86:89]
	v_mfma_f32_16x16x32_bf16 v[90:93], v[134:137], v[194:197], v[90:93]
	s_barrier
	s_mov_b32 m0, s43
	v_lshl_add_u64 v[182:183], s[0:1], 0, v[2:3]
	ds_read_b128 v[94:97], v15
	ds_read_b128 v[200:203], v15 offset:1024
	ds_read_b128 v[204:207], v15 offset:2048
	ds_read_b128 v[208:211], v15 offset:3072
	global_load_lds_dwordx4 v[182:183], off
	v_lshl_add_u64 v[212:213], s[0:1], 0, v[0:1]
	s_mov_b32 m0, s44
	s_nop 0
	global_load_lds_dwordx4 v[212:213], off
	s_barrier
	s_waitcnt lgkmcnt(0)
	s_waitcnt lgkmcnt(0)
	v_mfma_f32_16x16x32_bf16 v[114:117], v[94:97], v[138:141], v[114:117]
	v_mfma_f32_16x16x32_bf16 v[34:37], v[204:207], v[138:141], v[34:37]
	v_mfma_f32_16x16x32_bf16 v[38:41], v[94:97], v[170:173], v[38:41]
	v_mfma_f32_16x16x32_bf16 v[42:45], v[204:207], v[170:173], v[42:45]
	v_mfma_f32_16x16x32_bf16 v[46:49], v[94:97], v[178:181], v[46:49]
	v_mfma_f32_16x16x32_bf16 v[50:53], v[204:207], v[178:181], v[50:53]
	v_mfma_f32_16x16x32_bf16 v[54:57], v[94:97], v[190:193], v[54:57]
	v_mfma_f32_16x16x32_bf16 v[58:61], v[204:207], v[190:193], v[58:61]
	v_mfma_f32_16x16x32_bf16 v[114:117], v[200:203], v[142:145], v[114:117]
	v_mfma_f32_16x16x32_bf16 v[34:37], v[208:211], v[142:145], v[34:37]
	v_mfma_f32_16x16x32_bf16 v[38:41], v[200:203], v[174:177], v[38:41]
	v_mfma_f32_16x16x32_bf16 v[42:45], v[208:211], v[174:177], v[42:45]
	v_mfma_f32_16x16x32_bf16 v[46:49], v[200:203], v[186:189], v[46:49]
	v_mfma_f32_16x16x32_bf16 v[50:53], v[208:211], v[186:189], v[50:53]
	v_mfma_f32_16x16x32_bf16 v[54:57], v[200:203], v[194:197], v[54:57]
	v_mfma_f32_16x16x32_bf16 v[58:61], v[208:211], v[194:197], v[58:61]
	s_mov_b32 m0, s9
	v_lshl_add_u64 v[214:215], s[18:19], 0, v[2:3]
	s_barrier
	ds_read_b128 v[138:141], v14 offset:16384
	ds_read_b128 v[142:145], v14 offset:17408
	ds_read_b128 v[170:173], v14 offset:18432
	ds_read_b128 v[174:177], v14 offset:19456
	ds_read_b128 v[178:181], v14 offset:20480
	ds_read_b128 v[186:189], v14 offset:21504
	ds_read_b128 v[190:193], v14 offset:22528
	ds_read_b128 v[194:197], v14 offset:23552
	global_load_lds_dwordx4 v[214:215], off
	v_lshl_add_u64 v[216:217], s[18:19], 0, v[0:1]
	s_mov_b32 m0, s27
	s_nop 0
	global_load_lds_dwordx4 v[216:217], off
	s_barrier
	s_waitcnt lgkmcnt(0)
	s_waitcnt lgkmcnt(0)
	v_mfma_f32_16x16x32_bf16 v[146:149], v[122:125], v[138:141], v[146:149]
	v_mfma_f32_16x16x32_bf16 v[150:153], v[130:133], v[138:141], v[150:153]
	v_mfma_f32_16x16x32_bf16 v[154:157], v[122:125], v[170:173], v[154:157]
	v_mfma_f32_16x16x32_bf16 v[158:161], v[130:133], v[170:173], v[158:161]
	v_mfma_f32_16x16x32_bf16 v[162:165], v[122:125], v[178:181], v[162:165]
	v_mfma_f32_16x16x32_bf16 v[166:169], v[130:133], v[178:181], v[166:169]
	v_mfma_f32_16x16x32_bf16 v[18:21], v[122:125], v[190:193], v[18:21]
	v_mfma_f32_16x16x32_bf16 v[22:25], v[130:133], v[190:193], v[22:25]
	v_mfma_f32_16x16x32_bf16 v[146:149], v[126:129], v[142:145], v[146:149]
	v_mfma_f32_16x16x32_bf16 v[150:153], v[134:137], v[142:145], v[150:153]
	v_mfma_f32_16x16x32_bf16 v[154:157], v[126:129], v[174:177], v[154:157]
	v_mfma_f32_16x16x32_bf16 v[158:161], v[134:137], v[174:177], v[158:161]
	v_mfma_f32_16x16x32_bf16 v[162:165], v[126:129], v[186:189], v[162:165]
	v_mfma_f32_16x16x32_bf16 v[166:169], v[134:137], v[186:189], v[166:169]
	v_mfma_f32_16x16x32_bf16 v[18:21], v[126:129], v[194:197], v[18:21]
	v_mfma_f32_16x16x32_bf16 v[22:25], v[134:137], v[194:197], v[22:25]
	s_barrier
	s_add_u32 s20, s0, s2
	s_addc_u32 s21, s1, s3
	s_mov_b32 m0, s45
	v_lshl_add_u64 v[218:219], s[20:21], 0, v[2:3]
	global_load_lds_dwordx4 v[218:219], off
	v_lshl_add_u64 v[220:221], s[20:21], 0, v[0:1]
	s_mov_b32 m0, s46
	s_nop 0
	global_load_lds_dwordx4 v[220:221], off
	s_waitcnt vmcnt(6)
	s_barrier
	v_mfma_f32_16x16x32_bf16 v[26:29], v[94:97], v[138:141], v[26:29]
	v_mfma_f32_16x16x32_bf16 v[30:33], v[204:207], v[138:141], v[30:33]
	v_mfma_f32_16x16x32_bf16 v[62:65], v[94:97], v[170:173], v[62:65]
	v_mfma_f32_16x16x32_bf16 v[106:109], v[204:207], v[170:173], v[106:109]
	v_mfma_f32_16x16x32_bf16 v[110:113], v[94:97], v[178:181], v[110:113]
	v_mfma_f32_16x16x32_bf16 v[118:121], v[204:207], v[178:181], v[118:121]
	v_mfma_f32_16x16x32_bf16 v[94:97], v[94:97], v[190:193], v[98:101]
	v_mfma_f32_16x16x32_bf16 v[98:101], v[204:207], v[190:193], v[102:105]
	v_mfma_f32_16x16x32_bf16 v[26:29], v[200:203], v[142:145], v[26:29]
	v_mfma_f32_16x16x32_bf16 v[30:33], v[208:211], v[142:145], v[30:33]
	v_mfma_f32_16x16x32_bf16 v[62:65], v[200:203], v[174:177], v[62:65]
	v_mfma_f32_16x16x32_bf16 v[106:109], v[208:211], v[174:177], v[106:109]
	v_mfma_f32_16x16x32_bf16 v[110:113], v[200:203], v[186:189], v[110:113]
	v_mfma_f32_16x16x32_bf16 v[118:121], v[208:211], v[186:189], v[118:121]
	v_mfma_f32_16x16x32_bf16 v[94:97], v[200:203], v[194:197], v[94:97]
	v_mfma_f32_16x16x32_bf16 v[98:101], v[208:211], v[194:197], v[98:101]
	s_barrier
	ds_read_b128 v[102:105], v16
	ds_read_b128 v[122:125], v16 offset:1024
	ds_read_b128 v[126:129], v16 offset:2048
	ds_read_b128 v[130:133], v16 offset:3072
	s_add_u32 s20, s18, s2
	s_addc_u32 s21, s19, s3
	s_mov_b32 m0, s28
	v_lshl_add_u64 v[194:195], s[20:21], 0, v[2:3]
	ds_read_b128 v[134:137], v14 offset:32768
	ds_read_b128 v[138:141], v14 offset:33792
	ds_read_b128 v[142:145], v14 offset:34816
	ds_read_b128 v[170:173], v14 offset:35840
	ds_read_b128 v[174:177], v14 offset:36864
	ds_read_b128 v[178:181], v14 offset:37888
	ds_read_b128 v[186:189], v14 offset:38912
	ds_read_b128 v[190:193], v14 offset:39936
	global_load_lds_dwordx4 v[194:195], off
	v_lshl_add_u64 v[194:195], s[20:21], 0, v[0:1]
	s_mov_b32 m0, s29
	s_nop 0
	global_load_lds_dwordx4 v[194:195], off
	s_waitcnt lgkmcnt(8)
	s_barrier
	s_waitcnt lgkmcnt(0)
	s_waitcnt lgkmcnt(0)
	v_mfma_f32_16x16x32_bf16 v[4:7], v[102:105], v[134:137], v[4:7]
	v_mfma_f32_16x16x32_bf16 v[66:69], v[126:129], v[134:137], v[66:69]
	v_mfma_f32_16x16x32_bf16 v[70:73], v[102:105], v[142:145], v[70:73]
	v_mfma_f32_16x16x32_bf16 v[74:77], v[126:129], v[142:145], v[74:77]
	v_mfma_f32_16x16x32_bf16 v[78:81], v[102:105], v[174:177], v[78:81]
	v_mfma_f32_16x16x32_bf16 v[82:85], v[126:129], v[174:177], v[82:85]
	v_mfma_f32_16x16x32_bf16 v[86:89], v[102:105], v[186:189], v[86:89]
	v_mfma_f32_16x16x32_bf16 v[90:93], v[126:129], v[186:189], v[90:93]
	v_mfma_f32_16x16x32_bf16 v[4:7], v[122:125], v[138:141], v[4:7]
	v_mfma_f32_16x16x32_bf16 v[66:69], v[130:133], v[138:141], v[66:69]
	v_mfma_f32_16x16x32_bf16 v[70:73], v[122:125], v[170:173], v[70:73]
	v_mfma_f32_16x16x32_bf16 v[74:77], v[130:133], v[170:173], v[74:77]
	v_mfma_f32_16x16x32_bf16 v[78:81], v[122:125], v[178:181], v[78:81]
	v_mfma_f32_16x16x32_bf16 v[82:85], v[130:133], v[178:181], v[82:85]
	v_mfma_f32_16x16x32_bf16 v[86:89], v[122:125], v[190:193], v[86:89]
	v_mfma_f32_16x16x32_bf16 v[90:93], v[130:133], v[190:193], v[90:93]
	s_barrier
	s_mov_b32 m0, s47
	v_lshl_add_u64 v[182:183], v[182:183], 0, s[6:7]
	ds_read_b128 v[194:197], v17
	ds_read_b128 v[200:203], v17 offset:1024
	ds_read_b128 v[204:207], v17 offset:2048
	ds_read_b128 v[208:211], v17 offset:3072
	global_load_lds_dwordx4 v[182:183], off
	v_lshl_add_u64 v[182:183], v[212:213], 0, s[6:7]
	s_mov_b32 m0, s48
	s_nop 0
	global_load_lds_dwordx4 v[182:183], off
	s_barrier
	s_waitcnt lgkmcnt(0)
	s_waitcnt lgkmcnt(0)
	v_mfma_f32_16x16x32_bf16 v[114:117], v[194:197], v[134:137], v[114:117]
	v_mfma_f32_16x16x32_bf16 v[34:37], v[204:207], v[134:137], v[34:37]
	v_mfma_f32_16x16x32_bf16 v[38:41], v[194:197], v[142:145], v[38:41]
	v_mfma_f32_16x16x32_bf16 v[42:45], v[204:207], v[142:145], v[42:45]
	v_mfma_f32_16x16x32_bf16 v[46:49], v[194:197], v[174:177], v[46:49]
	v_mfma_f32_16x16x32_bf16 v[50:53], v[204:207], v[174:177], v[50:53]
	v_mfma_f32_16x16x32_bf16 v[54:57], v[194:197], v[186:189], v[54:57]
	v_mfma_f32_16x16x32_bf16 v[58:61], v[204:207], v[186:189], v[58:61]
	v_mfma_f32_16x16x32_bf16 v[114:117], v[200:203], v[138:141], v[114:117]
	v_mfma_f32_16x16x32_bf16 v[34:37], v[208:211], v[138:141], v[34:37]
	v_mfma_f32_16x16x32_bf16 v[38:41], v[200:203], v[170:173], v[38:41]
	v_mfma_f32_16x16x32_bf16 v[42:45], v[208:211], v[170:173], v[42:45]
	v_mfma_f32_16x16x32_bf16 v[46:49], v[200:203], v[178:181], v[46:49]
	v_mfma_f32_16x16x32_bf16 v[50:53], v[208:211], v[178:181], v[50:53]
	v_mfma_f32_16x16x32_bf16 v[54:57], v[200:203], v[190:193], v[54:57]
	v_mfma_f32_16x16x32_bf16 v[58:61], v[208:211], v[190:193], v[58:61]
	s_mov_b32 m0, s30
	v_lshl_add_u64 v[182:183], v[214:215], 0, s[6:7]
	s_barrier
	ds_read_b128 v[134:137], v14 offset:49152
	ds_read_b128 v[138:141], v14 offset:50176
	ds_read_b128 v[142:145], v14 offset:51200
	ds_read_b128 v[170:173], v14 offset:52224
	ds_read_b128 v[174:177], v14 offset:53248
	ds_read_b128 v[178:181], v14 offset:54272
	ds_read_b128 v[186:189], v14 offset:55296
	ds_read_b128 v[190:193], v14 offset:56320
	global_load_lds_dwordx4 v[182:183], off
	v_lshl_add_u64 v[182:183], v[216:217], 0, s[6:7]
	s_mov_b32 m0, s31
	s_nop 0
	global_load_lds_dwordx4 v[182:183], off
	s_barrier
	s_waitcnt lgkmcnt(0)
	s_waitcnt lgkmcnt(0)
	v_mfma_f32_16x16x32_bf16 v[146:149], v[102:105], v[134:137], v[146:149]
	v_mfma_f32_16x16x32_bf16 v[150:153], v[126:129], v[134:137], v[150:153]
	v_mfma_f32_16x16x32_bf16 v[154:157], v[102:105], v[142:145], v[154:157]
	v_mfma_f32_16x16x32_bf16 v[158:161], v[126:129], v[142:145], v[158:161]
	v_mfma_f32_16x16x32_bf16 v[162:165], v[102:105], v[174:177], v[162:165]
	v_mfma_f32_16x16x32_bf16 v[166:169], v[126:129], v[174:177], v[166:169]
	v_mfma_f32_16x16x32_bf16 v[18:21], v[102:105], v[186:189], v[18:21]
	v_mfma_f32_16x16x32_bf16 v[22:25], v[126:129], v[186:189], v[22:25]
	v_mfma_f32_16x16x32_bf16 v[146:149], v[122:125], v[138:141], v[146:149]
	v_mfma_f32_16x16x32_bf16 v[150:153], v[130:133], v[138:141], v[150:153]
	v_mfma_f32_16x16x32_bf16 v[154:157], v[122:125], v[170:173], v[154:157]
	v_mfma_f32_16x16x32_bf16 v[158:161], v[130:133], v[170:173], v[158:161]
	v_mfma_f32_16x16x32_bf16 v[162:165], v[122:125], v[178:181], v[162:165]
	v_mfma_f32_16x16x32_bf16 v[166:169], v[130:133], v[178:181], v[166:169]
	v_mfma_f32_16x16x32_bf16 v[18:21], v[122:125], v[190:193], v[18:21]
	v_mfma_f32_16x16x32_bf16 v[22:25], v[130:133], v[190:193], v[22:25]
	s_barrier
	s_mov_b32 m0, s49
	v_lshl_add_u64 v[102:103], v[218:219], 0, s[6:7]
	global_load_lds_dwordx4 v[102:103], off
	v_lshl_add_u64 v[102:103], v[220:221], 0, s[6:7]
	s_mov_b32 m0, s50
	s_nop 0
	global_load_lds_dwordx4 v[102:103], off
	s_waitcnt vmcnt(6)
	s_barrier
	v_mfma_f32_16x16x32_bf16 v[26:29], v[194:197], v[134:137], v[26:29]
	v_mfma_f32_16x16x32_bf16 v[30:33], v[204:207], v[134:137], v[30:33]
	v_mfma_f32_16x16x32_bf16 v[62:65], v[194:197], v[142:145], v[62:65]
	v_mfma_f32_16x16x32_bf16 v[102:105], v[204:207], v[142:145], v[106:109]
	v_mfma_f32_16x16x32_bf16 v[106:109], v[194:197], v[174:177], v[110:113]
	v_mfma_f32_16x16x32_bf16 v[110:113], v[204:207], v[174:177], v[118:121]
	v_mfma_f32_16x16x32_bf16 v[94:97], v[194:197], v[186:189], v[94:97]
	v_mfma_f32_16x16x32_bf16 v[98:101], v[204:207], v[186:189], v[98:101]
	v_mfma_f32_16x16x32_bf16 v[26:29], v[200:203], v[138:141], v[26:29]
	v_mfma_f32_16x16x32_bf16 v[30:33], v[208:211], v[138:141], v[30:33]
	v_mfma_f32_16x16x32_bf16 v[62:65], v[200:203], v[170:173], v[62:65]
	v_mfma_f32_16x16x32_bf16 v[102:105], v[208:211], v[170:173], v[102:105]
	v_mfma_f32_16x16x32_bf16 v[106:109], v[200:203], v[178:181], v[106:109]
	v_mfma_f32_16x16x32_bf16 v[110:113], v[208:211], v[178:181], v[110:113]
	v_mfma_f32_16x16x32_bf16 v[94:97], v[200:203], v[190:193], v[94:97]
	v_mfma_f32_16x16x32_bf16 v[98:101], v[208:211], v[190:193], v[98:101]
	s_ashr_i32 s20, s8, 8
	s_ashr_i32 s21, s20, 31
	s_lshl_b64 s[20:21], s[20:21], 21
	s_add_u32 s20, s88, s20
	s_addc_u32 s21, s89, s21
	s_lshl_b32 s8, s55, 8
	v_add_u32_e32 v118, s8, v8
	v_ashrrev_i32_e32 v119, 31, v118
	v_lshl_or_b32 v122, s54, 8, v12
	v_lshlrev_b64 v[120:121], 12, v[118:119]
	v_ashrrev_i32_e32 v123, 31, v122
	v_lshl_add_u64 v[120:121], s[20:21], 0, v[120:121]
	v_lshlrev_b64 v[122:123], 2, v[122:123]
	v_lshl_add_u64 v[120:121], v[120:121], 0, v[122:123]
	s_barrier
	global_store_dwordx4 v[120:121], v[4:7], off
	global_store_dwordx4 v[120:121], v[66:69], off offset:64
	global_store_dwordx4 v[120:121], v[114:117], off offset:512
	global_store_dwordx4 v[120:121], v[34:37], off offset:576
	v_add_u32_e32 v4, s8, v9
	v_ashrrev_i32_e32 v5, 31, v4
	v_lshlrev_b64 v[4:5], 12, v[4:5]
	v_lshl_add_u64 v[4:5], s[20:21], 0, v[4:5]
	v_lshl_add_u64 v[4:5], v[4:5], 0, v[122:123]
	global_store_dwordx4 v[4:5], v[70:73], off
	global_store_dwordx4 v[4:5], v[74:77], off offset:64
	global_store_dwordx4 v[4:5], v[38:41], off offset:512
	global_store_dwordx4 v[4:5], v[42:45], off offset:576
	v_add_u32_e32 v4, s8, v10
	v_ashrrev_i32_e32 v5, 31, v4
	v_lshlrev_b64 v[4:5], 12, v[4:5]
	v_lshl_add_u64 v[4:5], s[20:21], 0, v[4:5]
	v_lshl_add_u64 v[4:5], v[4:5], 0, v[122:123]
	global_store_dwordx4 v[4:5], v[78:81], off
	global_store_dwordx4 v[4:5], v[82:85], off offset:64
	global_store_dwordx4 v[4:5], v[46:49], off offset:512
	global_store_dwordx4 v[4:5], v[50:53], off offset:576
	v_add_u32_e32 v4, s8, v11
	v_ashrrev_i32_e32 v5, 31, v4
	v_lshlrev_b64 v[4:5], 12, v[4:5]
	v_lshl_add_u64 v[4:5], s[20:21], 0, v[4:5]
	v_lshl_add_u64 v[4:5], v[4:5], 0, v[122:123]
	global_store_dwordx4 v[4:5], v[86:89], off
	global_store_dwordx4 v[4:5], v[90:93], off offset:64
	global_store_dwordx4 v[4:5], v[54:57], off offset:512
	global_store_dwordx4 v[4:5], v[58:61], off offset:576
	v_add_u32_e32 v4, 0x80, v118
	v_ashrrev_i32_e32 v5, 31, v4
	v_lshlrev_b64 v[4:5], 12, v[4:5]
	v_lshl_add_u64 v[4:5], s[20:21], 0, v[4:5]
	v_lshl_add_u64 v[4:5], v[4:5], 0, v[122:123]
	global_store_dwordx4 v[4:5], v[146:149], off
	global_store_dwordx4 v[4:5], v[150:153], off offset:64
	global_store_dwordx4 v[4:5], v[26:29], off offset:512
	global_store_dwordx4 v[4:5], v[30:33], off offset:576
	v_add_u32_e32 v4, 0x90, v118
	v_ashrrev_i32_e32 v5, 31, v4
	v_lshlrev_b64 v[4:5], 12, v[4:5]
	v_lshl_add_u64 v[4:5], s[20:21], 0, v[4:5]
	v_lshl_add_u64 v[4:5], v[4:5], 0, v[122:123]
	global_store_dwordx4 v[4:5], v[154:157], off
	global_store_dwordx4 v[4:5], v[158:161], off offset:64
	global_store_dwordx4 v[4:5], v[62:65], off offset:512
	global_store_dwordx4 v[4:5], v[102:105], off offset:576
	v_add_u32_e32 v4, 0xa0, v118
	v_ashrrev_i32_e32 v5, 31, v4
	v_lshlrev_b64 v[4:5], 12, v[4:5]
	v_lshl_add_u64 v[4:5], s[20:21], 0, v[4:5]
	v_lshl_add_u64 v[4:5], v[4:5], 0, v[122:123]
	global_store_dwordx4 v[4:5], v[162:165], off
	global_store_dwordx4 v[4:5], v[166:169], off offset:64
	global_store_dwordx4 v[4:5], v[106:109], off offset:512
	global_store_dwordx4 v[4:5], v[110:113], off offset:576
	v_add_u32_e32 v4, 0xb0, v118
	v_ashrrev_i32_e32 v5, 31, v4
	v_lshlrev_b64 v[4:5], 12, v[4:5]
	v_lshl_add_u64 v[4:5], s[20:21], 0, v[4:5]
	v_lshl_add_u64 v[4:5], v[4:5], 0, v[122:123]
	s_add_i32 s33, s33, s40
	s_andn2_b64 vcc, exec, s[16:17]
	s_mov_b32 s8, s14
	s_mov_b32 s54, s52
	s_mov_b32 s55, s53
	s_mov_b64 s[20:21], s[0:1]
	s_mov_b64 s[22:23], s[18:19]
	global_store_dwordx4 v[4:5], v[18:21], off
	global_store_dwordx4 v[4:5], v[22:25], off offset:64
	global_store_dwordx4 v[4:5], v[94:97], off offset:512
	global_store_dwordx4 v[4:5], v[98:101], off offset:576
	s_cbranch_vccz .LBB0_1661

.LBB0_1779:
	ds_read_b128 v[150:153], v147
	ds_read_b128 v[154:157], v147 offset:1024
	ds_read_b128 v[158:161], v147 offset:2048
	ds_read_b128 v[162:165], v147 offset:3072
	ds_read_b128 v[166:169], v148
	ds_read_b128 v[170:173], v148 offset:1024
	ds_read_b128 v[174:177], v148 offset:2048
	ds_read_b128 v[178:181], v148 offset:3072
	s_add_u32 s22, s18, s20
	s_addc_u32 s23, s19, s21
	s_add_u32 s22, s22, 0x100
	s_addc_u32 s23, s23, 0
	s_add_u32 s50, s47, s20
	s_addc_u32 s51, s48, s21
	s_cmpk_eq_i32 s20, 0x700
	s_cselect_b32 s23, s3, s23
	s_cselect_b32 s22, s2, s22
	s_cselect_b32 s51, s17, s51
	s_cselect_b32 s50, s16, s50
	s_mov_b32 m0, s42
	v_lshl_add_u64 v[182:183], v[142:143], 0, s[20:21]
	ds_read_b128 v[186:189], v149
	ds_read_b128 v[190:193], v149 offset:1024
	ds_read_b128 v[194:197], v149 offset:2048
	ds_read_b128 v[200:203], v149 offset:3072
	ds_read_b128 v[204:207], v149 offset:4096
	ds_read_b128 v[208:211], v149 offset:5120
	ds_read_b128 v[212:215], v149 offset:6144
	ds_read_b128 v[216:219], v149 offset:7168
	global_load_lds_dwordx4 v[182:183], off
	v_lshl_add_u64 v[182:183], v[140:141], 0, s[20:21]
	s_add_i32 m0, s25, 0xe000
	s_nop 0
	global_load_lds_dwordx4 v[182:183], off
	s_waitcnt vmcnt(8)
	s_waitcnt lgkmcnt(0)
	s_barrier
	s_waitcnt lgkmcnt(0)
	v_mfma_f32_16x16x32_bf16 v[124:127], v[150:153], v[186:189], v[124:127]
	v_mfma_f32_16x16x32_bf16 v[120:123], v[158:161], v[186:189], v[120:123]
	v_mfma_f32_16x16x32_bf16 v[108:111], v[150:153], v[194:197], v[108:111]
	v_mfma_f32_16x16x32_bf16 v[104:107], v[158:161], v[194:197], v[104:107]
	v_mfma_f32_16x16x32_bf16 v[92:95], v[150:153], v[204:207], v[92:95]
	v_mfma_f32_16x16x32_bf16 v[88:91], v[158:161], v[204:207], v[88:91]
	v_mfma_f32_16x16x32_bf16 v[76:79], v[150:153], v[212:215], v[76:79]
	v_mfma_f32_16x16x32_bf16 v[72:75], v[158:161], v[212:215], v[72:75]
	v_mfma_f32_16x16x32_bf16 v[124:127], v[154:157], v[190:193], v[124:127]
	v_mfma_f32_16x16x32_bf16 v[120:123], v[162:165], v[190:193], v[120:123]
	v_mfma_f32_16x16x32_bf16 v[108:111], v[154:157], v[200:203], v[108:111]
	v_mfma_f32_16x16x32_bf16 v[104:107], v[162:165], v[200:203], v[104:107]
	v_mfma_f32_16x16x32_bf16 v[92:95], v[154:157], v[208:211], v[92:95]
	v_mfma_f32_16x16x32_bf16 v[88:91], v[162:165], v[208:211], v[88:91]
	v_mfma_f32_16x16x32_bf16 v[76:79], v[154:157], v[216:219], v[76:79]
	v_mfma_f32_16x16x32_bf16 v[72:75], v[162:165], v[216:219], v[72:75]
	v_mfma_f32_16x16x32_bf16 v[116:119], v[166:169], v[186:189], v[116:119]
	v_mfma_f32_16x16x32_bf16 v[112:115], v[174:177], v[186:189], v[112:115]
	v_mfma_f32_16x16x32_bf16 v[100:103], v[166:169], v[194:197], v[100:103]
	v_mfma_f32_16x16x32_bf16 v[96:99], v[174:177], v[194:197], v[96:99]
	v_mfma_f32_16x16x32_bf16 v[84:87], v[166:169], v[204:207], v[84:87]
	v_mfma_f32_16x16x32_bf16 v[80:83], v[174:177], v[204:207], v[80:83]
	v_mfma_f32_16x16x32_bf16 v[68:71], v[166:169], v[212:215], v[68:71]
	v_mfma_f32_16x16x32_bf16 v[64:67], v[174:177], v[212:215], v[64:67]
	v_mfma_f32_16x16x32_bf16 v[116:119], v[170:173], v[190:193], v[116:119]
	v_mfma_f32_16x16x32_bf16 v[112:115], v[178:181], v[190:193], v[112:115]
	v_mfma_f32_16x16x32_bf16 v[100:103], v[170:173], v[200:203], v[100:103]
	v_mfma_f32_16x16x32_bf16 v[96:99], v[178:181], v[200:203], v[96:99]
	v_mfma_f32_16x16x32_bf16 v[84:87], v[170:173], v[208:211], v[84:87]
	v_mfma_f32_16x16x32_bf16 v[80:83], v[178:181], v[208:211], v[80:83]
	v_mfma_f32_16x16x32_bf16 v[68:71], v[170:173], v[216:219], v[68:71]
	v_mfma_f32_16x16x32_bf16 v[64:67], v[178:181], v[216:219], v[64:67]
	s_barrier
	s_add_i32 s52, s33, s24
	v_lshl_add_u64 v[182:183], s[50:51], 0, v[128:129]
	s_mov_b32 m0, s52
	ds_read_b128 v[186:189], v149 offset:16384
	ds_read_b128 v[190:193], v149 offset:17408
	ds_read_b128 v[194:197], v149 offset:18432
	ds_read_b128 v[200:203], v149 offset:19456
	ds_read_b128 v[204:207], v149 offset:20480
	ds_read_b128 v[208:211], v149 offset:21504
	ds_read_b128 v[212:215], v149 offset:22528
	ds_read_b128 v[216:219], v149 offset:23552
	global_load_lds_dwordx4 v[182:183], off
	s_add_i32 m0, s52, 0x2000
	v_lshl_add_u64 v[220:221], s[50:51], 0, v[130:131]
	s_add_u32 s50, s50, s4
	s_addc_u32 s51, s51, s5
	s_add_i32 s52, s40, s24
	global_load_lds_dwordx4 v[220:221], off
	v_lshl_add_u64 v[222:223], s[50:51], 0, v[128:129]
	s_mov_b32 m0, s52
	v_lshl_add_u64 v[224:225], s[50:51], 0, v[130:131]
	global_load_lds_dwordx4 v[222:223], off
	s_add_i32 m0, s52, 0x2000
	v_lshl_add_u64 v[226:227], s[22:23], 0, v[128:129]
	global_load_lds_dwordx4 v[224:225], off
	s_mov_b32 m0, s25
	v_lshl_add_u64 v[228:229], s[22:23], 0, v[130:131]
	global_load_lds_dwordx4 v[226:227], off
	s_mov_b32 m0, s26
	s_nop 0
	global_load_lds_dwordx4 v[228:229], off
	s_waitcnt vmcnt(8)
	s_waitcnt lgkmcnt(0)
	s_barrier
	s_waitcnt lgkmcnt(0)
	v_mfma_f32_16x16x32_bf16 v[60:63], v[150:153], v[186:189], v[60:63]
	v_mfma_f32_16x16x32_bf16 v[56:59], v[158:161], v[186:189], v[56:59]
	v_mfma_f32_16x16x32_bf16 v[44:47], v[150:153], v[194:197], v[44:47]
	v_mfma_f32_16x16x32_bf16 v[40:43], v[158:161], v[194:197], v[40:43]
	v_mfma_f32_16x16x32_bf16 v[28:31], v[150:153], v[204:207], v[28:31]
	v_mfma_f32_16x16x32_bf16 v[24:27], v[158:161], v[204:207], v[24:27]
	v_mfma_f32_16x16x32_bf16 v[12:15], v[150:153], v[212:215], v[12:15]
	v_mfma_f32_16x16x32_bf16 v[8:11], v[158:161], v[212:215], v[8:11]
	v_mfma_f32_16x16x32_bf16 v[60:63], v[154:157], v[190:193], v[60:63]
	v_mfma_f32_16x16x32_bf16 v[56:59], v[162:165], v[190:193], v[56:59]
	v_mfma_f32_16x16x32_bf16 v[44:47], v[154:157], v[200:203], v[44:47]
	v_mfma_f32_16x16x32_bf16 v[40:43], v[162:165], v[200:203], v[40:43]
	v_mfma_f32_16x16x32_bf16 v[28:31], v[154:157], v[208:211], v[28:31]
	v_mfma_f32_16x16x32_bf16 v[24:27], v[162:165], v[208:211], v[24:27]
	v_mfma_f32_16x16x32_bf16 v[12:15], v[154:157], v[216:219], v[12:15]
	v_mfma_f32_16x16x32_bf16 v[8:11], v[162:165], v[216:219], v[8:11]
	v_mfma_f32_16x16x32_bf16 v[52:55], v[166:169], v[186:189], v[52:55]
	v_mfma_f32_16x16x32_bf16 v[48:51], v[174:177], v[186:189], v[48:51]
	v_mfma_f32_16x16x32_bf16 v[36:39], v[166:169], v[194:197], v[36:39]
	v_mfma_f32_16x16x32_bf16 v[32:35], v[174:177], v[194:197], v[32:35]
	v_mfma_f32_16x16x32_bf16 v[20:23], v[166:169], v[204:207], v[20:23]
	v_mfma_f32_16x16x32_bf16 v[16:19], v[174:177], v[204:207], v[16:19]
	v_mfma_f32_16x16x32_bf16 v[4:7], v[166:169], v[212:215], v[4:7]
	v_mfma_f32_16x16x32_bf16 v[0:3], v[174:177], v[212:215], v[0:3]
	v_mfma_f32_16x16x32_bf16 v[52:55], v[170:173], v[190:193], v[52:55]
	v_mfma_f32_16x16x32_bf16 v[48:51], v[178:181], v[190:193], v[48:51]
	v_mfma_f32_16x16x32_bf16 v[36:39], v[170:173], v[200:203], v[36:39]
	v_mfma_f32_16x16x32_bf16 v[32:35], v[178:181], v[200:203], v[32:35]
	v_mfma_f32_16x16x32_bf16 v[20:23], v[170:173], v[208:211], v[20:23]
	v_mfma_f32_16x16x32_bf16 v[16:19], v[178:181], v[208:211], v[16:19]
	v_mfma_f32_16x16x32_bf16 v[4:7], v[170:173], v[216:219], v[4:7]
	v_mfma_f32_16x16x32_bf16 v[0:3], v[178:181], v[216:219], v[0:3]
	s_barrier
	s_add_i32 s50, 0, 0x18000
	s_add_i32 s51, 0, 0x1c000
	v_add_u32_e32 v162, s50, v145
	v_add_u32_e32 v178, s51, v145
	ds_read_b128 v[150:153], v162
	ds_read_b128 v[154:157], v162 offset:1024
	ds_read_b128 v[158:161], v162 offset:2048
	ds_read_b128 v[162:165], v162 offset:3072
	ds_read_b128 v[166:169], v178
	ds_read_b128 v[170:173], v178 offset:1024
	ds_read_b128 v[174:177], v178 offset:2048
	ds_read_b128 v[178:181], v178 offset:3072
	s_add_u32 s22, s22, s4
	s_addc_u32 s23, s23, s5
	s_mov_b32 m0, s27
	v_lshl_add_u64 v[230:231], s[22:23], 0, v[128:129]
	ds_read_b128 v[186:189], v149 offset:32768
	ds_read_b128 v[190:193], v149 offset:33792
	ds_read_b128 v[194:197], v149 offset:34816
	ds_read_b128 v[200:203], v149 offset:35840
	ds_read_b128 v[204:207], v149 offset:36864
	ds_read_b128 v[208:211], v149 offset:37888
	ds_read_b128 v[212:215], v149 offset:38912
	ds_read_b128 v[216:219], v149 offset:39936
	global_load_lds_dwordx4 v[230:231], off
	v_lshl_add_u64 v[230:231], s[22:23], 0, v[130:131]
	s_mov_b32 m0, s28
	s_nop 0
	global_load_lds_dwordx4 v[230:231], off
	s_waitcnt vmcnt(8)
	s_waitcnt lgkmcnt(0)
	s_barrier
	s_waitcnt lgkmcnt(0)
	v_mfma_f32_16x16x32_bf16 v[124:127], v[150:153], v[186:189], v[124:127]
	v_mfma_f32_16x16x32_bf16 v[120:123], v[158:161], v[186:189], v[120:123]
	v_mfma_f32_16x16x32_bf16 v[108:111], v[150:153], v[194:197], v[108:111]
	v_mfma_f32_16x16x32_bf16 v[104:107], v[158:161], v[194:197], v[104:107]
	v_mfma_f32_16x16x32_bf16 v[92:95], v[150:153], v[204:207], v[92:95]
	v_mfma_f32_16x16x32_bf16 v[88:91], v[158:161], v[204:207], v[88:91]
	v_mfma_f32_16x16x32_bf16 v[76:79], v[150:153], v[212:215], v[76:79]
	v_mfma_f32_16x16x32_bf16 v[72:75], v[158:161], v[212:215], v[72:75]
	v_mfma_f32_16x16x32_bf16 v[124:127], v[154:157], v[190:193], v[124:127]
	v_mfma_f32_16x16x32_bf16 v[120:123], v[162:165], v[190:193], v[120:123]
	v_mfma_f32_16x16x32_bf16 v[108:111], v[154:157], v[200:203], v[108:111]
	v_mfma_f32_16x16x32_bf16 v[104:107], v[162:165], v[200:203], v[104:107]
	v_mfma_f32_16x16x32_bf16 v[92:95], v[154:157], v[208:211], v[92:95]
	v_mfma_f32_16x16x32_bf16 v[88:91], v[162:165], v[208:211], v[88:91]
	v_mfma_f32_16x16x32_bf16 v[76:79], v[154:157], v[216:219], v[76:79]
	v_mfma_f32_16x16x32_bf16 v[72:75], v[162:165], v[216:219], v[72:75]
	v_mfma_f32_16x16x32_bf16 v[116:119], v[166:169], v[186:189], v[116:119]
	v_mfma_f32_16x16x32_bf16 v[112:115], v[174:177], v[186:189], v[112:115]
	v_mfma_f32_16x16x32_bf16 v[100:103], v[166:169], v[194:197], v[100:103]
	v_mfma_f32_16x16x32_bf16 v[96:99], v[174:177], v[194:197], v[96:99]
	v_mfma_f32_16x16x32_bf16 v[84:87], v[166:169], v[204:207], v[84:87]
	v_mfma_f32_16x16x32_bf16 v[80:83], v[174:177], v[204:207], v[80:83]
	v_mfma_f32_16x16x32_bf16 v[68:71], v[166:169], v[212:215], v[68:71]
	v_mfma_f32_16x16x32_bf16 v[64:67], v[174:177], v[212:215], v[64:67]
	v_mfma_f32_16x16x32_bf16 v[116:119], v[170:173], v[190:193], v[116:119]
	v_mfma_f32_16x16x32_bf16 v[112:115], v[178:181], v[190:193], v[112:115]
	v_mfma_f32_16x16x32_bf16 v[100:103], v[170:173], v[200:203], v[100:103]
	v_mfma_f32_16x16x32_bf16 v[96:99], v[178:181], v[200:203], v[96:99]
	v_mfma_f32_16x16x32_bf16 v[84:87], v[170:173], v[208:211], v[84:87]
	v_mfma_f32_16x16x32_bf16 v[80:83], v[178:181], v[208:211], v[80:83]
	v_mfma_f32_16x16x32_bf16 v[68:71], v[170:173], v[216:219], v[68:71]
	v_mfma_f32_16x16x32_bf16 v[64:67], v[178:181], v[216:219], v[64:67]
	s_barrier
	s_add_i32 s22, s50, s24
	v_lshl_add_u64 v[182:183], v[182:183], 0, s[12:13]
	s_mov_b32 m0, s22
	ds_read_b128 v[186:189], v149 offset:49152
	ds_read_b128 v[190:193], v149 offset:50176
	ds_read_b128 v[194:197], v149 offset:51200
	ds_read_b128 v[200:203], v149 offset:52224
	ds_read_b128 v[204:207], v149 offset:53248
	ds_read_b128 v[208:211], v149 offset:54272
	ds_read_b128 v[212:215], v149 offset:55296
	ds_read_b128 v[216:219], v149 offset:56320
	global_load_lds_dwordx4 v[182:183], off
	v_lshl_add_u64 v[182:183], v[220:221], 0, s[12:13]
	s_add_i32 m0, s22, 0x2000
	s_add_i32 s22, s51, s24
	global_load_lds_dwordx4 v[182:183], off
	v_lshl_add_u64 v[182:183], v[222:223], 0, s[12:13]
	s_mov_b32 m0, s22
	s_nop 0
	global_load_lds_dwordx4 v[182:183], off
	v_lshl_add_u64 v[182:183], v[224:225], 0, s[12:13]
	s_add_i32 m0, s22, 0x2000
	s_nop 0
	global_load_lds_dwordx4 v[182:183], off
	v_lshl_add_u64 v[182:183], v[226:227], 0, s[12:13]
	s_mov_b32 m0, s30
	s_nop 0
	global_load_lds_dwordx4 v[182:183], off
	v_lshl_add_u64 v[182:183], v[228:229], 0, s[12:13]
	s_mov_b32 m0, s31
	s_nop 0
	global_load_lds_dwordx4 v[182:183], off
	s_waitcnt vmcnt(8)
	s_waitcnt lgkmcnt(0)
	s_barrier
	s_waitcnt lgkmcnt(0)
	v_mfma_f32_16x16x32_bf16 v[60:63], v[150:153], v[186:189], v[60:63]
	v_mfma_f32_16x16x32_bf16 v[56:59], v[158:161], v[186:189], v[56:59]
	v_mfma_f32_16x16x32_bf16 v[44:47], v[150:153], v[194:197], v[44:47]
	v_mfma_f32_16x16x32_bf16 v[40:43], v[158:161], v[194:197], v[40:43]
	v_mfma_f32_16x16x32_bf16 v[28:31], v[150:153], v[204:207], v[28:31]
	v_mfma_f32_16x16x32_bf16 v[24:27], v[158:161], v[204:207], v[24:27]
	v_mfma_f32_16x16x32_bf16 v[12:15], v[150:153], v[212:215], v[12:15]
	v_mfma_f32_16x16x32_bf16 v[8:11], v[158:161], v[212:215], v[8:11]
	v_mfma_f32_16x16x32_bf16 v[60:63], v[154:157], v[190:193], v[60:63]
	v_mfma_f32_16x16x32_bf16 v[56:59], v[162:165], v[190:193], v[56:59]
	v_mfma_f32_16x16x32_bf16 v[44:47], v[154:157], v[200:203], v[44:47]
	v_mfma_f32_16x16x32_bf16 v[40:43], v[162:165], v[200:203], v[40:43]
	v_mfma_f32_16x16x32_bf16 v[28:31], v[154:157], v[208:211], v[28:31]
	v_mfma_f32_16x16x32_bf16 v[24:27], v[162:165], v[208:211], v[24:27]
	v_mfma_f32_16x16x32_bf16 v[12:15], v[154:157], v[216:219], v[12:15]
	v_mfma_f32_16x16x32_bf16 v[8:11], v[162:165], v[216:219], v[8:11]
	v_mfma_f32_16x16x32_bf16 v[52:55], v[166:169], v[186:189], v[52:55]
	v_mfma_f32_16x16x32_bf16 v[48:51], v[174:177], v[186:189], v[48:51]
	v_mfma_f32_16x16x32_bf16 v[36:39], v[166:169], v[194:197], v[36:39]
	v_mfma_f32_16x16x32_bf16 v[32:35], v[174:177], v[194:197], v[32:35]
	v_mfma_f32_16x16x32_bf16 v[20:23], v[166:169], v[204:207], v[20:23]
	v_mfma_f32_16x16x32_bf16 v[16:19], v[174:177], v[204:207], v[16:19]
	v_mfma_f32_16x16x32_bf16 v[4:7], v[166:169], v[212:215], v[4:7]
	v_mfma_f32_16x16x32_bf16 v[0:3], v[174:177], v[212:215], v[0:3]
	v_mfma_f32_16x16x32_bf16 v[52:55], v[170:173], v[190:193], v[52:55]
	v_mfma_f32_16x16x32_bf16 v[48:51], v[178:181], v[190:193], v[48:51]
	v_mfma_f32_16x16x32_bf16 v[36:39], v[170:173], v[200:203], v[36:39]
	v_mfma_f32_16x16x32_bf16 v[32:35], v[178:181], v[200:203], v[32:35]
	v_mfma_f32_16x16x32_bf16 v[20:23], v[170:173], v[208:211], v[20:23]
	v_mfma_f32_16x16x32_bf16 v[16:19], v[178:181], v[208:211], v[16:19]
	v_mfma_f32_16x16x32_bf16 v[4:7], v[170:173], v[216:219], v[4:7]
	v_mfma_f32_16x16x32_bf16 v[0:3], v[178:181], v[216:219], v[0:3]
	s_barrier
	s_add_i32 s49, s49, 2
	s_add_u32 s20, s20, 0x100
	s_addc_u32 s21, s21, 0
	s_cmp_gt_u32 s49, 13
	s_cbranch_scc0 .LBB0_1779
	s_and_b64 vcc, exec, s[14:15]
	s_cbranch_vccz .LBB0_1782
	s_barrier

.LBB0_1853:
	ds_read_b128 v[146:149], v156
	ds_read_b128 v[160:163], v156 offset:1024
	ds_read_b128 v[164:167], v156 offset:2048
	ds_read_b128 v[168:171], v156 offset:3072
	ds_read_b128 v[172:175], v157
	ds_read_b128 v[176:179], v157 offset:1024
	ds_read_b128 v[180:183], v157 offset:2048
	ds_read_b128 v[186:189], v157 offset:3072
	s_add_u32 s22, s18, s20
	s_addc_u32 s23, s19, s21
	s_add_u32 s22, s22, 0x100
	s_addc_u32 s23, s23, 0
	s_add_u32 s49, s46, s20
	s_addc_u32 s50, s47, s21
	s_cmpk_eq_i32 s20, 0x1500
	s_cselect_b32 s23, s3, s23
	s_cselect_b32 s22, s2, s22
	s_cselect_b32 s51, s17, s50
	s_cselect_b32 s50, s16, s49
	s_mov_b32 m0, s37
	v_lshl_add_u64 v[224:225], v[142:143], 0, s[20:21]
	ds_read_b128 v[190:193], v158
	ds_read_b128 v[194:197], v158 offset:1024
	ds_read_b128 v[200:203], v158 offset:2048
	ds_read_b128 v[204:207], v158 offset:3072
	ds_read_b128 v[208:211], v158 offset:4096
	ds_read_b128 v[212:215], v158 offset:5120
	ds_read_b128 v[216:219], v158 offset:6144
	ds_read_b128 v[220:223], v158 offset:7168
	global_load_lds_dwordx4 v[224:225], off
	v_lshl_add_u64 v[224:225], v[144:145], 0, s[20:21]
	s_mov_b32 m0, s40
	s_nop 0
	global_load_lds_dwordx4 v[224:225], off
	s_waitcnt vmcnt(8)
	s_waitcnt lgkmcnt(0)
	s_barrier
	s_waitcnt lgkmcnt(0)
	v_mfma_f32_16x16x32_bf16 v[124:127], v[146:149], v[190:193], v[124:127]
	v_mfma_f32_16x16x32_bf16 v[120:123], v[164:167], v[190:193], v[120:123]
	v_mfma_f32_16x16x32_bf16 v[108:111], v[146:149], v[200:203], v[108:111]
	v_mfma_f32_16x16x32_bf16 v[104:107], v[164:167], v[200:203], v[104:107]
	v_mfma_f32_16x16x32_bf16 v[92:95], v[146:149], v[208:211], v[92:95]
	v_mfma_f32_16x16x32_bf16 v[88:91], v[164:167], v[208:211], v[88:91]
	v_mfma_f32_16x16x32_bf16 v[76:79], v[146:149], v[216:219], v[76:79]
	v_mfma_f32_16x16x32_bf16 v[72:75], v[164:167], v[216:219], v[72:75]
	v_mfma_f32_16x16x32_bf16 v[124:127], v[160:163], v[194:197], v[124:127]
	v_mfma_f32_16x16x32_bf16 v[120:123], v[168:171], v[194:197], v[120:123]
	v_mfma_f32_16x16x32_bf16 v[108:111], v[160:163], v[204:207], v[108:111]
	v_mfma_f32_16x16x32_bf16 v[104:107], v[168:171], v[204:207], v[104:107]
	v_mfma_f32_16x16x32_bf16 v[92:95], v[160:163], v[212:215], v[92:95]
	v_mfma_f32_16x16x32_bf16 v[88:91], v[168:171], v[212:215], v[88:91]
	v_mfma_f32_16x16x32_bf16 v[76:79], v[160:163], v[220:223], v[76:79]
	v_mfma_f32_16x16x32_bf16 v[72:75], v[168:171], v[220:223], v[72:75]
	v_mfma_f32_16x16x32_bf16 v[116:119], v[172:175], v[190:193], v[116:119]
	v_mfma_f32_16x16x32_bf16 v[112:115], v[180:183], v[190:193], v[112:115]
	v_mfma_f32_16x16x32_bf16 v[100:103], v[172:175], v[200:203], v[100:103]
	v_mfma_f32_16x16x32_bf16 v[96:99], v[180:183], v[200:203], v[96:99]
	v_mfma_f32_16x16x32_bf16 v[84:87], v[172:175], v[208:211], v[84:87]
	v_mfma_f32_16x16x32_bf16 v[80:83], v[180:183], v[208:211], v[80:83]
	v_mfma_f32_16x16x32_bf16 v[68:71], v[172:175], v[216:219], v[68:71]
	v_mfma_f32_16x16x32_bf16 v[64:67], v[180:183], v[216:219], v[64:67]
	v_mfma_f32_16x16x32_bf16 v[116:119], v[176:179], v[194:197], v[116:119]
	v_mfma_f32_16x16x32_bf16 v[112:115], v[186:189], v[194:197], v[112:115]
	v_mfma_f32_16x16x32_bf16 v[100:103], v[176:179], v[204:207], v[100:103]
	v_mfma_f32_16x16x32_bf16 v[96:99], v[186:189], v[204:207], v[96:99]
	v_mfma_f32_16x16x32_bf16 v[84:87], v[176:179], v[212:215], v[84:87]
	v_mfma_f32_16x16x32_bf16 v[80:83], v[186:189], v[212:215], v[80:83]
	v_mfma_f32_16x16x32_bf16 v[68:71], v[176:179], v[220:223], v[68:71]
	v_mfma_f32_16x16x32_bf16 v[64:67], v[186:189], v[220:223], v[64:67]
	s_barrier
	s_mov_b32 m0, s41
	v_lshl_add_u64 v[224:225], s[50:51], 0, v[128:129]
	ds_read_b128 v[190:193], v158 offset:16384
	ds_read_b128 v[194:197], v158 offset:17408
	ds_read_b128 v[200:203], v158 offset:18432
	ds_read_b128 v[204:207], v158 offset:19456
	ds_read_b128 v[208:211], v158 offset:20480
	ds_read_b128 v[212:215], v158 offset:21504
	ds_read_b128 v[216:219], v158 offset:22528
	ds_read_b128 v[220:223], v158 offset:23552
	global_load_lds_dwordx4 v[224:225], off
	s_add_i32 m0, s41, 0x2000
	v_lshl_add_u64 v[226:227], s[50:51], 0, v[130:131]
	s_add_u32 s50, s50, s4
	s_addc_u32 s51, s51, s5
	s_add_i32 s49, s33, s24
	global_load_lds_dwordx4 v[226:227], off
	v_lshl_add_u64 v[228:229], s[50:51], 0, v[128:129]
	s_mov_b32 m0, s49
	v_lshl_add_u64 v[230:231], s[50:51], 0, v[130:131]
	global_load_lds_dwordx4 v[228:229], off
	s_add_i32 m0, s49, 0x2000
	v_lshl_add_u64 v[232:233], s[22:23], 0, v[128:129]
	global_load_lds_dwordx4 v[230:231], off
	s_mov_b32 m0, s25
	v_lshl_add_u64 v[234:235], s[22:23], 0, v[130:131]
	global_load_lds_dwordx4 v[232:233], off
	s_mov_b32 m0, s26
	s_nop 0
	global_load_lds_dwordx4 v[234:235], off
	s_waitcnt vmcnt(8)
	s_waitcnt lgkmcnt(0)
	s_barrier
	s_waitcnt lgkmcnt(0)
	v_mfma_f32_16x16x32_bf16 v[60:63], v[146:149], v[190:193], v[60:63]
	v_mfma_f32_16x16x32_bf16 v[56:59], v[164:167], v[190:193], v[56:59]
	v_mfma_f32_16x16x32_bf16 v[44:47], v[146:149], v[200:203], v[44:47]
	v_mfma_f32_16x16x32_bf16 v[40:43], v[164:167], v[200:203], v[40:43]
	v_mfma_f32_16x16x32_bf16 v[28:31], v[146:149], v[208:211], v[28:31]
	v_mfma_f32_16x16x32_bf16 v[24:27], v[164:167], v[208:211], v[24:27]
	v_mfma_f32_16x16x32_bf16 v[12:15], v[146:149], v[216:219], v[12:15]
	v_mfma_f32_16x16x32_bf16 v[8:11], v[164:167], v[216:219], v[8:11]
	v_mfma_f32_16x16x32_bf16 v[60:63], v[160:163], v[194:197], v[60:63]
	v_mfma_f32_16x16x32_bf16 v[56:59], v[168:171], v[194:197], v[56:59]
	v_mfma_f32_16x16x32_bf16 v[44:47], v[160:163], v[204:207], v[44:47]
	v_mfma_f32_16x16x32_bf16 v[40:43], v[168:171], v[204:207], v[40:43]
	v_mfma_f32_16x16x32_bf16 v[28:31], v[160:163], v[212:215], v[28:31]
	v_mfma_f32_16x16x32_bf16 v[24:27], v[168:171], v[212:215], v[24:27]
	v_mfma_f32_16x16x32_bf16 v[12:15], v[160:163], v[220:223], v[12:15]
	v_mfma_f32_16x16x32_bf16 v[8:11], v[168:171], v[220:223], v[8:11]
	v_mfma_f32_16x16x32_bf16 v[52:55], v[172:175], v[190:193], v[52:55]
	v_mfma_f32_16x16x32_bf16 v[48:51], v[180:183], v[190:193], v[48:51]
	v_mfma_f32_16x16x32_bf16 v[36:39], v[172:175], v[200:203], v[36:39]
	v_mfma_f32_16x16x32_bf16 v[32:35], v[180:183], v[200:203], v[32:35]
	v_mfma_f32_16x16x32_bf16 v[20:23], v[172:175], v[208:211], v[20:23]
	v_mfma_f32_16x16x32_bf16 v[16:19], v[180:183], v[208:211], v[16:19]
	v_mfma_f32_16x16x32_bf16 v[4:7], v[172:175], v[216:219], v[4:7]
	v_mfma_f32_16x16x32_bf16 v[0:3], v[180:183], v[216:219], v[0:3]
	v_mfma_f32_16x16x32_bf16 v[52:55], v[176:179], v[194:197], v[52:55]
	v_mfma_f32_16x16x32_bf16 v[48:51], v[186:189], v[194:197], v[48:51]
	v_mfma_f32_16x16x32_bf16 v[36:39], v[176:179], v[204:207], v[36:39]
	v_mfma_f32_16x16x32_bf16 v[32:35], v[186:189], v[204:207], v[32:35]
	v_mfma_f32_16x16x32_bf16 v[20:23], v[176:179], v[212:215], v[20:23]
	v_mfma_f32_16x16x32_bf16 v[16:19], v[186:189], v[212:215], v[16:19]
	v_mfma_f32_16x16x32_bf16 v[4:7], v[176:179], v[220:223], v[4:7]
	v_mfma_f32_16x16x32_bf16 v[0:3], v[186:189], v[220:223], v[0:3]
	s_barrier
	s_add_i32 s49, 0, 0x18000
	v_add_u32_e32 v132, s49, v151
	s_add_i32 s50, 0, 0x1c000
	ds_read_b128 v[146:149], v132
	ds_read_b128 v[160:163], v132 offset:1024
	ds_read_b128 v[164:167], v132 offset:2048
	ds_read_b128 v[168:171], v132 offset:3072
	v_add_u32_e32 v132, s50, v151
	ds_read_b128 v[172:175], v132
	ds_read_b128 v[176:179], v132 offset:1024
	ds_read_b128 v[180:183], v132 offset:2048
	ds_read_b128 v[186:189], v132 offset:3072
	s_add_u32 s22, s22, s4
	s_addc_u32 s23, s23, s5
	s_mov_b32 m0, s27
	v_lshl_add_u64 v[236:237], s[22:23], 0, v[128:129]
	ds_read_b128 v[190:193], v158 offset:32768
	ds_read_b128 v[194:197], v158 offset:33792
	ds_read_b128 v[200:203], v158 offset:34816
	ds_read_b128 v[204:207], v158 offset:35840
	ds_read_b128 v[208:211], v158 offset:36864
	ds_read_b128 v[212:215], v158 offset:37888
	ds_read_b128 v[216:219], v158 offset:38912
	ds_read_b128 v[220:223], v158 offset:39936
	global_load_lds_dwordx4 v[236:237], off
	v_lshl_add_u64 v[236:237], s[22:23], 0, v[130:131]
	s_mov_b32 m0, s28
	s_nop 0
	global_load_lds_dwordx4 v[236:237], off
	s_waitcnt vmcnt(8)
	s_waitcnt lgkmcnt(0)
	s_barrier
	s_waitcnt lgkmcnt(0)
	v_mfma_f32_16x16x32_bf16 v[124:127], v[146:149], v[190:193], v[124:127]
	v_mfma_f32_16x16x32_bf16 v[120:123], v[164:167], v[190:193], v[120:123]
	v_mfma_f32_16x16x32_bf16 v[108:111], v[146:149], v[200:203], v[108:111]
	v_mfma_f32_16x16x32_bf16 v[104:107], v[164:167], v[200:203], v[104:107]
	v_mfma_f32_16x16x32_bf16 v[92:95], v[146:149], v[208:211], v[92:95]
	v_mfma_f32_16x16x32_bf16 v[88:91], v[164:167], v[208:211], v[88:91]
	v_mfma_f32_16x16x32_bf16 v[76:79], v[146:149], v[216:219], v[76:79]
	v_mfma_f32_16x16x32_bf16 v[72:75], v[164:167], v[216:219], v[72:75]
	v_mfma_f32_16x16x32_bf16 v[124:127], v[160:163], v[194:197], v[124:127]
	v_mfma_f32_16x16x32_bf16 v[120:123], v[168:171], v[194:197], v[120:123]
	v_mfma_f32_16x16x32_bf16 v[108:111], v[160:163], v[204:207], v[108:111]
	v_mfma_f32_16x16x32_bf16 v[104:107], v[168:171], v[204:207], v[104:107]
	v_mfma_f32_16x16x32_bf16 v[92:95], v[160:163], v[212:215], v[92:95]
	v_mfma_f32_16x16x32_bf16 v[88:91], v[168:171], v[212:215], v[88:91]
	v_mfma_f32_16x16x32_bf16 v[76:79], v[160:163], v[220:223], v[76:79]
	v_mfma_f32_16x16x32_bf16 v[72:75], v[168:171], v[220:223], v[72:75]
	v_mfma_f32_16x16x32_bf16 v[116:119], v[172:175], v[190:193], v[116:119]
	v_mfma_f32_16x16x32_bf16 v[112:115], v[180:183], v[190:193], v[112:115]
	v_mfma_f32_16x16x32_bf16 v[100:103], v[172:175], v[200:203], v[100:103]
	v_mfma_f32_16x16x32_bf16 v[96:99], v[180:183], v[200:203], v[96:99]
	v_mfma_f32_16x16x32_bf16 v[84:87], v[172:175], v[208:211], v[84:87]
	v_mfma_f32_16x16x32_bf16 v[80:83], v[180:183], v[208:211], v[80:83]
	v_mfma_f32_16x16x32_bf16 v[68:71], v[172:175], v[216:219], v[68:71]
	v_mfma_f32_16x16x32_bf16 v[64:67], v[180:183], v[216:219], v[64:67]
	v_mfma_f32_16x16x32_bf16 v[116:119], v[176:179], v[194:197], v[116:119]
	v_mfma_f32_16x16x32_bf16 v[112:115], v[186:189], v[194:197], v[112:115]
	v_mfma_f32_16x16x32_bf16 v[100:103], v[176:179], v[204:207], v[100:103]
	v_mfma_f32_16x16x32_bf16 v[96:99], v[186:189], v[204:207], v[96:99]
	v_mfma_f32_16x16x32_bf16 v[84:87], v[176:179], v[212:215], v[84:87]
	v_mfma_f32_16x16x32_bf16 v[80:83], v[186:189], v[212:215], v[80:83]
	v_mfma_f32_16x16x32_bf16 v[68:71], v[176:179], v[220:223], v[68:71]
	v_mfma_f32_16x16x32_bf16 v[64:67], v[186:189], v[220:223], v[64:67]
	s_barrier
	s_add_i32 s22, s49, s24
	v_lshl_add_u64 v[224:225], v[224:225], 0, s[12:13]
	s_mov_b32 m0, s22
	ds_read_b128 v[190:193], v158 offset:49152
	ds_read_b128 v[194:197], v158 offset:50176
	ds_read_b128 v[200:203], v158 offset:51200
	ds_read_b128 v[204:207], v158 offset:52224
	ds_read_b128 v[208:211], v158 offset:53248
	ds_read_b128 v[212:215], v158 offset:54272
	ds_read_b128 v[216:219], v158 offset:55296
	ds_read_b128 v[220:223], v158 offset:56320
	global_load_lds_dwordx4 v[224:225], off
	v_lshl_add_u64 v[224:225], v[226:227], 0, s[12:13]
	s_add_i32 m0, s22, 0x2000
	s_add_i32 s22, s50, s24
	global_load_lds_dwordx4 v[224:225], off
	v_lshl_add_u64 v[224:225], v[228:229], 0, s[12:13]
	s_mov_b32 m0, s22
	s_nop 0
	global_load_lds_dwordx4 v[224:225], off
	v_lshl_add_u64 v[224:225], v[230:231], 0, s[12:13]
	s_add_i32 m0, s22, 0x2000
	s_nop 0
	global_load_lds_dwordx4 v[224:225], off
	v_lshl_add_u64 v[224:225], v[232:233], 0, s[12:13]
	s_mov_b32 m0, s30
	s_nop 0
	global_load_lds_dwordx4 v[224:225], off
	v_lshl_add_u64 v[224:225], v[234:235], 0, s[12:13]
	s_mov_b32 m0, s31
	s_nop 0
	global_load_lds_dwordx4 v[224:225], off
	s_waitcnt vmcnt(8)
	s_waitcnt lgkmcnt(0)
	s_barrier
	s_waitcnt lgkmcnt(0)
	v_mfma_f32_16x16x32_bf16 v[60:63], v[146:149], v[190:193], v[60:63]
	v_mfma_f32_16x16x32_bf16 v[56:59], v[164:167], v[190:193], v[56:59]
	v_mfma_f32_16x16x32_bf16 v[44:47], v[146:149], v[200:203], v[44:47]
	v_mfma_f32_16x16x32_bf16 v[40:43], v[164:167], v[200:203], v[40:43]
	v_mfma_f32_16x16x32_bf16 v[28:31], v[146:149], v[208:211], v[28:31]
	v_mfma_f32_16x16x32_bf16 v[24:27], v[164:167], v[208:211], v[24:27]
	v_mfma_f32_16x16x32_bf16 v[12:15], v[146:149], v[216:219], v[12:15]
	v_mfma_f32_16x16x32_bf16 v[8:11], v[164:167], v[216:219], v[8:11]
	v_mfma_f32_16x16x32_bf16 v[60:63], v[160:163], v[194:197], v[60:63]
	v_mfma_f32_16x16x32_bf16 v[56:59], v[168:171], v[194:197], v[56:59]
	v_mfma_f32_16x16x32_bf16 v[44:47], v[160:163], v[204:207], v[44:47]
	v_mfma_f32_16x16x32_bf16 v[40:43], v[168:171], v[204:207], v[40:43]
	v_mfma_f32_16x16x32_bf16 v[28:31], v[160:163], v[212:215], v[28:31]
	v_mfma_f32_16x16x32_bf16 v[24:27], v[168:171], v[212:215], v[24:27]
	v_mfma_f32_16x16x32_bf16 v[12:15], v[160:163], v[220:223], v[12:15]
	v_mfma_f32_16x16x32_bf16 v[8:11], v[168:171], v[220:223], v[8:11]
	v_mfma_f32_16x16x32_bf16 v[52:55], v[172:175], v[190:193], v[52:55]
	v_mfma_f32_16x16x32_bf16 v[48:51], v[180:183], v[190:193], v[48:51]
	v_mfma_f32_16x16x32_bf16 v[36:39], v[172:175], v[200:203], v[36:39]
	v_mfma_f32_16x16x32_bf16 v[32:35], v[180:183], v[200:203], v[32:35]
	v_mfma_f32_16x16x32_bf16 v[20:23], v[172:175], v[208:211], v[20:23]
	v_mfma_f32_16x16x32_bf16 v[16:19], v[180:183], v[208:211], v[16:19]
	v_mfma_f32_16x16x32_bf16 v[4:7], v[172:175], v[216:219], v[4:7]
	v_mfma_f32_16x16x32_bf16 v[0:3], v[180:183], v[216:219], v[0:3]
	v_mfma_f32_16x16x32_bf16 v[52:55], v[176:179], v[194:197], v[52:55]
	v_mfma_f32_16x16x32_bf16 v[48:51], v[186:189], v[194:197], v[48:51]
	v_mfma_f32_16x16x32_bf16 v[36:39], v[176:179], v[204:207], v[36:39]
	v_mfma_f32_16x16x32_bf16 v[32:35], v[186:189], v[204:207], v[32:35]
	v_mfma_f32_16x16x32_bf16 v[20:23], v[176:179], v[212:215], v[20:23]
	v_mfma_f32_16x16x32_bf16 v[16:19], v[186:189], v[212:215], v[16:19]
	v_mfma_f32_16x16x32_bf16 v[4:7], v[176:179], v[220:223], v[4:7]
	v_mfma_f32_16x16x32_bf16 v[0:3], v[186:189], v[220:223], v[0:3]
	s_barrier
	s_add_i32 s48, s48, 2
	s_add_u32 s20, s20, 0x100
	s_addc_u32 s21, s21, 0
	s_cmp_gt_u32 s48, 41
	s_cbranch_scc0 .LBB0_1853
	s_and_b64 vcc, exec, s[14:15]
	s_cbranch_vccz .LBB0_1856
	s_barrier

.LBB0_1896:
	ds_read_b128 v[4:7], v77
	ds_read_b128 v[8:11], v77 offset:1024
	ds_read_b128 v[12:15], v77 offset:2048
	ds_read_b128 v[16:19], v77 offset:3072
	s_add_u32 s50, s24, s2
	s_addc_u32 s51, s25, s3
	v_lshl_add_u64 v[0:1], s[50:51], 0, v[66:67]
	s_mov_b32 m0, s38
	v_lshl_add_u64 v[2:3], v[0:1], 0, s[8:9]
	ds_read_b128 v[20:23], v78
	ds_read_b128 v[24:27], v78 offset:1024
	ds_read_b128 v[28:31], v78 offset:2048
	ds_read_b128 v[32:35], v78 offset:3072
	ds_read_b128 v[36:39], v78 offset:4096
	ds_read_b128 v[40:43], v78 offset:5120
	ds_read_b128 v[44:47], v78 offset:6144
	ds_read_b128 v[48:51], v78 offset:7168
	global_load_lds_dwordx4 v[2:3], off
	v_lshl_add_u64 v[2:3], s[50:51], 0, v[64:65]
	v_lshl_add_u64 v[52:53], v[2:3], 0, s[8:9]
	s_mov_b32 m0, s39
	s_nop 0
	global_load_lds_dwordx4 v[52:53], off
	s_waitcnt lgkmcnt(8)
	s_barrier
	s_waitcnt lgkmcnt(0)
	s_waitcnt lgkmcnt(0)
	v_mfma_f32_16x16x32_bf16 v[52:55], v[4:7], v[20:23], 0
	v_mfma_f32_16x16x32_bf16 v[56:59], v[12:15], v[20:23], 0
	v_mfma_f32_16x16x32_bf16 v[60:63], v[4:7], v[28:31], 0
	v_mfma_f32_16x16x32_bf16 v[68:71], v[12:15], v[28:31], 0
	v_mfma_f32_16x16x32_bf16 v[82:85], v[4:7], v[36:39], 0
	v_mfma_f32_16x16x32_bf16 v[86:89], v[12:15], v[36:39], 0
	v_mfma_f32_16x16x32_bf16 v[90:93], v[4:7], v[44:47], 0
	v_mfma_f32_16x16x32_bf16 v[94:97], v[12:15], v[44:47], 0
	v_mfma_f32_16x16x32_bf16 v[52:55], v[8:11], v[24:27], v[52:55]
	v_mfma_f32_16x16x32_bf16 v[56:59], v[16:19], v[24:27], v[56:59]
	v_mfma_f32_16x16x32_bf16 v[60:63], v[8:11], v[32:35], v[60:63]
	v_mfma_f32_16x16x32_bf16 v[68:71], v[16:19], v[32:35], v[68:71]
	v_mfma_f32_16x16x32_bf16 v[82:85], v[8:11], v[40:43], v[82:85]
	v_mfma_f32_16x16x32_bf16 v[86:89], v[16:19], v[40:43], v[86:89]
	v_mfma_f32_16x16x32_bf16 v[90:93], v[8:11], v[48:51], v[90:93]
	v_mfma_f32_16x16x32_bf16 v[94:97], v[16:19], v[48:51], v[94:97]
	s_barrier
	v_lshl_add_u64 v[182:183], s[22:23], 0, v[66:67]
	s_mov_b32 m0, s40
	v_lshl_add_u64 v[114:115], v[182:183], 0, s[10:11]
	v_lshl_add_u64 v[216:217], s[22:23], 0, v[64:65]
	ds_read_b128 v[98:101], v79
	ds_read_b128 v[102:105], v79 offset:1024
	ds_read_b128 v[106:109], v79 offset:2048
	ds_read_b128 v[110:113], v79 offset:3072
	global_load_lds_dwordx4 v[114:115], off
	v_lshl_add_u64 v[114:115], v[216:217], 0, s[10:11]
	s_mov_b32 m0, s41
	s_nop 0
	global_load_lds_dwordx4 v[114:115], off
	s_barrier
	s_waitcnt lgkmcnt(0)
	s_waitcnt lgkmcnt(0)
	v_mfma_f32_16x16x32_bf16 v[114:117], v[98:101], v[20:23], 0
	v_mfma_f32_16x16x32_bf16 v[20:23], v[106:109], v[20:23], 0
	v_mfma_f32_16x16x32_bf16 v[114:117], v[102:105], v[24:27], v[114:117]
	v_mfma_f32_16x16x32_bf16 v[20:23], v[110:113], v[24:27], v[20:23]
	v_mfma_f32_16x16x32_bf16 v[24:27], v[98:101], v[28:31], 0
	v_mfma_f32_16x16x32_bf16 v[28:31], v[106:109], v[28:31], 0
	v_mfma_f32_16x16x32_bf16 v[24:27], v[102:105], v[32:35], v[24:27]
	v_mfma_f32_16x16x32_bf16 v[28:31], v[110:113], v[32:35], v[28:31]
	v_mfma_f32_16x16x32_bf16 v[32:35], v[98:101], v[36:39], 0
	v_mfma_f32_16x16x32_bf16 v[36:39], v[106:109], v[36:39], 0
	v_mfma_f32_16x16x32_bf16 v[32:35], v[102:105], v[40:43], v[32:35]
	v_mfma_f32_16x16x32_bf16 v[36:39], v[110:113], v[40:43], v[36:39]
	v_mfma_f32_16x16x32_bf16 v[40:43], v[98:101], v[44:47], 0
	v_mfma_f32_16x16x32_bf16 v[44:47], v[106:109], v[44:47], 0
	v_mfma_f32_16x16x32_bf16 v[40:43], v[102:105], v[48:51], v[40:43]
	v_mfma_f32_16x16x32_bf16 v[44:47], v[110:113], v[48:51], v[44:47]
	v_lshl_add_u64 v[218:219], s[24:25], 0, v[66:67]
	s_mov_b32 m0, s27
	v_lshl_add_u64 v[146:147], v[218:219], 0, s[10:11]
	v_lshl_add_u64 v[220:221], s[24:25], 0, v[64:65]
	s_barrier
	ds_read_b128 v[48:51], v78 offset:16384
	ds_read_b128 v[118:121], v78 offset:17408
	ds_read_b128 v[122:125], v78 offset:18432
	ds_read_b128 v[126:129], v78 offset:19456
	ds_read_b128 v[130:133], v78 offset:20480
	ds_read_b128 v[134:137], v78 offset:21504
	ds_read_b128 v[138:141], v78 offset:22528
	ds_read_b128 v[142:145], v78 offset:23552
	global_load_lds_dwordx4 v[146:147], off
	v_lshl_add_u64 v[146:147], v[220:221], 0, s[10:11]
	s_mov_b32 m0, s28
	s_nop 0
	global_load_lds_dwordx4 v[146:147], off
	s_barrier
	s_waitcnt lgkmcnt(0)
	s_waitcnt lgkmcnt(0)
	v_mfma_f32_16x16x32_bf16 v[146:149], v[4:7], v[48:51], 0
	v_mfma_f32_16x16x32_bf16 v[154:157], v[4:7], v[122:125], 0
	v_mfma_f32_16x16x32_bf16 v[162:165], v[4:7], v[130:133], 0
	v_mfma_f32_16x16x32_bf16 v[4:7], v[4:7], v[138:141], 0
	v_mfma_f32_16x16x32_bf16 v[146:149], v[8:11], v[118:121], v[146:149]
	v_mfma_f32_16x16x32_bf16 v[150:153], v[12:15], v[48:51], 0
	v_mfma_f32_16x16x32_bf16 v[154:157], v[8:11], v[126:129], v[154:157]
	v_mfma_f32_16x16x32_bf16 v[158:161], v[12:15], v[122:125], 0
	v_mfma_f32_16x16x32_bf16 v[162:165], v[8:11], v[134:137], v[162:165]
	v_mfma_f32_16x16x32_bf16 v[166:169], v[12:15], v[130:133], 0
	v_mfma_f32_16x16x32_bf16 v[4:7], v[8:11], v[142:145], v[4:7]
	v_mfma_f32_16x16x32_bf16 v[8:11], v[12:15], v[138:141], 0
	v_mfma_f32_16x16x32_bf16 v[150:153], v[16:19], v[118:121], v[150:153]
	v_mfma_f32_16x16x32_bf16 v[158:161], v[16:19], v[126:129], v[158:161]
	v_mfma_f32_16x16x32_bf16 v[166:169], v[16:19], v[134:137], v[166:169]
	v_mfma_f32_16x16x32_bf16 v[8:11], v[16:19], v[142:145], v[8:11]
	s_barrier
	s_add_u32 s22, s22, s2
	s_addc_u32 s23, s23, s3
	v_lshl_add_u64 v[222:223], s[22:23], 0, v[66:67]
	s_mov_b32 m0, s42
	v_lshl_add_u64 v[12:13], v[222:223], 0, s[10:11]
	v_lshl_add_u64 v[224:225], s[22:23], 0, v[64:65]
	global_load_lds_dwordx4 v[12:13], off
	v_lshl_add_u64 v[12:13], v[224:225], 0, s[10:11]
	s_mov_b32 m0, s43
	s_nop 0
	global_load_lds_dwordx4 v[12:13], off
	s_waitcnt vmcnt(6)
	s_barrier
	v_mfma_f32_16x16x32_bf16 v[12:15], v[98:101], v[48:51], 0
	v_mfma_f32_16x16x32_bf16 v[16:19], v[106:109], v[48:51], 0
	v_mfma_f32_16x16x32_bf16 v[12:15], v[102:105], v[118:121], v[12:15]
	v_mfma_f32_16x16x32_bf16 v[16:19], v[110:113], v[118:121], v[16:19]
	v_mfma_f32_16x16x32_bf16 v[48:51], v[98:101], v[122:125], 0
	v_mfma_f32_16x16x32_bf16 v[118:121], v[106:109], v[122:125], 0
	v_mfma_f32_16x16x32_bf16 v[122:125], v[98:101], v[130:133], 0
	v_mfma_f32_16x16x32_bf16 v[98:101], v[98:101], v[138:141], 0
	v_mfma_f32_16x16x32_bf16 v[48:51], v[102:105], v[126:129], v[48:51]
	v_mfma_f32_16x16x32_bf16 v[118:121], v[110:113], v[126:129], v[118:121]
	v_mfma_f32_16x16x32_bf16 v[122:125], v[102:105], v[134:137], v[122:125]
	v_mfma_f32_16x16x32_bf16 v[126:129], v[106:109], v[130:133], 0
	v_mfma_f32_16x16x32_bf16 v[98:101], v[102:105], v[142:145], v[98:101]
	v_mfma_f32_16x16x32_bf16 v[102:105], v[106:109], v[138:141], 0
	v_mfma_f32_16x16x32_bf16 v[126:129], v[110:113], v[134:137], v[126:129]
	v_mfma_f32_16x16x32_bf16 v[102:105], v[110:113], v[142:145], v[102:105]
	s_barrier
	ds_read_b128 v[106:109], v80
	ds_read_b128 v[110:113], v80 offset:1024
	ds_read_b128 v[130:133], v80 offset:2048
	ds_read_b128 v[134:137], v80 offset:3072
	s_mov_b32 m0, s29
	v_lshl_add_u64 v[200:201], v[0:1], 0, s[10:11]
	ds_read_b128 v[138:141], v78 offset:32768
	ds_read_b128 v[142:145], v78 offset:33792
	ds_read_b128 v[170:173], v78 offset:34816
	ds_read_b128 v[174:177], v78 offset:35840
	ds_read_b128 v[178:181], v78 offset:36864
	ds_read_b128 v[186:189], v78 offset:37888
	ds_read_b128 v[190:193], v78 offset:38912
	ds_read_b128 v[194:197], v78 offset:39936
	global_load_lds_dwordx4 v[200:201], off
	v_lshl_add_u64 v[200:201], v[2:3], 0, s[10:11]
	s_mov_b32 m0, s30
	s_nop 0
	global_load_lds_dwordx4 v[200:201], off
	s_waitcnt lgkmcnt(8)
	s_barrier
	s_waitcnt lgkmcnt(0)
	s_waitcnt lgkmcnt(0)
	v_mfma_f32_16x16x32_bf16 v[52:55], v[106:109], v[138:141], v[52:55]
	v_mfma_f32_16x16x32_bf16 v[56:59], v[130:133], v[138:141], v[56:59]
	v_mfma_f32_16x16x32_bf16 v[60:63], v[106:109], v[170:173], v[60:63]
	v_mfma_f32_16x16x32_bf16 v[68:71], v[130:133], v[170:173], v[68:71]
	v_mfma_f32_16x16x32_bf16 v[82:85], v[106:109], v[178:181], v[82:85]
	v_mfma_f32_16x16x32_bf16 v[86:89], v[130:133], v[178:181], v[86:89]
	v_mfma_f32_16x16x32_bf16 v[90:93], v[106:109], v[190:193], v[90:93]
	v_mfma_f32_16x16x32_bf16 v[94:97], v[130:133], v[190:193], v[94:97]
	v_mfma_f32_16x16x32_bf16 v[52:55], v[110:113], v[142:145], v[52:55]
	v_mfma_f32_16x16x32_bf16 v[56:59], v[134:137], v[142:145], v[56:59]
	v_mfma_f32_16x16x32_bf16 v[60:63], v[110:113], v[174:177], v[60:63]
	v_mfma_f32_16x16x32_bf16 v[68:71], v[134:137], v[174:177], v[68:71]
	v_mfma_f32_16x16x32_bf16 v[82:85], v[110:113], v[186:189], v[82:85]
	v_mfma_f32_16x16x32_bf16 v[86:89], v[134:137], v[186:189], v[86:89]
	v_mfma_f32_16x16x32_bf16 v[90:93], v[110:113], v[194:197], v[90:93]
	v_mfma_f32_16x16x32_bf16 v[94:97], v[134:137], v[194:197], v[94:97]
	s_barrier
	s_mov_b32 m0, s44
	v_lshl_add_u64 v[182:183], v[182:183], 0, s[12:13]
	ds_read_b128 v[200:203], v81
	ds_read_b128 v[204:207], v81 offset:1024
	ds_read_b128 v[208:211], v81 offset:2048
	ds_read_b128 v[212:215], v81 offset:3072
	global_load_lds_dwordx4 v[182:183], off
	v_lshl_add_u64 v[182:183], v[216:217], 0, s[12:13]
	s_mov_b32 m0, s45
	s_nop 0
	global_load_lds_dwordx4 v[182:183], off
	s_barrier
	s_waitcnt lgkmcnt(0)
	s_waitcnt lgkmcnt(0)
	v_mfma_f32_16x16x32_bf16 v[114:117], v[200:203], v[138:141], v[114:117]
	v_mfma_f32_16x16x32_bf16 v[20:23], v[208:211], v[138:141], v[20:23]
	v_mfma_f32_16x16x32_bf16 v[24:27], v[200:203], v[170:173], v[24:27]
	v_mfma_f32_16x16x32_bf16 v[28:31], v[208:211], v[170:173], v[28:31]
	v_mfma_f32_16x16x32_bf16 v[32:35], v[200:203], v[178:181], v[32:35]
	v_mfma_f32_16x16x32_bf16 v[36:39], v[208:211], v[178:181], v[36:39]
	v_mfma_f32_16x16x32_bf16 v[40:43], v[200:203], v[190:193], v[40:43]
	v_mfma_f32_16x16x32_bf16 v[44:47], v[208:211], v[190:193], v[44:47]
	v_mfma_f32_16x16x32_bf16 v[114:117], v[204:207], v[142:145], v[114:117]
	v_mfma_f32_16x16x32_bf16 v[20:23], v[212:215], v[142:145], v[20:23]
	v_mfma_f32_16x16x32_bf16 v[24:27], v[204:207], v[174:177], v[24:27]
	v_mfma_f32_16x16x32_bf16 v[28:31], v[212:215], v[174:177], v[28:31]
	v_mfma_f32_16x16x32_bf16 v[32:35], v[204:207], v[186:189], v[32:35]
	v_mfma_f32_16x16x32_bf16 v[36:39], v[212:215], v[186:189], v[36:39]
	v_mfma_f32_16x16x32_bf16 v[40:43], v[204:207], v[194:197], v[40:43]
	v_mfma_f32_16x16x32_bf16 v[44:47], v[212:215], v[194:197], v[44:47]
	s_mov_b32 m0, s31
	v_lshl_add_u64 v[182:183], v[218:219], 0, s[12:13]
	s_barrier
	ds_read_b128 v[138:141], v78 offset:49152
	ds_read_b128 v[142:145], v78 offset:50176
	ds_read_b128 v[170:173], v78 offset:51200
	ds_read_b128 v[174:177], v78 offset:52224
	ds_read_b128 v[178:181], v78 offset:53248
	ds_read_b128 v[186:189], v78 offset:54272
	ds_read_b128 v[190:193], v78 offset:55296
	ds_read_b128 v[194:197], v78 offset:56320
	global_load_lds_dwordx4 v[182:183], off
	v_lshl_add_u64 v[182:183], v[220:221], 0, s[12:13]
	s_mov_b32 m0, s33
	s_nop 0
	global_load_lds_dwordx4 v[182:183], off
	s_barrier
	s_waitcnt lgkmcnt(0)
	s_waitcnt lgkmcnt(0)
	v_mfma_f32_16x16x32_bf16 v[146:149], v[106:109], v[138:141], v[146:149]
	v_mfma_f32_16x16x32_bf16 v[150:153], v[130:133], v[138:141], v[150:153]
	v_mfma_f32_16x16x32_bf16 v[154:157], v[106:109], v[170:173], v[154:157]
	v_mfma_f32_16x16x32_bf16 v[158:161], v[130:133], v[170:173], v[158:161]
	v_mfma_f32_16x16x32_bf16 v[162:165], v[106:109], v[178:181], v[162:165]
	v_mfma_f32_16x16x32_bf16 v[166:169], v[130:133], v[178:181], v[166:169]
	v_mfma_f32_16x16x32_bf16 v[4:7], v[106:109], v[190:193], v[4:7]
	v_mfma_f32_16x16x32_bf16 v[8:11], v[130:133], v[190:193], v[8:11]
	v_mfma_f32_16x16x32_bf16 v[146:149], v[110:113], v[142:145], v[146:149]
	v_mfma_f32_16x16x32_bf16 v[150:153], v[134:137], v[142:145], v[150:153]
	v_mfma_f32_16x16x32_bf16 v[154:157], v[110:113], v[174:177], v[154:157]
	v_mfma_f32_16x16x32_bf16 v[158:161], v[134:137], v[174:177], v[158:161]
	v_mfma_f32_16x16x32_bf16 v[162:165], v[110:113], v[186:189], v[162:165]
	v_mfma_f32_16x16x32_bf16 v[166:169], v[134:137], v[186:189], v[166:169]
	v_mfma_f32_16x16x32_bf16 v[4:7], v[110:113], v[194:197], v[4:7]
	v_mfma_f32_16x16x32_bf16 v[8:11], v[134:137], v[194:197], v[8:11]
	s_barrier
	s_mov_b32 m0, s46
	v_lshl_add_u64 v[106:107], v[222:223], 0, s[12:13]
	global_load_lds_dwordx4 v[106:107], off
	v_lshl_add_u64 v[106:107], v[224:225], 0, s[12:13]
	s_mov_b32 m0, s47
	s_nop 0
	global_load_lds_dwordx4 v[106:107], off
	s_waitcnt vmcnt(6)
	s_barrier
	v_mfma_f32_16x16x32_bf16 v[12:15], v[200:203], v[138:141], v[12:15]
	v_mfma_f32_16x16x32_bf16 v[16:19], v[208:211], v[138:141], v[16:19]
	v_mfma_f32_16x16x32_bf16 v[48:51], v[200:203], v[170:173], v[48:51]
	v_mfma_f32_16x16x32_bf16 v[106:109], v[208:211], v[170:173], v[118:121]
	v_mfma_f32_16x16x32_bf16 v[110:113], v[200:203], v[178:181], v[122:125]
	v_mfma_f32_16x16x32_bf16 v[118:121], v[208:211], v[178:181], v[126:129]
	v_mfma_f32_16x16x32_bf16 v[98:101], v[200:203], v[190:193], v[98:101]
	v_mfma_f32_16x16x32_bf16 v[102:105], v[208:211], v[190:193], v[102:105]
	v_mfma_f32_16x16x32_bf16 v[12:15], v[204:207], v[142:145], v[12:15]
	v_mfma_f32_16x16x32_bf16 v[16:19], v[212:215], v[142:145], v[16:19]
	v_mfma_f32_16x16x32_bf16 v[48:51], v[204:207], v[174:177], v[48:51]
	v_mfma_f32_16x16x32_bf16 v[106:109], v[212:215], v[174:177], v[106:109]
	v_mfma_f32_16x16x32_bf16 v[110:113], v[204:207], v[186:189], v[110:113]
	v_mfma_f32_16x16x32_bf16 v[118:121], v[212:215], v[186:189], v[118:121]
	v_mfma_f32_16x16x32_bf16 v[98:101], v[204:207], v[194:197], v[98:101]
	v_mfma_f32_16x16x32_bf16 v[102:105], v[212:215], v[194:197], v[102:105]
	s_barrier
	ds_read_b128 v[122:125], v77
	ds_read_b128 v[126:129], v77 offset:1024
	ds_read_b128 v[130:133], v77 offset:2048
	ds_read_b128 v[134:137], v77 offset:3072
	s_mov_b32 m0, s38
	v_lshl_add_u64 v[0:1], v[0:1], 0, s[12:13]
	ds_read_b128 v[138:141], v78
	ds_read_b128 v[142:145], v78 offset:1024
	ds_read_b128 v[170:173], v78 offset:2048
	ds_read_b128 v[174:177], v78 offset:3072
	ds_read_b128 v[178:181], v78 offset:4096
	ds_read_b128 v[186:189], v78 offset:5120
	ds_read_b128 v[190:193], v78 offset:6144
	ds_read_b128 v[194:197], v78 offset:7168
	global_load_lds_dwordx4 v[0:1], off
	v_lshl_add_u64 v[0:1], v[2:3], 0, s[12:13]
	s_mov_b32 m0, s39
	s_nop 0
	global_load_lds_dwordx4 v[0:1], off
	s_waitcnt lgkmcnt(8)
	s_barrier
	s_waitcnt lgkmcnt(0)
	s_waitcnt lgkmcnt(0)
	v_mfma_f32_16x16x32_bf16 v[0:3], v[122:125], v[138:141], v[52:55]
	v_mfma_f32_16x16x32_bf16 v[52:55], v[130:133], v[138:141], v[56:59]
	v_mfma_f32_16x16x32_bf16 v[56:59], v[122:125], v[170:173], v[60:63]
	v_mfma_f32_16x16x32_bf16 v[60:63], v[130:133], v[170:173], v[68:71]
	v_mfma_f32_16x16x32_bf16 v[68:71], v[122:125], v[178:181], v[82:85]
	v_mfma_f32_16x16x32_bf16 v[82:85], v[130:133], v[178:181], v[86:89]
	v_mfma_f32_16x16x32_bf16 v[86:89], v[122:125], v[190:193], v[90:93]
	v_mfma_f32_16x16x32_bf16 v[90:93], v[130:133], v[190:193], v[94:97]
	v_mfma_f32_16x16x32_bf16 v[0:3], v[126:129], v[142:145], v[0:3]
	v_mfma_f32_16x16x32_bf16 v[52:55], v[134:137], v[142:145], v[52:55]
	v_mfma_f32_16x16x32_bf16 v[56:59], v[126:129], v[174:177], v[56:59]
	v_mfma_f32_16x16x32_bf16 v[60:63], v[134:137], v[174:177], v[60:63]
	v_mfma_f32_16x16x32_bf16 v[68:71], v[126:129], v[186:189], v[68:71]
	v_mfma_f32_16x16x32_bf16 v[82:85], v[134:137], v[186:189], v[82:85]
	v_mfma_f32_16x16x32_bf16 v[86:89], v[126:129], v[194:197], v[86:89]
	v_mfma_f32_16x16x32_bf16 v[90:93], v[134:137], v[194:197], v[90:93]
	s_barrier
	s_mov_b32 m0, s40
	v_lshl_add_u64 v[182:183], s[0:1], 0, v[66:67]
	ds_read_b128 v[94:97], v79
	ds_read_b128 v[200:203], v79 offset:1024
	ds_read_b128 v[204:207], v79 offset:2048
	ds_read_b128 v[208:211], v79 offset:3072
	global_load_lds_dwordx4 v[182:183], off
	v_lshl_add_u64 v[224:225], s[0:1], 0, v[64:65]
	s_mov_b32 m0, s41
	s_nop 0
	global_load_lds_dwordx4 v[224:225], off
	s_barrier
	s_waitcnt lgkmcnt(0)
	s_waitcnt lgkmcnt(0)
	v_mfma_f32_16x16x32_bf16 v[114:117], v[94:97], v[138:141], v[114:117]
	v_mfma_f32_16x16x32_bf16 v[20:23], v[204:207], v[138:141], v[20:23]
	v_mfma_f32_16x16x32_bf16 v[24:27], v[94:97], v[170:173], v[24:27]
	v_mfma_f32_16x16x32_bf16 v[28:31], v[204:207], v[170:173], v[28:31]
	v_mfma_f32_16x16x32_bf16 v[32:35], v[94:97], v[178:181], v[32:35]
	v_mfma_f32_16x16x32_bf16 v[36:39], v[204:207], v[178:181], v[36:39]
	v_mfma_f32_16x16x32_bf16 v[40:43], v[94:97], v[190:193], v[40:43]
	v_mfma_f32_16x16x32_bf16 v[44:47], v[204:207], v[190:193], v[44:47]
	v_mfma_f32_16x16x32_bf16 v[114:117], v[200:203], v[142:145], v[114:117]
	v_mfma_f32_16x16x32_bf16 v[20:23], v[208:211], v[142:145], v[20:23]
	v_mfma_f32_16x16x32_bf16 v[24:27], v[200:203], v[174:177], v[24:27]
	v_mfma_f32_16x16x32_bf16 v[28:31], v[208:211], v[174:177], v[28:31]
	v_mfma_f32_16x16x32_bf16 v[32:35], v[200:203], v[186:189], v[32:35]
	v_mfma_f32_16x16x32_bf16 v[36:39], v[208:211], v[186:189], v[36:39]
	v_mfma_f32_16x16x32_bf16 v[40:43], v[200:203], v[194:197], v[40:43]
	v_mfma_f32_16x16x32_bf16 v[44:47], v[208:211], v[194:197], v[44:47]
	s_mov_b32 m0, s27
	v_lshl_add_u64 v[240:241], s[18:19], 0, v[66:67]
	s_barrier
	ds_read_b128 v[138:141], v78 offset:16384
	ds_read_b128 v[142:145], v78 offset:17408
	ds_read_b128 v[170:173], v78 offset:18432
	ds_read_b128 v[174:177], v78 offset:19456
	ds_read_b128 v[178:181], v78 offset:20480
	ds_read_b128 v[186:189], v78 offset:21504
	ds_read_b128 v[190:193], v78 offset:22528
	ds_read_b128 v[194:197], v78 offset:23552
	global_load_lds_dwordx4 v[240:241], off
	v_lshl_add_u64 v[242:243], s[18:19], 0, v[64:65]
	s_mov_b32 m0, s28
	s_nop 0
	global_load_lds_dwordx4 v[242:243], off
	s_barrier
	s_waitcnt lgkmcnt(0)
	s_waitcnt lgkmcnt(0)
	v_mfma_f32_16x16x32_bf16 v[146:149], v[122:125], v[138:141], v[146:149]
	v_mfma_f32_16x16x32_bf16 v[150:153], v[130:133], v[138:141], v[150:153]
	v_mfma_f32_16x16x32_bf16 v[154:157], v[122:125], v[170:173], v[154:157]
	v_mfma_f32_16x16x32_bf16 v[158:161], v[130:133], v[170:173], v[158:161]
	v_mfma_f32_16x16x32_bf16 v[162:165], v[122:125], v[178:181], v[162:165]
	v_mfma_f32_16x16x32_bf16 v[166:169], v[130:133], v[178:181], v[166:169]
	v_mfma_f32_16x16x32_bf16 v[4:7], v[122:125], v[190:193], v[4:7]
	v_mfma_f32_16x16x32_bf16 v[8:11], v[130:133], v[190:193], v[8:11]
	v_mfma_f32_16x16x32_bf16 v[146:149], v[126:129], v[142:145], v[146:149]
	v_mfma_f32_16x16x32_bf16 v[150:153], v[134:137], v[142:145], v[150:153]
	v_mfma_f32_16x16x32_bf16 v[154:157], v[126:129], v[174:177], v[154:157]
	v_mfma_f32_16x16x32_bf16 v[158:161], v[134:137], v[174:177], v[158:161]
	v_mfma_f32_16x16x32_bf16 v[162:165], v[126:129], v[186:189], v[162:165]
	v_mfma_f32_16x16x32_bf16 v[166:169], v[134:137], v[186:189], v[166:169]
	v_mfma_f32_16x16x32_bf16 v[4:7], v[126:129], v[194:197], v[4:7]
	v_mfma_f32_16x16x32_bf16 v[8:11], v[134:137], v[194:197], v[8:11]
	s_barrier
	s_add_u32 s22, s0, s2
	s_addc_u32 s23, s1, s3
	s_mov_b32 m0, s42
	v_lshl_add_u64 v[244:245], s[22:23], 0, v[66:67]
	global_load_lds_dwordx4 v[244:245], off
	v_lshl_add_u64 v[246:247], s[22:23], 0, v[64:65]
	s_mov_b32 m0, s43
	s_nop 0
	global_load_lds_dwordx4 v[246:247], off
	s_waitcnt vmcnt(6)
	s_barrier
	v_mfma_f32_16x16x32_bf16 v[16:19], v[204:207], v[138:141], v[16:19]
	v_mfma_f32_16x16x32_bf16 v[122:125], v[208:211], v[142:145], v[16:19]
	v_mfma_f32_16x16x32_bf16 v[16:19], v[94:97], v[170:173], v[48:51]
	v_mfma_f32_16x16x32_bf16 v[126:129], v[200:203], v[174:177], v[16:19]
	v_mfma_f32_16x16x32_bf16 v[16:19], v[204:207], v[170:173], v[106:109]
	v_mfma_f32_16x16x32_bf16 v[106:109], v[208:211], v[174:177], v[16:19]
	v_mfma_f32_16x16x32_bf16 v[16:19], v[94:97], v[178:181], v[110:113]
	v_mfma_f32_16x16x32_bf16 v[110:113], v[200:203], v[186:189], v[16:19]
	v_mfma_f32_16x16x32_bf16 v[16:19], v[204:207], v[178:181], v[118:121]
	v_mfma_f32_16x16x32_bf16 v[118:121], v[208:211], v[186:189], v[16:19]
	v_mfma_f32_16x16x32_bf16 v[16:19], v[94:97], v[190:193], v[98:101]
	v_mfma_f32_16x16x32_bf16 v[12:15], v[94:97], v[138:141], v[12:15]
	v_mfma_f32_16x16x32_bf16 v[94:97], v[200:203], v[194:197], v[16:19]
	v_mfma_f32_16x16x32_bf16 v[16:19], v[204:207], v[190:193], v[102:105]
	v_mfma_f32_16x16x32_bf16 v[12:15], v[200:203], v[142:145], v[12:15]
	v_mfma_f32_16x16x32_bf16 v[98:101], v[208:211], v[194:197], v[16:19]
	s_barrier
	ds_read_b128 v[102:105], v80
	ds_read_b128 v[130:133], v80 offset:1024
	ds_read_b128 v[134:137], v80 offset:2048
	ds_read_b128 v[138:141], v80 offset:3072
	s_add_u32 s22, s18, s2
	s_addc_u32 s23, s19, s3
	s_mov_b32 m0, s29
	v_lshl_add_u64 v[48:49], s[22:23], 0, v[66:67]
	ds_read_b128 v[16:19], v78 offset:32768
	ds_read_b128 v[142:145], v78 offset:33792
	ds_read_b128 v[170:173], v78 offset:34816
	ds_read_b128 v[174:177], v78 offset:35840
	ds_read_b128 v[178:181], v78 offset:36864
	ds_read_b128 v[186:189], v78 offset:37888
	ds_read_b128 v[190:193], v78 offset:38912
	ds_read_b128 v[194:197], v78 offset:39936
	global_load_lds_dwordx4 v[48:49], off
	v_lshl_add_u64 v[48:49], s[22:23], 0, v[64:65]
	s_mov_b32 m0, s30
	s_nop 0
	global_load_lds_dwordx4 v[48:49], off
	s_waitcnt lgkmcnt(8)
	s_barrier
	s_waitcnt lgkmcnt(0)
	s_waitcnt lgkmcnt(0)
	v_mfma_f32_16x16x32_bf16 v[0:3], v[102:105], v[16:19], v[0:3]
	v_mfma_f32_16x16x32_bf16 v[200:203], v[130:133], v[142:145], v[0:3]
	v_mfma_f32_16x16x32_bf16 v[0:3], v[134:137], v[16:19], v[52:55]
	v_mfma_f32_16x16x32_bf16 v[204:207], v[138:141], v[142:145], v[0:3]
	v_mfma_f32_16x16x32_bf16 v[0:3], v[102:105], v[170:173], v[56:59]
	v_mfma_f32_16x16x32_bf16 v[208:211], v[130:133], v[174:177], v[0:3]
	v_mfma_f32_16x16x32_bf16 v[0:3], v[134:137], v[170:173], v[60:63]
	v_mfma_f32_16x16x32_bf16 v[212:215], v[138:141], v[174:177], v[0:3]
	v_mfma_f32_16x16x32_bf16 v[0:3], v[102:105], v[178:181], v[68:71]
	v_mfma_f32_16x16x32_bf16 v[216:219], v[130:133], v[186:189], v[0:3]
	v_mfma_f32_16x16x32_bf16 v[0:3], v[134:137], v[178:181], v[82:85]
	v_mfma_f32_16x16x32_bf16 v[82:85], v[138:141], v[186:189], v[0:3]
	v_mfma_f32_16x16x32_bf16 v[0:3], v[102:105], v[190:193], v[86:89]
	v_mfma_f32_16x16x32_bf16 v[52:55], v[130:133], v[194:197], v[0:3]
	v_mfma_f32_16x16x32_bf16 v[0:3], v[134:137], v[190:193], v[90:93]
	v_mfma_f32_16x16x32_bf16 v[48:51], v[138:141], v[194:197], v[0:3]
	s_barrier
	s_mov_b32 m0, s44
	s_nop 3
	v_lshl_add_u64 v[0:1], v[182:183], 0, s[8:9]
	ds_read_b128 v[68:71], v81
	ds_read_b128 v[86:89], v81 offset:1024
	ds_read_b128 v[90:93], v81 offset:2048
	ds_read_b128 v[220:223], v81 offset:3072
	global_load_lds_dwordx4 v[0:1], off
	v_lshl_add_u64 v[0:1], v[224:225], 0, s[8:9]
	s_mov_b32 m0, s45
	s_nop 0
	global_load_lds_dwordx4 v[0:1], off
	s_barrier
	s_waitcnt lgkmcnt(0)
	s_waitcnt lgkmcnt(0)
	v_mfma_f32_16x16x32_bf16 v[0:3], v[68:71], v[16:19], v[114:117]
	v_mfma_f32_16x16x32_bf16 v[114:117], v[86:89], v[142:145], v[0:3]
	v_mfma_f32_16x16x32_bf16 v[0:3], v[90:93], v[16:19], v[20:23]
	v_mfma_f32_16x16x32_bf16 v[142:145], v[220:223], v[142:145], v[0:3]
	v_mfma_f32_16x16x32_bf16 v[0:3], v[68:71], v[170:173], v[24:27]
	v_mfma_f32_16x16x32_bf16 v[224:227], v[86:89], v[174:177], v[0:3]
	v_mfma_f32_16x16x32_bf16 v[0:3], v[90:93], v[170:173], v[28:31]
	v_mfma_f32_16x16x32_bf16 v[170:173], v[220:223], v[174:177], v[0:3]
	v_mfma_f32_16x16x32_bf16 v[0:3], v[68:71], v[178:181], v[32:35]
	v_mfma_f32_16x16x32_bf16 v[174:177], v[86:89], v[186:189], v[0:3]
	v_mfma_f32_16x16x32_bf16 v[0:3], v[90:93], v[178:181], v[36:39]
	v_mfma_f32_16x16x32_bf16 v[178:181], v[220:223], v[186:189], v[0:3]
	v_mfma_f32_16x16x32_bf16 v[0:3], v[68:71], v[190:193], v[40:43]
	v_mfma_f32_16x16x32_bf16 v[186:189], v[86:89], v[194:197], v[0:3]
	v_mfma_f32_16x16x32_bf16 v[0:3], v[90:93], v[190:193], v[44:47]
	v_mfma_f32_16x16x32_bf16 v[60:63], v[220:223], v[194:197], v[0:3]
	s_mov_b32 m0, s31
	s_nop 4
	v_lshl_add_u64 v[0:1], v[240:241], 0, s[8:9]
	s_barrier
	ds_read_b128 v[24:27], v78 offset:49152
	ds_read_b128 v[28:31], v78 offset:50176
	ds_read_b128 v[40:43], v78 offset:51200
	ds_read_b128 v[190:193], v78 offset:52224
	ds_read_b128 v[194:197], v78 offset:53248
	ds_read_b128 v[228:231], v78 offset:54272
	ds_read_b128 v[232:235], v78 offset:55296
	ds_read_b128 v[236:239], v78 offset:56320
	global_load_lds_dwordx4 v[0:1], off
	v_lshl_add_u64 v[0:1], v[242:243], 0, s[8:9]
	s_mov_b32 m0, s33
	s_nop 0
	global_load_lds_dwordx4 v[0:1], off
	s_barrier
	s_waitcnt lgkmcnt(0)
	s_waitcnt lgkmcnt(0)
	v_mfma_f32_16x16x32_bf16 v[0:3], v[102:105], v[24:27], v[146:149]
	v_mfma_f32_16x16x32_bf16 v[146:149], v[130:133], v[28:31], v[0:3]
	v_mfma_f32_16x16x32_bf16 v[0:3], v[134:137], v[24:27], v[150:153]
	v_mfma_f32_16x16x32_bf16 v[56:59], v[138:141], v[28:31], v[0:3]
	v_mfma_f32_16x16x32_bf16 v[0:3], v[102:105], v[40:43], v[154:157]
	v_mfma_f32_16x16x32_bf16 v[36:39], v[130:133], v[190:193], v[0:3]
	v_mfma_f32_16x16x32_bf16 v[0:3], v[134:137], v[40:43], v[158:161]
	v_mfma_f32_16x16x32_bf16 v[32:35], v[138:141], v[190:193], v[0:3]
	v_mfma_f32_16x16x32_bf16 v[0:3], v[102:105], v[194:197], v[162:165]
	v_mfma_f32_16x16x32_bf16 v[20:23], v[130:133], v[228:231], v[0:3]
	v_mfma_f32_16x16x32_bf16 v[0:3], v[134:137], v[194:197], v[166:169]
	v_mfma_f32_16x16x32_bf16 v[16:19], v[138:141], v[228:231], v[0:3]
	v_mfma_f32_16x16x32_bf16 v[0:3], v[102:105], v[232:235], v[4:7]
	v_mfma_f32_16x16x32_bf16 v[4:7], v[130:133], v[236:239], v[0:3]
	v_mfma_f32_16x16x32_bf16 v[0:3], v[134:137], v[232:235], v[8:11]
	v_mfma_f32_16x16x32_bf16 v[0:3], v[138:141], v[236:239], v[0:3]
	s_barrier
	s_mov_b32 m0, s46
	v_lshl_add_u64 v[8:9], v[244:245], 0, s[8:9]
	global_load_lds_dwordx4 v[8:9], off
	v_lshl_add_u64 v[8:9], v[246:247], 0, s[8:9]
	s_mov_b32 m0, s47
	s_nop 0
	global_load_lds_dwordx4 v[8:9], off
	s_waitcnt vmcnt(6)
	s_barrier
	v_mfma_f32_16x16x32_bf16 v[8:11], v[68:71], v[24:27], v[12:15]
	v_mfma_f32_16x16x32_bf16 v[102:105], v[86:89], v[28:31], v[8:11]
	v_mfma_f32_16x16x32_bf16 v[8:11], v[90:93], v[24:27], v[122:125]
	v_mfma_f32_16x16x32_bf16 v[122:125], v[220:223], v[28:31], v[8:11]
	v_mfma_f32_16x16x32_bf16 v[8:11], v[68:71], v[40:43], v[126:129]
	v_mfma_f32_16x16x32_bf16 v[44:47], v[86:89], v[190:193], v[8:11]
	v_mfma_f32_16x16x32_bf16 v[8:11], v[90:93], v[40:43], v[106:109]
	v_mfma_f32_16x16x32_bf16 v[40:43], v[220:223], v[190:193], v[8:11]
	v_mfma_f32_16x16x32_bf16 v[8:11], v[68:71], v[194:197], v[110:113]
	v_mfma_f32_16x16x32_bf16 v[28:31], v[86:89], v[228:231], v[8:11]
	v_mfma_f32_16x16x32_bf16 v[8:11], v[90:93], v[194:197], v[118:121]
	v_mfma_f32_16x16x32_bf16 v[24:27], v[220:223], v[228:231], v[8:11]
	v_mfma_f32_16x16x32_bf16 v[8:11], v[68:71], v[232:235], v[94:97]
	v_mfma_f32_16x16x32_bf16 v[12:15], v[86:89], v[236:239], v[8:11]
	v_mfma_f32_16x16x32_bf16 v[8:11], v[90:93], v[232:235], v[98:101]
	v_mfma_f32_16x16x32_bf16 v[8:11], v[220:223], v[236:239], v[8:11]
	s_ashr_i32 s20, s20, 8
	s_ashr_i32 s21, s20, 31
	s_lshl_b64 s[20:21], s[20:21], 21
	s_add_u32 s20, s88, s20
	s_addc_u32 s21, s89, s21
	s_lshl_b32 s15, s90, 8
	v_add_u32_e32 v68, s15, v72
	v_ashrrev_i32_e32 v69, 31, v68
	v_lshlrev_b64 v[70:71], 12, v[68:69]
	v_lshl_add_u64 v[90:91], s[20:21], 0, v[70:71]
	v_lshl_or_b32 v70, s87, 8, v76
	v_ashrrev_i32_e32 v71, 31, v70
	v_lshlrev_b64 v[70:71], 2, v[70:71]
	v_pk_mul_f32 v[88:89], v[202:203], 0.5 op_sel_hi:[1,0]
	v_pk_mul_f32 v[86:87], v[200:201], 0.5 op_sel_hi:[1,0]
	v_lshl_add_u64 v[90:91], v[90:91], 0, v[70:71]
	s_barrier
	global_store_dwordx4 v[90:91], v[86:89], off
	v_pk_mul_f32 v[84:85], v[84:85], 0.5 op_sel_hi:[1,0]
	v_pk_mul_f32 v[82:83], v[82:83], 0.5 op_sel_hi:[1,0]
	v_pk_mul_f32 v[88:89], v[206:207], 0.5 op_sel_hi:[1,0]
	v_pk_mul_f32 v[86:87], v[204:205], 0.5 op_sel_hi:[1,0]
	global_store_dwordx4 v[90:91], v[86:89], off offset:64
	v_pk_mul_f32 v[50:51], v[50:51], 0.5 op_sel_hi:[1,0]
	v_pk_mul_f32 v[48:49], v[48:49], 0.5 op_sel_hi:[1,0]
	v_pk_mul_f32 v[88:89], v[116:117], 0.5 op_sel_hi:[1,0]
	v_pk_mul_f32 v[86:87], v[114:115], 0.5 op_sel_hi:[1,0]
	global_store_dwordx4 v[90:91], v[86:89], off offset:512
	v_pk_mul_f32 v[54:55], v[54:55], 0.5 op_sel_hi:[1,0]
	v_pk_mul_f32 v[52:53], v[52:53], 0.5 op_sel_hi:[1,0]
	v_pk_mul_f32 v[88:89], v[144:145], 0.5 op_sel_hi:[1,0]
	v_pk_mul_f32 v[86:87], v[142:143], 0.5 op_sel_hi:[1,0]
	global_store_dwordx4 v[90:91], v[86:89], off offset:576
	v_pk_mul_f32 v[34:35], v[34:35], 0.5 op_sel_hi:[1,0]
	v_pk_mul_f32 v[32:33], v[32:33], 0.5 op_sel_hi:[1,0]
	v_add_u32_e32 v86, s15, v73
	v_ashrrev_i32_e32 v87, 31, v86
	v_lshlrev_b64 v[86:87], 12, v[86:87]
	v_lshl_add_u64 v[90:91], s[20:21], 0, v[86:87]
	v_pk_mul_f32 v[88:89], v[210:211], 0.5 op_sel_hi:[1,0]
	v_pk_mul_f32 v[86:87], v[208:209], 0.5 op_sel_hi:[1,0]
	v_lshl_add_u64 v[90:91], v[90:91], 0, v[70:71]
	global_store_dwordx4 v[90:91], v[86:89], off
	v_pk_mul_f32 v[18:19], v[18:19], 0.5 op_sel_hi:[1,0]
	v_pk_mul_f32 v[16:17], v[16:17], 0.5 op_sel_hi:[1,0]
	v_pk_mul_f32 v[88:89], v[214:215], 0.5 op_sel_hi:[1,0]
	v_pk_mul_f32 v[86:87], v[212:213], 0.5 op_sel_hi:[1,0]
	global_store_dwordx4 v[90:91], v[86:89], off offset:64
	v_pk_mul_f32 v[2:3], v[2:3], 0.5 op_sel_hi:[1,0]
	v_pk_mul_f32 v[0:1], v[0:1], 0.5 op_sel_hi:[1,0]
	v_pk_mul_f32 v[88:89], v[226:227], 0.5 op_sel_hi:[1,0]
	v_pk_mul_f32 v[86:87], v[224:225], 0.5 op_sel_hi:[1,0]
	global_store_dwordx4 v[90:91], v[86:89], off offset:512
	v_pk_mul_f32 v[38:39], v[38:39], 0.5 op_sel_hi:[1,0]
	v_pk_mul_f32 v[36:37], v[36:37], 0.5 op_sel_hi:[1,0]
	v_pk_mul_f32 v[88:89], v[172:173], 0.5 op_sel_hi:[1,0]
	v_pk_mul_f32 v[86:87], v[170:171], 0.5 op_sel_hi:[1,0]
	global_store_dwordx4 v[90:91], v[86:89], off offset:576
	v_pk_mul_f32 v[22:23], v[22:23], 0.5 op_sel_hi:[1,0]
	v_pk_mul_f32 v[20:21], v[20:21], 0.5 op_sel_hi:[1,0]
	v_add_u32_e32 v86, s15, v74
	v_ashrrev_i32_e32 v87, 31, v86
	v_lshlrev_b64 v[86:87], 12, v[86:87]
	v_lshl_add_u64 v[90:91], s[20:21], 0, v[86:87]
	v_lshl_add_u64 v[90:91], v[90:91], 0, v[70:71]
	global_store_dwordx4 v[90:91], v[82:85], off offset:64
	v_pk_mul_f32 v[88:89], v[218:219], 0.5 op_sel_hi:[1,0]
	v_pk_mul_f32 v[86:87], v[216:217], 0.5 op_sel_hi:[1,0]
	v_pk_mul_f32 v[84:85], v[176:177], 0.5 op_sel_hi:[1,0]
	v_pk_mul_f32 v[82:83], v[174:175], 0.5 op_sel_hi:[1,0]
	global_store_dwordx4 v[90:91], v[82:85], off offset:512
	v_pk_mul_f32 v[6:7], v[6:7], 0.5 op_sel_hi:[1,0]
	v_pk_mul_f32 v[4:5], v[4:5], 0.5 op_sel_hi:[1,0]
	v_pk_mul_f32 v[84:85], v[180:181], 0.5 op_sel_hi:[1,0]
	v_pk_mul_f32 v[82:83], v[178:179], 0.5 op_sel_hi:[1,0]
	global_store_dwordx4 v[90:91], v[82:85], off offset:576
	s_add_i32 s36, s36, s37
	s_andn2_b64 vcc, exec, s[16:17]
	v_add_u32_e32 v82, s15, v75
	v_ashrrev_i32_e32 v83, 31, v82
	v_lshlrev_b64 v[82:83], 12, v[82:83]
	v_lshl_add_u64 v[82:83], s[20:21], 0, v[82:83]
	v_lshl_add_u64 v[82:83], v[82:83], 0, v[70:71]
	global_store_dwordx4 v[82:83], v[48:51], off offset:64
	global_store_dwordx4 v[82:83], v[52:55], off
	s_mov_b32 s87, s48
	v_pk_mul_f32 v[50:51], v[188:189], 0.5 op_sel_hi:[1,0]
	v_pk_mul_f32 v[48:49], v[186:187], 0.5 op_sel_hi:[1,0]
	global_store_dwordx4 v[82:83], v[48:51], off offset:512
	s_mov_b32 s90, s49
	s_mov_b64 s[22:23], s[0:1]
	v_pk_mul_f32 v[50:51], v[62:63], 0.5 op_sel_hi:[1,0]
	v_pk_mul_f32 v[48:49], v[60:61], 0.5 op_sel_hi:[1,0]
	global_store_dwordx4 v[82:83], v[48:51], off offset:576
	s_mov_b64 s[24:25], s[18:19]
	global_store_dwordx4 v[90:91], v[86:89], off
	v_add_u32_e32 v48, 0x80, v68
	v_ashrrev_i32_e32 v49, 31, v48
	v_lshlrev_b64 v[48:49], 12, v[48:49]
	v_lshl_add_u64 v[52:53], s[20:21], 0, v[48:49]
	v_pk_mul_f32 v[50:51], v[148:149], 0.5 op_sel_hi:[1,0]
	v_pk_mul_f32 v[48:49], v[146:147], 0.5 op_sel_hi:[1,0]
	v_lshl_add_u64 v[52:53], v[52:53], 0, v[70:71]
	global_store_dwordx4 v[52:53], v[48:51], off
	s_nop 1
	v_pk_mul_f32 v[50:51], v[58:59], 0.5 op_sel_hi:[1,0]
	v_pk_mul_f32 v[48:49], v[56:57], 0.5 op_sel_hi:[1,0]
	global_store_dwordx4 v[52:53], v[48:51], off offset:64
	s_nop 1
	v_pk_mul_f32 v[50:51], v[104:105], 0.5 op_sel_hi:[1,0]
	v_pk_mul_f32 v[48:49], v[102:103], 0.5 op_sel_hi:[1,0]
	global_store_dwordx4 v[52:53], v[48:51], off offset:512
	s_nop 1
	v_pk_mul_f32 v[50:51], v[124:125], 0.5 op_sel_hi:[1,0]
	v_pk_mul_f32 v[48:49], v[122:123], 0.5 op_sel_hi:[1,0]
	global_store_dwordx4 v[52:53], v[48:51], off offset:576
	s_nop 1
	v_add_u32_e32 v48, 0x90, v68
	v_ashrrev_i32_e32 v49, 31, v48
	v_lshlrev_b64 v[48:49], 12, v[48:49]
	v_lshl_add_u64 v[48:49], s[20:21], 0, v[48:49]
	v_lshl_add_u64 v[48:49], v[48:49], 0, v[70:71]
	global_store_dwordx4 v[48:49], v[32:35], off offset:64
	global_store_dwordx4 v[48:49], v[36:39], off
	s_nop 0
	v_pk_mul_f32 v[34:35], v[46:47], 0.5 op_sel_hi:[1,0]
	v_pk_mul_f32 v[32:33], v[44:45], 0.5 op_sel_hi:[1,0]
	global_store_dwordx4 v[48:49], v[32:35], off offset:512
	s_nop 1
	v_pk_mul_f32 v[34:35], v[42:43], 0.5 op_sel_hi:[1,0]
	v_pk_mul_f32 v[32:33], v[40:41], 0.5 op_sel_hi:[1,0]
	global_store_dwordx4 v[48:49], v[32:35], off offset:576
	s_nop 1
	v_add_u32_e32 v32, 0xa0, v68
	v_ashrrev_i32_e32 v33, 31, v32
	v_lshlrev_b64 v[32:33], 12, v[32:33]
	v_lshl_add_u64 v[32:33], s[20:21], 0, v[32:33]
	v_lshl_add_u64 v[32:33], v[32:33], 0, v[70:71]
	global_store_dwordx4 v[32:33], v[16:19], off offset:64
	global_store_dwordx4 v[32:33], v[20:23], off
	s_nop 0
	v_pk_mul_f32 v[18:19], v[30:31], 0.5 op_sel_hi:[1,0]
	v_pk_mul_f32 v[16:17], v[28:29], 0.5 op_sel_hi:[1,0]
	global_store_dwordx4 v[32:33], v[16:19], off offset:512
	s_nop 1
	v_pk_mul_f32 v[18:19], v[26:27], 0.5 op_sel_hi:[1,0]
	v_pk_mul_f32 v[16:17], v[24:25], 0.5 op_sel_hi:[1,0]
	global_store_dwordx4 v[32:33], v[16:19], off offset:576
	s_nop 1
	v_add_u32_e32 v16, 0xb0, v68
	v_ashrrev_i32_e32 v17, 31, v16
	v_lshlrev_b64 v[16:17], 12, v[16:17]
	v_lshl_add_u64 v[16:17], s[20:21], 0, v[16:17]
	v_lshl_add_u64 v[16:17], v[16:17], 0, v[70:71]
	global_store_dwordx4 v[16:17], v[0:3], off offset:64
	s_mov_b32 s20, s14
	global_store_dwordx4 v[16:17], v[4:7], off
	v_pk_mul_f32 v[2:3], v[14:15], 0.5 op_sel_hi:[1,0]
	v_pk_mul_f32 v[0:1], v[12:13], 0.5 op_sel_hi:[1,0]
	global_store_dwordx4 v[16:17], v[0:3], off offset:512
	s_nop 1
	v_pk_mul_f32 v[2:3], v[10:11], 0.5 op_sel_hi:[1,0]
	v_pk_mul_f32 v[0:1], v[8:9], 0.5 op_sel_hi:[1,0]
	global_store_dwordx4 v[16:17], v[0:3], off offset:576
	s_cbranch_vccz .LBB0_1903
